# baseline (speedup 1.0000x reference)
;     DI size_t aoff(const Unit& u, size_t tstep) const { return (size_t)u.pm * tstep; }
;     DI size_t boff(const Unit& u, size_t tstep) const { return (size_t)u.pn * tstep; }
;     DI bool next(int i, Unit& u) const { const long L = (long)i * G + c; if (L >= np) return false; u.pm = pmv; u.pn = (int)(L % nN); u.ks = (int)(L / nN); return true; }
;     DI size_t aoff(const Unit& u, size_t) const { return (size_t)u.ks * kbytes; }
;     DI size_t boff(const Unit& u, size_t tstep) const { return (size_t)u.pn * tstep + (size_t)u.ks * kbytes; }
;     DI bool next(int i, Unit& u) const { Unit t; if (!S.next(i / 3, t)) return false; u.pm = t.pm; u.pn = t.pn; u.ks = i % 3; return true; }
;     DI size_t aoff(const Unit& u, size_t tstep) const { return (u.ks < 2 ? offU : offOA) + (size_t)u.pm * tstep; }
; #define PG8_LDA(dst, b, h) do { _Pragma("unroll") for (int m = 0; m < 4; ++m) _Pragma("unroll") for (int k = 0; k < 2; ++k) dst[m][k] = *(const LAS bf16x8*)(lds + PG8_SA(b, h) + aoff + m * 2048 + k * 1024); } while (0)
; template <class Epi, class Sched>
; DI void gemm_phase(LAS unsigned char* lds, const Gemm g, const Sched& S, const Epi& E) {
;     ...
;         const bool has_next = S.next(ui + 1, nxt);
;         const char* nA = has_next ? (const char*)g.A + S.aoff(nxt, tstep) : cA; const char* nB = has_next ? (const char*)g.Bt + S.boff(nxt, tstep) : cB;
;         for (int t = 0; t < nt; t += 2) {
;             if constexpr (Epi::HAS_MID) { if (t == E.mid_t(nt)) { int fr3 = fr, fq3 = fq; asm volatile("" : "+v"(fr3), "+v"(fq3)); E.mid(acc, cur, wr, wc, fr3, fq3); } }
;             const bool last = (t == nt - 2);
;             const char* a1 = cA + (size_t)(t + 1) * kstep;
;             const char* a2 = last ? nA : cA + (size_t)(t + 2) * kstep; const char* b2 = last ? nB : cB + (size_t)(t + 2) * kstep;
;             const char* a3 = a2 + kstep; const char* b3 = b2 + kstep;
;             PG8_LDB(B0, 0, 0); PG8_SCHED; PG8_LDA(At, 0, 0); PG8_STAGE(PG8_SA(1, 1), a1 + hstep, voffA);
;             PG8_WAIT_L(8); PG8_BAR; PG8_WAIT_L(0); PG8_MMA(0, 0, At, B0); PG8_BAR; PG8_SCHED;
;             PG8_LDB(B1, 0, 1); PG8_STAGE(PG8_SB(0, 0), b2, voffB);
;             PG8_BAR; PG8_WAIT_L(0); PG8_MMA(0, 1, At, B1); PG8_BAR;
;             PG8_LDA(At, 0, 1); PG8_STAGE(PG8_SA(0, 0), a2, voffA);
;             PG8_BAR; PG8_WAIT_L(0); PG8_MMA(1, 0, At, B0); PG8_BAR; PG8_SCHED;
.LBB0_218:
	s_ashr_i32 s17, s16, 31
	s_lshl_b64 s[0:1], s[16:17], 20
	v_cmp_lt_i64_e32 vcc, s[18:19], v[140:141]
	s_add_u32 s18, s47, s0
	s_addc_u32 s19, s48, s1
	s_and_b64 s[0:1], vcc, exec
	s_cselect_b32 s17, s19, s41
	s_cselect_b32 s65, s18, s40
	s_ashr_i32 s15, s14, 31
	s_lshl_b64 s[0:1], s[14:15], 20
	s_add_u32 s36, s49, s0
	s_addc_u32 s37, s50, s1
	s_and_b64 s[0:1], vcc, exec
	s_cselect_b32 s15, s37, s43
	s_cselect_b32 s66, s36, s42
	s_add_u32 s40, s40, 0x80080
	s_addc_u32 s41, s41, 0
	s_add_u32 s67, s42, 0x100
	v_mov_b32_e32 v0, 0
	s_addc_u32 s68, s43, 0
	s_mov_b32 s69, -2
	ds_read_b128 v[150:153], v147
	ds_read_b128 v[154:157], v147 offset:1024
	ds_read_b128 v[162:165], v147 offset:2048
	ds_read_b128 v[166:169], v147 offset:3072
	s_add_u32 s0, s40, 0xfff80080
	s_addc_u32 s1, s41, -1
	s_cmp_eq_u32 s69, 28
	s_cselect_b32 s45, s17, s1
	s_cselect_b32 s44, s65, s0
	s_cselect_b32 s43, s15, s68
	s_cselect_b32 s42, s66, s67
	s_add_i32 m0, s39, 0xc000
	ds_read_b128 v[170:173], v148
	ds_read_b128 v[174:177], v148 offset:1024
	ds_read_b128 v[178:181], v148 offset:2048
	ds_read_b128 v[188:191], v148 offset:3072
	ds_read_b128 v[194:197], v148 offset:4096
	ds_read_b128 v[198:201], v148 offset:5120
	ds_read_b128 v[202:205], v148 offset:6144
	global_load_lds_dwordx4 v136, s[40:41]
	s_add_i32 m0, s39, 0xe000
	ds_read_b128 v[206:209], v148 offset:7168
	global_load_lds_dwordx4 v138, s[40:41]
	s_waitcnt lgkmcnt(8)
	s_barrier
	s_waitcnt lgkmcnt(0)
	s_setprio 1
	v_mfma_f32_16x16x32_bf16 v[124:127], v[150:153], v[170:173], 0
	v_mfma_f32_16x16x32_bf16 v[120:123], v[162:165], v[170:173], 0
	v_mfma_f32_16x16x32_bf16 v[108:111], v[150:153], v[178:181], 0
	v_mfma_f32_16x16x32_bf16 v[104:107], v[162:165], v[178:181], 0
	v_mfma_f32_16x16x32_bf16 v[92:95], v[150:153], v[194:197], 0
	v_mfma_f32_16x16x32_bf16 v[88:91], v[162:165], v[194:197], 0
	v_mfma_f32_16x16x32_bf16 v[76:79], v[150:153], v[202:205], 0
	v_mfma_f32_16x16x32_bf16 v[72:75], v[162:165], v[202:205], 0
	v_mfma_f32_16x16x32_bf16 v[124:127], v[154:157], v[174:177], v[124:127]
	v_mfma_f32_16x16x32_bf16 v[120:123], v[166:169], v[174:177], v[120:123]
	v_mfma_f32_16x16x32_bf16 v[108:111], v[154:157], v[188:191], v[108:111]
	v_mfma_f32_16x16x32_bf16 v[104:107], v[166:169], v[188:191], v[104:107]
	v_mfma_f32_16x16x32_bf16 v[92:95], v[154:157], v[198:201], v[92:95]
	v_mfma_f32_16x16x32_bf16 v[88:91], v[166:169], v[198:201], v[88:91]
	v_mfma_f32_16x16x32_bf16 v[76:79], v[154:157], v[206:209], v[76:79]
	v_mfma_f32_16x16x32_bf16 v[72:75], v[166:169], v[206:209], v[72:75]
	s_setprio 0
	s_barrier
	s_add_i32 s0, s34, s52
	s_mov_b32 s12, s0
	s_mov_b32 m0, s0
	ds_read_b128 v[210:213], v149
	ds_read_b128 v[214:217], v149 offset:1024
	ds_read_b128 v[218:221], v149 offset:2048
	global_load_lds_dwordx4 v130, s[42:43]
	s_add_i32 m0, s0, 0x2000
	ds_read_b128 v[222:225], v149 offset:3072
	global_load_lds_dwordx4 v134, s[42:43]
	s_barrier
	s_waitcnt lgkmcnt(0)
	s_setprio 1
	v_mfma_f32_16x16x32_bf16 v[116:119], v[210:213], v[170:173], 0
	v_mfma_f32_16x16x32_bf16 v[112:115], v[218:221], v[170:173], 0
	v_mfma_f32_16x16x32_bf16 v[100:103], v[210:213], v[178:181], 0
	v_mfma_f32_16x16x32_bf16 v[96:99], v[218:221], v[178:181], 0
	v_mfma_f32_16x16x32_bf16 v[84:87], v[210:213], v[194:197], 0
	v_mfma_f32_16x16x32_bf16 v[80:83], v[218:221], v[194:197], 0
	v_mfma_f32_16x16x32_bf16 v[68:71], v[210:213], v[202:205], 0
	v_mfma_f32_16x16x32_bf16 v[64:67], v[218:221], v[202:205], 0
	v_mfma_f32_16x16x32_bf16 v[116:119], v[214:217], v[174:177], v[116:119]
	v_mfma_f32_16x16x32_bf16 v[112:115], v[222:225], v[174:177], v[112:115]
	v_mfma_f32_16x16x32_bf16 v[100:103], v[214:217], v[188:191], v[100:103]
	v_mfma_f32_16x16x32_bf16 v[96:99], v[222:225], v[188:191], v[96:99]
	v_mfma_f32_16x16x32_bf16 v[84:87], v[214:217], v[198:201], v[84:87]
	v_mfma_f32_16x16x32_bf16 v[80:83], v[222:225], v[198:201], v[80:83]
	v_mfma_f32_16x16x32_bf16 v[68:71], v[214:217], v[206:209], v[68:71]
	v_mfma_f32_16x16x32_bf16 v[64:67], v[222:225], v[206:209], v[64:67]
	s_setprio 0
	s_mov_b32 m0, s39
	s_barrier
	ds_read_b128 v[170:173], v148 offset:16384
	ds_read_b128 v[174:177], v148 offset:17408
	ds_read_b128 v[178:181], v148 offset:18432
	ds_read_b128 v[188:191], v148 offset:19456
	ds_read_b128 v[194:197], v148 offset:20480
	ds_read_b128 v[198:201], v148 offset:21504
	ds_read_b128 v[202:205], v148 offset:22528
	global_load_lds_dwordx4 v128, s[44:45]
	s_mov_b32 m0, s53
	ds_read_b128 v[206:209], v148 offset:23552
	global_load_lds_dwordx4 v132, s[44:45]
	s_barrier
	s_waitcnt lgkmcnt(0)
	s_setprio 1
	v_mfma_f32_16x16x32_bf16 v[60:63], v[150:153], v[170:173], 0
	v_mfma_f32_16x16x32_bf16 v[56:59], v[162:165], v[170:173], 0
	v_mfma_f32_16x16x32_bf16 v[44:47], v[150:153], v[178:181], 0
	v_mfma_f32_16x16x32_bf16 v[40:43], v[162:165], v[178:181], 0
	v_mfma_f32_16x16x32_bf16 v[28:31], v[150:153], v[194:197], 0
	v_mfma_f32_16x16x32_bf16 v[24:27], v[162:165], v[194:197], 0
	v_mfma_f32_16x16x32_bf16 v[12:15], v[150:153], v[202:205], 0
	v_mfma_f32_16x16x32_bf16 v[8:11], v[162:165], v[202:205], 0
	v_mfma_f32_16x16x32_bf16 v[60:63], v[154:157], v[174:177], v[60:63]
	v_mfma_f32_16x16x32_bf16 v[56:59], v[166:169], v[174:177], v[56:59]
	v_mfma_f32_16x16x32_bf16 v[44:47], v[154:157], v[188:191], v[44:47]
	v_mfma_f32_16x16x32_bf16 v[40:43], v[166:169], v[188:191], v[40:43]
	v_mfma_f32_16x16x32_bf16 v[28:31], v[154:157], v[198:201], v[28:31]
	v_mfma_f32_16x16x32_bf16 v[24:27], v[166:169], v[198:201], v[24:27]
	v_mfma_f32_16x16x32_bf16 v[12:15], v[154:157], v[206:209], v[12:15]
	v_mfma_f32_16x16x32_bf16 v[8:11], v[166:169], v[206:209], v[8:11]
	s_setprio 0
	s_barrier
; #define PG8_STAGE(bufoff, gbase, voff) do { _Pragma("unroll") for (int _i = 0; _i < 2; ++_i) \
;         __builtin_amdgcn_global_load_lds((const unsigned*)((const char*)(gbase) + (voff)[_i]), (LAS unsigned*)(lds + (bufoff) + ldsw + _i * 8192), 16, 0, 0); } while (0)
; #define PG8_LDA(dst, b, h) do { _Pragma("unroll") for (int m = 0; m < 4; ++m) _Pragma("unroll") for (int k = 0; k < 2; ++k) dst[m][k] = *(const LAS bf16x8*)(lds + PG8_SA(b, h) + aoff + m * 2048 + k * 1024); } while (0)
; #define PG8_LDB(dst, b, h) do { _Pragma("unroll") for (int n = 0; n < 2; ++n) _Pragma("unroll") for (int k = 0; k < 2; ++k) dst[n][k] = *(const LAS bf16x8*)(lds + PG8_SB(b, h) + boff + n * 2048 + k * 1024); } while (0)
; #define PG8_MMA(ai, bj, At, Bt) do { __builtin_amdgcn_s_setprio(1); _Pragma("unroll") for (int m = 0; m < 4; ++m) _Pragma("unroll") for (int n = 0; n < 2; ++n) _Pragma("unroll") for (int k = 0; k < 2; ++k) \
;         acc[ai][bj][m][n] = __builtin_amdgcn_mfma_f32_16x16x32_bf16(Bt[n][k], At[m][k], acc[ai][bj][m][n], 0, 0, 0); __builtin_amdgcn_s_setprio(0); } while (0)
; #define PG8_WAIT_V(n) asm volatile("s_waitcnt vmcnt(" #n ")" ::: "memory")
; #define PG8_WAIT_L(n) asm volatile("s_waitcnt lgkmcnt(" #n ")" ::: "memory")
; #define PG8_BAR __builtin_amdgcn_s_barrier()
; #define PG8_SCHED __builtin_amdgcn_sched_barrier(0)
; template <class Epi, class Sched>
; DI void gemm_phase(LAS unsigned char* lds, const Gemm g, const Sched& S, const Epi& E) {
;     ...
;             PG8_STAGE(PG8_SB(0, 1), b2 + hstep, voffB);
;             PG8_WAIT_V(6); PG8_BAR; PG8_MMA(1, 1, At, B1); PG8_BAR;
;             PG8_LDB(B0, 1, 0); PG8_SCHED; PG8_LDA(At, 1, 0); PG8_STAGE(PG8_SA(0, 1), a2 + hstep, voffA);
;             PG8_WAIT_L(8); PG8_BAR; PG8_WAIT_L(0); PG8_MMA(0, 0, At, B0); PG8_BAR; PG8_SCHED;
;             PG8_LDB(B1, 1, 1); PG8_STAGE(PG8_SB(1, 0), b3, voffB);
;             PG8_BAR; PG8_WAIT_L(0); PG8_MMA(0, 1, At, B1); PG8_BAR;
;             PG8_LDA(At, 1, 1); PG8_STAGE(PG8_SA(1, 0), a3, voffA);
	s_add_i32 s4, s35, s52
	s_mov_b32 s13, s4
	s_mov_b32 m0, s4
	s_add_u32 s0, s42, 0x80000
	s_addc_u32 s1, s43, 0
	global_load_lds_dwordx4 v130, s[0:1]
	s_add_i32 m0, s4, 0x2000
	s_nop 0
	global_load_lds_dwordx4 v134, s[0:1]
	s_waitcnt vmcnt(6)
	s_barrier
	s_setprio 1
	v_mfma_f32_16x16x32_bf16 v[52:55], v[210:213], v[170:173], 0
	v_mfma_f32_16x16x32_bf16 v[48:51], v[218:221], v[170:173], 0
	v_mfma_f32_16x16x32_bf16 v[36:39], v[210:213], v[178:181], 0
	v_mfma_f32_16x16x32_bf16 v[32:35], v[218:221], v[178:181], 0
	v_mfma_f32_16x16x32_bf16 v[20:23], v[210:213], v[194:197], 0
	v_mfma_f32_16x16x32_bf16 v[16:19], v[218:221], v[194:197], 0
	v_mfma_f32_16x16x32_bf16 v[4:7], v[210:213], v[202:205], 0
	v_mfma_f32_16x16x32_bf16 v[0:3], v[218:221], v[202:205], 0
	v_mfma_f32_16x16x32_bf16 v[52:55], v[214:217], v[174:177], v[52:55]
	v_mfma_f32_16x16x32_bf16 v[48:51], v[222:225], v[174:177], v[48:51]
	v_mfma_f32_16x16x32_bf16 v[36:39], v[214:217], v[188:191], v[36:39]
	v_mfma_f32_16x16x32_bf16 v[32:35], v[222:225], v[188:191], v[32:35]
	v_mfma_f32_16x16x32_bf16 v[20:23], v[214:217], v[198:201], v[20:23]
	v_mfma_f32_16x16x32_bf16 v[16:19], v[222:225], v[198:201], v[16:19]
	v_mfma_f32_16x16x32_bf16 v[4:7], v[214:217], v[206:209], v[4:7]
	v_mfma_f32_16x16x32_bf16 v[0:3], v[222:225], v[206:209], v[0:3]
	s_setprio 0
	s_add_i32 s4, 0, 0x18000
	v_add_u32_e32 v158, s4, v146
	s_barrier
	ds_read_b128 v[150:153], v158
	ds_read_b128 v[154:157], v158 offset:1024
	ds_read_b128 v[162:165], v158 offset:2048
	ds_read_b128 v[166:169], v158 offset:3072
	s_add_u32 s0, s44, 0x80000
	s_addc_u32 s1, s45, 0
	s_mov_b32 m0, s54
	ds_read_b128 v[170:173], v148 offset:32768
	ds_read_b128 v[174:177], v148 offset:33792
	ds_read_b128 v[178:181], v148 offset:34816
	ds_read_b128 v[188:191], v148 offset:35840
	ds_read_b128 v[194:197], v148 offset:36864
	ds_read_b128 v[198:201], v148 offset:37888
	ds_read_b128 v[202:205], v148 offset:38912
	global_load_lds_dwordx4 v128, s[0:1]
	s_mov_b32 m0, s55
	ds_read_b128 v[206:209], v148 offset:39936
	global_load_lds_dwordx4 v132, s[0:1]
	s_waitcnt lgkmcnt(8)
	s_barrier
	s_waitcnt lgkmcnt(0)
	s_setprio 1
	v_mfma_f32_16x16x32_bf16 v[124:127], v[150:153], v[170:173], v[124:127]
	v_mfma_f32_16x16x32_bf16 v[120:123], v[162:165], v[170:173], v[120:123]
	v_mfma_f32_16x16x32_bf16 v[108:111], v[150:153], v[178:181], v[108:111]
	v_mfma_f32_16x16x32_bf16 v[104:107], v[162:165], v[178:181], v[104:107]
	v_mfma_f32_16x16x32_bf16 v[92:95], v[150:153], v[194:197], v[92:95]
	v_mfma_f32_16x16x32_bf16 v[88:91], v[162:165], v[194:197], v[88:91]
	v_mfma_f32_16x16x32_bf16 v[76:79], v[150:153], v[202:205], v[76:79]
	v_mfma_f32_16x16x32_bf16 v[72:75], v[162:165], v[202:205], v[72:75]
	v_mfma_f32_16x16x32_bf16 v[124:127], v[154:157], v[174:177], v[124:127]
	v_mfma_f32_16x16x32_bf16 v[120:123], v[166:169], v[174:177], v[120:123]
	v_mfma_f32_16x16x32_bf16 v[108:111], v[154:157], v[188:191], v[108:111]
	v_mfma_f32_16x16x32_bf16 v[104:107], v[166:169], v[188:191], v[104:107]
	v_mfma_f32_16x16x32_bf16 v[92:95], v[154:157], v[198:201], v[92:95]
	v_mfma_f32_16x16x32_bf16 v[88:91], v[166:169], v[198:201], v[88:91]
	v_mfma_f32_16x16x32_bf16 v[76:79], v[154:157], v[206:209], v[76:79]
	v_mfma_f32_16x16x32_bf16 v[72:75], v[166:169], v[206:209], v[72:75]
	s_setprio 0
	s_barrier
	s_add_i32 s5, 0, 0x1c000
	s_add_i32 s0, s4, s52
	s_mov_b32 s32, s0
	v_add_u32_e32 v159, s5, v146
	s_add_i32 m0, s0, 0xffffff80
	ds_read_b128 v[210:213], v159
	ds_read_b128 v[214:217], v159 offset:1024
	ds_read_b128 v[218:221], v159 offset:2048
	global_load_lds_dwordx4 v130, s[42:43] offset:128
	s_add_i32 m0, s0, 0x1f80
	ds_read_b128 v[222:225], v159 offset:3072
	global_load_lds_dwordx4 v134, s[42:43] offset:128
	s_barrier
	s_waitcnt lgkmcnt(0)
	s_setprio 1
	v_mfma_f32_16x16x32_bf16 v[116:119], v[210:213], v[170:173], v[116:119]
	v_mfma_f32_16x16x32_bf16 v[112:115], v[218:221], v[170:173], v[112:115]
	v_mfma_f32_16x16x32_bf16 v[100:103], v[210:213], v[178:181], v[100:103]
	v_mfma_f32_16x16x32_bf16 v[96:99], v[218:221], v[178:181], v[96:99]
	v_mfma_f32_16x16x32_bf16 v[84:87], v[210:213], v[194:197], v[84:87]
	v_mfma_f32_16x16x32_bf16 v[80:83], v[218:221], v[194:197], v[80:83]
	v_mfma_f32_16x16x32_bf16 v[68:71], v[210:213], v[202:205], v[68:71]
	v_mfma_f32_16x16x32_bf16 v[64:67], v[218:221], v[202:205], v[64:67]
	v_mfma_f32_16x16x32_bf16 v[116:119], v[214:217], v[174:177], v[116:119]
	v_mfma_f32_16x16x32_bf16 v[112:115], v[222:225], v[174:177], v[112:115]
	v_mfma_f32_16x16x32_bf16 v[100:103], v[214:217], v[188:191], v[100:103]
	v_mfma_f32_16x16x32_bf16 v[96:99], v[222:225], v[188:191], v[96:99]
	v_mfma_f32_16x16x32_bf16 v[84:87], v[214:217], v[198:201], v[84:87]
	v_mfma_f32_16x16x32_bf16 v[80:83], v[222:225], v[198:201], v[80:83]
	v_mfma_f32_16x16x32_bf16 v[68:71], v[214:217], v[206:209], v[68:71]
	v_mfma_f32_16x16x32_bf16 v[64:67], v[222:225], v[206:209], v[64:67]
	s_setprio 0
	s_add_i32 m0, s59, 0xffffff80
	s_barrier
	ds_read_b128 v[170:173], v148 offset:49152
	ds_read_b128 v[174:177], v148 offset:50176
	ds_read_b128 v[178:181], v148 offset:51200
	ds_read_b128 v[188:191], v148 offset:52224
	ds_read_b128 v[194:197], v148 offset:53248
	ds_read_b128 v[198:201], v148 offset:54272
	ds_read_b128 v[202:205], v148 offset:55296
	global_load_lds_dwordx4 v128, s[44:45] offset:128
	s_add_i32 m0, s60, 0xffffff80
	ds_read_b128 v[206:209], v148 offset:56320
	global_load_lds_dwordx4 v132, s[44:45] offset:128
	s_barrier
; #define PG8_STAGE(bufoff, gbase, voff) do { _Pragma("unroll") for (int _i = 0; _i < 2; ++_i) \
;         __builtin_amdgcn_global_load_lds((const unsigned*)((const char*)(gbase) + (voff)[_i]), (LAS unsigned*)(lds + (bufoff) + ldsw + _i * 8192), 16, 0, 0); } while (0)
; #define PG8_LDA(dst, b, h) do { _Pragma("unroll") for (int m = 0; m < 4; ++m) _Pragma("unroll") for (int k = 0; k < 2; ++k) dst[m][k] = *(const LAS bf16x8*)(lds + PG8_SA(b, h) + aoff + m * 2048 + k * 1024); } while (0)
; #define PG8_LDB(dst, b, h) do { _Pragma("unroll") for (int n = 0; n < 2; ++n) _Pragma("unroll") for (int k = 0; k < 2; ++k) dst[n][k] = *(const LAS bf16x8*)(lds + PG8_SB(b, h) + boff + n * 2048 + k * 1024); } while (0)
; #define PG8_MMA(ai, bj, At, Bt) do { __builtin_amdgcn_s_setprio(1); _Pragma("unroll") for (int m = 0; m < 4; ++m) _Pragma("unroll") for (int n = 0; n < 2; ++n) _Pragma("unroll") for (int k = 0; k < 2; ++k) \
;         acc[ai][bj][m][n] = __builtin_amdgcn_mfma_f32_16x16x32_bf16(Bt[n][k], At[m][k], acc[ai][bj][m][n], 0, 0, 0); __builtin_amdgcn_s_setprio(0); } while (0)
; #define PG8_WAIT_V(n) asm volatile("s_waitcnt vmcnt(" #n ")" ::: "memory")
; #define PG8_WAIT_L(n) asm volatile("s_waitcnt lgkmcnt(" #n ")" ::: "memory")
; #define PG8_BAR __builtin_amdgcn_s_barrier()
; #define PG8_SCHED __builtin_amdgcn_sched_barrier(0)
; template <class Epi, class Sched>
; DI void gemm_phase(LAS unsigned char* lds, const Gemm g, const Sched& S, const Epi& E) {
;     ...
;             PG8_LDB(B0, 0, 0); PG8_SCHED; PG8_LDA(At, 0, 0); PG8_STAGE(PG8_SA(1, 1), a1 + hstep, voffA);
;             PG8_WAIT_L(8); PG8_BAR; PG8_WAIT_L(0); PG8_MMA(0, 0, At, B0); PG8_BAR; PG8_SCHED;
;             PG8_LDB(B1, 0, 1); PG8_STAGE(PG8_SB(0, 0), b2, voffB);
;     ...
;             PG8_BAR; PG8_WAIT_L(0); PG8_MMA(1, 0, At, B0); PG8_BAR; PG8_SCHED;
;             PG8_STAGE(PG8_SB(1, 1), b3 + hstep, voffB);
;             PG8_WAIT_V(6); PG8_BAR; PG8_MMA(1, 1, At, B1); PG8_BAR;
	s_waitcnt lgkmcnt(0)
	s_setprio 1
	v_mfma_f32_16x16x32_bf16 v[60:63], v[150:153], v[170:173], v[60:63]
	v_mfma_f32_16x16x32_bf16 v[56:59], v[162:165], v[170:173], v[56:59]
	v_mfma_f32_16x16x32_bf16 v[44:47], v[150:153], v[178:181], v[44:47]
	v_mfma_f32_16x16x32_bf16 v[40:43], v[162:165], v[178:181], v[40:43]
	v_mfma_f32_16x16x32_bf16 v[28:31], v[150:153], v[194:197], v[28:31]
	v_mfma_f32_16x16x32_bf16 v[24:27], v[162:165], v[194:197], v[24:27]
	v_mfma_f32_16x16x32_bf16 v[12:15], v[150:153], v[202:205], v[12:15]
	v_mfma_f32_16x16x32_bf16 v[8:11], v[162:165], v[202:205], v[8:11]
	v_mfma_f32_16x16x32_bf16 v[60:63], v[154:157], v[174:177], v[60:63]
	v_mfma_f32_16x16x32_bf16 v[56:59], v[166:169], v[174:177], v[56:59]
	v_mfma_f32_16x16x32_bf16 v[44:47], v[154:157], v[188:191], v[44:47]
	v_mfma_f32_16x16x32_bf16 v[40:43], v[166:169], v[188:191], v[40:43]
	v_mfma_f32_16x16x32_bf16 v[28:31], v[154:157], v[198:201], v[28:31]
	v_mfma_f32_16x16x32_bf16 v[24:27], v[166:169], v[198:201], v[24:27]
	v_mfma_f32_16x16x32_bf16 v[12:15], v[154:157], v[206:209], v[12:15]
	v_mfma_f32_16x16x32_bf16 v[8:11], v[166:169], v[206:209], v[8:11]
	s_setprio 0
	s_barrier
	s_add_i32 s4, s5, s52
	s_mov_b32 s74, s4
	s_mov_b32 m0, s4
	s_add_u32 s0, s42, 0x80080
	s_addc_u32 s1, s43, 0
	global_load_lds_dwordx4 v130, s[0:1]
	s_add_i32 m0, s4, 0x2000
	s_nop 0
	global_load_lds_dwordx4 v134, s[0:1]
	s_waitcnt vmcnt(6)
	s_barrier
	s_setprio 1
	v_mfma_f32_16x16x32_bf16 v[52:55], v[210:213], v[170:173], v[52:55]
	v_mfma_f32_16x16x32_bf16 v[48:51], v[218:221], v[170:173], v[48:51]
	v_mfma_f32_16x16x32_bf16 v[36:39], v[210:213], v[178:181], v[36:39]
	v_mfma_f32_16x16x32_bf16 v[32:35], v[218:221], v[178:181], v[32:35]
	v_mfma_f32_16x16x32_bf16 v[20:23], v[210:213], v[194:197], v[20:23]
	v_mfma_f32_16x16x32_bf16 v[16:19], v[218:221], v[194:197], v[16:19]
	v_mfma_f32_16x16x32_bf16 v[4:7], v[210:213], v[202:205], v[4:7]
	v_mfma_f32_16x16x32_bf16 v[0:3], v[218:221], v[202:205], v[0:3]
	v_mfma_f32_16x16x32_bf16 v[52:55], v[214:217], v[174:177], v[52:55]
	v_mfma_f32_16x16x32_bf16 v[48:51], v[222:225], v[174:177], v[48:51]
	v_mfma_f32_16x16x32_bf16 v[36:39], v[214:217], v[188:191], v[36:39]
	v_mfma_f32_16x16x32_bf16 v[32:35], v[222:225], v[188:191], v[32:35]
	v_mfma_f32_16x16x32_bf16 v[20:23], v[214:217], v[198:201], v[20:23]
	v_mfma_f32_16x16x32_bf16 v[16:19], v[222:225], v[198:201], v[16:19]
	v_mfma_f32_16x16x32_bf16 v[4:7], v[214:217], v[206:209], v[4:7]
	v_mfma_f32_16x16x32_bf16 v[0:3], v[222:225], v[206:209], v[0:3]
	s_setprio 0
	s_add_i32 s69, s69, 2
	s_add_u32 s40, s40, 0x100
	s_addc_u32 s41, s41, 0
	s_add_u32 s67, s67, 0x100
	s_addc_u32 s68, s68, 0
	s_cmp_gt_u32 s69, 29
	s_barrier
	s_cbranch_scc0 .LBB0_219
	s_branch .Lpeel_done_219
.LBB0_219:
	ds_read_b128 v[150:153], v147
	ds_read_b128 v[154:157], v147 offset:1024
	ds_read_b128 v[162:165], v147 offset:2048
	ds_read_b128 v[166:169], v147 offset:3072
	s_add_u32 s0, s40, 0xfff80080
	s_addc_u32 s1, s41, -1
	s_cmp_eq_u32 s69, 28
	s_cselect_b32 s45, s17, s1
	s_cselect_b32 s44, s65, s0
	s_cselect_b32 s43, s15, s68
	s_cselect_b32 s42, s66, s67
	s_add_i32 m0, s39, 0xc000
	ds_read_b128 v[170:173], v148
	ds_read_b128 v[174:177], v148 offset:1024
	ds_read_b128 v[178:181], v148 offset:2048
	ds_read_b128 v[188:191], v148 offset:3072
	ds_read_b128 v[194:197], v148 offset:4096
	ds_read_b128 v[198:201], v148 offset:5120
	ds_read_b128 v[202:205], v148 offset:6144
	global_load_lds_dwordx4 v136, s[40:41]
	s_add_i32 m0, s39, 0xe000
	ds_read_b128 v[206:209], v148 offset:7168
	global_load_lds_dwordx4 v138, s[40:41]
	s_waitcnt lgkmcnt(8)
	s_barrier
	s_waitcnt lgkmcnt(0)
	s_setprio 1
	v_mfma_f32_16x16x32_bf16 v[124:127], v[150:153], v[170:173], v[124:127]
	v_mfma_f32_16x16x32_bf16 v[120:123], v[162:165], v[170:173], v[120:123]
	v_mfma_f32_16x16x32_bf16 v[108:111], v[150:153], v[178:181], v[108:111]
	v_mfma_f32_16x16x32_bf16 v[104:107], v[162:165], v[178:181], v[104:107]
	v_mfma_f32_16x16x32_bf16 v[92:95], v[150:153], v[194:197], v[92:95]
	v_mfma_f32_16x16x32_bf16 v[88:91], v[162:165], v[194:197], v[88:91]
	v_mfma_f32_16x16x32_bf16 v[76:79], v[150:153], v[202:205], v[76:79]
	v_mfma_f32_16x16x32_bf16 v[72:75], v[162:165], v[202:205], v[72:75]
	v_mfma_f32_16x16x32_bf16 v[124:127], v[154:157], v[174:177], v[124:127]
	v_mfma_f32_16x16x32_bf16 v[120:123], v[166:169], v[174:177], v[120:123]
	v_mfma_f32_16x16x32_bf16 v[108:111], v[154:157], v[188:191], v[108:111]
	v_mfma_f32_16x16x32_bf16 v[104:107], v[166:169], v[188:191], v[104:107]
	v_mfma_f32_16x16x32_bf16 v[92:95], v[154:157], v[198:201], v[92:95]
	v_mfma_f32_16x16x32_bf16 v[88:91], v[166:169], v[198:201], v[88:91]
	v_mfma_f32_16x16x32_bf16 v[76:79], v[154:157], v[206:209], v[76:79]
	v_mfma_f32_16x16x32_bf16 v[72:75], v[166:169], v[206:209], v[72:75]
	s_setprio 0
	s_barrier
	s_mov_b32 m0, s12
	ds_read_b128 v[210:213], v149
	ds_read_b128 v[214:217], v149 offset:1024
	ds_read_b128 v[218:221], v149 offset:2048
	global_load_lds_dwordx4 v130, s[42:43]
	s_add_i32 m0, s12, 0x2000
	ds_read_b128 v[222:225], v149 offset:3072
	global_load_lds_dwordx4 v134, s[42:43]
	s_barrier
; #define PG8_STAGE(bufoff, gbase, voff) do { _Pragma("unroll") for (int _i = 0; _i < 2; ++_i) \
;         __builtin_amdgcn_global_load_lds((const unsigned*)((const char*)(gbase) + (voff)[_i]), (LAS unsigned*)(lds + (bufoff) + ldsw + _i * 8192), 16, 0, 0); } while (0)
; #define PG8_LDA(dst, b, h) do { _Pragma("unroll") for (int m = 0; m < 4; ++m) _Pragma("unroll") for (int k = 0; k < 2; ++k) dst[m][k] = *(const LAS bf16x8*)(lds + PG8_SA(b, h) + aoff + m * 2048 + k * 1024); } while (0)
; #define PG8_LDB(dst, b, h) do { _Pragma("unroll") for (int n = 0; n < 2; ++n) _Pragma("unroll") for (int k = 0; k < 2; ++k) dst[n][k] = *(const LAS bf16x8*)(lds + PG8_SB(b, h) + boff + n * 2048 + k * 1024); } while (0)
; #define PG8_MMA(ai, bj, At, Bt) do { __builtin_amdgcn_s_setprio(1); _Pragma("unroll") for (int m = 0; m < 4; ++m) _Pragma("unroll") for (int n = 0; n < 2; ++n) _Pragma("unroll") for (int k = 0; k < 2; ++k) \
;         acc[ai][bj][m][n] = __builtin_amdgcn_mfma_f32_16x16x32_bf16(Bt[n][k], At[m][k], acc[ai][bj][m][n], 0, 0, 0); __builtin_amdgcn_s_setprio(0); } while (0)
; #define PG8_WAIT_V(n) asm volatile("s_waitcnt vmcnt(" #n ")" ::: "memory")
; #define PG8_WAIT_L(n) asm volatile("s_waitcnt lgkmcnt(" #n ")" ::: "memory")
; #define PG8_BAR __builtin_amdgcn_s_barrier()
; #define PG8_SCHED __builtin_amdgcn_sched_barrier(0)
; template <class Epi, class Sched>
; DI void gemm_phase(LAS unsigned char* lds, const Gemm g, const Sched& S, const Epi& E) {
;     ...
;             PG8_BAR; PG8_WAIT_L(0); PG8_MMA(0, 1, At, B1); PG8_BAR;
;             PG8_LDA(At, 0, 1); PG8_STAGE(PG8_SA(0, 0), a2, voffA);
;             PG8_BAR; PG8_WAIT_L(0); PG8_MMA(1, 0, At, B0); PG8_BAR; PG8_SCHED;
;             PG8_STAGE(PG8_SB(0, 1), b2 + hstep, voffB);
;             PG8_WAIT_V(6); PG8_BAR; PG8_MMA(1, 1, At, B1); PG8_BAR;
;             PG8_LDB(B0, 1, 0); PG8_SCHED; PG8_LDA(At, 1, 0); PG8_STAGE(PG8_SA(0, 1), a2 + hstep, voffA);
;             PG8_WAIT_L(8); PG8_BAR; PG8_WAIT_L(0); PG8_MMA(0, 0, At, B0); PG8_BAR; PG8_SCHED;
	s_waitcnt lgkmcnt(0)
	s_setprio 1
	v_mfma_f32_16x16x32_bf16 v[116:119], v[210:213], v[170:173], v[116:119]
	v_mfma_f32_16x16x32_bf16 v[112:115], v[218:221], v[170:173], v[112:115]
	v_mfma_f32_16x16x32_bf16 v[100:103], v[210:213], v[178:181], v[100:103]
	v_mfma_f32_16x16x32_bf16 v[96:99], v[218:221], v[178:181], v[96:99]
	v_mfma_f32_16x16x32_bf16 v[84:87], v[210:213], v[194:197], v[84:87]
	v_mfma_f32_16x16x32_bf16 v[80:83], v[218:221], v[194:197], v[80:83]
	v_mfma_f32_16x16x32_bf16 v[68:71], v[210:213], v[202:205], v[68:71]
	v_mfma_f32_16x16x32_bf16 v[64:67], v[218:221], v[202:205], v[64:67]
	v_mfma_f32_16x16x32_bf16 v[116:119], v[214:217], v[174:177], v[116:119]
	v_mfma_f32_16x16x32_bf16 v[112:115], v[222:225], v[174:177], v[112:115]
	v_mfma_f32_16x16x32_bf16 v[100:103], v[214:217], v[188:191], v[100:103]
	v_mfma_f32_16x16x32_bf16 v[96:99], v[222:225], v[188:191], v[96:99]
	v_mfma_f32_16x16x32_bf16 v[84:87], v[214:217], v[198:201], v[84:87]
	v_mfma_f32_16x16x32_bf16 v[80:83], v[222:225], v[198:201], v[80:83]
	v_mfma_f32_16x16x32_bf16 v[68:71], v[214:217], v[206:209], v[68:71]
	v_mfma_f32_16x16x32_bf16 v[64:67], v[222:225], v[206:209], v[64:67]
	s_setprio 0
	s_mov_b32 m0, s39
	s_barrier
	ds_read_b128 v[170:173], v148 offset:16384
	ds_read_b128 v[174:177], v148 offset:17408
	ds_read_b128 v[178:181], v148 offset:18432
	ds_read_b128 v[188:191], v148 offset:19456
	ds_read_b128 v[194:197], v148 offset:20480
	ds_read_b128 v[198:201], v148 offset:21504
	ds_read_b128 v[202:205], v148 offset:22528
	global_load_lds_dwordx4 v128, s[44:45]
	s_mov_b32 m0, s53
	ds_read_b128 v[206:209], v148 offset:23552
	global_load_lds_dwordx4 v132, s[44:45]
	s_barrier
	s_waitcnt lgkmcnt(0)
	s_setprio 1
	v_mfma_f32_16x16x32_bf16 v[60:63], v[150:153], v[170:173], v[60:63]
	v_mfma_f32_16x16x32_bf16 v[56:59], v[162:165], v[170:173], v[56:59]
	v_mfma_f32_16x16x32_bf16 v[44:47], v[150:153], v[178:181], v[44:47]
	v_mfma_f32_16x16x32_bf16 v[40:43], v[162:165], v[178:181], v[40:43]
	v_mfma_f32_16x16x32_bf16 v[28:31], v[150:153], v[194:197], v[28:31]
	v_mfma_f32_16x16x32_bf16 v[24:27], v[162:165], v[194:197], v[24:27]
	v_mfma_f32_16x16x32_bf16 v[12:15], v[150:153], v[202:205], v[12:15]
	v_mfma_f32_16x16x32_bf16 v[8:11], v[162:165], v[202:205], v[8:11]
	v_mfma_f32_16x16x32_bf16 v[60:63], v[154:157], v[174:177], v[60:63]
	v_mfma_f32_16x16x32_bf16 v[56:59], v[166:169], v[174:177], v[56:59]
	v_mfma_f32_16x16x32_bf16 v[44:47], v[154:157], v[188:191], v[44:47]
	v_mfma_f32_16x16x32_bf16 v[40:43], v[166:169], v[188:191], v[40:43]
	v_mfma_f32_16x16x32_bf16 v[28:31], v[154:157], v[198:201], v[28:31]
	v_mfma_f32_16x16x32_bf16 v[24:27], v[166:169], v[198:201], v[24:27]
	v_mfma_f32_16x16x32_bf16 v[12:15], v[154:157], v[206:209], v[12:15]
	v_mfma_f32_16x16x32_bf16 v[8:11], v[166:169], v[206:209], v[8:11]
	s_setprio 0
	s_barrier
	s_mov_b32 m0, s13
	s_add_u32 s0, s42, 0x80000
	s_addc_u32 s1, s43, 0
	global_load_lds_dwordx4 v130, s[0:1]
	s_add_i32 m0, s13, 0x2000
	s_nop 0
	global_load_lds_dwordx4 v134, s[0:1]
	s_waitcnt vmcnt(6)
	s_barrier
	s_setprio 1
	v_mfma_f32_16x16x32_bf16 v[52:55], v[210:213], v[170:173], v[52:55]
	v_mfma_f32_16x16x32_bf16 v[48:51], v[218:221], v[170:173], v[48:51]
	v_mfma_f32_16x16x32_bf16 v[36:39], v[210:213], v[178:181], v[36:39]
	v_mfma_f32_16x16x32_bf16 v[32:35], v[218:221], v[178:181], v[32:35]
	v_mfma_f32_16x16x32_bf16 v[20:23], v[210:213], v[194:197], v[20:23]
	v_mfma_f32_16x16x32_bf16 v[16:19], v[218:221], v[194:197], v[16:19]
	v_mfma_f32_16x16x32_bf16 v[4:7], v[210:213], v[202:205], v[4:7]
	v_mfma_f32_16x16x32_bf16 v[0:3], v[218:221], v[202:205], v[0:3]
	v_mfma_f32_16x16x32_bf16 v[52:55], v[214:217], v[174:177], v[52:55]
	v_mfma_f32_16x16x32_bf16 v[48:51], v[222:225], v[174:177], v[48:51]
	v_mfma_f32_16x16x32_bf16 v[36:39], v[214:217], v[188:191], v[36:39]
	v_mfma_f32_16x16x32_bf16 v[32:35], v[222:225], v[188:191], v[32:35]
	v_mfma_f32_16x16x32_bf16 v[20:23], v[214:217], v[198:201], v[20:23]
	v_mfma_f32_16x16x32_bf16 v[16:19], v[222:225], v[198:201], v[16:19]
	v_mfma_f32_16x16x32_bf16 v[4:7], v[214:217], v[206:209], v[4:7]
	v_mfma_f32_16x16x32_bf16 v[0:3], v[222:225], v[206:209], v[0:3]
	s_setprio 0
	s_add_i32 s4, 0, 0x18000
	s_barrier
	ds_read_b128 v[150:153], v158
	ds_read_b128 v[154:157], v158 offset:1024
	ds_read_b128 v[162:165], v158 offset:2048
	ds_read_b128 v[166:169], v158 offset:3072
	s_add_u32 s0, s44, 0x80000
	s_addc_u32 s1, s45, 0
	s_mov_b32 m0, s54
	ds_read_b128 v[170:173], v148 offset:32768
	ds_read_b128 v[174:177], v148 offset:33792
	ds_read_b128 v[178:181], v148 offset:34816
	ds_read_b128 v[188:191], v148 offset:35840
	ds_read_b128 v[194:197], v148 offset:36864
	ds_read_b128 v[198:201], v148 offset:37888
	ds_read_b128 v[202:205], v148 offset:38912
	global_load_lds_dwordx4 v128, s[0:1]
	s_mov_b32 m0, s55
	ds_read_b128 v[206:209], v148 offset:39936
	global_load_lds_dwordx4 v132, s[0:1]
	s_waitcnt lgkmcnt(8)
	s_barrier
; #define PG8_STAGE(bufoff, gbase, voff) do { _Pragma("unroll") for (int _i = 0; _i < 2; ++_i) \
;         __builtin_amdgcn_global_load_lds((const unsigned*)((const char*)(gbase) + (voff)[_i]), (LAS unsigned*)(lds + (bufoff) + ldsw + _i * 8192), 16, 0, 0); } while (0)
; #define PG8_LDA(dst, b, h) do { _Pragma("unroll") for (int m = 0; m < 4; ++m) _Pragma("unroll") for (int k = 0; k < 2; ++k) dst[m][k] = *(const LAS bf16x8*)(lds + PG8_SA(b, h) + aoff + m * 2048 + k * 1024); } while (0)
; #define PG8_LDB(dst, b, h) do { _Pragma("unroll") for (int n = 0; n < 2; ++n) _Pragma("unroll") for (int k = 0; k < 2; ++k) dst[n][k] = *(const LAS bf16x8*)(lds + PG8_SB(b, h) + boff + n * 2048 + k * 1024); } while (0)
; #define PG8_MMA(ai, bj, At, Bt) do { __builtin_amdgcn_s_setprio(1); _Pragma("unroll") for (int m = 0; m < 4; ++m) _Pragma("unroll") for (int n = 0; n < 2; ++n) _Pragma("unroll") for (int k = 0; k < 2; ++k) \
;         acc[ai][bj][m][n] = __builtin_amdgcn_mfma_f32_16x16x32_bf16(Bt[n][k], At[m][k], acc[ai][bj][m][n], 0, 0, 0); __builtin_amdgcn_s_setprio(0); } while (0)
; #define PG8_WAIT_V(n) asm volatile("s_waitcnt vmcnt(" #n ")" ::: "memory")
; #define PG8_WAIT_L(n) asm volatile("s_waitcnt lgkmcnt(" #n ")" ::: "memory")
; #define PG8_BAR __builtin_amdgcn_s_barrier()
; #define PG8_SCHED __builtin_amdgcn_sched_barrier(0)
; template <class Epi, class Sched>
; DI void gemm_phase(LAS unsigned char* lds, const Gemm g, const Sched& S, const Epi& E) {
;     ...
;             PG8_WAIT_L(8); PG8_BAR; PG8_WAIT_L(0); PG8_MMA(0, 0, At, B0); PG8_BAR; PG8_SCHED;
;             PG8_LDB(B1, 1, 1); PG8_STAGE(PG8_SB(1, 0), b3, voffB);
;             PG8_BAR; PG8_WAIT_L(0); PG8_MMA(0, 1, At, B1); PG8_BAR;
;             PG8_LDA(At, 1, 1); PG8_STAGE(PG8_SA(1, 0), a3, voffA);
;             PG8_BAR; PG8_WAIT_L(0); PG8_MMA(1, 0, At, B0); PG8_BAR; PG8_SCHED;
;             PG8_STAGE(PG8_SB(1, 1), b3 + hstep, voffB);
;             PG8_WAIT_V(6); PG8_BAR; PG8_MMA(1, 1, At, B1); PG8_BAR;
	s_waitcnt lgkmcnt(0)
	s_setprio 1
	v_mfma_f32_16x16x32_bf16 v[124:127], v[150:153], v[170:173], v[124:127]
	v_mfma_f32_16x16x32_bf16 v[120:123], v[162:165], v[170:173], v[120:123]
	v_mfma_f32_16x16x32_bf16 v[108:111], v[150:153], v[178:181], v[108:111]
	v_mfma_f32_16x16x32_bf16 v[104:107], v[162:165], v[178:181], v[104:107]
	v_mfma_f32_16x16x32_bf16 v[92:95], v[150:153], v[194:197], v[92:95]
	v_mfma_f32_16x16x32_bf16 v[88:91], v[162:165], v[194:197], v[88:91]
	v_mfma_f32_16x16x32_bf16 v[76:79], v[150:153], v[202:205], v[76:79]
	v_mfma_f32_16x16x32_bf16 v[72:75], v[162:165], v[202:205], v[72:75]
	v_mfma_f32_16x16x32_bf16 v[124:127], v[154:157], v[174:177], v[124:127]
	v_mfma_f32_16x16x32_bf16 v[120:123], v[166:169], v[174:177], v[120:123]
	v_mfma_f32_16x16x32_bf16 v[108:111], v[154:157], v[188:191], v[108:111]
	v_mfma_f32_16x16x32_bf16 v[104:107], v[166:169], v[188:191], v[104:107]
	v_mfma_f32_16x16x32_bf16 v[92:95], v[154:157], v[198:201], v[92:95]
	v_mfma_f32_16x16x32_bf16 v[88:91], v[166:169], v[198:201], v[88:91]
	v_mfma_f32_16x16x32_bf16 v[76:79], v[154:157], v[206:209], v[76:79]
	v_mfma_f32_16x16x32_bf16 v[72:75], v[166:169], v[206:209], v[72:75]
	s_setprio 0
	s_barrier
	s_add_i32 s5, 0, 0x1c000
	s_add_i32 m0, s32, 0xffffff80
	ds_read_b128 v[210:213], v159
	ds_read_b128 v[214:217], v159 offset:1024
	ds_read_b128 v[218:221], v159 offset:2048
	global_load_lds_dwordx4 v130, s[42:43] offset:128
	s_add_i32 m0, s32, 0x1f80
	ds_read_b128 v[222:225], v159 offset:3072
	global_load_lds_dwordx4 v134, s[42:43] offset:128
	s_barrier
	s_waitcnt lgkmcnt(0)
	s_setprio 1
	v_mfma_f32_16x16x32_bf16 v[116:119], v[210:213], v[170:173], v[116:119]
	v_mfma_f32_16x16x32_bf16 v[112:115], v[218:221], v[170:173], v[112:115]
	v_mfma_f32_16x16x32_bf16 v[100:103], v[210:213], v[178:181], v[100:103]
	v_mfma_f32_16x16x32_bf16 v[96:99], v[218:221], v[178:181], v[96:99]
	v_mfma_f32_16x16x32_bf16 v[84:87], v[210:213], v[194:197], v[84:87]
	v_mfma_f32_16x16x32_bf16 v[80:83], v[218:221], v[194:197], v[80:83]
	v_mfma_f32_16x16x32_bf16 v[68:71], v[210:213], v[202:205], v[68:71]
	v_mfma_f32_16x16x32_bf16 v[64:67], v[218:221], v[202:205], v[64:67]
	v_mfma_f32_16x16x32_bf16 v[116:119], v[214:217], v[174:177], v[116:119]
	v_mfma_f32_16x16x32_bf16 v[112:115], v[222:225], v[174:177], v[112:115]
	v_mfma_f32_16x16x32_bf16 v[100:103], v[214:217], v[188:191], v[100:103]
	v_mfma_f32_16x16x32_bf16 v[96:99], v[222:225], v[188:191], v[96:99]
	v_mfma_f32_16x16x32_bf16 v[84:87], v[214:217], v[198:201], v[84:87]
	v_mfma_f32_16x16x32_bf16 v[80:83], v[222:225], v[198:201], v[80:83]
	v_mfma_f32_16x16x32_bf16 v[68:71], v[214:217], v[206:209], v[68:71]
	v_mfma_f32_16x16x32_bf16 v[64:67], v[222:225], v[206:209], v[64:67]
	s_setprio 0
	s_add_i32 m0, s59, 0xffffff80
	s_barrier
	ds_read_b128 v[170:173], v148 offset:49152
	ds_read_b128 v[174:177], v148 offset:50176
	ds_read_b128 v[178:181], v148 offset:51200
	ds_read_b128 v[188:191], v148 offset:52224
	ds_read_b128 v[194:197], v148 offset:53248
	ds_read_b128 v[198:201], v148 offset:54272
	ds_read_b128 v[202:205], v148 offset:55296
	global_load_lds_dwordx4 v128, s[44:45] offset:128
	s_add_i32 m0, s60, 0xffffff80
	ds_read_b128 v[206:209], v148 offset:56320
	global_load_lds_dwordx4 v132, s[44:45] offset:128
	s_barrier
	s_waitcnt lgkmcnt(0)
	s_setprio 1
	v_mfma_f32_16x16x32_bf16 v[60:63], v[150:153], v[170:173], v[60:63]
	v_mfma_f32_16x16x32_bf16 v[56:59], v[162:165], v[170:173], v[56:59]
	v_mfma_f32_16x16x32_bf16 v[44:47], v[150:153], v[178:181], v[44:47]
	v_mfma_f32_16x16x32_bf16 v[40:43], v[162:165], v[178:181], v[40:43]
	v_mfma_f32_16x16x32_bf16 v[28:31], v[150:153], v[194:197], v[28:31]
	v_mfma_f32_16x16x32_bf16 v[24:27], v[162:165], v[194:197], v[24:27]
	v_mfma_f32_16x16x32_bf16 v[12:15], v[150:153], v[202:205], v[12:15]
	v_mfma_f32_16x16x32_bf16 v[8:11], v[162:165], v[202:205], v[8:11]
	v_mfma_f32_16x16x32_bf16 v[60:63], v[154:157], v[174:177], v[60:63]
	v_mfma_f32_16x16x32_bf16 v[56:59], v[166:169], v[174:177], v[56:59]
	v_mfma_f32_16x16x32_bf16 v[44:47], v[154:157], v[188:191], v[44:47]
	v_mfma_f32_16x16x32_bf16 v[40:43], v[166:169], v[188:191], v[40:43]
	v_mfma_f32_16x16x32_bf16 v[28:31], v[154:157], v[198:201], v[28:31]
	v_mfma_f32_16x16x32_bf16 v[24:27], v[166:169], v[198:201], v[24:27]
	v_mfma_f32_16x16x32_bf16 v[12:15], v[154:157], v[206:209], v[12:15]
	v_mfma_f32_16x16x32_bf16 v[8:11], v[166:169], v[206:209], v[8:11]
	s_setprio 0
	s_barrier
	s_mov_b32 m0, s74
	s_add_u32 s0, s42, 0x80080
	s_addc_u32 s1, s43, 0
	global_load_lds_dwordx4 v130, s[0:1]
	s_add_i32 m0, s74, 0x2000
	s_nop 0
	global_load_lds_dwordx4 v134, s[0:1]
	s_waitcnt vmcnt(6)
	s_barrier
	s_setprio 1
	v_mfma_f32_16x16x32_bf16 v[52:55], v[210:213], v[170:173], v[52:55]
	v_mfma_f32_16x16x32_bf16 v[48:51], v[218:221], v[170:173], v[48:51]
	v_mfma_f32_16x16x32_bf16 v[36:39], v[210:213], v[178:181], v[36:39]
	v_mfma_f32_16x16x32_bf16 v[32:35], v[218:221], v[178:181], v[32:35]
	v_mfma_f32_16x16x32_bf16 v[20:23], v[210:213], v[194:197], v[20:23]
	v_mfma_f32_16x16x32_bf16 v[16:19], v[218:221], v[194:197], v[16:19]
	v_mfma_f32_16x16x32_bf16 v[4:7], v[210:213], v[202:205], v[4:7]
	v_mfma_f32_16x16x32_bf16 v[0:3], v[218:221], v[202:205], v[0:3]
	v_mfma_f32_16x16x32_bf16 v[52:55], v[214:217], v[174:177], v[52:55]
	v_mfma_f32_16x16x32_bf16 v[48:51], v[222:225], v[174:177], v[48:51]
	v_mfma_f32_16x16x32_bf16 v[36:39], v[214:217], v[188:191], v[36:39]
	v_mfma_f32_16x16x32_bf16 v[32:35], v[222:225], v[188:191], v[32:35]
	v_mfma_f32_16x16x32_bf16 v[20:23], v[214:217], v[198:201], v[20:23]
	v_mfma_f32_16x16x32_bf16 v[16:19], v[222:225], v[198:201], v[16:19]
	v_mfma_f32_16x16x32_bf16 v[4:7], v[214:217], v[206:209], v[4:7]
	v_mfma_f32_16x16x32_bf16 v[0:3], v[222:225], v[206:209], v[0:3]
	s_setprio 0
	s_add_i32 s69, s69, 2
	s_add_u32 s40, s40, 0x100
	s_addc_u32 s41, s41, 0
	s_add_u32 s67, s67, 0x100
	s_addc_u32 s68, s68, 0
	s_cmp_gt_u32 s69, 29
	s_barrier
	s_cbranch_scc0 .LBB0_219

;     DI size_t aoff(const Unit& u, size_t tstep) const { return (size_t)u.pm * tstep; }
;     DI size_t boff(const Unit& u, size_t tstep) const { return (size_t)u.pn * tstep; }
;     DI bool next(int i, Unit& u) const { const long L = (long)i * G + c; if (L >= np) return false; u.pm = pmv; u.pn = (int)(L % nN); u.ks = (int)(L / nN); return true; }
;     DI size_t aoff(const Unit& u, size_t) const { return (size_t)u.ks * kbytes; }
;     DI size_t boff(const Unit& u, size_t tstep) const { return (size_t)u.pn * tstep + (size_t)u.ks * kbytes; }
;     DI bool next(int i, Unit& u) const { Unit t; if (!S.next(i / 3, t)) return false; u.pm = t.pm; u.pn = t.pn; u.ks = i % 3; return true; }
;     DI size_t aoff(const Unit& u, size_t tstep) const { return (u.ks < 2 ? offU : offOA) + (size_t)u.pm * tstep; }
; #define PG8_WAIT_V(n) asm volatile("s_waitcnt vmcnt(" #n ")" ::: "memory")
; template <class Epi, class Sched>
; DI void gemm_phase(LAS unsigned char* lds, const Gemm g, const Sched& S, const Epi& E) {
;     ...
;         const bool has_next = S.next(ui + 1, nxt);
;         const char* nA = has_next ? (const char*)g.A + S.aoff(nxt, tstep) : cA; const char* nB = has_next ? (const char*)g.Bt + S.boff(nxt, tstep) : cB;
;         for (int t = 0; t < nt; t += 2) {
;             if constexpr (Epi::HAS_MID) { if (t == E.mid_t(nt)) { int fr3 = fr, fq3 = fq; asm volatile("" : "+v"(fr3), "+v"(fq3)); E.mid(acc, cur, wr, wc, fr3, fq3); } }
;             const bool last = (t == nt - 2);
;             const char* a1 = cA + (size_t)(t + 1) * kstep;
;             const char* a2 = last ? nA : cA + (size_t)(t + 2) * kstep; const char* b2 = last ? nB : cB + (size_t)(t + 2) * kstep;
;             const char* a3 = a2 + kstep; const char* b3 = b2 + kstep;
;             PG8_LDB(B0, 0, 0); PG8_SCHED; PG8_LDA(At, 0, 0); PG8_STAGE(PG8_SA(1, 1), a1 + hstep, voffA);
;             PG8_WAIT_L(8); PG8_BAR; PG8_WAIT_L(0); PG8_MMA(0, 0, At, B0); PG8_BAR; PG8_SCHED;
;             PG8_LDB(B1, 0, 1); PG8_STAGE(PG8_SB(0, 0), b2, voffB);
;             PG8_BAR; PG8_WAIT_L(0); PG8_MMA(0, 1, At, B1); PG8_BAR;
;             PG8_LDA(At, 0, 1); PG8_STAGE(PG8_SA(0, 0), a2, voffA);
;             PG8_BAR; PG8_WAIT_L(0); PG8_MMA(1, 0, At, B0); PG8_BAR; PG8_SCHED;
;             PG8_STAGE(PG8_SB(0, 1), b2 + hstep, voffB);
;             PG8_WAIT_V(6); PG8_BAR; PG8_MMA(1, 1, At, B1); PG8_BAR;
.LBB0_296:
	s_add_u32 s40, s40, 0x160080
	s_addc_u32 s41, s41, 0
	s_add_u32 s35, s42, 0x100
	v_mov_b32_e32 v0, 0
	s_addc_u32 s68, s43, 0
	s_mov_b32 s69, -2
	s_waitcnt lgkmcnt(0)
	ds_read_b128 v[144:147], v158
	ds_read_b128 v[164:167], v158 offset:1024
	ds_read_b128 v[168:171], v158 offset:2048
	ds_read_b128 v[172:175], v158 offset:3072
	s_add_u32 s0, s40, 0xffea0080
	s_addc_u32 s1, s41, -1
	s_cmpk_eq_i32 s69, 0x54
	s_cselect_b32 s45, s9, s1
	s_cselect_b32 s44, s8, s0
	s_cselect_b32 s43, s11, s68
	s_cselect_b32 s42, s10, s35
	s_add_i32 m0, s54, 0xc000
	ds_read_b128 v[176:179], v159
	ds_read_b128 v[180:183], v159 offset:1024
	ds_read_b128 v[188:191], v159 offset:2048
	ds_read_b128 v[194:197], v159 offset:3072
	ds_read_b128 v[198:201], v159 offset:4096
	ds_read_b128 v[202:205], v159 offset:5120
	ds_read_b128 v[206:209], v159 offset:6144
	global_load_lds_dwordx4 v136, s[40:41]
	s_add_i32 m0, s54, 0xe000
	ds_read_b128 v[210:213], v159 offset:7168
	global_load_lds_dwordx4 v138, s[40:41]
	s_waitcnt lgkmcnt(8)
	s_barrier
	s_waitcnt lgkmcnt(0)
	s_setprio 1
	v_mfma_f32_16x16x32_bf16 v[124:127], v[144:147], v[176:179], 0
	v_mfma_f32_16x16x32_bf16 v[120:123], v[168:171], v[176:179], 0
	v_mfma_f32_16x16x32_bf16 v[108:111], v[144:147], v[188:191], 0
	v_mfma_f32_16x16x32_bf16 v[104:107], v[168:171], v[188:191], 0
	v_mfma_f32_16x16x32_bf16 v[92:95], v[144:147], v[198:201], 0
	v_mfma_f32_16x16x32_bf16 v[88:91], v[168:171], v[198:201], 0
	v_mfma_f32_16x16x32_bf16 v[76:79], v[144:147], v[206:209], 0
	v_mfma_f32_16x16x32_bf16 v[72:75], v[168:171], v[206:209], 0
	v_mfma_f32_16x16x32_bf16 v[124:127], v[164:167], v[180:183], v[124:127]
	v_mfma_f32_16x16x32_bf16 v[120:123], v[172:175], v[180:183], v[120:123]
	v_mfma_f32_16x16x32_bf16 v[108:111], v[164:167], v[194:197], v[108:111]
	v_mfma_f32_16x16x32_bf16 v[104:107], v[172:175], v[194:197], v[104:107]
	v_mfma_f32_16x16x32_bf16 v[92:95], v[164:167], v[202:205], v[92:95]
	v_mfma_f32_16x16x32_bf16 v[88:91], v[172:175], v[202:205], v[88:91]
	v_mfma_f32_16x16x32_bf16 v[76:79], v[164:167], v[210:213], v[76:79]
	v_mfma_f32_16x16x32_bf16 v[72:75], v[172:175], v[210:213], v[72:75]
	s_setprio 0
	s_barrier
	s_add_i32 s0, s63, s53
	s_mov_b32 s32, s0
	s_mov_b32 m0, s0
	ds_read_b128 v[214:217], v161
	ds_read_b128 v[218:221], v161 offset:1024
	ds_read_b128 v[222:225], v161 offset:2048
	global_load_lds_dwordx4 v130, s[42:43]
	s_add_i32 m0, s0, 0x2000
	ds_read_b128 v[226:229], v161 offset:3072
	global_load_lds_dwordx4 v134, s[42:43]
	s_barrier
	s_waitcnt lgkmcnt(0)
	s_setprio 1
	v_mfma_f32_16x16x32_bf16 v[116:119], v[214:217], v[176:179], 0
	v_mfma_f32_16x16x32_bf16 v[112:115], v[222:225], v[176:179], 0
	v_mfma_f32_16x16x32_bf16 v[100:103], v[214:217], v[188:191], 0
	v_mfma_f32_16x16x32_bf16 v[96:99], v[222:225], v[188:191], 0
	v_mfma_f32_16x16x32_bf16 v[84:87], v[214:217], v[198:201], 0
	v_mfma_f32_16x16x32_bf16 v[80:83], v[222:225], v[198:201], 0
	v_mfma_f32_16x16x32_bf16 v[68:71], v[214:217], v[206:209], 0
	v_mfma_f32_16x16x32_bf16 v[64:67], v[222:225], v[206:209], 0
	v_mfma_f32_16x16x32_bf16 v[116:119], v[218:221], v[180:183], v[116:119]
	v_mfma_f32_16x16x32_bf16 v[112:115], v[226:229], v[180:183], v[112:115]
	v_mfma_f32_16x16x32_bf16 v[100:103], v[218:221], v[194:197], v[100:103]
	v_mfma_f32_16x16x32_bf16 v[96:99], v[226:229], v[194:197], v[96:99]
	v_mfma_f32_16x16x32_bf16 v[84:87], v[218:221], v[202:205], v[84:87]
	v_mfma_f32_16x16x32_bf16 v[80:83], v[226:229], v[202:205], v[80:83]
	v_mfma_f32_16x16x32_bf16 v[68:71], v[218:221], v[210:213], v[68:71]
	v_mfma_f32_16x16x32_bf16 v[64:67], v[226:229], v[210:213], v[64:67]
	s_setprio 0
	s_mov_b32 m0, s54
	s_barrier
	ds_read_b128 v[176:179], v159 offset:16384
	ds_read_b128 v[180:183], v159 offset:17408
	ds_read_b128 v[188:191], v159 offset:18432
	ds_read_b128 v[194:197], v159 offset:19456
	ds_read_b128 v[198:201], v159 offset:20480
	ds_read_b128 v[202:205], v159 offset:21504
	ds_read_b128 v[206:209], v159 offset:22528
	global_load_lds_dwordx4 v128, s[44:45]
	s_mov_b32 m0, s55
	ds_read_b128 v[210:213], v159 offset:23552
	global_load_lds_dwordx4 v132, s[44:45]
	s_barrier
	s_waitcnt lgkmcnt(0)
	s_setprio 1
	v_mfma_f32_16x16x32_bf16 v[60:63], v[144:147], v[176:179], 0
	v_mfma_f32_16x16x32_bf16 v[56:59], v[168:171], v[176:179], 0
	v_mfma_f32_16x16x32_bf16 v[44:47], v[144:147], v[188:191], 0
	v_mfma_f32_16x16x32_bf16 v[40:43], v[168:171], v[188:191], 0
	v_mfma_f32_16x16x32_bf16 v[28:31], v[144:147], v[198:201], 0
	v_mfma_f32_16x16x32_bf16 v[24:27], v[168:171], v[198:201], 0
	v_mfma_f32_16x16x32_bf16 v[12:15], v[144:147], v[206:209], 0
	v_mfma_f32_16x16x32_bf16 v[8:11], v[168:171], v[206:209], 0
	v_mfma_f32_16x16x32_bf16 v[60:63], v[164:167], v[180:183], v[60:63]
	v_mfma_f32_16x16x32_bf16 v[56:59], v[172:175], v[180:183], v[56:59]
	v_mfma_f32_16x16x32_bf16 v[44:47], v[164:167], v[194:197], v[44:47]
	v_mfma_f32_16x16x32_bf16 v[40:43], v[172:175], v[194:197], v[40:43]
	v_mfma_f32_16x16x32_bf16 v[28:31], v[164:167], v[202:205], v[28:31]
	v_mfma_f32_16x16x32_bf16 v[24:27], v[172:175], v[202:205], v[24:27]
	v_mfma_f32_16x16x32_bf16 v[12:15], v[164:167], v[210:213], v[12:15]
	v_mfma_f32_16x16x32_bf16 v[8:11], v[172:175], v[210:213], v[8:11]
	s_setprio 0
	s_barrier
	s_add_i32 s4, s64, s53
	s_mov_b32 s74, s4
	s_mov_b32 m0, s4
	s_add_u32 s0, s42, 0x160000
	s_addc_u32 s1, s43, 0
	global_load_lds_dwordx4 v130, s[0:1]
	s_add_i32 m0, s4, 0x2000
	s_nop 0
	global_load_lds_dwordx4 v134, s[0:1]
	s_waitcnt vmcnt(6)
	s_barrier
; #define PG8_STAGE(bufoff, gbase, voff) do { _Pragma("unroll") for (int _i = 0; _i < 2; ++_i) \
;         __builtin_amdgcn_global_load_lds((const unsigned*)((const char*)(gbase) + (voff)[_i]), (LAS unsigned*)(lds + (bufoff) + ldsw + _i * 8192), 16, 0, 0); } while (0)
; #define PG8_LDA(dst, b, h) do { _Pragma("unroll") for (int m = 0; m < 4; ++m) _Pragma("unroll") for (int k = 0; k < 2; ++k) dst[m][k] = *(const LAS bf16x8*)(lds + PG8_SA(b, h) + aoff + m * 2048 + k * 1024); } while (0)
; #define PG8_LDB(dst, b, h) do { _Pragma("unroll") for (int n = 0; n < 2; ++n) _Pragma("unroll") for (int k = 0; k < 2; ++k) dst[n][k] = *(const LAS bf16x8*)(lds + PG8_SB(b, h) + boff + n * 2048 + k * 1024); } while (0)
; #define PG8_MMA(ai, bj, At, Bt) do { __builtin_amdgcn_s_setprio(1); _Pragma("unroll") for (int m = 0; m < 4; ++m) _Pragma("unroll") for (int n = 0; n < 2; ++n) _Pragma("unroll") for (int k = 0; k < 2; ++k) \
;         acc[ai][bj][m][n] = __builtin_amdgcn_mfma_f32_16x16x32_bf16(Bt[n][k], At[m][k], acc[ai][bj][m][n], 0, 0, 0); __builtin_amdgcn_s_setprio(0); } while (0)
; #define PG8_WAIT_V(n) asm volatile("s_waitcnt vmcnt(" #n ")" ::: "memory")
; #define PG8_WAIT_L(n) asm volatile("s_waitcnt lgkmcnt(" #n ")" ::: "memory")
; #define PG8_BAR __builtin_amdgcn_s_barrier()
; #define PG8_SCHED __builtin_amdgcn_sched_barrier(0)
; template <class Epi, class Sched>
; DI void gemm_phase(LAS unsigned char* lds, const Gemm g, const Sched& S, const Epi& E) {
;     ...
;             PG8_WAIT_V(6); PG8_BAR; PG8_MMA(1, 1, At, B1); PG8_BAR;
;             PG8_LDB(B0, 1, 0); PG8_SCHED; PG8_LDA(At, 1, 0); PG8_STAGE(PG8_SA(0, 1), a2 + hstep, voffA);
;             PG8_WAIT_L(8); PG8_BAR; PG8_WAIT_L(0); PG8_MMA(0, 0, At, B0); PG8_BAR; PG8_SCHED;
;             PG8_LDB(B1, 1, 1); PG8_STAGE(PG8_SB(1, 0), b3, voffB);
;             PG8_BAR; PG8_WAIT_L(0); PG8_MMA(0, 1, At, B1); PG8_BAR;
;             PG8_LDA(At, 1, 1); PG8_STAGE(PG8_SA(1, 0), a3, voffA);
	s_setprio 1
	v_mfma_f32_16x16x32_bf16 v[52:55], v[214:217], v[176:179], 0
	v_mfma_f32_16x16x32_bf16 v[48:51], v[222:225], v[176:179], 0
	v_mfma_f32_16x16x32_bf16 v[36:39], v[214:217], v[188:191], 0
	v_mfma_f32_16x16x32_bf16 v[32:35], v[222:225], v[188:191], 0
	v_mfma_f32_16x16x32_bf16 v[20:23], v[214:217], v[198:201], 0
	v_mfma_f32_16x16x32_bf16 v[16:19], v[222:225], v[198:201], 0
	v_mfma_f32_16x16x32_bf16 v[4:7], v[214:217], v[206:209], 0
	v_mfma_f32_16x16x32_bf16 v[0:3], v[222:225], v[206:209], 0
	v_mfma_f32_16x16x32_bf16 v[52:55], v[218:221], v[180:183], v[52:55]
	v_mfma_f32_16x16x32_bf16 v[48:51], v[226:229], v[180:183], v[48:51]
	v_mfma_f32_16x16x32_bf16 v[36:39], v[218:221], v[194:197], v[36:39]
	v_mfma_f32_16x16x32_bf16 v[32:35], v[226:229], v[194:197], v[32:35]
	v_mfma_f32_16x16x32_bf16 v[20:23], v[218:221], v[202:205], v[20:23]
	v_mfma_f32_16x16x32_bf16 v[16:19], v[226:229], v[202:205], v[16:19]
	v_mfma_f32_16x16x32_bf16 v[4:7], v[218:221], v[210:213], v[4:7]
	v_mfma_f32_16x16x32_bf16 v[0:3], v[226:229], v[210:213], v[0:3]
	s_setprio 0
	s_add_i32 s4, 0, 0x18000
	v_add_u32_e32 v230, s4, v157
	s_barrier
	ds_read_b128 v[144:147], v230
	ds_read_b128 v[164:167], v230 offset:1024
	ds_read_b128 v[168:171], v230 offset:2048
	ds_read_b128 v[172:175], v230 offset:3072
	s_add_u32 s0, s44, 0x160000
	s_addc_u32 s1, s45, 0
	s_mov_b32 m0, s56
	ds_read_b128 v[176:179], v159 offset:32768
	ds_read_b128 v[180:183], v159 offset:33792
	ds_read_b128 v[188:191], v159 offset:34816
	ds_read_b128 v[194:197], v159 offset:35840
	ds_read_b128 v[198:201], v159 offset:36864
	ds_read_b128 v[202:205], v159 offset:37888
	ds_read_b128 v[206:209], v159 offset:38912
	global_load_lds_dwordx4 v128, s[0:1]
	s_mov_b32 m0, s57
	ds_read_b128 v[210:213], v159 offset:39936
	global_load_lds_dwordx4 v132, s[0:1]
	s_waitcnt lgkmcnt(8)
	s_barrier
	s_waitcnt lgkmcnt(0)
	s_setprio 1
	v_mfma_f32_16x16x32_bf16 v[124:127], v[144:147], v[176:179], v[124:127]
	v_mfma_f32_16x16x32_bf16 v[120:123], v[168:171], v[176:179], v[120:123]
	v_mfma_f32_16x16x32_bf16 v[108:111], v[144:147], v[188:191], v[108:111]
	v_mfma_f32_16x16x32_bf16 v[104:107], v[168:171], v[188:191], v[104:107]
	v_mfma_f32_16x16x32_bf16 v[92:95], v[144:147], v[198:201], v[92:95]
	v_mfma_f32_16x16x32_bf16 v[88:91], v[168:171], v[198:201], v[88:91]
	v_mfma_f32_16x16x32_bf16 v[76:79], v[144:147], v[206:209], v[76:79]
	v_mfma_f32_16x16x32_bf16 v[72:75], v[168:171], v[206:209], v[72:75]
	v_mfma_f32_16x16x32_bf16 v[124:127], v[164:167], v[180:183], v[124:127]
	v_mfma_f32_16x16x32_bf16 v[120:123], v[172:175], v[180:183], v[120:123]
	v_mfma_f32_16x16x32_bf16 v[108:111], v[164:167], v[194:197], v[108:111]
	v_mfma_f32_16x16x32_bf16 v[104:107], v[172:175], v[194:197], v[104:107]
	v_mfma_f32_16x16x32_bf16 v[92:95], v[164:167], v[202:205], v[92:95]
	v_mfma_f32_16x16x32_bf16 v[88:91], v[172:175], v[202:205], v[88:91]
	v_mfma_f32_16x16x32_bf16 v[76:79], v[164:167], v[210:213], v[76:79]
	v_mfma_f32_16x16x32_bf16 v[72:75], v[172:175], v[210:213], v[72:75]
	s_setprio 0
	s_barrier
	s_add_i32 s5, 0, 0x1c000
	s_add_i32 s0, s4, s53
	s_mov_b32 s75, s0
	v_add_u32_e32 v231, s5, v157
	s_add_i32 m0, s0, 0xffffff80
	ds_read_b128 v[214:217], v231
	ds_read_b128 v[218:221], v231 offset:1024
	ds_read_b128 v[222:225], v231 offset:2048
	global_load_lds_dwordx4 v130, s[42:43] offset:128
	s_add_i32 m0, s0, 0x1f80
	ds_read_b128 v[226:229], v231 offset:3072
	global_load_lds_dwordx4 v134, s[42:43] offset:128
	s_barrier
	s_waitcnt lgkmcnt(0)
	s_setprio 1
	v_mfma_f32_16x16x32_bf16 v[116:119], v[214:217], v[176:179], v[116:119]
	v_mfma_f32_16x16x32_bf16 v[112:115], v[222:225], v[176:179], v[112:115]
	v_mfma_f32_16x16x32_bf16 v[100:103], v[214:217], v[188:191], v[100:103]
	v_mfma_f32_16x16x32_bf16 v[96:99], v[222:225], v[188:191], v[96:99]
	v_mfma_f32_16x16x32_bf16 v[84:87], v[214:217], v[198:201], v[84:87]
	v_mfma_f32_16x16x32_bf16 v[80:83], v[222:225], v[198:201], v[80:83]
	v_mfma_f32_16x16x32_bf16 v[68:71], v[214:217], v[206:209], v[68:71]
	v_mfma_f32_16x16x32_bf16 v[64:67], v[222:225], v[206:209], v[64:67]
	v_mfma_f32_16x16x32_bf16 v[116:119], v[218:221], v[180:183], v[116:119]
	v_mfma_f32_16x16x32_bf16 v[112:115], v[226:229], v[180:183], v[112:115]
	v_mfma_f32_16x16x32_bf16 v[100:103], v[218:221], v[194:197], v[100:103]
	v_mfma_f32_16x16x32_bf16 v[96:99], v[226:229], v[194:197], v[96:99]
	v_mfma_f32_16x16x32_bf16 v[84:87], v[218:221], v[202:205], v[84:87]
	v_mfma_f32_16x16x32_bf16 v[80:83], v[226:229], v[202:205], v[80:83]
	v_mfma_f32_16x16x32_bf16 v[68:71], v[218:221], v[210:213], v[68:71]
	v_mfma_f32_16x16x32_bf16 v[64:67], v[226:229], v[210:213], v[64:67]
	s_setprio 0
	s_add_i32 m0, s61, 0xffffff80
	s_barrier
	ds_read_b128 v[176:179], v159 offset:49152
	ds_read_b128 v[180:183], v159 offset:50176
	ds_read_b128 v[188:191], v159 offset:51200
	ds_read_b128 v[194:197], v159 offset:52224
	ds_read_b128 v[198:201], v159 offset:53248
	ds_read_b128 v[202:205], v159 offset:54272
	ds_read_b128 v[206:209], v159 offset:55296
	global_load_lds_dwordx4 v128, s[44:45] offset:128
	s_add_i32 m0, s62, 0xffffff80
	ds_read_b128 v[210:213], v159 offset:56320
	global_load_lds_dwordx4 v132, s[44:45] offset:128
	s_barrier
; #define PG8_STAGE(bufoff, gbase, voff) do { _Pragma("unroll") for (int _i = 0; _i < 2; ++_i) \
;         __builtin_amdgcn_global_load_lds((const unsigned*)((const char*)(gbase) + (voff)[_i]), (LAS unsigned*)(lds + (bufoff) + ldsw + _i * 8192), 16, 0, 0); } while (0)
; #define PG8_LDA(dst, b, h) do { _Pragma("unroll") for (int m = 0; m < 4; ++m) _Pragma("unroll") for (int k = 0; k < 2; ++k) dst[m][k] = *(const LAS bf16x8*)(lds + PG8_SA(b, h) + aoff + m * 2048 + k * 1024); } while (0)
; #define PG8_LDB(dst, b, h) do { _Pragma("unroll") for (int n = 0; n < 2; ++n) _Pragma("unroll") for (int k = 0; k < 2; ++k) dst[n][k] = *(const LAS bf16x8*)(lds + PG8_SB(b, h) + boff + n * 2048 + k * 1024); } while (0)
; #define PG8_MMA(ai, bj, At, Bt) do { __builtin_amdgcn_s_setprio(1); _Pragma("unroll") for (int m = 0; m < 4; ++m) _Pragma("unroll") for (int n = 0; n < 2; ++n) _Pragma("unroll") for (int k = 0; k < 2; ++k) \
;         acc[ai][bj][m][n] = __builtin_amdgcn_mfma_f32_16x16x32_bf16(Bt[n][k], At[m][k], acc[ai][bj][m][n], 0, 0, 0); __builtin_amdgcn_s_setprio(0); } while (0)
; #define PG8_WAIT_V(n) asm volatile("s_waitcnt vmcnt(" #n ")" ::: "memory")
; #define PG8_WAIT_L(n) asm volatile("s_waitcnt lgkmcnt(" #n ")" ::: "memory")
; #define PG8_BAR __builtin_amdgcn_s_barrier()
; #define PG8_SCHED __builtin_amdgcn_sched_barrier(0)
; template <class Epi, class Sched>
; DI void gemm_phase(LAS unsigned char* lds, const Gemm g, const Sched& S, const Epi& E) {
;     ...
;             PG8_LDB(B0, 0, 0); PG8_SCHED; PG8_LDA(At, 0, 0); PG8_STAGE(PG8_SA(1, 1), a1 + hstep, voffA);
;             PG8_WAIT_L(8); PG8_BAR; PG8_WAIT_L(0); PG8_MMA(0, 0, At, B0); PG8_BAR; PG8_SCHED;
;             PG8_LDB(B1, 0, 1); PG8_STAGE(PG8_SB(0, 0), b2, voffB);
;     ...
;             PG8_BAR; PG8_WAIT_L(0); PG8_MMA(1, 0, At, B0); PG8_BAR; PG8_SCHED;
;             PG8_STAGE(PG8_SB(1, 1), b3 + hstep, voffB);
;             PG8_WAIT_V(6); PG8_BAR; PG8_MMA(1, 1, At, B1); PG8_BAR;
	s_waitcnt lgkmcnt(0)
	s_setprio 1
	v_mfma_f32_16x16x32_bf16 v[60:63], v[144:147], v[176:179], v[60:63]
	v_mfma_f32_16x16x32_bf16 v[56:59], v[168:171], v[176:179], v[56:59]
	v_mfma_f32_16x16x32_bf16 v[44:47], v[144:147], v[188:191], v[44:47]
	v_mfma_f32_16x16x32_bf16 v[40:43], v[168:171], v[188:191], v[40:43]
	v_mfma_f32_16x16x32_bf16 v[28:31], v[144:147], v[198:201], v[28:31]
	v_mfma_f32_16x16x32_bf16 v[24:27], v[168:171], v[198:201], v[24:27]
	v_mfma_f32_16x16x32_bf16 v[12:15], v[144:147], v[206:209], v[12:15]
	v_mfma_f32_16x16x32_bf16 v[8:11], v[168:171], v[206:209], v[8:11]
	v_mfma_f32_16x16x32_bf16 v[60:63], v[164:167], v[180:183], v[60:63]
	v_mfma_f32_16x16x32_bf16 v[56:59], v[172:175], v[180:183], v[56:59]
	v_mfma_f32_16x16x32_bf16 v[44:47], v[164:167], v[194:197], v[44:47]
	v_mfma_f32_16x16x32_bf16 v[40:43], v[172:175], v[194:197], v[40:43]
	v_mfma_f32_16x16x32_bf16 v[28:31], v[164:167], v[202:205], v[28:31]
	v_mfma_f32_16x16x32_bf16 v[24:27], v[172:175], v[202:205], v[24:27]
	v_mfma_f32_16x16x32_bf16 v[12:15], v[164:167], v[210:213], v[12:15]
	v_mfma_f32_16x16x32_bf16 v[8:11], v[172:175], v[210:213], v[8:11]
	s_setprio 0
	s_barrier
	s_add_i32 s4, s5, s53
	s_mov_b32 s76, s4
	s_mov_b32 m0, s4
	s_add_u32 s0, s42, 0x160080
	s_addc_u32 s1, s43, 0
	global_load_lds_dwordx4 v130, s[0:1]
	s_add_i32 m0, s4, 0x2000
	s_nop 0
	global_load_lds_dwordx4 v134, s[0:1]
	s_waitcnt vmcnt(6)
	s_barrier
	s_setprio 1
	v_mfma_f32_16x16x32_bf16 v[52:55], v[214:217], v[176:179], v[52:55]
	v_mfma_f32_16x16x32_bf16 v[48:51], v[222:225], v[176:179], v[48:51]
	v_mfma_f32_16x16x32_bf16 v[36:39], v[214:217], v[188:191], v[36:39]
	v_mfma_f32_16x16x32_bf16 v[32:35], v[222:225], v[188:191], v[32:35]
	v_mfma_f32_16x16x32_bf16 v[20:23], v[214:217], v[198:201], v[20:23]
	v_mfma_f32_16x16x32_bf16 v[16:19], v[222:225], v[198:201], v[16:19]
	v_mfma_f32_16x16x32_bf16 v[4:7], v[214:217], v[206:209], v[4:7]
	v_mfma_f32_16x16x32_bf16 v[0:3], v[222:225], v[206:209], v[0:3]
	v_mfma_f32_16x16x32_bf16 v[52:55], v[218:221], v[180:183], v[52:55]
	v_mfma_f32_16x16x32_bf16 v[48:51], v[226:229], v[180:183], v[48:51]
	v_mfma_f32_16x16x32_bf16 v[36:39], v[218:221], v[194:197], v[36:39]
	v_mfma_f32_16x16x32_bf16 v[32:35], v[226:229], v[194:197], v[32:35]
	v_mfma_f32_16x16x32_bf16 v[20:23], v[218:221], v[202:205], v[20:23]
	v_mfma_f32_16x16x32_bf16 v[16:19], v[226:229], v[202:205], v[16:19]
	v_mfma_f32_16x16x32_bf16 v[4:7], v[218:221], v[210:213], v[4:7]
	v_mfma_f32_16x16x32_bf16 v[0:3], v[226:229], v[210:213], v[0:3]
	s_setprio 0
	s_add_i32 s69, s69, 2
	s_add_u32 s40, s40, 0x100
	s_addc_u32 s41, s41, 0
	s_add_u32 s35, s35, 0x100
	s_addc_u32 s68, s68, 0
	s_cmpk_gt_u32 s69, 0x55
	s_barrier
	s_cbranch_scc0 .LBB0_297
	s_branch .Lpeel_done_297
.LBB0_297:
	ds_read_b128 v[144:147], v158
	ds_read_b128 v[164:167], v158 offset:1024
	ds_read_b128 v[168:171], v158 offset:2048
	ds_read_b128 v[172:175], v158 offset:3072
	s_add_u32 s0, s40, 0xffea0080
	s_addc_u32 s1, s41, -1
	s_cmpk_eq_i32 s69, 0x54
	s_cselect_b32 s45, s9, s1
	s_cselect_b32 s44, s8, s0
	s_cselect_b32 s43, s11, s68
	s_cselect_b32 s42, s10, s35
	s_add_i32 m0, s54, 0xc000
	ds_read_b128 v[176:179], v159
	ds_read_b128 v[180:183], v159 offset:1024
	ds_read_b128 v[188:191], v159 offset:2048
	ds_read_b128 v[194:197], v159 offset:3072
	ds_read_b128 v[198:201], v159 offset:4096
	ds_read_b128 v[202:205], v159 offset:5120
	ds_read_b128 v[206:209], v159 offset:6144
	global_load_lds_dwordx4 v136, s[40:41]
	s_add_i32 m0, s54, 0xe000
	ds_read_b128 v[210:213], v159 offset:7168
	global_load_lds_dwordx4 v138, s[40:41]
	s_waitcnt lgkmcnt(8)
	s_barrier
	s_waitcnt lgkmcnt(0)
	s_setprio 1
	v_mfma_f32_16x16x32_bf16 v[124:127], v[144:147], v[176:179], v[124:127]
	v_mfma_f32_16x16x32_bf16 v[120:123], v[168:171], v[176:179], v[120:123]
	v_mfma_f32_16x16x32_bf16 v[108:111], v[144:147], v[188:191], v[108:111]
	v_mfma_f32_16x16x32_bf16 v[104:107], v[168:171], v[188:191], v[104:107]
	v_mfma_f32_16x16x32_bf16 v[92:95], v[144:147], v[198:201], v[92:95]
	v_mfma_f32_16x16x32_bf16 v[88:91], v[168:171], v[198:201], v[88:91]
	v_mfma_f32_16x16x32_bf16 v[76:79], v[144:147], v[206:209], v[76:79]
	v_mfma_f32_16x16x32_bf16 v[72:75], v[168:171], v[206:209], v[72:75]
	v_mfma_f32_16x16x32_bf16 v[124:127], v[164:167], v[180:183], v[124:127]
	v_mfma_f32_16x16x32_bf16 v[120:123], v[172:175], v[180:183], v[120:123]
	v_mfma_f32_16x16x32_bf16 v[108:111], v[164:167], v[194:197], v[108:111]
	v_mfma_f32_16x16x32_bf16 v[104:107], v[172:175], v[194:197], v[104:107]
	v_mfma_f32_16x16x32_bf16 v[92:95], v[164:167], v[202:205], v[92:95]
	v_mfma_f32_16x16x32_bf16 v[88:91], v[172:175], v[202:205], v[88:91]
	v_mfma_f32_16x16x32_bf16 v[76:79], v[164:167], v[210:213], v[76:79]
	v_mfma_f32_16x16x32_bf16 v[72:75], v[172:175], v[210:213], v[72:75]
	s_setprio 0
	s_barrier
	s_mov_b32 m0, s32
	ds_read_b128 v[214:217], v161
	ds_read_b128 v[218:221], v161 offset:1024
	ds_read_b128 v[222:225], v161 offset:2048
	global_load_lds_dwordx4 v130, s[42:43]
	s_add_i32 m0, s32, 0x2000
	ds_read_b128 v[226:229], v161 offset:3072
	global_load_lds_dwordx4 v134, s[42:43]
	s_barrier
; #define PG8_STAGE(bufoff, gbase, voff) do { _Pragma("unroll") for (int _i = 0; _i < 2; ++_i) \
;         __builtin_amdgcn_global_load_lds((const unsigned*)((const char*)(gbase) + (voff)[_i]), (LAS unsigned*)(lds + (bufoff) + ldsw + _i * 8192), 16, 0, 0); } while (0)
; #define PG8_LDA(dst, b, h) do { _Pragma("unroll") for (int m = 0; m < 4; ++m) _Pragma("unroll") for (int k = 0; k < 2; ++k) dst[m][k] = *(const LAS bf16x8*)(lds + PG8_SA(b, h) + aoff + m * 2048 + k * 1024); } while (0)
; #define PG8_LDB(dst, b, h) do { _Pragma("unroll") for (int n = 0; n < 2; ++n) _Pragma("unroll") for (int k = 0; k < 2; ++k) dst[n][k] = *(const LAS bf16x8*)(lds + PG8_SB(b, h) + boff + n * 2048 + k * 1024); } while (0)
; #define PG8_MMA(ai, bj, At, Bt) do { __builtin_amdgcn_s_setprio(1); _Pragma("unroll") for (int m = 0; m < 4; ++m) _Pragma("unroll") for (int n = 0; n < 2; ++n) _Pragma("unroll") for (int k = 0; k < 2; ++k) \
;         acc[ai][bj][m][n] = __builtin_amdgcn_mfma_f32_16x16x32_bf16(Bt[n][k], At[m][k], acc[ai][bj][m][n], 0, 0, 0); __builtin_amdgcn_s_setprio(0); } while (0)
; #define PG8_WAIT_V(n) asm volatile("s_waitcnt vmcnt(" #n ")" ::: "memory")
; #define PG8_WAIT_L(n) asm volatile("s_waitcnt lgkmcnt(" #n ")" ::: "memory")
; #define PG8_BAR __builtin_amdgcn_s_barrier()
; #define PG8_SCHED __builtin_amdgcn_sched_barrier(0)
; template <class Epi, class Sched>
; DI void gemm_phase(LAS unsigned char* lds, const Gemm g, const Sched& S, const Epi& E) {
;     ...
;             PG8_BAR; PG8_WAIT_L(0); PG8_MMA(0, 1, At, B1); PG8_BAR;
;             PG8_LDA(At, 0, 1); PG8_STAGE(PG8_SA(0, 0), a2, voffA);
;             PG8_BAR; PG8_WAIT_L(0); PG8_MMA(1, 0, At, B0); PG8_BAR; PG8_SCHED;
;             PG8_STAGE(PG8_SB(0, 1), b2 + hstep, voffB);
;             PG8_WAIT_V(6); PG8_BAR; PG8_MMA(1, 1, At, B1); PG8_BAR;
;             PG8_LDB(B0, 1, 0); PG8_SCHED; PG8_LDA(At, 1, 0); PG8_STAGE(PG8_SA(0, 1), a2 + hstep, voffA);
;             PG8_WAIT_L(8); PG8_BAR; PG8_WAIT_L(0); PG8_MMA(0, 0, At, B0); PG8_BAR; PG8_SCHED;
	s_waitcnt lgkmcnt(0)
	s_setprio 1
	v_mfma_f32_16x16x32_bf16 v[116:119], v[214:217], v[176:179], v[116:119]
	v_mfma_f32_16x16x32_bf16 v[112:115], v[222:225], v[176:179], v[112:115]
	v_mfma_f32_16x16x32_bf16 v[100:103], v[214:217], v[188:191], v[100:103]
	v_mfma_f32_16x16x32_bf16 v[96:99], v[222:225], v[188:191], v[96:99]
	v_mfma_f32_16x16x32_bf16 v[84:87], v[214:217], v[198:201], v[84:87]
	v_mfma_f32_16x16x32_bf16 v[80:83], v[222:225], v[198:201], v[80:83]
	v_mfma_f32_16x16x32_bf16 v[68:71], v[214:217], v[206:209], v[68:71]
	v_mfma_f32_16x16x32_bf16 v[64:67], v[222:225], v[206:209], v[64:67]
	v_mfma_f32_16x16x32_bf16 v[116:119], v[218:221], v[180:183], v[116:119]
	v_mfma_f32_16x16x32_bf16 v[112:115], v[226:229], v[180:183], v[112:115]
	v_mfma_f32_16x16x32_bf16 v[100:103], v[218:221], v[194:197], v[100:103]
	v_mfma_f32_16x16x32_bf16 v[96:99], v[226:229], v[194:197], v[96:99]
	v_mfma_f32_16x16x32_bf16 v[84:87], v[218:221], v[202:205], v[84:87]
	v_mfma_f32_16x16x32_bf16 v[80:83], v[226:229], v[202:205], v[80:83]
	v_mfma_f32_16x16x32_bf16 v[68:71], v[218:221], v[210:213], v[68:71]
	v_mfma_f32_16x16x32_bf16 v[64:67], v[226:229], v[210:213], v[64:67]
	s_setprio 0
	s_mov_b32 m0, s54
	s_barrier
	ds_read_b128 v[176:179], v159 offset:16384
	ds_read_b128 v[180:183], v159 offset:17408
	ds_read_b128 v[188:191], v159 offset:18432
	ds_read_b128 v[194:197], v159 offset:19456
	ds_read_b128 v[198:201], v159 offset:20480
	ds_read_b128 v[202:205], v159 offset:21504
	ds_read_b128 v[206:209], v159 offset:22528
	global_load_lds_dwordx4 v128, s[44:45]
	s_mov_b32 m0, s55
	ds_read_b128 v[210:213], v159 offset:23552
	global_load_lds_dwordx4 v132, s[44:45]
	s_barrier
	s_waitcnt lgkmcnt(0)
	s_setprio 1
	v_mfma_f32_16x16x32_bf16 v[60:63], v[144:147], v[176:179], v[60:63]
	v_mfma_f32_16x16x32_bf16 v[56:59], v[168:171], v[176:179], v[56:59]
	v_mfma_f32_16x16x32_bf16 v[44:47], v[144:147], v[188:191], v[44:47]
	v_mfma_f32_16x16x32_bf16 v[40:43], v[168:171], v[188:191], v[40:43]
	v_mfma_f32_16x16x32_bf16 v[28:31], v[144:147], v[198:201], v[28:31]
	v_mfma_f32_16x16x32_bf16 v[24:27], v[168:171], v[198:201], v[24:27]
	v_mfma_f32_16x16x32_bf16 v[12:15], v[144:147], v[206:209], v[12:15]
	v_mfma_f32_16x16x32_bf16 v[8:11], v[168:171], v[206:209], v[8:11]
	v_mfma_f32_16x16x32_bf16 v[60:63], v[164:167], v[180:183], v[60:63]
	v_mfma_f32_16x16x32_bf16 v[56:59], v[172:175], v[180:183], v[56:59]
	v_mfma_f32_16x16x32_bf16 v[44:47], v[164:167], v[194:197], v[44:47]
	v_mfma_f32_16x16x32_bf16 v[40:43], v[172:175], v[194:197], v[40:43]
	v_mfma_f32_16x16x32_bf16 v[28:31], v[164:167], v[202:205], v[28:31]
	v_mfma_f32_16x16x32_bf16 v[24:27], v[172:175], v[202:205], v[24:27]
	v_mfma_f32_16x16x32_bf16 v[12:15], v[164:167], v[210:213], v[12:15]
	v_mfma_f32_16x16x32_bf16 v[8:11], v[172:175], v[210:213], v[8:11]
	s_setprio 0
	s_barrier
	s_mov_b32 m0, s74
	s_add_u32 s0, s42, 0x160000
	s_addc_u32 s1, s43, 0
	global_load_lds_dwordx4 v130, s[0:1]
	s_add_i32 m0, s74, 0x2000
	s_nop 0
	global_load_lds_dwordx4 v134, s[0:1]
	s_waitcnt vmcnt(6)
	s_barrier
	s_setprio 1
	v_mfma_f32_16x16x32_bf16 v[52:55], v[214:217], v[176:179], v[52:55]
	v_mfma_f32_16x16x32_bf16 v[48:51], v[222:225], v[176:179], v[48:51]
	v_mfma_f32_16x16x32_bf16 v[36:39], v[214:217], v[188:191], v[36:39]
	v_mfma_f32_16x16x32_bf16 v[32:35], v[222:225], v[188:191], v[32:35]
	v_mfma_f32_16x16x32_bf16 v[20:23], v[214:217], v[198:201], v[20:23]
	v_mfma_f32_16x16x32_bf16 v[16:19], v[222:225], v[198:201], v[16:19]
	v_mfma_f32_16x16x32_bf16 v[4:7], v[214:217], v[206:209], v[4:7]
	v_mfma_f32_16x16x32_bf16 v[0:3], v[222:225], v[206:209], v[0:3]
	v_mfma_f32_16x16x32_bf16 v[52:55], v[218:221], v[180:183], v[52:55]
	v_mfma_f32_16x16x32_bf16 v[48:51], v[226:229], v[180:183], v[48:51]
	v_mfma_f32_16x16x32_bf16 v[36:39], v[218:221], v[194:197], v[36:39]
	v_mfma_f32_16x16x32_bf16 v[32:35], v[226:229], v[194:197], v[32:35]
	v_mfma_f32_16x16x32_bf16 v[20:23], v[218:221], v[202:205], v[20:23]
	v_mfma_f32_16x16x32_bf16 v[16:19], v[226:229], v[202:205], v[16:19]
	v_mfma_f32_16x16x32_bf16 v[4:7], v[218:221], v[210:213], v[4:7]
	v_mfma_f32_16x16x32_bf16 v[0:3], v[226:229], v[210:213], v[0:3]
	s_setprio 0
	s_add_i32 s4, 0, 0x18000
	s_barrier
	ds_read_b128 v[144:147], v230
	ds_read_b128 v[164:167], v230 offset:1024
	ds_read_b128 v[168:171], v230 offset:2048
	ds_read_b128 v[172:175], v230 offset:3072
	s_add_u32 s0, s44, 0x160000
	s_addc_u32 s1, s45, 0
	s_mov_b32 m0, s56
	ds_read_b128 v[176:179], v159 offset:32768
	ds_read_b128 v[180:183], v159 offset:33792
	ds_read_b128 v[188:191], v159 offset:34816
	ds_read_b128 v[194:197], v159 offset:35840
	ds_read_b128 v[198:201], v159 offset:36864
	ds_read_b128 v[202:205], v159 offset:37888
	ds_read_b128 v[206:209], v159 offset:38912
	global_load_lds_dwordx4 v128, s[0:1]
	s_mov_b32 m0, s57
	ds_read_b128 v[210:213], v159 offset:39936
	global_load_lds_dwordx4 v132, s[0:1]
	s_waitcnt lgkmcnt(8)
	s_barrier
; #define PG8_STAGE(bufoff, gbase, voff) do { _Pragma("unroll") for (int _i = 0; _i < 2; ++_i) \
;         __builtin_amdgcn_global_load_lds((const unsigned*)((const char*)(gbase) + (voff)[_i]), (LAS unsigned*)(lds + (bufoff) + ldsw + _i * 8192), 16, 0, 0); } while (0)
; #define PG8_LDA(dst, b, h) do { _Pragma("unroll") for (int m = 0; m < 4; ++m) _Pragma("unroll") for (int k = 0; k < 2; ++k) dst[m][k] = *(const LAS bf16x8*)(lds + PG8_SA(b, h) + aoff + m * 2048 + k * 1024); } while (0)
; #define PG8_LDB(dst, b, h) do { _Pragma("unroll") for (int n = 0; n < 2; ++n) _Pragma("unroll") for (int k = 0; k < 2; ++k) dst[n][k] = *(const LAS bf16x8*)(lds + PG8_SB(b, h) + boff + n * 2048 + k * 1024); } while (0)
; #define PG8_MMA(ai, bj, At, Bt) do { __builtin_amdgcn_s_setprio(1); _Pragma("unroll") for (int m = 0; m < 4; ++m) _Pragma("unroll") for (int n = 0; n < 2; ++n) _Pragma("unroll") for (int k = 0; k < 2; ++k) \
;         acc[ai][bj][m][n] = __builtin_amdgcn_mfma_f32_16x16x32_bf16(Bt[n][k], At[m][k], acc[ai][bj][m][n], 0, 0, 0); __builtin_amdgcn_s_setprio(0); } while (0)
; #define PG8_WAIT_V(n) asm volatile("s_waitcnt vmcnt(" #n ")" ::: "memory")
; #define PG8_WAIT_L(n) asm volatile("s_waitcnt lgkmcnt(" #n ")" ::: "memory")
; #define PG8_BAR __builtin_amdgcn_s_barrier()
; #define PG8_SCHED __builtin_amdgcn_sched_barrier(0)
; template <class Epi, class Sched>
; DI void gemm_phase(LAS unsigned char* lds, const Gemm g, const Sched& S, const Epi& E) {
;     ...
;             PG8_WAIT_L(8); PG8_BAR; PG8_WAIT_L(0); PG8_MMA(0, 0, At, B0); PG8_BAR; PG8_SCHED;
;             PG8_LDB(B1, 1, 1); PG8_STAGE(PG8_SB(1, 0), b3, voffB);
;             PG8_BAR; PG8_WAIT_L(0); PG8_MMA(0, 1, At, B1); PG8_BAR;
;             PG8_LDA(At, 1, 1); PG8_STAGE(PG8_SA(1, 0), a3, voffA);
;             PG8_BAR; PG8_WAIT_L(0); PG8_MMA(1, 0, At, B0); PG8_BAR; PG8_SCHED;
;             PG8_STAGE(PG8_SB(1, 1), b3 + hstep, voffB);
;             PG8_WAIT_V(6); PG8_BAR; PG8_MMA(1, 1, At, B1); PG8_BAR;
;         }
	s_waitcnt lgkmcnt(0)
	s_setprio 1
	v_mfma_f32_16x16x32_bf16 v[124:127], v[144:147], v[176:179], v[124:127]
	v_mfma_f32_16x16x32_bf16 v[120:123], v[168:171], v[176:179], v[120:123]
	v_mfma_f32_16x16x32_bf16 v[108:111], v[144:147], v[188:191], v[108:111]
	v_mfma_f32_16x16x32_bf16 v[104:107], v[168:171], v[188:191], v[104:107]
	v_mfma_f32_16x16x32_bf16 v[92:95], v[144:147], v[198:201], v[92:95]
	v_mfma_f32_16x16x32_bf16 v[88:91], v[168:171], v[198:201], v[88:91]
	v_mfma_f32_16x16x32_bf16 v[76:79], v[144:147], v[206:209], v[76:79]
	v_mfma_f32_16x16x32_bf16 v[72:75], v[168:171], v[206:209], v[72:75]
	v_mfma_f32_16x16x32_bf16 v[124:127], v[164:167], v[180:183], v[124:127]
	v_mfma_f32_16x16x32_bf16 v[120:123], v[172:175], v[180:183], v[120:123]
	v_mfma_f32_16x16x32_bf16 v[108:111], v[164:167], v[194:197], v[108:111]
	v_mfma_f32_16x16x32_bf16 v[104:107], v[172:175], v[194:197], v[104:107]
	v_mfma_f32_16x16x32_bf16 v[92:95], v[164:167], v[202:205], v[92:95]
	v_mfma_f32_16x16x32_bf16 v[88:91], v[172:175], v[202:205], v[88:91]
	v_mfma_f32_16x16x32_bf16 v[76:79], v[164:167], v[210:213], v[76:79]
	v_mfma_f32_16x16x32_bf16 v[72:75], v[172:175], v[210:213], v[72:75]
	s_setprio 0
	s_barrier
	s_add_i32 s5, 0, 0x1c000
	s_add_i32 m0, s75, 0xffffff80
	ds_read_b128 v[214:217], v231
	ds_read_b128 v[218:221], v231 offset:1024
	ds_read_b128 v[222:225], v231 offset:2048
	global_load_lds_dwordx4 v130, s[42:43] offset:128
	s_add_i32 m0, s75, 0x1f80
	ds_read_b128 v[226:229], v231 offset:3072
	global_load_lds_dwordx4 v134, s[42:43] offset:128
	s_barrier
	s_waitcnt lgkmcnt(0)
	s_setprio 1
	v_mfma_f32_16x16x32_bf16 v[116:119], v[214:217], v[176:179], v[116:119]
	v_mfma_f32_16x16x32_bf16 v[112:115], v[222:225], v[176:179], v[112:115]
	v_mfma_f32_16x16x32_bf16 v[100:103], v[214:217], v[188:191], v[100:103]
	v_mfma_f32_16x16x32_bf16 v[96:99], v[222:225], v[188:191], v[96:99]
	v_mfma_f32_16x16x32_bf16 v[84:87], v[214:217], v[198:201], v[84:87]
	v_mfma_f32_16x16x32_bf16 v[80:83], v[222:225], v[198:201], v[80:83]
	v_mfma_f32_16x16x32_bf16 v[68:71], v[214:217], v[206:209], v[68:71]
	v_mfma_f32_16x16x32_bf16 v[64:67], v[222:225], v[206:209], v[64:67]
	v_mfma_f32_16x16x32_bf16 v[116:119], v[218:221], v[180:183], v[116:119]
	v_mfma_f32_16x16x32_bf16 v[112:115], v[226:229], v[180:183], v[112:115]
	v_mfma_f32_16x16x32_bf16 v[100:103], v[218:221], v[194:197], v[100:103]
	v_mfma_f32_16x16x32_bf16 v[96:99], v[226:229], v[194:197], v[96:99]
	v_mfma_f32_16x16x32_bf16 v[84:87], v[218:221], v[202:205], v[84:87]
	v_mfma_f32_16x16x32_bf16 v[80:83], v[226:229], v[202:205], v[80:83]
	v_mfma_f32_16x16x32_bf16 v[68:71], v[218:221], v[210:213], v[68:71]
	v_mfma_f32_16x16x32_bf16 v[64:67], v[226:229], v[210:213], v[64:67]
	s_setprio 0
	s_add_i32 m0, s61, 0xffffff80
	s_barrier
	ds_read_b128 v[176:179], v159 offset:49152
	ds_read_b128 v[180:183], v159 offset:50176
	ds_read_b128 v[188:191], v159 offset:51200
	ds_read_b128 v[194:197], v159 offset:52224
	ds_read_b128 v[198:201], v159 offset:53248
	ds_read_b128 v[202:205], v159 offset:54272
	ds_read_b128 v[206:209], v159 offset:55296
	global_load_lds_dwordx4 v128, s[44:45] offset:128
	s_add_i32 m0, s62, 0xffffff80
	ds_read_b128 v[210:213], v159 offset:56320
	global_load_lds_dwordx4 v132, s[44:45] offset:128
	s_barrier
	s_waitcnt lgkmcnt(0)
	s_setprio 1
	v_mfma_f32_16x16x32_bf16 v[60:63], v[144:147], v[176:179], v[60:63]
	v_mfma_f32_16x16x32_bf16 v[56:59], v[168:171], v[176:179], v[56:59]
	v_mfma_f32_16x16x32_bf16 v[44:47], v[144:147], v[188:191], v[44:47]
	v_mfma_f32_16x16x32_bf16 v[40:43], v[168:171], v[188:191], v[40:43]
	v_mfma_f32_16x16x32_bf16 v[28:31], v[144:147], v[198:201], v[28:31]
	v_mfma_f32_16x16x32_bf16 v[24:27], v[168:171], v[198:201], v[24:27]
	v_mfma_f32_16x16x32_bf16 v[12:15], v[144:147], v[206:209], v[12:15]
	v_mfma_f32_16x16x32_bf16 v[8:11], v[168:171], v[206:209], v[8:11]
	v_mfma_f32_16x16x32_bf16 v[60:63], v[164:167], v[180:183], v[60:63]
	v_mfma_f32_16x16x32_bf16 v[56:59], v[172:175], v[180:183], v[56:59]
	v_mfma_f32_16x16x32_bf16 v[44:47], v[164:167], v[194:197], v[44:47]
	v_mfma_f32_16x16x32_bf16 v[40:43], v[172:175], v[194:197], v[40:43]
	v_mfma_f32_16x16x32_bf16 v[28:31], v[164:167], v[202:205], v[28:31]
	v_mfma_f32_16x16x32_bf16 v[24:27], v[172:175], v[202:205], v[24:27]
	v_mfma_f32_16x16x32_bf16 v[12:15], v[164:167], v[210:213], v[12:15]
	v_mfma_f32_16x16x32_bf16 v[8:11], v[172:175], v[210:213], v[8:11]
	s_setprio 0
	s_barrier
	s_mov_b32 m0, s76
	s_add_u32 s0, s42, 0x160080
	s_addc_u32 s1, s43, 0
	global_load_lds_dwordx4 v130, s[0:1]
	s_add_i32 m0, s76, 0x2000
	s_nop 0
	global_load_lds_dwordx4 v134, s[0:1]
	s_waitcnt vmcnt(6)
	s_barrier
	s_setprio 1
	v_mfma_f32_16x16x32_bf16 v[52:55], v[214:217], v[176:179], v[52:55]
	v_mfma_f32_16x16x32_bf16 v[48:51], v[222:225], v[176:179], v[48:51]
	v_mfma_f32_16x16x32_bf16 v[36:39], v[214:217], v[188:191], v[36:39]
	v_mfma_f32_16x16x32_bf16 v[32:35], v[222:225], v[188:191], v[32:35]
	v_mfma_f32_16x16x32_bf16 v[20:23], v[214:217], v[198:201], v[20:23]
	v_mfma_f32_16x16x32_bf16 v[16:19], v[222:225], v[198:201], v[16:19]
	v_mfma_f32_16x16x32_bf16 v[4:7], v[214:217], v[206:209], v[4:7]
	v_mfma_f32_16x16x32_bf16 v[0:3], v[222:225], v[206:209], v[0:3]
	v_mfma_f32_16x16x32_bf16 v[52:55], v[218:221], v[180:183], v[52:55]
	v_mfma_f32_16x16x32_bf16 v[48:51], v[226:229], v[180:183], v[48:51]
	v_mfma_f32_16x16x32_bf16 v[36:39], v[218:221], v[194:197], v[36:39]
	v_mfma_f32_16x16x32_bf16 v[32:35], v[226:229], v[194:197], v[32:35]
	v_mfma_f32_16x16x32_bf16 v[20:23], v[218:221], v[202:205], v[20:23]
	v_mfma_f32_16x16x32_bf16 v[16:19], v[226:229], v[202:205], v[16:19]
	v_mfma_f32_16x16x32_bf16 v[4:7], v[218:221], v[210:213], v[4:7]
	v_mfma_f32_16x16x32_bf16 v[0:3], v[226:229], v[210:213], v[0:3]
	s_setprio 0
	s_add_i32 s69, s69, 2
	s_add_u32 s40, s40, 0x100
	s_addc_u32 s41, s41, 0
	s_add_u32 s35, s35, 0x100
	s_addc_u32 s68, s68, 0
	s_cmpk_gt_u32 s69, 0x55
	s_barrier
	s_cbranch_scc0 .LBB0_297

;     DI size_t aoff(const Unit& u, size_t tstep) const { return (size_t)u.pm * tstep; }
;     DI size_t boff(const Unit& u, size_t tstep) const { return (size_t)u.pn * tstep; }
;     DI bool next(int i, Unit& u) const { const long L = (long)i * G + c; if (L >= np) return false; u.pm = pmv; u.pn = (int)(L % nN); u.ks = (int)(L / nN); return true; }
;     DI size_t aoff(const Unit& u, size_t) const { return (size_t)u.ks * kbytes; }
;     DI size_t boff(const Unit& u, size_t tstep) const { return (size_t)u.pn * tstep + (size_t)u.ks * kbytes; }
;     DI bool next(int i, Unit& u) const { Unit t; if (!S.next(i / 3, t)) return false; u.pm = t.pm; u.pn = t.pn; u.ks = i % 3; return true; }
;     DI size_t aoff(const Unit& u, size_t tstep) const { return (u.ks < 2 ? offU : offOA) + (size_t)u.pm * tstep; }
; #define PG8_WAIT_V(n) asm volatile("s_waitcnt vmcnt(" #n ")" ::: "memory")
; template <class Epi, class Sched>
; DI void gemm_phase(LAS unsigned char* lds, const Gemm g, const Sched& S, const Epi& E) {
;     ...
;         const bool has_next = S.next(ui + 1, nxt);
;         const char* nA = has_next ? (const char*)g.A + S.aoff(nxt, tstep) : cA; const char* nB = has_next ? (const char*)g.Bt + S.boff(nxt, tstep) : cB;
;         for (int t = 0; t < nt; t += 2) {
;             if constexpr (Epi::HAS_MID) { if (t == E.mid_t(nt)) { int fr3 = fr, fq3 = fq; asm volatile("" : "+v"(fr3), "+v"(fq3)); E.mid(acc, cur, wr, wc, fr3, fq3); } }
;             const bool last = (t == nt - 2);
;             const char* a1 = cA + (size_t)(t + 1) * kstep;
;             const char* a2 = last ? nA : cA + (size_t)(t + 2) * kstep; const char* b2 = last ? nB : cB + (size_t)(t + 2) * kstep;
;             const char* a3 = a2 + kstep; const char* b3 = b2 + kstep;
;             PG8_LDB(B0, 0, 0); PG8_SCHED; PG8_LDA(At, 0, 0); PG8_STAGE(PG8_SA(1, 1), a1 + hstep, voffA);
;             PG8_WAIT_L(8); PG8_BAR; PG8_WAIT_L(0); PG8_MMA(0, 0, At, B0); PG8_BAR; PG8_SCHED;
;             PG8_LDB(B1, 0, 1); PG8_STAGE(PG8_SB(0, 0), b2, voffB);
;             PG8_BAR; PG8_WAIT_L(0); PG8_MMA(0, 1, At, B1); PG8_BAR;
;             PG8_LDA(At, 0, 1); PG8_STAGE(PG8_SA(0, 0), a2, voffA);
;             PG8_BAR; PG8_WAIT_L(0); PG8_MMA(1, 0, At, B0); PG8_BAR; PG8_SCHED;
;             PG8_STAGE(PG8_SB(0, 1), b2 + hstep, voffB);
;             PG8_WAIT_V(6); PG8_BAR; PG8_MMA(1, 1, At, B1); PG8_BAR;
.LBB0_325:
	s_add_u32 s28, s40, s28
	s_addc_u32 s29, s41, s29
	s_and_b64 s[0:1], s[8:9], exec
	s_cselect_b32 s15, s29, s39
	s_cselect_b32 s17, s28, s38
	s_add_u32 s8, s38, 0x160080
	s_addc_u32 s9, s39, 0
	s_add_u32 s66, s36, 0x100
	v_mov_b32_e32 v0, 0
	s_addc_u32 s67, s37, 0
	s_mov_b32 s68, -2
	ds_read_b128 v[150:153], v141
	ds_read_b128 v[154:157], v141 offset:1024
	ds_read_b128 v[162:165], v141 offset:2048
	ds_read_b128 v[166:169], v141 offset:3072
	s_add_u32 s0, s8, 0xffea0080
	s_addc_u32 s1, s9, -1
	s_cmp_eq_u32 s68, 4
	s_cselect_b32 s39, s15, s1
	s_cselect_b32 s38, s17, s0
	s_cselect_b32 s37, s19, s67
	s_cselect_b32 s36, s18, s66
	s_mov_b32 m0, s58
	ds_read_b128 v[170:173], v142
	ds_read_b128 v[174:177], v142 offset:1024
	ds_read_b128 v[178:181], v142 offset:2048
	ds_read_b128 v[188:191], v142 offset:3072
	ds_read_b128 v[194:197], v142 offset:4096
	ds_read_b128 v[198:201], v142 offset:5120
	ds_read_b128 v[202:205], v142 offset:6144
	global_load_lds_dwordx4 v132, s[8:9]
	s_mov_b32 m0, s59
	ds_read_b128 v[206:209], v142 offset:7168
	global_load_lds_dwordx4 v134, s[8:9]
	s_waitcnt lgkmcnt(8)
	s_barrier
	s_waitcnt lgkmcnt(0)
	s_setprio 1
	v_mfma_f32_16x16x32_bf16 v[124:127], v[150:153], v[170:173], 0
	v_mfma_f32_16x16x32_bf16 v[120:123], v[162:165], v[170:173], 0
	v_mfma_f32_16x16x32_bf16 v[116:119], v[150:153], v[178:181], 0
	v_mfma_f32_16x16x32_bf16 v[112:115], v[162:165], v[178:181], 0
	v_mfma_f32_16x16x32_bf16 v[104:107], v[150:153], v[194:197], 0
	v_mfma_f32_16x16x32_bf16 v[96:99], v[162:165], v[194:197], 0
	v_mfma_f32_16x16x32_bf16 v[88:91], v[150:153], v[202:205], 0
	v_mfma_f32_16x16x32_bf16 v[80:83], v[162:165], v[202:205], 0
	v_mfma_f32_16x16x32_bf16 v[124:127], v[154:157], v[174:177], v[124:127]
	v_mfma_f32_16x16x32_bf16 v[120:123], v[166:169], v[174:177], v[120:123]
	v_mfma_f32_16x16x32_bf16 v[116:119], v[154:157], v[188:191], v[116:119]
	v_mfma_f32_16x16x32_bf16 v[112:115], v[166:169], v[188:191], v[112:115]
	v_mfma_f32_16x16x32_bf16 v[104:107], v[154:157], v[198:201], v[104:107]
	v_mfma_f32_16x16x32_bf16 v[96:99], v[166:169], v[198:201], v[96:99]
	v_mfma_f32_16x16x32_bf16 v[88:91], v[154:157], v[206:209], v[88:91]
	v_mfma_f32_16x16x32_bf16 v[80:83], v[166:169], v[206:209], v[80:83]
	s_setprio 0
	s_barrier
	s_mov_b32 m0, s60
	ds_read_b128 v[210:213], v143
	ds_read_b128 v[214:217], v143 offset:1024
	ds_read_b128 v[218:221], v143 offset:2048
	global_load_lds_dwordx4 v130, s[36:37]
	s_mov_b32 m0, s61
	ds_read_b128 v[222:225], v143 offset:3072
	global_load_lds_dwordx4 v128, s[36:37]
	s_barrier
	s_waitcnt lgkmcnt(0)
	s_setprio 1
	v_mfma_f32_16x16x32_bf16 v[108:111], v[210:213], v[170:173], 0
	v_mfma_f32_16x16x32_bf16 v[100:103], v[218:221], v[170:173], 0
	v_mfma_f32_16x16x32_bf16 v[92:95], v[210:213], v[178:181], 0
	v_mfma_f32_16x16x32_bf16 v[84:87], v[218:221], v[178:181], 0
	v_mfma_f32_16x16x32_bf16 v[76:79], v[210:213], v[194:197], 0
	v_mfma_f32_16x16x32_bf16 v[72:75], v[218:221], v[194:197], 0
	v_mfma_f32_16x16x32_bf16 v[68:71], v[210:213], v[202:205], 0
	v_mfma_f32_16x16x32_bf16 v[64:67], v[218:221], v[202:205], 0
	v_mfma_f32_16x16x32_bf16 v[108:111], v[214:217], v[174:177], v[108:111]
	v_mfma_f32_16x16x32_bf16 v[100:103], v[222:225], v[174:177], v[100:103]
	v_mfma_f32_16x16x32_bf16 v[92:95], v[214:217], v[188:191], v[92:95]
	v_mfma_f32_16x16x32_bf16 v[84:87], v[222:225], v[188:191], v[84:87]
	v_mfma_f32_16x16x32_bf16 v[76:79], v[214:217], v[198:201], v[76:79]
	v_mfma_f32_16x16x32_bf16 v[72:75], v[222:225], v[198:201], v[72:75]
	v_mfma_f32_16x16x32_bf16 v[68:71], v[214:217], v[206:209], v[68:71]
	v_mfma_f32_16x16x32_bf16 v[64:67], v[222:225], v[206:209], v[64:67]
	s_setprio 0
	s_mov_b32 m0, s42
	s_barrier
	ds_read_b128 v[170:173], v142 offset:16384
	ds_read_b128 v[174:177], v142 offset:17408
	ds_read_b128 v[178:181], v142 offset:18432
	ds_read_b128 v[188:191], v142 offset:19456
	ds_read_b128 v[194:197], v142 offset:20480
	ds_read_b128 v[198:201], v142 offset:21504
	ds_read_b128 v[202:205], v142 offset:22528
	global_load_lds_dwordx4 v130, s[38:39]
	s_mov_b32 m0, s43
	ds_read_b128 v[206:209], v142 offset:23552
	global_load_lds_dwordx4 v128, s[38:39]
	s_barrier
	s_waitcnt lgkmcnt(0)
	s_setprio 1
	v_mfma_f32_16x16x32_bf16 v[60:63], v[150:153], v[170:173], 0
	v_mfma_f32_16x16x32_bf16 v[56:59], v[162:165], v[170:173], 0
	v_mfma_f32_16x16x32_bf16 v[52:55], v[150:153], v[178:181], 0
	v_mfma_f32_16x16x32_bf16 v[48:51], v[162:165], v[178:181], 0
	v_mfma_f32_16x16x32_bf16 v[40:43], v[150:153], v[194:197], 0
	v_mfma_f32_16x16x32_bf16 v[32:35], v[162:165], v[194:197], 0
	v_mfma_f32_16x16x32_bf16 v[24:27], v[150:153], v[202:205], 0
	v_mfma_f32_16x16x32_bf16 v[16:19], v[162:165], v[202:205], 0
	v_mfma_f32_16x16x32_bf16 v[60:63], v[154:157], v[174:177], v[60:63]
	v_mfma_f32_16x16x32_bf16 v[56:59], v[166:169], v[174:177], v[56:59]
	v_mfma_f32_16x16x32_bf16 v[52:55], v[154:157], v[188:191], v[52:55]
	v_mfma_f32_16x16x32_bf16 v[48:51], v[166:169], v[188:191], v[48:51]
	v_mfma_f32_16x16x32_bf16 v[40:43], v[154:157], v[198:201], v[40:43]
	v_mfma_f32_16x16x32_bf16 v[32:35], v[166:169], v[198:201], v[32:35]
	v_mfma_f32_16x16x32_bf16 v[24:27], v[154:157], v[206:209], v[24:27]
	v_mfma_f32_16x16x32_bf16 v[16:19], v[166:169], v[206:209], v[16:19]
	s_setprio 0
	s_barrier
	s_add_u32 s0, s36, 0x160000
	s_addc_u32 s1, s37, 0
	s_mov_b32 m0, s62
	s_nop 0
	global_load_lds_dwordx4 v130, s[0:1]
	s_mov_b32 m0, s63
	s_nop 0
	global_load_lds_dwordx4 v128, s[0:1]
	s_waitcnt vmcnt(6)
	s_barrier
; #define PG8_STAGE(bufoff, gbase, voff) do { _Pragma("unroll") for (int _i = 0; _i < 2; ++_i) \
;         __builtin_amdgcn_global_load_lds((const unsigned*)((const char*)(gbase) + (voff)[_i]), (LAS unsigned*)(lds + (bufoff) + ldsw + _i * 8192), 16, 0, 0); } while (0)
; #define PG8_LDA(dst, b, h) do { _Pragma("unroll") for (int m = 0; m < 4; ++m) _Pragma("unroll") for (int k = 0; k < 2; ++k) dst[m][k] = *(const LAS bf16x8*)(lds + PG8_SA(b, h) + aoff + m * 2048 + k * 1024); } while (0)
; #define PG8_LDB(dst, b, h) do { _Pragma("unroll") for (int n = 0; n < 2; ++n) _Pragma("unroll") for (int k = 0; k < 2; ++k) dst[n][k] = *(const LAS bf16x8*)(lds + PG8_SB(b, h) + boff + n * 2048 + k * 1024); } while (0)
; #define PG8_MMA(ai, bj, At, Bt) do { __builtin_amdgcn_s_setprio(1); _Pragma("unroll") for (int m = 0; m < 4; ++m) _Pragma("unroll") for (int n = 0; n < 2; ++n) _Pragma("unroll") for (int k = 0; k < 2; ++k) \
;         acc[ai][bj][m][n] = __builtin_amdgcn_mfma_f32_16x16x32_bf16(Bt[n][k], At[m][k], acc[ai][bj][m][n], 0, 0, 0); __builtin_amdgcn_s_setprio(0); } while (0)
; #define PG8_WAIT_L(n) asm volatile("s_waitcnt lgkmcnt(" #n ")" ::: "memory")
; #define PG8_BAR __builtin_amdgcn_s_barrier()
; #define PG8_SCHED __builtin_amdgcn_sched_barrier(0)
; template <class Epi, class Sched>
; DI void gemm_phase(LAS unsigned char* lds, const Gemm g, const Sched& S, const Epi& E) {
;     ...
;             PG8_LDB(B0, 1, 0); PG8_SCHED; PG8_LDA(At, 1, 0); PG8_STAGE(PG8_SA(0, 1), a2 + hstep, voffA);
;             PG8_WAIT_L(8); PG8_BAR; PG8_WAIT_L(0); PG8_MMA(0, 0, At, B0); PG8_BAR; PG8_SCHED;
;             PG8_LDB(B1, 1, 1); PG8_STAGE(PG8_SB(1, 0), b3, voffB);
;             PG8_BAR; PG8_WAIT_L(0); PG8_MMA(0, 1, At, B1); PG8_BAR;
;             PG8_LDA(At, 1, 1); PG8_STAGE(PG8_SA(1, 0), a3, voffA);
	s_setprio 1
	v_mfma_f32_16x16x32_bf16 v[44:47], v[210:213], v[170:173], 0
	v_mfma_f32_16x16x32_bf16 v[36:39], v[218:221], v[170:173], 0
	v_mfma_f32_16x16x32_bf16 v[28:31], v[210:213], v[178:181], 0
	v_mfma_f32_16x16x32_bf16 v[20:23], v[218:221], v[178:181], 0
	v_mfma_f32_16x16x32_bf16 v[12:15], v[210:213], v[194:197], 0
	v_mfma_f32_16x16x32_bf16 v[8:11], v[218:221], v[194:197], 0
	v_mfma_f32_16x16x32_bf16 v[4:7], v[210:213], v[202:205], 0
	v_mfma_f32_16x16x32_bf16 v[0:3], v[218:221], v[202:205], 0
	v_mfma_f32_16x16x32_bf16 v[44:47], v[214:217], v[174:177], v[44:47]
	v_mfma_f32_16x16x32_bf16 v[36:39], v[222:225], v[174:177], v[36:39]
	v_mfma_f32_16x16x32_bf16 v[28:31], v[214:217], v[188:191], v[28:31]
	v_mfma_f32_16x16x32_bf16 v[20:23], v[222:225], v[188:191], v[20:23]
	v_mfma_f32_16x16x32_bf16 v[12:15], v[214:217], v[198:201], v[12:15]
	v_mfma_f32_16x16x32_bf16 v[8:11], v[222:225], v[198:201], v[8:11]
	v_mfma_f32_16x16x32_bf16 v[4:7], v[214:217], v[206:209], v[4:7]
	v_mfma_f32_16x16x32_bf16 v[0:3], v[222:225], v[206:209], v[0:3]
	s_setprio 0
	s_barrier
	ds_read_b128 v[150:153], v144
	ds_read_b128 v[154:157], v144 offset:1024
	ds_read_b128 v[162:165], v144 offset:2048
	ds_read_b128 v[166:169], v144 offset:3072
	s_add_u32 s0, s38, 0x160000
	s_addc_u32 s1, s39, 0
	s_mov_b32 m0, s44
	ds_read_b128 v[170:173], v142 offset:32768
	ds_read_b128 v[174:177], v142 offset:33792
	ds_read_b128 v[178:181], v142 offset:34816
	ds_read_b128 v[188:191], v142 offset:35840
	ds_read_b128 v[194:197], v142 offset:36864
	ds_read_b128 v[198:201], v142 offset:37888
	ds_read_b128 v[202:205], v142 offset:38912
	global_load_lds_dwordx4 v130, s[0:1]
	s_mov_b32 m0, s45
	ds_read_b128 v[206:209], v142 offset:39936
	global_load_lds_dwordx4 v128, s[0:1]
	s_waitcnt lgkmcnt(8)
	s_barrier
	s_waitcnt lgkmcnt(0)
	s_setprio 1
	v_mfma_f32_16x16x32_bf16 v[124:127], v[150:153], v[170:173], v[124:127]
	v_mfma_f32_16x16x32_bf16 v[120:123], v[162:165], v[170:173], v[120:123]
	v_mfma_f32_16x16x32_bf16 v[116:119], v[150:153], v[178:181], v[116:119]
	v_mfma_f32_16x16x32_bf16 v[112:115], v[162:165], v[178:181], v[112:115]
	v_mfma_f32_16x16x32_bf16 v[104:107], v[150:153], v[194:197], v[104:107]
	v_mfma_f32_16x16x32_bf16 v[96:99], v[162:165], v[194:197], v[96:99]
	v_mfma_f32_16x16x32_bf16 v[88:91], v[150:153], v[202:205], v[88:91]
	v_mfma_f32_16x16x32_bf16 v[80:83], v[162:165], v[202:205], v[80:83]
	v_mfma_f32_16x16x32_bf16 v[124:127], v[154:157], v[174:177], v[124:127]
	v_mfma_f32_16x16x32_bf16 v[120:123], v[166:169], v[174:177], v[120:123]
	v_mfma_f32_16x16x32_bf16 v[116:119], v[154:157], v[188:191], v[116:119]
	v_mfma_f32_16x16x32_bf16 v[112:115], v[166:169], v[188:191], v[112:115]
	v_mfma_f32_16x16x32_bf16 v[104:107], v[154:157], v[198:201], v[104:107]
	v_mfma_f32_16x16x32_bf16 v[96:99], v[166:169], v[198:201], v[96:99]
	v_mfma_f32_16x16x32_bf16 v[88:91], v[154:157], v[206:209], v[88:91]
	v_mfma_f32_16x16x32_bf16 v[80:83], v[166:169], v[206:209], v[80:83]
	s_setprio 0
	s_barrier
	s_add_i32 s4, 0, 0x1c000
	s_add_i32 s0, s64, s35
	s_mov_b32 s10, s0
	v_add_u32_e32 v145, s4, v140
	s_add_i32 m0, s0, 0xffffff80
	ds_read_b128 v[210:213], v145
	ds_read_b128 v[214:217], v145 offset:1024
	ds_read_b128 v[218:221], v145 offset:2048
	global_load_lds_dwordx4 v130, s[36:37] offset:128
	s_add_i32 m0, s0, 0x1f80
	ds_read_b128 v[222:225], v145 offset:3072
	global_load_lds_dwordx4 v128, s[36:37] offset:128
	s_barrier
	s_waitcnt lgkmcnt(0)
	s_setprio 1
	v_mfma_f32_16x16x32_bf16 v[108:111], v[210:213], v[170:173], v[108:111]
	v_mfma_f32_16x16x32_bf16 v[100:103], v[218:221], v[170:173], v[100:103]
	v_mfma_f32_16x16x32_bf16 v[92:95], v[210:213], v[178:181], v[92:95]
	v_mfma_f32_16x16x32_bf16 v[84:87], v[218:221], v[178:181], v[84:87]
	v_mfma_f32_16x16x32_bf16 v[76:79], v[210:213], v[194:197], v[76:79]
	v_mfma_f32_16x16x32_bf16 v[72:75], v[218:221], v[194:197], v[72:75]
	v_mfma_f32_16x16x32_bf16 v[68:71], v[210:213], v[202:205], v[68:71]
	v_mfma_f32_16x16x32_bf16 v[64:67], v[218:221], v[202:205], v[64:67]
	v_mfma_f32_16x16x32_bf16 v[108:111], v[214:217], v[174:177], v[108:111]
	v_mfma_f32_16x16x32_bf16 v[100:103], v[222:225], v[174:177], v[100:103]
	v_mfma_f32_16x16x32_bf16 v[92:95], v[214:217], v[188:191], v[92:95]
	v_mfma_f32_16x16x32_bf16 v[84:87], v[222:225], v[188:191], v[84:87]
	v_mfma_f32_16x16x32_bf16 v[76:79], v[214:217], v[198:201], v[76:79]
	v_mfma_f32_16x16x32_bf16 v[72:75], v[222:225], v[198:201], v[72:75]
	v_mfma_f32_16x16x32_bf16 v[68:71], v[214:217], v[206:209], v[68:71]
	v_mfma_f32_16x16x32_bf16 v[64:67], v[222:225], v[206:209], v[64:67]
	s_setprio 0
	s_add_i32 m0, s56, 0xffffff80
	s_barrier
	ds_read_b128 v[170:173], v142 offset:49152
	ds_read_b128 v[174:177], v142 offset:50176
	ds_read_b128 v[178:181], v142 offset:51200
	ds_read_b128 v[188:191], v142 offset:52224
	ds_read_b128 v[194:197], v142 offset:53248
	ds_read_b128 v[198:201], v142 offset:54272
	ds_read_b128 v[202:205], v142 offset:55296
	global_load_lds_dwordx4 v130, s[38:39] offset:128
	s_add_i32 m0, s57, 0xffffff80
	ds_read_b128 v[206:209], v142 offset:56320
	global_load_lds_dwordx4 v128, s[38:39] offset:128
	s_barrier
; #define PG8_STAGE(bufoff, gbase, voff) do { _Pragma("unroll") for (int _i = 0; _i < 2; ++_i) \
;         __builtin_amdgcn_global_load_lds((const unsigned*)((const char*)(gbase) + (voff)[_i]), (LAS unsigned*)(lds + (bufoff) + ldsw + _i * 8192), 16, 0, 0); } while (0)
; #define PG8_LDA(dst, b, h) do { _Pragma("unroll") for (int m = 0; m < 4; ++m) _Pragma("unroll") for (int k = 0; k < 2; ++k) dst[m][k] = *(const LAS bf16x8*)(lds + PG8_SA(b, h) + aoff + m * 2048 + k * 1024); } while (0)
; #define PG8_LDB(dst, b, h) do { _Pragma("unroll") for (int n = 0; n < 2; ++n) _Pragma("unroll") for (int k = 0; k < 2; ++k) dst[n][k] = *(const LAS bf16x8*)(lds + PG8_SB(b, h) + boff + n * 2048 + k * 1024); } while (0)
; #define PG8_MMA(ai, bj, At, Bt) do { __builtin_amdgcn_s_setprio(1); _Pragma("unroll") for (int m = 0; m < 4; ++m) _Pragma("unroll") for (int n = 0; n < 2; ++n) _Pragma("unroll") for (int k = 0; k < 2; ++k) \
;         acc[ai][bj][m][n] = __builtin_amdgcn_mfma_f32_16x16x32_bf16(Bt[n][k], At[m][k], acc[ai][bj][m][n], 0, 0, 0); __builtin_amdgcn_s_setprio(0); } while (0)
; #define PG8_WAIT_V(n) asm volatile("s_waitcnt vmcnt(" #n ")" ::: "memory")
; #define PG8_WAIT_L(n) asm volatile("s_waitcnt lgkmcnt(" #n ")" ::: "memory")
; #define PG8_BAR __builtin_amdgcn_s_barrier()
; #define PG8_SCHED __builtin_amdgcn_sched_barrier(0)
; template <class Epi, class Sched>
; DI void gemm_phase(LAS unsigned char* lds, const Gemm g, const Sched& S, const Epi& E) {
;     ...
;             PG8_LDB(B0, 0, 0); PG8_SCHED; PG8_LDA(At, 0, 0); PG8_STAGE(PG8_SA(1, 1), a1 + hstep, voffA);
;             PG8_WAIT_L(8); PG8_BAR; PG8_WAIT_L(0); PG8_MMA(0, 0, At, B0); PG8_BAR; PG8_SCHED;
;             PG8_LDB(B1, 0, 1); PG8_STAGE(PG8_SB(0, 0), b2, voffB);
;             PG8_BAR; PG8_WAIT_L(0); PG8_MMA(0, 1, At, B1); PG8_BAR;
;     ...
;             PG8_BAR; PG8_WAIT_L(0); PG8_MMA(1, 0, At, B0); PG8_BAR; PG8_SCHED;
;             PG8_STAGE(PG8_SB(1, 1), b3 + hstep, voffB);
;             PG8_WAIT_V(6); PG8_BAR; PG8_MMA(1, 1, At, B1); PG8_BAR;
	s_waitcnt lgkmcnt(0)
	s_setprio 1
	v_mfma_f32_16x16x32_bf16 v[60:63], v[150:153], v[170:173], v[60:63]
	v_mfma_f32_16x16x32_bf16 v[56:59], v[162:165], v[170:173], v[56:59]
	v_mfma_f32_16x16x32_bf16 v[52:55], v[150:153], v[178:181], v[52:55]
	v_mfma_f32_16x16x32_bf16 v[48:51], v[162:165], v[178:181], v[48:51]
	v_mfma_f32_16x16x32_bf16 v[40:43], v[150:153], v[194:197], v[40:43]
	v_mfma_f32_16x16x32_bf16 v[32:35], v[162:165], v[194:197], v[32:35]
	v_mfma_f32_16x16x32_bf16 v[24:27], v[150:153], v[202:205], v[24:27]
	v_mfma_f32_16x16x32_bf16 v[16:19], v[162:165], v[202:205], v[16:19]
	v_mfma_f32_16x16x32_bf16 v[60:63], v[154:157], v[174:177], v[60:63]
	v_mfma_f32_16x16x32_bf16 v[56:59], v[166:169], v[174:177], v[56:59]
	v_mfma_f32_16x16x32_bf16 v[52:55], v[154:157], v[188:191], v[52:55]
	v_mfma_f32_16x16x32_bf16 v[48:51], v[166:169], v[188:191], v[48:51]
	v_mfma_f32_16x16x32_bf16 v[40:43], v[154:157], v[198:201], v[40:43]
	v_mfma_f32_16x16x32_bf16 v[32:35], v[166:169], v[198:201], v[32:35]
	v_mfma_f32_16x16x32_bf16 v[24:27], v[154:157], v[206:209], v[24:27]
	v_mfma_f32_16x16x32_bf16 v[16:19], v[166:169], v[206:209], v[16:19]
	s_setprio 0
	s_barrier
	s_add_i32 s4, s4, s35
	s_mov_b32 s11, s4
	s_mov_b32 m0, s4
	s_add_u32 s0, s36, 0x160080
	s_addc_u32 s1, s37, 0
	global_load_lds_dwordx4 v130, s[0:1]
	s_add_i32 m0, s4, 0x2000
	s_nop 0
	global_load_lds_dwordx4 v128, s[0:1]
	s_waitcnt vmcnt(6)
	s_barrier
	s_setprio 1
	v_mfma_f32_16x16x32_bf16 v[44:47], v[210:213], v[170:173], v[44:47]
	v_mfma_f32_16x16x32_bf16 v[36:39], v[218:221], v[170:173], v[36:39]
	v_mfma_f32_16x16x32_bf16 v[28:31], v[210:213], v[178:181], v[28:31]
	v_mfma_f32_16x16x32_bf16 v[20:23], v[218:221], v[178:181], v[20:23]
	v_mfma_f32_16x16x32_bf16 v[12:15], v[210:213], v[194:197], v[12:15]
	v_mfma_f32_16x16x32_bf16 v[8:11], v[218:221], v[194:197], v[8:11]
	v_mfma_f32_16x16x32_bf16 v[4:7], v[210:213], v[202:205], v[4:7]
	v_mfma_f32_16x16x32_bf16 v[0:3], v[218:221], v[202:205], v[0:3]
	v_mfma_f32_16x16x32_bf16 v[44:47], v[214:217], v[174:177], v[44:47]
	v_mfma_f32_16x16x32_bf16 v[36:39], v[222:225], v[174:177], v[36:39]
	v_mfma_f32_16x16x32_bf16 v[28:31], v[214:217], v[188:191], v[28:31]
	v_mfma_f32_16x16x32_bf16 v[20:23], v[222:225], v[188:191], v[20:23]
	v_mfma_f32_16x16x32_bf16 v[12:15], v[214:217], v[198:201], v[12:15]
	v_mfma_f32_16x16x32_bf16 v[8:11], v[222:225], v[198:201], v[8:11]
	v_mfma_f32_16x16x32_bf16 v[4:7], v[214:217], v[206:209], v[4:7]
	v_mfma_f32_16x16x32_bf16 v[0:3], v[222:225], v[206:209], v[0:3]
	s_setprio 0
	s_add_i32 s68, s68, 2
	s_add_u32 s8, s8, 0x100
	s_addc_u32 s9, s9, 0
	s_add_u32 s66, s66, 0x100
	s_addc_u32 s67, s67, 0
	s_cmp_gt_u32 s68, 5
	s_barrier
	s_cbranch_scc0 .LBB0_326
	s_branch .Lpeel_done_326
.LBB0_326:
	ds_read_b128 v[150:153], v141
	ds_read_b128 v[154:157], v141 offset:1024
	ds_read_b128 v[162:165], v141 offset:2048
	ds_read_b128 v[166:169], v141 offset:3072
	s_add_u32 s0, s8, 0xffea0080
	s_addc_u32 s1, s9, -1
	s_cmp_eq_u32 s68, 4
	s_cselect_b32 s39, s15, s1
	s_cselect_b32 s38, s17, s0
	s_cselect_b32 s37, s19, s67
	s_cselect_b32 s36, s18, s66
	s_mov_b32 m0, s58
	ds_read_b128 v[170:173], v142
	ds_read_b128 v[174:177], v142 offset:1024
	ds_read_b128 v[178:181], v142 offset:2048
	ds_read_b128 v[188:191], v142 offset:3072
	ds_read_b128 v[194:197], v142 offset:4096
	ds_read_b128 v[198:201], v142 offset:5120
	ds_read_b128 v[202:205], v142 offset:6144
	global_load_lds_dwordx4 v132, s[8:9]
	s_mov_b32 m0, s59
	ds_read_b128 v[206:209], v142 offset:7168
	global_load_lds_dwordx4 v134, s[8:9]
	s_waitcnt lgkmcnt(8)
	s_barrier
	s_waitcnt lgkmcnt(0)
	s_setprio 1
	v_mfma_f32_16x16x32_bf16 v[124:127], v[150:153], v[170:173], v[124:127]
	v_mfma_f32_16x16x32_bf16 v[120:123], v[162:165], v[170:173], v[120:123]
	v_mfma_f32_16x16x32_bf16 v[116:119], v[150:153], v[178:181], v[116:119]
	v_mfma_f32_16x16x32_bf16 v[112:115], v[162:165], v[178:181], v[112:115]
	v_mfma_f32_16x16x32_bf16 v[104:107], v[150:153], v[194:197], v[104:107]
	v_mfma_f32_16x16x32_bf16 v[96:99], v[162:165], v[194:197], v[96:99]
	v_mfma_f32_16x16x32_bf16 v[88:91], v[150:153], v[202:205], v[88:91]
	v_mfma_f32_16x16x32_bf16 v[80:83], v[162:165], v[202:205], v[80:83]
	v_mfma_f32_16x16x32_bf16 v[124:127], v[154:157], v[174:177], v[124:127]
	v_mfma_f32_16x16x32_bf16 v[120:123], v[166:169], v[174:177], v[120:123]
	v_mfma_f32_16x16x32_bf16 v[116:119], v[154:157], v[188:191], v[116:119]
	v_mfma_f32_16x16x32_bf16 v[112:115], v[166:169], v[188:191], v[112:115]
	v_mfma_f32_16x16x32_bf16 v[104:107], v[154:157], v[198:201], v[104:107]
	v_mfma_f32_16x16x32_bf16 v[96:99], v[166:169], v[198:201], v[96:99]
	v_mfma_f32_16x16x32_bf16 v[88:91], v[154:157], v[206:209], v[88:91]
	v_mfma_f32_16x16x32_bf16 v[80:83], v[166:169], v[206:209], v[80:83]
	s_setprio 0
	s_barrier
	s_mov_b32 m0, s60
	ds_read_b128 v[210:213], v143
	ds_read_b128 v[214:217], v143 offset:1024
	ds_read_b128 v[218:221], v143 offset:2048
	global_load_lds_dwordx4 v130, s[36:37]
	s_mov_b32 m0, s61
	ds_read_b128 v[222:225], v143 offset:3072
	global_load_lds_dwordx4 v128, s[36:37]
	s_barrier
; #define PG8_STAGE(bufoff, gbase, voff) do { _Pragma("unroll") for (int _i = 0; _i < 2; ++_i) \
;         __builtin_amdgcn_global_load_lds((const unsigned*)((const char*)(gbase) + (voff)[_i]), (LAS unsigned*)(lds + (bufoff) + ldsw + _i * 8192), 16, 0, 0); } while (0)
; #define PG8_LDA(dst, b, h) do { _Pragma("unroll") for (int m = 0; m < 4; ++m) _Pragma("unroll") for (int k = 0; k < 2; ++k) dst[m][k] = *(const LAS bf16x8*)(lds + PG8_SA(b, h) + aoff + m * 2048 + k * 1024); } while (0)
; #define PG8_LDB(dst, b, h) do { _Pragma("unroll") for (int n = 0; n < 2; ++n) _Pragma("unroll") for (int k = 0; k < 2; ++k) dst[n][k] = *(const LAS bf16x8*)(lds + PG8_SB(b, h) + boff + n * 2048 + k * 1024); } while (0)
; #define PG8_MMA(ai, bj, At, Bt) do { __builtin_amdgcn_s_setprio(1); _Pragma("unroll") for (int m = 0; m < 4; ++m) _Pragma("unroll") for (int n = 0; n < 2; ++n) _Pragma("unroll") for (int k = 0; k < 2; ++k) \
;         acc[ai][bj][m][n] = __builtin_amdgcn_mfma_f32_16x16x32_bf16(Bt[n][k], At[m][k], acc[ai][bj][m][n], 0, 0, 0); __builtin_amdgcn_s_setprio(0); } while (0)
; #define PG8_WAIT_V(n) asm volatile("s_waitcnt vmcnt(" #n ")" ::: "memory")
; #define PG8_WAIT_L(n) asm volatile("s_waitcnt lgkmcnt(" #n ")" ::: "memory")
; #define PG8_BAR __builtin_amdgcn_s_barrier()
; #define PG8_SCHED __builtin_amdgcn_sched_barrier(0)
; template <class Epi, class Sched>
; DI void gemm_phase(LAS unsigned char* lds, const Gemm g, const Sched& S, const Epi& E) {
;     ...
;             PG8_BAR; PG8_WAIT_L(0); PG8_MMA(0, 1, At, B1); PG8_BAR;
;             PG8_LDA(At, 0, 1); PG8_STAGE(PG8_SA(0, 0), a2, voffA);
;             PG8_BAR; PG8_WAIT_L(0); PG8_MMA(1, 0, At, B0); PG8_BAR; PG8_SCHED;
;             PG8_STAGE(PG8_SB(0, 1), b2 + hstep, voffB);
;             PG8_WAIT_V(6); PG8_BAR; PG8_MMA(1, 1, At, B1); PG8_BAR;
;             PG8_LDB(B0, 1, 0); PG8_SCHED; PG8_LDA(At, 1, 0); PG8_STAGE(PG8_SA(0, 1), a2 + hstep, voffA);
;             PG8_WAIT_L(8); PG8_BAR; PG8_WAIT_L(0); PG8_MMA(0, 0, At, B0); PG8_BAR; PG8_SCHED;
	s_waitcnt lgkmcnt(0)
	s_setprio 1
	v_mfma_f32_16x16x32_bf16 v[108:111], v[210:213], v[170:173], v[108:111]
	v_mfma_f32_16x16x32_bf16 v[100:103], v[218:221], v[170:173], v[100:103]
	v_mfma_f32_16x16x32_bf16 v[92:95], v[210:213], v[178:181], v[92:95]
	v_mfma_f32_16x16x32_bf16 v[84:87], v[218:221], v[178:181], v[84:87]
	v_mfma_f32_16x16x32_bf16 v[76:79], v[210:213], v[194:197], v[76:79]
	v_mfma_f32_16x16x32_bf16 v[72:75], v[218:221], v[194:197], v[72:75]
	v_mfma_f32_16x16x32_bf16 v[68:71], v[210:213], v[202:205], v[68:71]
	v_mfma_f32_16x16x32_bf16 v[64:67], v[218:221], v[202:205], v[64:67]
	v_mfma_f32_16x16x32_bf16 v[108:111], v[214:217], v[174:177], v[108:111]
	v_mfma_f32_16x16x32_bf16 v[100:103], v[222:225], v[174:177], v[100:103]
	v_mfma_f32_16x16x32_bf16 v[92:95], v[214:217], v[188:191], v[92:95]
	v_mfma_f32_16x16x32_bf16 v[84:87], v[222:225], v[188:191], v[84:87]
	v_mfma_f32_16x16x32_bf16 v[76:79], v[214:217], v[198:201], v[76:79]
	v_mfma_f32_16x16x32_bf16 v[72:75], v[222:225], v[198:201], v[72:75]
	v_mfma_f32_16x16x32_bf16 v[68:71], v[214:217], v[206:209], v[68:71]
	v_mfma_f32_16x16x32_bf16 v[64:67], v[222:225], v[206:209], v[64:67]
	s_setprio 0
	s_mov_b32 m0, s42
	s_barrier
	ds_read_b128 v[170:173], v142 offset:16384
	ds_read_b128 v[174:177], v142 offset:17408
	ds_read_b128 v[178:181], v142 offset:18432
	ds_read_b128 v[188:191], v142 offset:19456
	ds_read_b128 v[194:197], v142 offset:20480
	ds_read_b128 v[198:201], v142 offset:21504
	ds_read_b128 v[202:205], v142 offset:22528
	global_load_lds_dwordx4 v130, s[38:39]
	s_mov_b32 m0, s43
	ds_read_b128 v[206:209], v142 offset:23552
	global_load_lds_dwordx4 v128, s[38:39]
	s_barrier
	s_waitcnt lgkmcnt(0)
	s_setprio 1
	v_mfma_f32_16x16x32_bf16 v[60:63], v[150:153], v[170:173], v[60:63]
	v_mfma_f32_16x16x32_bf16 v[56:59], v[162:165], v[170:173], v[56:59]
	v_mfma_f32_16x16x32_bf16 v[52:55], v[150:153], v[178:181], v[52:55]
	v_mfma_f32_16x16x32_bf16 v[48:51], v[162:165], v[178:181], v[48:51]
	v_mfma_f32_16x16x32_bf16 v[40:43], v[150:153], v[194:197], v[40:43]
	v_mfma_f32_16x16x32_bf16 v[32:35], v[162:165], v[194:197], v[32:35]
	v_mfma_f32_16x16x32_bf16 v[24:27], v[150:153], v[202:205], v[24:27]
	v_mfma_f32_16x16x32_bf16 v[16:19], v[162:165], v[202:205], v[16:19]
	v_mfma_f32_16x16x32_bf16 v[60:63], v[154:157], v[174:177], v[60:63]
	v_mfma_f32_16x16x32_bf16 v[56:59], v[166:169], v[174:177], v[56:59]
	v_mfma_f32_16x16x32_bf16 v[52:55], v[154:157], v[188:191], v[52:55]
	v_mfma_f32_16x16x32_bf16 v[48:51], v[166:169], v[188:191], v[48:51]
	v_mfma_f32_16x16x32_bf16 v[40:43], v[154:157], v[198:201], v[40:43]
	v_mfma_f32_16x16x32_bf16 v[32:35], v[166:169], v[198:201], v[32:35]
	v_mfma_f32_16x16x32_bf16 v[24:27], v[154:157], v[206:209], v[24:27]
	v_mfma_f32_16x16x32_bf16 v[16:19], v[166:169], v[206:209], v[16:19]
	s_setprio 0
	s_barrier
	s_add_u32 s0, s36, 0x160000
	s_addc_u32 s1, s37, 0
	s_mov_b32 m0, s62
	s_nop 0
	global_load_lds_dwordx4 v130, s[0:1]
	s_mov_b32 m0, s63
	s_nop 0
	global_load_lds_dwordx4 v128, s[0:1]
	s_waitcnt vmcnt(6)
	s_barrier
	s_setprio 1
	v_mfma_f32_16x16x32_bf16 v[44:47], v[210:213], v[170:173], v[44:47]
	v_mfma_f32_16x16x32_bf16 v[36:39], v[218:221], v[170:173], v[36:39]
	v_mfma_f32_16x16x32_bf16 v[28:31], v[210:213], v[178:181], v[28:31]
	v_mfma_f32_16x16x32_bf16 v[20:23], v[218:221], v[178:181], v[20:23]
	v_mfma_f32_16x16x32_bf16 v[12:15], v[210:213], v[194:197], v[12:15]
	v_mfma_f32_16x16x32_bf16 v[8:11], v[218:221], v[194:197], v[8:11]
	v_mfma_f32_16x16x32_bf16 v[4:7], v[210:213], v[202:205], v[4:7]
	v_mfma_f32_16x16x32_bf16 v[0:3], v[218:221], v[202:205], v[0:3]
	v_mfma_f32_16x16x32_bf16 v[44:47], v[214:217], v[174:177], v[44:47]
	v_mfma_f32_16x16x32_bf16 v[36:39], v[222:225], v[174:177], v[36:39]
	v_mfma_f32_16x16x32_bf16 v[28:31], v[214:217], v[188:191], v[28:31]
	v_mfma_f32_16x16x32_bf16 v[20:23], v[222:225], v[188:191], v[20:23]
	v_mfma_f32_16x16x32_bf16 v[12:15], v[214:217], v[198:201], v[12:15]
	v_mfma_f32_16x16x32_bf16 v[8:11], v[222:225], v[198:201], v[8:11]
	v_mfma_f32_16x16x32_bf16 v[4:7], v[214:217], v[206:209], v[4:7]
	v_mfma_f32_16x16x32_bf16 v[0:3], v[222:225], v[206:209], v[0:3]
	s_setprio 0
	s_barrier
	ds_read_b128 v[150:153], v144
	ds_read_b128 v[154:157], v144 offset:1024
	ds_read_b128 v[162:165], v144 offset:2048
	ds_read_b128 v[166:169], v144 offset:3072
	s_add_u32 s0, s38, 0x160000
	s_addc_u32 s1, s39, 0
	s_mov_b32 m0, s44
	ds_read_b128 v[170:173], v142 offset:32768
	ds_read_b128 v[174:177], v142 offset:33792
	ds_read_b128 v[178:181], v142 offset:34816
	ds_read_b128 v[188:191], v142 offset:35840
	ds_read_b128 v[194:197], v142 offset:36864
	ds_read_b128 v[198:201], v142 offset:37888
	ds_read_b128 v[202:205], v142 offset:38912
	global_load_lds_dwordx4 v130, s[0:1]
	s_mov_b32 m0, s45
	ds_read_b128 v[206:209], v142 offset:39936
	global_load_lds_dwordx4 v128, s[0:1]
	s_waitcnt lgkmcnt(8)
	s_barrier
; #define PG8_STAGE(bufoff, gbase, voff) do { _Pragma("unroll") for (int _i = 0; _i < 2; ++_i) \
;         __builtin_amdgcn_global_load_lds((const unsigned*)((const char*)(gbase) + (voff)[_i]), (LAS unsigned*)(lds + (bufoff) + ldsw + _i * 8192), 16, 0, 0); } while (0)
; #define PG8_LDA(dst, b, h) do { _Pragma("unroll") for (int m = 0; m < 4; ++m) _Pragma("unroll") for (int k = 0; k < 2; ++k) dst[m][k] = *(const LAS bf16x8*)(lds + PG8_SA(b, h) + aoff + m * 2048 + k * 1024); } while (0)
; #define PG8_LDB(dst, b, h) do { _Pragma("unroll") for (int n = 0; n < 2; ++n) _Pragma("unroll") for (int k = 0; k < 2; ++k) dst[n][k] = *(const LAS bf16x8*)(lds + PG8_SB(b, h) + boff + n * 2048 + k * 1024); } while (0)
; #define PG8_MMA(ai, bj, At, Bt) do { __builtin_amdgcn_s_setprio(1); _Pragma("unroll") for (int m = 0; m < 4; ++m) _Pragma("unroll") for (int n = 0; n < 2; ++n) _Pragma("unroll") for (int k = 0; k < 2; ++k) \
;         acc[ai][bj][m][n] = __builtin_amdgcn_mfma_f32_16x16x32_bf16(Bt[n][k], At[m][k], acc[ai][bj][m][n], 0, 0, 0); __builtin_amdgcn_s_setprio(0); } while (0)
; #define PG8_WAIT_V(n) asm volatile("s_waitcnt vmcnt(" #n ")" ::: "memory")
; #define PG8_WAIT_L(n) asm volatile("s_waitcnt lgkmcnt(" #n ")" ::: "memory")
; #define PG8_BAR __builtin_amdgcn_s_barrier()
; #define PG8_SCHED __builtin_amdgcn_sched_barrier(0)
; template <class Epi, class Sched>
; DI void gemm_phase(LAS unsigned char* lds, const Gemm g, const Sched& S, const Epi& E) {
;     ...
;             PG8_WAIT_L(8); PG8_BAR; PG8_WAIT_L(0); PG8_MMA(0, 0, At, B0); PG8_BAR; PG8_SCHED;
;             PG8_LDB(B1, 1, 1); PG8_STAGE(PG8_SB(1, 0), b3, voffB);
;             PG8_BAR; PG8_WAIT_L(0); PG8_MMA(0, 1, At, B1); PG8_BAR;
;             PG8_LDA(At, 1, 1); PG8_STAGE(PG8_SA(1, 0), a3, voffA);
;             PG8_BAR; PG8_WAIT_L(0); PG8_MMA(1, 0, At, B0); PG8_BAR; PG8_SCHED;
;             PG8_STAGE(PG8_SB(1, 1), b3 + hstep, voffB);
;             PG8_WAIT_V(6); PG8_BAR; PG8_MMA(1, 1, At, B1); PG8_BAR;
;         }
	s_waitcnt lgkmcnt(0)
	s_setprio 1
	v_mfma_f32_16x16x32_bf16 v[124:127], v[150:153], v[170:173], v[124:127]
	v_mfma_f32_16x16x32_bf16 v[120:123], v[162:165], v[170:173], v[120:123]
	v_mfma_f32_16x16x32_bf16 v[116:119], v[150:153], v[178:181], v[116:119]
	v_mfma_f32_16x16x32_bf16 v[112:115], v[162:165], v[178:181], v[112:115]
	v_mfma_f32_16x16x32_bf16 v[104:107], v[150:153], v[194:197], v[104:107]
	v_mfma_f32_16x16x32_bf16 v[96:99], v[162:165], v[194:197], v[96:99]
	v_mfma_f32_16x16x32_bf16 v[88:91], v[150:153], v[202:205], v[88:91]
	v_mfma_f32_16x16x32_bf16 v[80:83], v[162:165], v[202:205], v[80:83]
	v_mfma_f32_16x16x32_bf16 v[124:127], v[154:157], v[174:177], v[124:127]
	v_mfma_f32_16x16x32_bf16 v[120:123], v[166:169], v[174:177], v[120:123]
	v_mfma_f32_16x16x32_bf16 v[116:119], v[154:157], v[188:191], v[116:119]
	v_mfma_f32_16x16x32_bf16 v[112:115], v[166:169], v[188:191], v[112:115]
	v_mfma_f32_16x16x32_bf16 v[104:107], v[154:157], v[198:201], v[104:107]
	v_mfma_f32_16x16x32_bf16 v[96:99], v[166:169], v[198:201], v[96:99]
	v_mfma_f32_16x16x32_bf16 v[88:91], v[154:157], v[206:209], v[88:91]
	v_mfma_f32_16x16x32_bf16 v[80:83], v[166:169], v[206:209], v[80:83]
	s_setprio 0
	s_barrier
	s_add_i32 s4, 0, 0x1c000
	v_add_u32_e32 v145, s4, v140
	s_add_i32 m0, s10, 0xffffff80
	ds_read_b128 v[210:213], v145
	ds_read_b128 v[214:217], v145 offset:1024
	ds_read_b128 v[218:221], v145 offset:2048
	global_load_lds_dwordx4 v130, s[36:37] offset:128
	s_add_i32 m0, s10, 0x1f80
	ds_read_b128 v[222:225], v145 offset:3072
	global_load_lds_dwordx4 v128, s[36:37] offset:128
	s_barrier
	s_waitcnt lgkmcnt(0)
	s_setprio 1
	v_mfma_f32_16x16x32_bf16 v[108:111], v[210:213], v[170:173], v[108:111]
	v_mfma_f32_16x16x32_bf16 v[100:103], v[218:221], v[170:173], v[100:103]
	v_mfma_f32_16x16x32_bf16 v[92:95], v[210:213], v[178:181], v[92:95]
	v_mfma_f32_16x16x32_bf16 v[84:87], v[218:221], v[178:181], v[84:87]
	v_mfma_f32_16x16x32_bf16 v[76:79], v[210:213], v[194:197], v[76:79]
	v_mfma_f32_16x16x32_bf16 v[72:75], v[218:221], v[194:197], v[72:75]
	v_mfma_f32_16x16x32_bf16 v[68:71], v[210:213], v[202:205], v[68:71]
	v_mfma_f32_16x16x32_bf16 v[64:67], v[218:221], v[202:205], v[64:67]
	v_mfma_f32_16x16x32_bf16 v[108:111], v[214:217], v[174:177], v[108:111]
	v_mfma_f32_16x16x32_bf16 v[100:103], v[222:225], v[174:177], v[100:103]
	v_mfma_f32_16x16x32_bf16 v[92:95], v[214:217], v[188:191], v[92:95]
	v_mfma_f32_16x16x32_bf16 v[84:87], v[222:225], v[188:191], v[84:87]
	v_mfma_f32_16x16x32_bf16 v[76:79], v[214:217], v[198:201], v[76:79]
	v_mfma_f32_16x16x32_bf16 v[72:75], v[222:225], v[198:201], v[72:75]
	v_mfma_f32_16x16x32_bf16 v[68:71], v[214:217], v[206:209], v[68:71]
	v_mfma_f32_16x16x32_bf16 v[64:67], v[222:225], v[206:209], v[64:67]
	s_setprio 0
	s_add_i32 m0, s56, 0xffffff80
	s_barrier
	ds_read_b128 v[170:173], v142 offset:49152
	ds_read_b128 v[174:177], v142 offset:50176
	ds_read_b128 v[178:181], v142 offset:51200
	ds_read_b128 v[188:191], v142 offset:52224
	ds_read_b128 v[194:197], v142 offset:53248
	ds_read_b128 v[198:201], v142 offset:54272
	ds_read_b128 v[202:205], v142 offset:55296
	global_load_lds_dwordx4 v130, s[38:39] offset:128
	s_add_i32 m0, s57, 0xffffff80
	ds_read_b128 v[206:209], v142 offset:56320
	global_load_lds_dwordx4 v128, s[38:39] offset:128
	s_barrier
	s_waitcnt lgkmcnt(0)
	s_setprio 1
	v_mfma_f32_16x16x32_bf16 v[60:63], v[150:153], v[170:173], v[60:63]
	v_mfma_f32_16x16x32_bf16 v[56:59], v[162:165], v[170:173], v[56:59]
	v_mfma_f32_16x16x32_bf16 v[52:55], v[150:153], v[178:181], v[52:55]
	v_mfma_f32_16x16x32_bf16 v[48:51], v[162:165], v[178:181], v[48:51]
	v_mfma_f32_16x16x32_bf16 v[40:43], v[150:153], v[194:197], v[40:43]
	v_mfma_f32_16x16x32_bf16 v[32:35], v[162:165], v[194:197], v[32:35]
	v_mfma_f32_16x16x32_bf16 v[24:27], v[150:153], v[202:205], v[24:27]
	v_mfma_f32_16x16x32_bf16 v[16:19], v[162:165], v[202:205], v[16:19]
	v_mfma_f32_16x16x32_bf16 v[60:63], v[154:157], v[174:177], v[60:63]
	v_mfma_f32_16x16x32_bf16 v[56:59], v[166:169], v[174:177], v[56:59]
	v_mfma_f32_16x16x32_bf16 v[52:55], v[154:157], v[188:191], v[52:55]
	v_mfma_f32_16x16x32_bf16 v[48:51], v[166:169], v[188:191], v[48:51]
	v_mfma_f32_16x16x32_bf16 v[40:43], v[154:157], v[198:201], v[40:43]
	v_mfma_f32_16x16x32_bf16 v[32:35], v[166:169], v[198:201], v[32:35]
	v_mfma_f32_16x16x32_bf16 v[24:27], v[154:157], v[206:209], v[24:27]
	v_mfma_f32_16x16x32_bf16 v[16:19], v[166:169], v[206:209], v[16:19]
	s_setprio 0
	s_barrier
	s_mov_b32 m0, s11
	s_add_u32 s0, s36, 0x160080
	s_addc_u32 s1, s37, 0
	global_load_lds_dwordx4 v130, s[0:1]
	s_add_i32 m0, s11, 0x2000
	s_nop 0
	global_load_lds_dwordx4 v128, s[0:1]
	s_waitcnt vmcnt(6)
	s_barrier
	s_setprio 1
	v_mfma_f32_16x16x32_bf16 v[44:47], v[210:213], v[170:173], v[44:47]
	v_mfma_f32_16x16x32_bf16 v[36:39], v[218:221], v[170:173], v[36:39]
	v_mfma_f32_16x16x32_bf16 v[28:31], v[210:213], v[178:181], v[28:31]
	v_mfma_f32_16x16x32_bf16 v[20:23], v[218:221], v[178:181], v[20:23]
	v_mfma_f32_16x16x32_bf16 v[12:15], v[210:213], v[194:197], v[12:15]
	v_mfma_f32_16x16x32_bf16 v[8:11], v[218:221], v[194:197], v[8:11]
	v_mfma_f32_16x16x32_bf16 v[4:7], v[210:213], v[202:205], v[4:7]
	v_mfma_f32_16x16x32_bf16 v[0:3], v[218:221], v[202:205], v[0:3]
	v_mfma_f32_16x16x32_bf16 v[44:47], v[214:217], v[174:177], v[44:47]
	v_mfma_f32_16x16x32_bf16 v[36:39], v[222:225], v[174:177], v[36:39]
	v_mfma_f32_16x16x32_bf16 v[28:31], v[214:217], v[188:191], v[28:31]
	v_mfma_f32_16x16x32_bf16 v[20:23], v[222:225], v[188:191], v[20:23]
	v_mfma_f32_16x16x32_bf16 v[12:15], v[214:217], v[198:201], v[12:15]
	v_mfma_f32_16x16x32_bf16 v[8:11], v[222:225], v[198:201], v[8:11]
	v_mfma_f32_16x16x32_bf16 v[4:7], v[214:217], v[206:209], v[4:7]
	v_mfma_f32_16x16x32_bf16 v[0:3], v[222:225], v[206:209], v[0:3]
	s_setprio 0
	s_add_i32 s68, s68, 2
	s_add_u32 s8, s8, 0x100
	s_addc_u32 s9, s9, 0
	s_add_u32 s66, s66, 0x100
	s_addc_u32 s67, s67, 0
	s_cmp_gt_u32 s68, 5
	s_barrier
	s_cbranch_scc0 .LBB0_326

;     DI size_t aoff(const Unit& u, size_t tstep) const { return (size_t)u.pm * tstep; }
;     DI size_t boff(const Unit& u, size_t tstep) const { return (size_t)u.pn * tstep; }
;     DI bool next(int i, Unit& u) const { const long L = (long)i * G + c; if (L >= np) return false; u.pm = pmv; u.pn = (int)(L % nN); u.ks = (int)(L / nN); return true; }
;     DI size_t aoff(const Unit& u, size_t) const { return (size_t)u.ks * kbytes; }
;     DI size_t boff(const Unit& u, size_t tstep) const { return (size_t)u.pn * tstep + (size_t)u.ks * kbytes; }
;     DI bool next(int i, Unit& u) const { Unit t; if (!S.next(i / 3, t)) return false; u.pm = t.pm; u.pn = t.pn; u.ks = i % 3; return true; }
;     DI size_t aoff(const Unit& u, size_t tstep) const { return (u.ks < 2 ? offU : offOA) + (size_t)u.pm * tstep; }
; #define PG8_WAIT_V(n) asm volatile("s_waitcnt vmcnt(" #n ")" ::: "memory")
; template <class Epi, class Sched>
; DI void gemm_phase(LAS unsigned char* lds, const Gemm g, const Sched& S, const Epi& E) {
;     ...
;         const bool has_next = S.next(ui + 1, nxt);
;         const char* nA = has_next ? (const char*)g.A + S.aoff(nxt, tstep) : cA; const char* nB = has_next ? (const char*)g.Bt + S.boff(nxt, tstep) : cB;
;         for (int t = 0; t < nt; t += 2) {
;             if constexpr (Epi::HAS_MID) { if (t == E.mid_t(nt)) { int fr3 = fr, fq3 = fq; asm volatile("" : "+v"(fr3), "+v"(fq3)); E.mid(acc, cur, wr, wc, fr3, fq3); } }
;             const bool last = (t == nt - 2);
;             const char* a1 = cA + (size_t)(t + 1) * kstep;
;             const char* a2 = last ? nA : cA + (size_t)(t + 2) * kstep; const char* b2 = last ? nB : cB + (size_t)(t + 2) * kstep;
;             const char* a3 = a2 + kstep; const char* b3 = b2 + kstep;
;             PG8_LDB(B0, 0, 0); PG8_SCHED; PG8_LDA(At, 0, 0); PG8_STAGE(PG8_SA(1, 1), a1 + hstep, voffA);
;             PG8_WAIT_L(8); PG8_BAR; PG8_WAIT_L(0); PG8_MMA(0, 0, At, B0); PG8_BAR; PG8_SCHED;
;             PG8_LDB(B1, 0, 1); PG8_STAGE(PG8_SB(0, 0), b2, voffB);
;             PG8_BAR; PG8_WAIT_L(0); PG8_MMA(0, 1, At, B1); PG8_BAR;
;             PG8_LDA(At, 0, 1); PG8_STAGE(PG8_SA(0, 0), a2, voffA);
;             PG8_BAR; PG8_WAIT_L(0); PG8_MMA(1, 0, At, B0); PG8_BAR; PG8_SCHED;
;             PG8_STAGE(PG8_SB(0, 1), b2 + hstep, voffB);
;             PG8_WAIT_V(6); PG8_BAR; PG8_MMA(1, 1, At, B1); PG8_BAR;
.LBB0_526:
	s_ashr_i32 s51, s50, 31
	s_lshl_b64 s[0:1], s[50:51], 20
	s_add_u32 s52, s70, s0
	v_cmp_lt_i64_e32 vcc, s[12:13], v[142:143]
	s_addc_u32 s53, s71, s1
	s_and_b64 s[0:1], vcc, exec
	s_cselect_b32 s14, s53, s9
	s_cselect_b32 s15, s52, s8
	s_ashr_i32 s49, s48, 31
	s_lshl_b64 s[0:1], s[48:49], 20
	s_add_u32 s54, s72, s0
	s_addc_u32 s55, s73, s1
	s_and_b64 s[0:1], vcc, exec
	s_cselect_b32 s16, s55, s11
	s_cselect_b32 s17, s54, s10
	s_add_u32 s8, s8, 0x80080
	s_addc_u32 s9, s9, 0
	s_add_u32 s28, s10, 0x100
	v_mov_b32_e32 v0, 0
	s_addc_u32 s34, s11, 0
	s_mov_b32 s35, -2
	ds_read_b128 v[146:149], v164
	ds_read_b128 v[150:153], v164 offset:1024
	ds_read_b128 v[154:157], v164 offset:2048
	ds_read_b128 v[170:173], v164 offset:3072
	s_add_u32 s0, s8, 0xfff80080
	s_addc_u32 s1, s9, -1
	s_cmp_eq_u32 s35, 28
	s_cselect_b32 s13, s14, s1
	s_cselect_b32 s12, s15, s0
	s_cselect_b32 s11, s16, s34
	s_cselect_b32 s10, s17, s28
	s_add_i32 m0, s59, 0xc000
	ds_read_b128 v[174:177], v165
	ds_read_b128 v[178:181], v165 offset:1024
	ds_read_b128 v[188:191], v165 offset:2048
	ds_read_b128 v[194:197], v165 offset:3072
	ds_read_b128 v[198:201], v165 offset:4096
	ds_read_b128 v[202:205], v165 offset:5120
	ds_read_b128 v[206:209], v165 offset:6144
	global_load_lds_dwordx4 v138, s[8:9]
	s_add_i32 m0, s59, 0xe000
	ds_read_b128 v[210:213], v165 offset:7168
	global_load_lds_dwordx4 v140, s[8:9]
	s_waitcnt lgkmcnt(8)
	s_barrier
	s_waitcnt lgkmcnt(0)
	s_setprio 1
	v_mfma_f32_16x16x32_bf16 v[124:127], v[146:149], v[174:177], 0
	v_mfma_f32_16x16x32_bf16 v[120:123], v[154:157], v[174:177], 0
	v_mfma_f32_16x16x32_bf16 v[108:111], v[146:149], v[188:191], 0
	v_mfma_f32_16x16x32_bf16 v[104:107], v[154:157], v[188:191], 0
	v_mfma_f32_16x16x32_bf16 v[92:95], v[146:149], v[198:201], 0
	v_mfma_f32_16x16x32_bf16 v[88:91], v[154:157], v[198:201], 0
	v_mfma_f32_16x16x32_bf16 v[76:79], v[146:149], v[206:209], 0
	v_mfma_f32_16x16x32_bf16 v[72:75], v[154:157], v[206:209], 0
	v_mfma_f32_16x16x32_bf16 v[124:127], v[150:153], v[178:181], v[124:127]
	v_mfma_f32_16x16x32_bf16 v[120:123], v[170:173], v[178:181], v[120:123]
	v_mfma_f32_16x16x32_bf16 v[108:111], v[150:153], v[194:197], v[108:111]
	v_mfma_f32_16x16x32_bf16 v[104:107], v[170:173], v[194:197], v[104:107]
	v_mfma_f32_16x16x32_bf16 v[92:95], v[150:153], v[202:205], v[92:95]
	v_mfma_f32_16x16x32_bf16 v[88:91], v[170:173], v[202:205], v[88:91]
	v_mfma_f32_16x16x32_bf16 v[76:79], v[150:153], v[210:213], v[76:79]
	v_mfma_f32_16x16x32_bf16 v[72:75], v[170:173], v[210:213], v[72:75]
	s_setprio 0
	s_barrier
	s_add_i32 s0, s47, s74
	s_mov_b32 s32, s0
	s_mov_b32 m0, s0
	ds_read_b128 v[214:217], v166
	ds_read_b128 v[218:221], v166 offset:1024
	ds_read_b128 v[222:225], v166 offset:2048
	global_load_lds_dwordx4 v130, s[10:11]
	s_add_i32 m0, s0, 0x2000
	ds_read_b128 v[226:229], v166 offset:3072
	global_load_lds_dwordx4 v134, s[10:11]
	s_barrier
	s_waitcnt lgkmcnt(0)
	s_setprio 1
	v_mfma_f32_16x16x32_bf16 v[116:119], v[214:217], v[174:177], 0
	v_mfma_f32_16x16x32_bf16 v[112:115], v[222:225], v[174:177], 0
	v_mfma_f32_16x16x32_bf16 v[100:103], v[214:217], v[188:191], 0
	v_mfma_f32_16x16x32_bf16 v[96:99], v[222:225], v[188:191], 0
	v_mfma_f32_16x16x32_bf16 v[84:87], v[214:217], v[198:201], 0
	v_mfma_f32_16x16x32_bf16 v[80:83], v[222:225], v[198:201], 0
	v_mfma_f32_16x16x32_bf16 v[68:71], v[214:217], v[206:209], 0
	v_mfma_f32_16x16x32_bf16 v[64:67], v[222:225], v[206:209], 0
	v_mfma_f32_16x16x32_bf16 v[116:119], v[218:221], v[178:181], v[116:119]
	v_mfma_f32_16x16x32_bf16 v[112:115], v[226:229], v[178:181], v[112:115]
	v_mfma_f32_16x16x32_bf16 v[100:103], v[218:221], v[194:197], v[100:103]
	v_mfma_f32_16x16x32_bf16 v[96:99], v[226:229], v[194:197], v[96:99]
	v_mfma_f32_16x16x32_bf16 v[84:87], v[218:221], v[202:205], v[84:87]
	v_mfma_f32_16x16x32_bf16 v[80:83], v[226:229], v[202:205], v[80:83]
	v_mfma_f32_16x16x32_bf16 v[68:71], v[218:221], v[210:213], v[68:71]
	v_mfma_f32_16x16x32_bf16 v[64:67], v[226:229], v[210:213], v[64:67]
	s_setprio 0
	s_mov_b32 m0, s59
	s_barrier
	ds_read_b128 v[174:177], v165 offset:16384
	ds_read_b128 v[178:181], v165 offset:17408
	ds_read_b128 v[188:191], v165 offset:18432
	ds_read_b128 v[194:197], v165 offset:19456
	ds_read_b128 v[198:201], v165 offset:20480
	ds_read_b128 v[202:205], v165 offset:21504
	ds_read_b128 v[206:209], v165 offset:22528
	global_load_lds_dwordx4 v128, s[12:13]
	s_mov_b32 m0, s75
	ds_read_b128 v[210:213], v165 offset:23552
	global_load_lds_dwordx4 v132, s[12:13]
	s_barrier
	s_waitcnt lgkmcnt(0)
	s_setprio 1
	v_mfma_f32_16x16x32_bf16 v[60:63], v[146:149], v[174:177], 0
	v_mfma_f32_16x16x32_bf16 v[56:59], v[154:157], v[174:177], 0
	v_mfma_f32_16x16x32_bf16 v[44:47], v[146:149], v[188:191], 0
	v_mfma_f32_16x16x32_bf16 v[40:43], v[154:157], v[188:191], 0
	v_mfma_f32_16x16x32_bf16 v[28:31], v[146:149], v[198:201], 0
	v_mfma_f32_16x16x32_bf16 v[24:27], v[154:157], v[198:201], 0
	v_mfma_f32_16x16x32_bf16 v[12:15], v[146:149], v[206:209], 0
	v_mfma_f32_16x16x32_bf16 v[8:11], v[154:157], v[206:209], 0
	v_mfma_f32_16x16x32_bf16 v[60:63], v[150:153], v[178:181], v[60:63]
	v_mfma_f32_16x16x32_bf16 v[56:59], v[170:173], v[178:181], v[56:59]
	v_mfma_f32_16x16x32_bf16 v[44:47], v[150:153], v[194:197], v[44:47]
	v_mfma_f32_16x16x32_bf16 v[40:43], v[170:173], v[194:197], v[40:43]
	v_mfma_f32_16x16x32_bf16 v[28:31], v[150:153], v[202:205], v[28:31]
	v_mfma_f32_16x16x32_bf16 v[24:27], v[170:173], v[202:205], v[24:27]
	v_mfma_f32_16x16x32_bf16 v[12:15], v[150:153], v[210:213], v[12:15]
	v_mfma_f32_16x16x32_bf16 v[8:11], v[170:173], v[210:213], v[8:11]
	s_setprio 0
	s_barrier
; #define PG8_STAGE(bufoff, gbase, voff) do { _Pragma("unroll") for (int _i = 0; _i < 2; ++_i) \
;         __builtin_amdgcn_global_load_lds((const unsigned*)((const char*)(gbase) + (voff)[_i]), (LAS unsigned*)(lds + (bufoff) + ldsw + _i * 8192), 16, 0, 0); } while (0)
; #define PG8_LDA(dst, b, h) do { _Pragma("unroll") for (int m = 0; m < 4; ++m) _Pragma("unroll") for (int k = 0; k < 2; ++k) dst[m][k] = *(const LAS bf16x8*)(lds + PG8_SA(b, h) + aoff + m * 2048 + k * 1024); } while (0)
; #define PG8_LDB(dst, b, h) do { _Pragma("unroll") for (int n = 0; n < 2; ++n) _Pragma("unroll") for (int k = 0; k < 2; ++k) dst[n][k] = *(const LAS bf16x8*)(lds + PG8_SB(b, h) + boff + n * 2048 + k * 1024); } while (0)
; #define PG8_MMA(ai, bj, At, Bt) do { __builtin_amdgcn_s_setprio(1); _Pragma("unroll") for (int m = 0; m < 4; ++m) _Pragma("unroll") for (int n = 0; n < 2; ++n) _Pragma("unroll") for (int k = 0; k < 2; ++k) \
;         acc[ai][bj][m][n] = __builtin_amdgcn_mfma_f32_16x16x32_bf16(Bt[n][k], At[m][k], acc[ai][bj][m][n], 0, 0, 0); __builtin_amdgcn_s_setprio(0); } while (0)
; #define PG8_WAIT_V(n) asm volatile("s_waitcnt vmcnt(" #n ")" ::: "memory")
; #define PG8_WAIT_L(n) asm volatile("s_waitcnt lgkmcnt(" #n ")" ::: "memory")
; #define PG8_BAR __builtin_amdgcn_s_barrier()
; #define PG8_SCHED __builtin_amdgcn_sched_barrier(0)
; template <class Epi, class Sched>
; DI void gemm_phase(LAS unsigned char* lds, const Gemm g, const Sched& S, const Epi& E) {
;     ...
;             PG8_STAGE(PG8_SB(0, 1), b2 + hstep, voffB);
;             PG8_WAIT_V(6); PG8_BAR; PG8_MMA(1, 1, At, B1); PG8_BAR;
;             PG8_LDB(B0, 1, 0); PG8_SCHED; PG8_LDA(At, 1, 0); PG8_STAGE(PG8_SA(0, 1), a2 + hstep, voffA);
;             PG8_WAIT_L(8); PG8_BAR; PG8_WAIT_L(0); PG8_MMA(0, 0, At, B0); PG8_BAR; PG8_SCHED;
;             PG8_LDB(B1, 1, 1); PG8_STAGE(PG8_SB(1, 0), b3, voffB);
;             PG8_BAR; PG8_WAIT_L(0); PG8_MMA(0, 1, At, B1); PG8_BAR;
;             PG8_LDA(At, 1, 1); PG8_STAGE(PG8_SA(1, 0), a3, voffA);
	s_add_i32 s4, s87, s74
	s_mov_b32 s57, s4
	s_mov_b32 m0, s4
	s_add_u32 s0, s10, 0x80000
	s_addc_u32 s1, s11, 0
	global_load_lds_dwordx4 v130, s[0:1]
	s_add_i32 m0, s4, 0x2000
	s_nop 0
	global_load_lds_dwordx4 v134, s[0:1]
	s_waitcnt vmcnt(6)
	s_barrier
	s_setprio 1
	v_mfma_f32_16x16x32_bf16 v[52:55], v[214:217], v[174:177], 0
	v_mfma_f32_16x16x32_bf16 v[48:51], v[222:225], v[174:177], 0
	v_mfma_f32_16x16x32_bf16 v[36:39], v[214:217], v[188:191], 0
	v_mfma_f32_16x16x32_bf16 v[32:35], v[222:225], v[188:191], 0
	v_mfma_f32_16x16x32_bf16 v[20:23], v[214:217], v[198:201], 0
	v_mfma_f32_16x16x32_bf16 v[16:19], v[222:225], v[198:201], 0
	v_mfma_f32_16x16x32_bf16 v[4:7], v[214:217], v[206:209], 0
	v_mfma_f32_16x16x32_bf16 v[0:3], v[222:225], v[206:209], 0
	v_mfma_f32_16x16x32_bf16 v[52:55], v[218:221], v[178:181], v[52:55]
	v_mfma_f32_16x16x32_bf16 v[48:51], v[226:229], v[178:181], v[48:51]
	v_mfma_f32_16x16x32_bf16 v[36:39], v[218:221], v[194:197], v[36:39]
	v_mfma_f32_16x16x32_bf16 v[32:35], v[226:229], v[194:197], v[32:35]
	v_mfma_f32_16x16x32_bf16 v[20:23], v[218:221], v[202:205], v[20:23]
	v_mfma_f32_16x16x32_bf16 v[16:19], v[226:229], v[202:205], v[16:19]
	v_mfma_f32_16x16x32_bf16 v[4:7], v[218:221], v[210:213], v[4:7]
	v_mfma_f32_16x16x32_bf16 v[0:3], v[226:229], v[210:213], v[0:3]
	s_setprio 0
	s_add_i32 s4, 0, 0x18000
	v_add_u32_e32 v158, s4, v163
	s_barrier
	ds_read_b128 v[146:149], v158
	ds_read_b128 v[150:153], v158 offset:1024
	ds_read_b128 v[154:157], v158 offset:2048
	ds_read_b128 v[170:173], v158 offset:3072
	s_add_u32 s0, s12, 0x80000
	s_addc_u32 s1, s13, 0
	s_mov_b32 m0, s76
	ds_read_b128 v[174:177], v165 offset:32768
	ds_read_b128 v[178:181], v165 offset:33792
	ds_read_b128 v[188:191], v165 offset:34816
	ds_read_b128 v[194:197], v165 offset:35840
	ds_read_b128 v[198:201], v165 offset:36864
	ds_read_b128 v[202:205], v165 offset:37888
	ds_read_b128 v[206:209], v165 offset:38912
	global_load_lds_dwordx4 v128, s[0:1]
	s_mov_b32 m0, s77
	ds_read_b128 v[210:213], v165 offset:39936
	global_load_lds_dwordx4 v132, s[0:1]
	s_waitcnt lgkmcnt(8)
	s_barrier
	s_waitcnt lgkmcnt(0)
	s_setprio 1
	v_mfma_f32_16x16x32_bf16 v[124:127], v[146:149], v[174:177], v[124:127]
	v_mfma_f32_16x16x32_bf16 v[120:123], v[154:157], v[174:177], v[120:123]
	v_mfma_f32_16x16x32_bf16 v[108:111], v[146:149], v[188:191], v[108:111]
	v_mfma_f32_16x16x32_bf16 v[104:107], v[154:157], v[188:191], v[104:107]
	v_mfma_f32_16x16x32_bf16 v[92:95], v[146:149], v[198:201], v[92:95]
	v_mfma_f32_16x16x32_bf16 v[88:91], v[154:157], v[198:201], v[88:91]
	v_mfma_f32_16x16x32_bf16 v[76:79], v[146:149], v[206:209], v[76:79]
	v_mfma_f32_16x16x32_bf16 v[72:75], v[154:157], v[206:209], v[72:75]
	v_mfma_f32_16x16x32_bf16 v[124:127], v[150:153], v[178:181], v[124:127]
	v_mfma_f32_16x16x32_bf16 v[120:123], v[170:173], v[178:181], v[120:123]
	v_mfma_f32_16x16x32_bf16 v[108:111], v[150:153], v[194:197], v[108:111]
	v_mfma_f32_16x16x32_bf16 v[104:107], v[170:173], v[194:197], v[104:107]
	v_mfma_f32_16x16x32_bf16 v[92:95], v[150:153], v[202:205], v[92:95]
	v_mfma_f32_16x16x32_bf16 v[88:91], v[170:173], v[202:205], v[88:91]
	v_mfma_f32_16x16x32_bf16 v[76:79], v[150:153], v[210:213], v[76:79]
	v_mfma_f32_16x16x32_bf16 v[72:75], v[170:173], v[210:213], v[72:75]
	s_setprio 0
	s_barrier
	s_add_i32 s5, 0, 0x1c000
	s_add_i32 s0, s4, s74
	s_mov_b32 s60, s0
	v_add_u32_e32 v159, s5, v163
	s_add_i32 m0, s0, 0xffffff80
	ds_read_b128 v[214:217], v159
	ds_read_b128 v[218:221], v159 offset:1024
	ds_read_b128 v[222:225], v159 offset:2048
	global_load_lds_dwordx4 v130, s[10:11] offset:128
	s_add_i32 m0, s0, 0x1f80
	ds_read_b128 v[226:229], v159 offset:3072
	global_load_lds_dwordx4 v134, s[10:11] offset:128
	s_barrier
	s_waitcnt lgkmcnt(0)
	s_setprio 1
	v_mfma_f32_16x16x32_bf16 v[116:119], v[214:217], v[174:177], v[116:119]
	v_mfma_f32_16x16x32_bf16 v[112:115], v[222:225], v[174:177], v[112:115]
	v_mfma_f32_16x16x32_bf16 v[100:103], v[214:217], v[188:191], v[100:103]
	v_mfma_f32_16x16x32_bf16 v[96:99], v[222:225], v[188:191], v[96:99]
	v_mfma_f32_16x16x32_bf16 v[84:87], v[214:217], v[198:201], v[84:87]
	v_mfma_f32_16x16x32_bf16 v[80:83], v[222:225], v[198:201], v[80:83]
	v_mfma_f32_16x16x32_bf16 v[68:71], v[214:217], v[206:209], v[68:71]
	v_mfma_f32_16x16x32_bf16 v[64:67], v[222:225], v[206:209], v[64:67]
	v_mfma_f32_16x16x32_bf16 v[116:119], v[218:221], v[178:181], v[116:119]
	v_mfma_f32_16x16x32_bf16 v[112:115], v[226:229], v[178:181], v[112:115]
	v_mfma_f32_16x16x32_bf16 v[100:103], v[218:221], v[194:197], v[100:103]
	v_mfma_f32_16x16x32_bf16 v[96:99], v[226:229], v[194:197], v[96:99]
	v_mfma_f32_16x16x32_bf16 v[84:87], v[218:221], v[202:205], v[84:87]
	v_mfma_f32_16x16x32_bf16 v[80:83], v[226:229], v[202:205], v[80:83]
	v_mfma_f32_16x16x32_bf16 v[68:71], v[218:221], v[210:213], v[68:71]
	v_mfma_f32_16x16x32_bf16 v[64:67], v[226:229], v[210:213], v[64:67]
	s_setprio 0
	s_add_i32 m0, s97, 0xffffff80
	s_barrier
	ds_read_b128 v[174:177], v165 offset:49152
	ds_read_b128 v[178:181], v165 offset:50176
	ds_read_b128 v[188:191], v165 offset:51200
	ds_read_b128 v[194:197], v165 offset:52224
	ds_read_b128 v[198:201], v165 offset:53248
	ds_read_b128 v[202:205], v165 offset:54272
	ds_read_b128 v[206:209], v165 offset:55296
	global_load_lds_dwordx4 v128, s[12:13] offset:128
	s_add_i32 m0, s84, 0xffffff80
	ds_read_b128 v[210:213], v165 offset:56320
	global_load_lds_dwordx4 v132, s[12:13] offset:128
	s_barrier
; #define PG8_STAGE(bufoff, gbase, voff) do { _Pragma("unroll") for (int _i = 0; _i < 2; ++_i) \
;         __builtin_amdgcn_global_load_lds((const unsigned*)((const char*)(gbase) + (voff)[_i]), (LAS unsigned*)(lds + (bufoff) + ldsw + _i * 8192), 16, 0, 0); } while (0)
; #define PG8_LDA(dst, b, h) do { _Pragma("unroll") for (int m = 0; m < 4; ++m) _Pragma("unroll") for (int k = 0; k < 2; ++k) dst[m][k] = *(const LAS bf16x8*)(lds + PG8_SA(b, h) + aoff + m * 2048 + k * 1024); } while (0)
; #define PG8_LDB(dst, b, h) do { _Pragma("unroll") for (int n = 0; n < 2; ++n) _Pragma("unroll") for (int k = 0; k < 2; ++k) dst[n][k] = *(const LAS bf16x8*)(lds + PG8_SB(b, h) + boff + n * 2048 + k * 1024); } while (0)
; #define PG8_MMA(ai, bj, At, Bt) do { __builtin_amdgcn_s_setprio(1); _Pragma("unroll") for (int m = 0; m < 4; ++m) _Pragma("unroll") for (int n = 0; n < 2; ++n) _Pragma("unroll") for (int k = 0; k < 2; ++k) \
;         acc[ai][bj][m][n] = __builtin_amdgcn_mfma_f32_16x16x32_bf16(Bt[n][k], At[m][k], acc[ai][bj][m][n], 0, 0, 0); __builtin_amdgcn_s_setprio(0); } while (0)
; #define PG8_WAIT_V(n) asm volatile("s_waitcnt vmcnt(" #n ")" ::: "memory")
; #define PG8_BAR __builtin_amdgcn_s_barrier()
; template <class Epi, class Sched>
; DI void gemm_phase(LAS unsigned char* lds, const Gemm g, const Sched& S, const Epi& E) {
;     ...
;             PG8_LDB(B0, 0, 0); PG8_SCHED; PG8_LDA(At, 0, 0); PG8_STAGE(PG8_SA(1, 1), a1 + hstep, voffA);
;             PG8_WAIT_L(8); PG8_BAR; PG8_WAIT_L(0); PG8_MMA(0, 0, At, B0); PG8_BAR; PG8_SCHED;
;             PG8_LDB(B1, 0, 1); PG8_STAGE(PG8_SB(0, 0), b2, voffB);
;             PG8_BAR; PG8_WAIT_L(0); PG8_MMA(0, 1, At, B1); PG8_BAR;
;             PG8_LDA(At, 0, 1); PG8_STAGE(PG8_SA(0, 0), a2, voffA);
;             PG8_BAR; PG8_WAIT_L(0); PG8_MMA(1, 0, At, B0); PG8_BAR; PG8_SCHED;
;             PG8_STAGE(PG8_SB(0, 1), b2 + hstep, voffB);
;             PG8_WAIT_V(6); PG8_BAR; PG8_MMA(1, 1, At, B1); PG8_BAR;
;             PG8_LDB(B0, 1, 0); PG8_SCHED; PG8_LDA(At, 1, 0); PG8_STAGE(PG8_SA(0, 1), a2 + hstep, voffA);
;             PG8_WAIT_L(8); PG8_BAR; PG8_WAIT_L(0); PG8_MMA(0, 0, At, B0); PG8_BAR; PG8_SCHED;
;     ...
;             PG8_BAR; PG8_WAIT_L(0); PG8_MMA(1, 0, At, B0); PG8_BAR; PG8_SCHED;
;             PG8_STAGE(PG8_SB(1, 1), b3 + hstep, voffB);
;             PG8_WAIT_V(6); PG8_BAR; PG8_MMA(1, 1, At, B1); PG8_BAR;
;         }
	s_waitcnt lgkmcnt(0)
	s_setprio 1
	v_mfma_f32_16x16x32_bf16 v[60:63], v[146:149], v[174:177], v[60:63]
	v_mfma_f32_16x16x32_bf16 v[56:59], v[154:157], v[174:177], v[56:59]
	v_mfma_f32_16x16x32_bf16 v[44:47], v[146:149], v[188:191], v[44:47]
	v_mfma_f32_16x16x32_bf16 v[40:43], v[154:157], v[188:191], v[40:43]
	v_mfma_f32_16x16x32_bf16 v[28:31], v[146:149], v[198:201], v[28:31]
	v_mfma_f32_16x16x32_bf16 v[24:27], v[154:157], v[198:201], v[24:27]
	v_mfma_f32_16x16x32_bf16 v[12:15], v[146:149], v[206:209], v[12:15]
	v_mfma_f32_16x16x32_bf16 v[8:11], v[154:157], v[206:209], v[8:11]
	v_mfma_f32_16x16x32_bf16 v[60:63], v[150:153], v[178:181], v[60:63]
	v_mfma_f32_16x16x32_bf16 v[56:59], v[170:173], v[178:181], v[56:59]
	v_mfma_f32_16x16x32_bf16 v[44:47], v[150:153], v[194:197], v[44:47]
	v_mfma_f32_16x16x32_bf16 v[40:43], v[170:173], v[194:197], v[40:43]
	v_mfma_f32_16x16x32_bf16 v[28:31], v[150:153], v[202:205], v[28:31]
	v_mfma_f32_16x16x32_bf16 v[24:27], v[170:173], v[202:205], v[24:27]
	v_mfma_f32_16x16x32_bf16 v[12:15], v[150:153], v[210:213], v[12:15]
	v_mfma_f32_16x16x32_bf16 v[8:11], v[170:173], v[210:213], v[8:11]
	s_setprio 0
	s_barrier
	s_add_i32 s4, s5, s74
	s_mov_b32 s61, s4
	s_mov_b32 m0, s4
	s_add_u32 s0, s10, 0x80080
	s_addc_u32 s1, s11, 0
	global_load_lds_dwordx4 v130, s[0:1]
	v_lshl_add_u64 v[146:147], s[0:1], 0, v[134:135]
	s_add_i32 m0, s4, 0x2000
	s_nop 0
	global_load_lds_dwordx4 v134, s[0:1]
	s_waitcnt vmcnt(6)
	s_barrier
	s_setprio 1
	v_mfma_f32_16x16x32_bf16 v[52:55], v[214:217], v[174:177], v[52:55]
	v_mfma_f32_16x16x32_bf16 v[48:51], v[222:225], v[174:177], v[48:51]
	v_mfma_f32_16x16x32_bf16 v[36:39], v[214:217], v[188:191], v[36:39]
	v_mfma_f32_16x16x32_bf16 v[32:35], v[222:225], v[188:191], v[32:35]
	v_mfma_f32_16x16x32_bf16 v[20:23], v[214:217], v[198:201], v[20:23]
	v_mfma_f32_16x16x32_bf16 v[16:19], v[222:225], v[198:201], v[16:19]
	v_mfma_f32_16x16x32_bf16 v[4:7], v[214:217], v[206:209], v[4:7]
	v_mfma_f32_16x16x32_bf16 v[0:3], v[222:225], v[206:209], v[0:3]
	v_mfma_f32_16x16x32_bf16 v[52:55], v[218:221], v[178:181], v[52:55]
	v_mfma_f32_16x16x32_bf16 v[48:51], v[226:229], v[178:181], v[48:51]
	v_mfma_f32_16x16x32_bf16 v[36:39], v[218:221], v[194:197], v[36:39]
	v_mfma_f32_16x16x32_bf16 v[32:35], v[226:229], v[194:197], v[32:35]
	v_mfma_f32_16x16x32_bf16 v[20:23], v[218:221], v[202:205], v[20:23]
	v_mfma_f32_16x16x32_bf16 v[16:19], v[226:229], v[202:205], v[16:19]
	v_mfma_f32_16x16x32_bf16 v[4:7], v[218:221], v[210:213], v[4:7]
	v_mfma_f32_16x16x32_bf16 v[0:3], v[226:229], v[210:213], v[0:3]
	s_setprio 0
	s_add_i32 s35, s35, 2
	s_add_u32 s8, s8, 0x100
	s_addc_u32 s9, s9, 0
	s_add_u32 s28, s28, 0x100
	s_addc_u32 s34, s34, 0
	s_cmp_gt_u32 s35, 29
	s_barrier
	s_cbranch_scc0 .LBB0_527
	s_branch .Lpeel_done_527
.LBB0_527:
	ds_read_b128 v[146:149], v164
	ds_read_b128 v[150:153], v164 offset:1024
	ds_read_b128 v[154:157], v164 offset:2048
	ds_read_b128 v[170:173], v164 offset:3072
	s_add_u32 s0, s8, 0xfff80080
	s_addc_u32 s1, s9, -1
	s_cmp_eq_u32 s35, 28
	s_cselect_b32 s13, s14, s1
	s_cselect_b32 s12, s15, s0
	s_cselect_b32 s11, s16, s34
	s_cselect_b32 s10, s17, s28
	s_add_i32 m0, s59, 0xc000
	ds_read_b128 v[174:177], v165
	ds_read_b128 v[178:181], v165 offset:1024
	ds_read_b128 v[188:191], v165 offset:2048
	ds_read_b128 v[194:197], v165 offset:3072
	ds_read_b128 v[198:201], v165 offset:4096
	ds_read_b128 v[202:205], v165 offset:5120
	ds_read_b128 v[206:209], v165 offset:6144
	global_load_lds_dwordx4 v138, s[8:9]
	s_add_i32 m0, s59, 0xe000
	ds_read_b128 v[210:213], v165 offset:7168
	global_load_lds_dwordx4 v140, s[8:9]
	s_waitcnt lgkmcnt(8)
	s_barrier
	s_waitcnt lgkmcnt(0)
	s_setprio 1
	v_mfma_f32_16x16x32_bf16 v[124:127], v[146:149], v[174:177], v[124:127]
	v_mfma_f32_16x16x32_bf16 v[120:123], v[154:157], v[174:177], v[120:123]
	v_mfma_f32_16x16x32_bf16 v[108:111], v[146:149], v[188:191], v[108:111]
	v_mfma_f32_16x16x32_bf16 v[104:107], v[154:157], v[188:191], v[104:107]
	v_mfma_f32_16x16x32_bf16 v[92:95], v[146:149], v[198:201], v[92:95]
	v_mfma_f32_16x16x32_bf16 v[88:91], v[154:157], v[198:201], v[88:91]
	v_mfma_f32_16x16x32_bf16 v[76:79], v[146:149], v[206:209], v[76:79]
	v_mfma_f32_16x16x32_bf16 v[72:75], v[154:157], v[206:209], v[72:75]
	v_mfma_f32_16x16x32_bf16 v[124:127], v[150:153], v[178:181], v[124:127]
	v_mfma_f32_16x16x32_bf16 v[120:123], v[170:173], v[178:181], v[120:123]
	v_mfma_f32_16x16x32_bf16 v[108:111], v[150:153], v[194:197], v[108:111]
	v_mfma_f32_16x16x32_bf16 v[104:107], v[170:173], v[194:197], v[104:107]
	v_mfma_f32_16x16x32_bf16 v[92:95], v[150:153], v[202:205], v[92:95]
	v_mfma_f32_16x16x32_bf16 v[88:91], v[170:173], v[202:205], v[88:91]
	v_mfma_f32_16x16x32_bf16 v[76:79], v[150:153], v[210:213], v[76:79]
	v_mfma_f32_16x16x32_bf16 v[72:75], v[170:173], v[210:213], v[72:75]
	s_setprio 0
	s_barrier
	s_mov_b32 m0, s32
	ds_read_b128 v[214:217], v166
	ds_read_b128 v[218:221], v166 offset:1024
	ds_read_b128 v[222:225], v166 offset:2048
	global_load_lds_dwordx4 v130, s[10:11]
	s_add_i32 m0, s32, 0x2000
	ds_read_b128 v[226:229], v166 offset:3072
	global_load_lds_dwordx4 v134, s[10:11]
	s_barrier
; #define PG8_STAGE(bufoff, gbase, voff) do { _Pragma("unroll") for (int _i = 0; _i < 2; ++_i) \
;         __builtin_amdgcn_global_load_lds((const unsigned*)((const char*)(gbase) + (voff)[_i]), (LAS unsigned*)(lds + (bufoff) + ldsw + _i * 8192), 16, 0, 0); } while (0)
; #define PG8_LDA(dst, b, h) do { _Pragma("unroll") for (int m = 0; m < 4; ++m) _Pragma("unroll") for (int k = 0; k < 2; ++k) dst[m][k] = *(const LAS bf16x8*)(lds + PG8_SA(b, h) + aoff + m * 2048 + k * 1024); } while (0)
; #define PG8_LDB(dst, b, h) do { _Pragma("unroll") for (int n = 0; n < 2; ++n) _Pragma("unroll") for (int k = 0; k < 2; ++k) dst[n][k] = *(const LAS bf16x8*)(lds + PG8_SB(b, h) + boff + n * 2048 + k * 1024); } while (0)
; #define PG8_MMA(ai, bj, At, Bt) do { __builtin_amdgcn_s_setprio(1); _Pragma("unroll") for (int m = 0; m < 4; ++m) _Pragma("unroll") for (int n = 0; n < 2; ++n) _Pragma("unroll") for (int k = 0; k < 2; ++k) \
;         acc[ai][bj][m][n] = __builtin_amdgcn_mfma_f32_16x16x32_bf16(Bt[n][k], At[m][k], acc[ai][bj][m][n], 0, 0, 0); __builtin_amdgcn_s_setprio(0); } while (0)
; #define PG8_WAIT_V(n) asm volatile("s_waitcnt vmcnt(" #n ")" ::: "memory")
; #define PG8_WAIT_L(n) asm volatile("s_waitcnt lgkmcnt(" #n ")" ::: "memory")
; #define PG8_BAR __builtin_amdgcn_s_barrier()
; #define PG8_SCHED __builtin_amdgcn_sched_barrier(0)
; template <class Epi, class Sched>
; DI void gemm_phase(LAS unsigned char* lds, const Gemm g, const Sched& S, const Epi& E) {
;     ...
;             PG8_BAR; PG8_WAIT_L(0); PG8_MMA(0, 1, At, B1); PG8_BAR;
;             PG8_LDA(At, 0, 1); PG8_STAGE(PG8_SA(0, 0), a2, voffA);
;             PG8_BAR; PG8_WAIT_L(0); PG8_MMA(1, 0, At, B0); PG8_BAR; PG8_SCHED;
;             PG8_STAGE(PG8_SB(0, 1), b2 + hstep, voffB);
;             PG8_WAIT_V(6); PG8_BAR; PG8_MMA(1, 1, At, B1); PG8_BAR;
;             PG8_LDB(B0, 1, 0); PG8_SCHED; PG8_LDA(At, 1, 0); PG8_STAGE(PG8_SA(0, 1), a2 + hstep, voffA);
;             PG8_WAIT_L(8); PG8_BAR; PG8_WAIT_L(0); PG8_MMA(0, 0, At, B0); PG8_BAR; PG8_SCHED;
	s_waitcnt lgkmcnt(0)
	s_setprio 1
	v_mfma_f32_16x16x32_bf16 v[116:119], v[214:217], v[174:177], v[116:119]
	v_mfma_f32_16x16x32_bf16 v[112:115], v[222:225], v[174:177], v[112:115]
	v_mfma_f32_16x16x32_bf16 v[100:103], v[214:217], v[188:191], v[100:103]
	v_mfma_f32_16x16x32_bf16 v[96:99], v[222:225], v[188:191], v[96:99]
	v_mfma_f32_16x16x32_bf16 v[84:87], v[214:217], v[198:201], v[84:87]
	v_mfma_f32_16x16x32_bf16 v[80:83], v[222:225], v[198:201], v[80:83]
	v_mfma_f32_16x16x32_bf16 v[68:71], v[214:217], v[206:209], v[68:71]
	v_mfma_f32_16x16x32_bf16 v[64:67], v[222:225], v[206:209], v[64:67]
	v_mfma_f32_16x16x32_bf16 v[116:119], v[218:221], v[178:181], v[116:119]
	v_mfma_f32_16x16x32_bf16 v[112:115], v[226:229], v[178:181], v[112:115]
	v_mfma_f32_16x16x32_bf16 v[100:103], v[218:221], v[194:197], v[100:103]
	v_mfma_f32_16x16x32_bf16 v[96:99], v[226:229], v[194:197], v[96:99]
	v_mfma_f32_16x16x32_bf16 v[84:87], v[218:221], v[202:205], v[84:87]
	v_mfma_f32_16x16x32_bf16 v[80:83], v[226:229], v[202:205], v[80:83]
	v_mfma_f32_16x16x32_bf16 v[68:71], v[218:221], v[210:213], v[68:71]
	v_mfma_f32_16x16x32_bf16 v[64:67], v[226:229], v[210:213], v[64:67]
	s_setprio 0
	s_mov_b32 m0, s59
	s_barrier
	ds_read_b128 v[174:177], v165 offset:16384
	ds_read_b128 v[178:181], v165 offset:17408
	ds_read_b128 v[188:191], v165 offset:18432
	ds_read_b128 v[194:197], v165 offset:19456
	ds_read_b128 v[198:201], v165 offset:20480
	ds_read_b128 v[202:205], v165 offset:21504
	ds_read_b128 v[206:209], v165 offset:22528
	global_load_lds_dwordx4 v128, s[12:13]
	s_mov_b32 m0, s75
	ds_read_b128 v[210:213], v165 offset:23552
	global_load_lds_dwordx4 v132, s[12:13]
	s_barrier
	s_waitcnt lgkmcnt(0)
	s_setprio 1
	v_mfma_f32_16x16x32_bf16 v[60:63], v[146:149], v[174:177], v[60:63]
	v_mfma_f32_16x16x32_bf16 v[56:59], v[154:157], v[174:177], v[56:59]
	v_mfma_f32_16x16x32_bf16 v[44:47], v[146:149], v[188:191], v[44:47]
	v_mfma_f32_16x16x32_bf16 v[40:43], v[154:157], v[188:191], v[40:43]
	v_mfma_f32_16x16x32_bf16 v[28:31], v[146:149], v[198:201], v[28:31]
	v_mfma_f32_16x16x32_bf16 v[24:27], v[154:157], v[198:201], v[24:27]
	v_mfma_f32_16x16x32_bf16 v[12:15], v[146:149], v[206:209], v[12:15]
	v_mfma_f32_16x16x32_bf16 v[8:11], v[154:157], v[206:209], v[8:11]
	v_mfma_f32_16x16x32_bf16 v[60:63], v[150:153], v[178:181], v[60:63]
	v_mfma_f32_16x16x32_bf16 v[56:59], v[170:173], v[178:181], v[56:59]
	v_mfma_f32_16x16x32_bf16 v[44:47], v[150:153], v[194:197], v[44:47]
	v_mfma_f32_16x16x32_bf16 v[40:43], v[170:173], v[194:197], v[40:43]
	v_mfma_f32_16x16x32_bf16 v[28:31], v[150:153], v[202:205], v[28:31]
	v_mfma_f32_16x16x32_bf16 v[24:27], v[170:173], v[202:205], v[24:27]
	v_mfma_f32_16x16x32_bf16 v[12:15], v[150:153], v[210:213], v[12:15]
	v_mfma_f32_16x16x32_bf16 v[8:11], v[170:173], v[210:213], v[8:11]
	s_setprio 0
	s_barrier
	s_mov_b32 m0, s57
	s_add_u32 s0, s10, 0x80000
	s_addc_u32 s1, s11, 0
	global_load_lds_dwordx4 v130, s[0:1]
	s_add_i32 m0, s57, 0x2000
	s_nop 0
	global_load_lds_dwordx4 v134, s[0:1]
	s_waitcnt vmcnt(6)
	s_barrier
	s_setprio 1
	v_mfma_f32_16x16x32_bf16 v[52:55], v[214:217], v[174:177], v[52:55]
	v_mfma_f32_16x16x32_bf16 v[48:51], v[222:225], v[174:177], v[48:51]
	v_mfma_f32_16x16x32_bf16 v[36:39], v[214:217], v[188:191], v[36:39]
	v_mfma_f32_16x16x32_bf16 v[32:35], v[222:225], v[188:191], v[32:35]
	v_mfma_f32_16x16x32_bf16 v[20:23], v[214:217], v[198:201], v[20:23]
	v_mfma_f32_16x16x32_bf16 v[16:19], v[222:225], v[198:201], v[16:19]
	v_mfma_f32_16x16x32_bf16 v[4:7], v[214:217], v[206:209], v[4:7]
	v_mfma_f32_16x16x32_bf16 v[0:3], v[222:225], v[206:209], v[0:3]
	v_mfma_f32_16x16x32_bf16 v[52:55], v[218:221], v[178:181], v[52:55]
	v_mfma_f32_16x16x32_bf16 v[48:51], v[226:229], v[178:181], v[48:51]
	v_mfma_f32_16x16x32_bf16 v[36:39], v[218:221], v[194:197], v[36:39]
	v_mfma_f32_16x16x32_bf16 v[32:35], v[226:229], v[194:197], v[32:35]
	v_mfma_f32_16x16x32_bf16 v[20:23], v[218:221], v[202:205], v[20:23]
	v_mfma_f32_16x16x32_bf16 v[16:19], v[226:229], v[202:205], v[16:19]
	v_mfma_f32_16x16x32_bf16 v[4:7], v[218:221], v[210:213], v[4:7]
	v_mfma_f32_16x16x32_bf16 v[0:3], v[226:229], v[210:213], v[0:3]
	s_setprio 0
	s_add_i32 s4, 0, 0x18000
	s_barrier
	ds_read_b128 v[146:149], v158
	ds_read_b128 v[150:153], v158 offset:1024
	ds_read_b128 v[154:157], v158 offset:2048
	ds_read_b128 v[170:173], v158 offset:3072
	s_add_u32 s0, s12, 0x80000
	s_addc_u32 s1, s13, 0
	s_mov_b32 m0, s76
	ds_read_b128 v[174:177], v165 offset:32768
	ds_read_b128 v[178:181], v165 offset:33792
	ds_read_b128 v[188:191], v165 offset:34816
	ds_read_b128 v[194:197], v165 offset:35840
	ds_read_b128 v[198:201], v165 offset:36864
	ds_read_b128 v[202:205], v165 offset:37888
	ds_read_b128 v[206:209], v165 offset:38912
	global_load_lds_dwordx4 v128, s[0:1]
	s_mov_b32 m0, s77
	ds_read_b128 v[210:213], v165 offset:39936
	global_load_lds_dwordx4 v132, s[0:1]
	s_waitcnt lgkmcnt(8)
	s_barrier
; #define PG8_STAGE(bufoff, gbase, voff) do { _Pragma("unroll") for (int _i = 0; _i < 2; ++_i) \
;         __builtin_amdgcn_global_load_lds((const unsigned*)((const char*)(gbase) + (voff)[_i]), (LAS unsigned*)(lds + (bufoff) + ldsw + _i * 8192), 16, 0, 0); } while (0)
; #define PG8_LDA(dst, b, h) do { _Pragma("unroll") for (int m = 0; m < 4; ++m) _Pragma("unroll") for (int k = 0; k < 2; ++k) dst[m][k] = *(const LAS bf16x8*)(lds + PG8_SA(b, h) + aoff + m * 2048 + k * 1024); } while (0)
; #define PG8_LDB(dst, b, h) do { _Pragma("unroll") for (int n = 0; n < 2; ++n) _Pragma("unroll") for (int k = 0; k < 2; ++k) dst[n][k] = *(const LAS bf16x8*)(lds + PG8_SB(b, h) + boff + n * 2048 + k * 1024); } while (0)
; #define PG8_MMA(ai, bj, At, Bt) do { __builtin_amdgcn_s_setprio(1); _Pragma("unroll") for (int m = 0; m < 4; ++m) _Pragma("unroll") for (int n = 0; n < 2; ++n) _Pragma("unroll") for (int k = 0; k < 2; ++k) \
;         acc[ai][bj][m][n] = __builtin_amdgcn_mfma_f32_16x16x32_bf16(Bt[n][k], At[m][k], acc[ai][bj][m][n], 0, 0, 0); __builtin_amdgcn_s_setprio(0); } while (0)
; #define PG8_WAIT_V(n) asm volatile("s_waitcnt vmcnt(" #n ")" ::: "memory")
; #define PG8_WAIT_L(n) asm volatile("s_waitcnt lgkmcnt(" #n ")" ::: "memory")
; #define PG8_BAR __builtin_amdgcn_s_barrier()
; #define PG8_SCHED __builtin_amdgcn_sched_barrier(0)
; template <class Epi, class Sched>
; DI void gemm_phase(LAS unsigned char* lds, const Gemm g, const Sched& S, const Epi& E) {
;     ...
;             PG8_WAIT_L(8); PG8_BAR; PG8_WAIT_L(0); PG8_MMA(0, 0, At, B0); PG8_BAR; PG8_SCHED;
;             PG8_LDB(B1, 1, 1); PG8_STAGE(PG8_SB(1, 0), b3, voffB);
;             PG8_BAR; PG8_WAIT_L(0); PG8_MMA(0, 1, At, B1); PG8_BAR;
;             PG8_LDA(At, 1, 1); PG8_STAGE(PG8_SA(1, 0), a3, voffA);
;             PG8_BAR; PG8_WAIT_L(0); PG8_MMA(1, 0, At, B0); PG8_BAR; PG8_SCHED;
;             PG8_STAGE(PG8_SB(1, 1), b3 + hstep, voffB);
;             PG8_WAIT_V(6); PG8_BAR; PG8_MMA(1, 1, At, B1); PG8_BAR;
;         }
	s_waitcnt lgkmcnt(0)
	s_setprio 1
	v_mfma_f32_16x16x32_bf16 v[124:127], v[146:149], v[174:177], v[124:127]
	v_mfma_f32_16x16x32_bf16 v[120:123], v[154:157], v[174:177], v[120:123]
	v_mfma_f32_16x16x32_bf16 v[108:111], v[146:149], v[188:191], v[108:111]
	v_mfma_f32_16x16x32_bf16 v[104:107], v[154:157], v[188:191], v[104:107]
	v_mfma_f32_16x16x32_bf16 v[92:95], v[146:149], v[198:201], v[92:95]
	v_mfma_f32_16x16x32_bf16 v[88:91], v[154:157], v[198:201], v[88:91]
	v_mfma_f32_16x16x32_bf16 v[76:79], v[146:149], v[206:209], v[76:79]
	v_mfma_f32_16x16x32_bf16 v[72:75], v[154:157], v[206:209], v[72:75]
	v_mfma_f32_16x16x32_bf16 v[124:127], v[150:153], v[178:181], v[124:127]
	v_mfma_f32_16x16x32_bf16 v[120:123], v[170:173], v[178:181], v[120:123]
	v_mfma_f32_16x16x32_bf16 v[108:111], v[150:153], v[194:197], v[108:111]
	v_mfma_f32_16x16x32_bf16 v[104:107], v[170:173], v[194:197], v[104:107]
	v_mfma_f32_16x16x32_bf16 v[92:95], v[150:153], v[202:205], v[92:95]
	v_mfma_f32_16x16x32_bf16 v[88:91], v[170:173], v[202:205], v[88:91]
	v_mfma_f32_16x16x32_bf16 v[76:79], v[150:153], v[210:213], v[76:79]
	v_mfma_f32_16x16x32_bf16 v[72:75], v[170:173], v[210:213], v[72:75]
	s_setprio 0
	s_barrier
	s_add_i32 s5, 0, 0x1c000
	s_add_i32 m0, s60, 0xffffff80
	ds_read_b128 v[214:217], v159
	ds_read_b128 v[218:221], v159 offset:1024
	ds_read_b128 v[222:225], v159 offset:2048
	global_load_lds_dwordx4 v130, s[10:11] offset:128
	s_add_i32 m0, s60, 0x1f80
	ds_read_b128 v[226:229], v159 offset:3072
	global_load_lds_dwordx4 v134, s[10:11] offset:128
	s_barrier
	s_waitcnt lgkmcnt(0)
	s_setprio 1
	v_mfma_f32_16x16x32_bf16 v[116:119], v[214:217], v[174:177], v[116:119]
	v_mfma_f32_16x16x32_bf16 v[112:115], v[222:225], v[174:177], v[112:115]
	v_mfma_f32_16x16x32_bf16 v[100:103], v[214:217], v[188:191], v[100:103]
	v_mfma_f32_16x16x32_bf16 v[96:99], v[222:225], v[188:191], v[96:99]
	v_mfma_f32_16x16x32_bf16 v[84:87], v[214:217], v[198:201], v[84:87]
	v_mfma_f32_16x16x32_bf16 v[80:83], v[222:225], v[198:201], v[80:83]
	v_mfma_f32_16x16x32_bf16 v[68:71], v[214:217], v[206:209], v[68:71]
	v_mfma_f32_16x16x32_bf16 v[64:67], v[222:225], v[206:209], v[64:67]
	v_mfma_f32_16x16x32_bf16 v[116:119], v[218:221], v[178:181], v[116:119]
	v_mfma_f32_16x16x32_bf16 v[112:115], v[226:229], v[178:181], v[112:115]
	v_mfma_f32_16x16x32_bf16 v[100:103], v[218:221], v[194:197], v[100:103]
	v_mfma_f32_16x16x32_bf16 v[96:99], v[226:229], v[194:197], v[96:99]
	v_mfma_f32_16x16x32_bf16 v[84:87], v[218:221], v[202:205], v[84:87]
	v_mfma_f32_16x16x32_bf16 v[80:83], v[226:229], v[202:205], v[80:83]
	v_mfma_f32_16x16x32_bf16 v[68:71], v[218:221], v[210:213], v[68:71]
	v_mfma_f32_16x16x32_bf16 v[64:67], v[226:229], v[210:213], v[64:67]
	s_setprio 0
	s_add_i32 m0, s97, 0xffffff80
	s_barrier
	ds_read_b128 v[174:177], v165 offset:49152
	ds_read_b128 v[178:181], v165 offset:50176
	ds_read_b128 v[188:191], v165 offset:51200
	ds_read_b128 v[194:197], v165 offset:52224
	ds_read_b128 v[198:201], v165 offset:53248
	ds_read_b128 v[202:205], v165 offset:54272
	ds_read_b128 v[206:209], v165 offset:55296
	global_load_lds_dwordx4 v128, s[12:13] offset:128
	s_add_i32 m0, s84, 0xffffff80
	ds_read_b128 v[210:213], v165 offset:56320
	global_load_lds_dwordx4 v132, s[12:13] offset:128
	s_barrier
	s_waitcnt lgkmcnt(0)
	s_setprio 1
	v_mfma_f32_16x16x32_bf16 v[60:63], v[146:149], v[174:177], v[60:63]
	v_mfma_f32_16x16x32_bf16 v[56:59], v[154:157], v[174:177], v[56:59]
	v_mfma_f32_16x16x32_bf16 v[44:47], v[146:149], v[188:191], v[44:47]
	v_mfma_f32_16x16x32_bf16 v[40:43], v[154:157], v[188:191], v[40:43]
	v_mfma_f32_16x16x32_bf16 v[28:31], v[146:149], v[198:201], v[28:31]
	v_mfma_f32_16x16x32_bf16 v[24:27], v[154:157], v[198:201], v[24:27]
	v_mfma_f32_16x16x32_bf16 v[12:15], v[146:149], v[206:209], v[12:15]
	v_mfma_f32_16x16x32_bf16 v[8:11], v[154:157], v[206:209], v[8:11]
	v_mfma_f32_16x16x32_bf16 v[60:63], v[150:153], v[178:181], v[60:63]
	v_mfma_f32_16x16x32_bf16 v[56:59], v[170:173], v[178:181], v[56:59]
	v_mfma_f32_16x16x32_bf16 v[44:47], v[150:153], v[194:197], v[44:47]
	v_mfma_f32_16x16x32_bf16 v[40:43], v[170:173], v[194:197], v[40:43]
	v_mfma_f32_16x16x32_bf16 v[28:31], v[150:153], v[202:205], v[28:31]
	v_mfma_f32_16x16x32_bf16 v[24:27], v[170:173], v[202:205], v[24:27]
	v_mfma_f32_16x16x32_bf16 v[12:15], v[150:153], v[210:213], v[12:15]
	v_mfma_f32_16x16x32_bf16 v[8:11], v[170:173], v[210:213], v[8:11]
	s_setprio 0
	s_barrier
	s_mov_b32 m0, s61
	s_add_u32 s0, s10, 0x80080
	s_addc_u32 s1, s11, 0
	global_load_lds_dwordx4 v130, s[0:1]
	v_lshl_add_u64 v[146:147], s[0:1], 0, v[134:135]
	s_add_i32 m0, s61, 0x2000
	s_nop 0
	global_load_lds_dwordx4 v134, s[0:1]
	s_waitcnt vmcnt(6)
	s_barrier
	s_setprio 1
	v_mfma_f32_16x16x32_bf16 v[52:55], v[214:217], v[174:177], v[52:55]
	v_mfma_f32_16x16x32_bf16 v[48:51], v[222:225], v[174:177], v[48:51]
	v_mfma_f32_16x16x32_bf16 v[36:39], v[214:217], v[188:191], v[36:39]
	v_mfma_f32_16x16x32_bf16 v[32:35], v[222:225], v[188:191], v[32:35]
	v_mfma_f32_16x16x32_bf16 v[20:23], v[214:217], v[198:201], v[20:23]
	v_mfma_f32_16x16x32_bf16 v[16:19], v[222:225], v[198:201], v[16:19]
	v_mfma_f32_16x16x32_bf16 v[4:7], v[214:217], v[206:209], v[4:7]
	v_mfma_f32_16x16x32_bf16 v[0:3], v[222:225], v[206:209], v[0:3]
	v_mfma_f32_16x16x32_bf16 v[52:55], v[218:221], v[178:181], v[52:55]
	v_mfma_f32_16x16x32_bf16 v[48:51], v[226:229], v[178:181], v[48:51]
	v_mfma_f32_16x16x32_bf16 v[36:39], v[218:221], v[194:197], v[36:39]
	v_mfma_f32_16x16x32_bf16 v[32:35], v[226:229], v[194:197], v[32:35]
	v_mfma_f32_16x16x32_bf16 v[20:23], v[218:221], v[202:205], v[20:23]
	v_mfma_f32_16x16x32_bf16 v[16:19], v[226:229], v[202:205], v[16:19]
	v_mfma_f32_16x16x32_bf16 v[4:7], v[218:221], v[210:213], v[4:7]
	v_mfma_f32_16x16x32_bf16 v[0:3], v[226:229], v[210:213], v[0:3]
	s_setprio 0
	s_add_i32 s35, s35, 2
	s_add_u32 s8, s8, 0x100
	s_addc_u32 s9, s9, 0
	s_add_u32 s28, s28, 0x100
	s_addc_u32 s34, s34, 0
	s_cmp_gt_u32 s35, 29
	s_barrier
	s_cbranch_scc0 .LBB0_527

;     DI size_t aoff(const Unit& u, size_t tstep) const { return (size_t)u.pm * tstep; }
;     DI size_t boff(const Unit& u, size_t tstep) const { return (size_t)u.pn * tstep; }
;     DI bool next(int i, Unit& u) const { const long L = (long)i * G + c; if (L >= np) return false; u.pm = pmv; u.pn = (int)(L % nN); u.ks = (int)(L / nN); return true; }
;     DI size_t aoff(const Unit& u, size_t) const { return (size_t)u.ks * kbytes; }
;     DI size_t boff(const Unit& u, size_t tstep) const { return (size_t)u.pn * tstep + (size_t)u.ks * kbytes; }
;     DI bool next(int i, Unit& u) const { Unit t; if (!S.next(i / 3, t)) return false; u.pm = t.pm; u.pn = t.pn; u.ks = i % 3; return true; }
;     DI size_t aoff(const Unit& u, size_t tstep) const { return (u.ks < 2 ? offU : offOA) + (size_t)u.pm * tstep; }
; #define PG8_WAIT_V(n) asm volatile("s_waitcnt vmcnt(" #n ")" ::: "memory")
; template <class Epi, class Sched>
; DI void gemm_phase(LAS unsigned char* lds, const Gemm g, const Sched& S, const Epi& E) {
;     ...
;         const bool has_next = S.next(ui + 1, nxt);
;         const char* nA = has_next ? (const char*)g.A + S.aoff(nxt, tstep) : cA; const char* nB = has_next ? (const char*)g.Bt + S.boff(nxt, tstep) : cB;
;         for (int t = 0; t < nt; t += 2) {
;             if constexpr (Epi::HAS_MID) { if (t == E.mid_t(nt)) { int fr3 = fr, fq3 = fq; asm volatile("" : "+v"(fr3), "+v"(fq3)); E.mid(acc, cur, wr, wc, fr3, fq3); } }
;             const bool last = (t == nt - 2);
;             const char* a1 = cA + (size_t)(t + 1) * kstep;
;             const char* a2 = last ? nA : cA + (size_t)(t + 2) * kstep; const char* b2 = last ? nB : cB + (size_t)(t + 2) * kstep;
;             const char* a3 = a2 + kstep; const char* b3 = b2 + kstep;
;             PG8_LDB(B0, 0, 0); PG8_SCHED; PG8_LDA(At, 0, 0); PG8_STAGE(PG8_SA(1, 1), a1 + hstep, voffA);
;             PG8_WAIT_L(8); PG8_BAR; PG8_WAIT_L(0); PG8_MMA(0, 0, At, B0); PG8_BAR; PG8_SCHED;
;             PG8_LDB(B1, 0, 1); PG8_STAGE(PG8_SB(0, 0), b2, voffB);
;             PG8_BAR; PG8_WAIT_L(0); PG8_MMA(0, 1, At, B1); PG8_BAR;
;             PG8_LDA(At, 0, 1); PG8_STAGE(PG8_SA(0, 0), a2, voffA);
;             PG8_BAR; PG8_WAIT_L(0); PG8_MMA(1, 0, At, B0); PG8_BAR; PG8_SCHED;
;             PG8_STAGE(PG8_SB(0, 1), b2 + hstep, voffB);
;             PG8_WAIT_V(6); PG8_BAR; PG8_MMA(1, 1, At, B1); PG8_BAR;
.LBB0_937:
	s_add_u32 s8, s38, 0x30080
	s_addc_u32 s9, s39, 0
	s_add_u32 s35, s36, 0x100
	v_mov_b32_e32 v0, 0
	s_addc_u32 s40, s37, 0
	s_mov_b32 s41, -2
	ds_read_b128 v[144:147], v165
	ds_read_b128 v[168:171], v165 offset:1024
	ds_read_b128 v[172:175], v165 offset:2048
	ds_read_b128 v[176:179], v165 offset:3072
	s_add_u32 s0, s8, 0xfffd0080
	s_addc_u32 s1, s9, -1
	s_cmp_eq_u32 s41, 8
	s_cselect_b32 s39, s31, s1
	s_cselect_b32 s38, s30, s0
	s_cselect_b32 s37, s11, s40
	s_cselect_b32 s36, s10, s35
	s_add_i32 m0, s51, 0xc000
	ds_read_b128 v[180:183], v166
	ds_read_b128 v[188:191], v166 offset:1024
	ds_read_b128 v[194:197], v166 offset:2048
	ds_read_b128 v[198:201], v166 offset:3072
	ds_read_b128 v[202:205], v166 offset:4096
	ds_read_b128 v[206:209], v166 offset:5120
	ds_read_b128 v[210:213], v166 offset:6144
	global_load_lds_dwordx4 v136, s[8:9]
	s_add_i32 m0, s51, 0xe000
	ds_read_b128 v[214:217], v166 offset:7168
	global_load_lds_dwordx4 v138, s[8:9]
	s_waitcnt lgkmcnt(8)
	s_barrier
	s_waitcnt lgkmcnt(0)
	s_setprio 1
	v_mfma_f32_16x16x32_bf16 v[124:127], v[144:147], v[180:183], 0
	v_mfma_f32_16x16x32_bf16 v[120:123], v[172:175], v[180:183], 0
	v_mfma_f32_16x16x32_bf16 v[108:111], v[144:147], v[194:197], 0
	v_mfma_f32_16x16x32_bf16 v[104:107], v[172:175], v[194:197], 0
	v_mfma_f32_16x16x32_bf16 v[92:95], v[144:147], v[202:205], 0
	v_mfma_f32_16x16x32_bf16 v[88:91], v[172:175], v[202:205], 0
	v_mfma_f32_16x16x32_bf16 v[76:79], v[144:147], v[210:213], 0
	v_mfma_f32_16x16x32_bf16 v[72:75], v[172:175], v[210:213], 0
	v_mfma_f32_16x16x32_bf16 v[124:127], v[168:171], v[188:191], v[124:127]
	v_mfma_f32_16x16x32_bf16 v[120:123], v[176:179], v[188:191], v[120:123]
	v_mfma_f32_16x16x32_bf16 v[108:111], v[168:171], v[198:201], v[108:111]
	v_mfma_f32_16x16x32_bf16 v[104:107], v[176:179], v[198:201], v[104:107]
	v_mfma_f32_16x16x32_bf16 v[92:95], v[168:171], v[206:209], v[92:95]
	v_mfma_f32_16x16x32_bf16 v[88:91], v[176:179], v[206:209], v[88:91]
	v_mfma_f32_16x16x32_bf16 v[76:79], v[168:171], v[214:217], v[76:79]
	v_mfma_f32_16x16x32_bf16 v[72:75], v[176:179], v[214:217], v[72:75]
	s_setprio 0
	s_barrier
	s_add_i32 s0, s61, s50
	s_mov_b32 s32, s0
	s_mov_b32 m0, s0
	ds_read_b128 v[218:221], v167
	ds_read_b128 v[222:225], v167 offset:1024
	ds_read_b128 v[226:229], v167 offset:2048
	global_load_lds_dwordx4 v130, s[36:37]
	s_add_i32 m0, s0, 0x2000
	ds_read_b128 v[230:233], v167 offset:3072
	global_load_lds_dwordx4 v134, s[36:37]
	s_barrier
	s_waitcnt lgkmcnt(0)
	s_setprio 1
	v_mfma_f32_16x16x32_bf16 v[116:119], v[218:221], v[180:183], 0
	v_mfma_f32_16x16x32_bf16 v[112:115], v[226:229], v[180:183], 0
	v_mfma_f32_16x16x32_bf16 v[100:103], v[218:221], v[194:197], 0
	v_mfma_f32_16x16x32_bf16 v[96:99], v[226:229], v[194:197], 0
	v_mfma_f32_16x16x32_bf16 v[84:87], v[218:221], v[202:205], 0
	v_mfma_f32_16x16x32_bf16 v[80:83], v[226:229], v[202:205], 0
	v_mfma_f32_16x16x32_bf16 v[68:71], v[218:221], v[210:213], 0
	v_mfma_f32_16x16x32_bf16 v[64:67], v[226:229], v[210:213], 0
	v_mfma_f32_16x16x32_bf16 v[116:119], v[222:225], v[188:191], v[116:119]
	v_mfma_f32_16x16x32_bf16 v[112:115], v[230:233], v[188:191], v[112:115]
	v_mfma_f32_16x16x32_bf16 v[100:103], v[222:225], v[198:201], v[100:103]
	v_mfma_f32_16x16x32_bf16 v[96:99], v[230:233], v[198:201], v[96:99]
	v_mfma_f32_16x16x32_bf16 v[84:87], v[222:225], v[206:209], v[84:87]
	v_mfma_f32_16x16x32_bf16 v[80:83], v[230:233], v[206:209], v[80:83]
	v_mfma_f32_16x16x32_bf16 v[68:71], v[222:225], v[214:217], v[68:71]
	v_mfma_f32_16x16x32_bf16 v[64:67], v[230:233], v[214:217], v[64:67]
	s_setprio 0
	s_mov_b32 m0, s51
	s_barrier
	ds_read_b128 v[180:183], v166 offset:16384
	ds_read_b128 v[188:191], v166 offset:17408
	ds_read_b128 v[194:197], v166 offset:18432
	ds_read_b128 v[198:201], v166 offset:19456
	ds_read_b128 v[202:205], v166 offset:20480
	ds_read_b128 v[206:209], v166 offset:21504
	ds_read_b128 v[210:213], v166 offset:22528
	global_load_lds_dwordx4 v128, s[38:39]
	s_mov_b32 m0, s52
	ds_read_b128 v[214:217], v166 offset:23552
	global_load_lds_dwordx4 v132, s[38:39]
	s_barrier
	s_waitcnt lgkmcnt(0)
	s_setprio 1
	v_mfma_f32_16x16x32_bf16 v[60:63], v[144:147], v[180:183], 0
	v_mfma_f32_16x16x32_bf16 v[56:59], v[172:175], v[180:183], 0
	v_mfma_f32_16x16x32_bf16 v[44:47], v[144:147], v[194:197], 0
	v_mfma_f32_16x16x32_bf16 v[40:43], v[172:175], v[194:197], 0
	v_mfma_f32_16x16x32_bf16 v[28:31], v[144:147], v[202:205], 0
	v_mfma_f32_16x16x32_bf16 v[24:27], v[172:175], v[202:205], 0
	v_mfma_f32_16x16x32_bf16 v[12:15], v[144:147], v[210:213], 0
	v_mfma_f32_16x16x32_bf16 v[8:11], v[172:175], v[210:213], 0
	v_mfma_f32_16x16x32_bf16 v[60:63], v[168:171], v[188:191], v[60:63]
	v_mfma_f32_16x16x32_bf16 v[56:59], v[176:179], v[188:191], v[56:59]
	v_mfma_f32_16x16x32_bf16 v[44:47], v[168:171], v[198:201], v[44:47]
	v_mfma_f32_16x16x32_bf16 v[40:43], v[176:179], v[198:201], v[40:43]
	v_mfma_f32_16x16x32_bf16 v[28:31], v[168:171], v[206:209], v[28:31]
	v_mfma_f32_16x16x32_bf16 v[24:27], v[176:179], v[206:209], v[24:27]
	v_mfma_f32_16x16x32_bf16 v[12:15], v[168:171], v[214:217], v[12:15]
	v_mfma_f32_16x16x32_bf16 v[8:11], v[176:179], v[214:217], v[8:11]
	s_setprio 0
	s_barrier
	s_add_i32 s4, s62, s50
	s_mov_b32 s74, s4
	s_mov_b32 m0, s4
	s_add_u32 s0, s36, 0x30000
	s_addc_u32 s1, s37, 0
	global_load_lds_dwordx4 v130, s[0:1]
	s_add_i32 m0, s4, 0x2000
	s_nop 0
	global_load_lds_dwordx4 v134, s[0:1]
	s_waitcnt vmcnt(6)
	s_barrier
; #define PG8_STAGE(bufoff, gbase, voff) do { _Pragma("unroll") for (int _i = 0; _i < 2; ++_i) \
;         __builtin_amdgcn_global_load_lds((const unsigned*)((const char*)(gbase) + (voff)[_i]), (LAS unsigned*)(lds + (bufoff) + ldsw + _i * 8192), 16, 0, 0); } while (0)
; #define PG8_LDA(dst, b, h) do { _Pragma("unroll") for (int m = 0; m < 4; ++m) _Pragma("unroll") for (int k = 0; k < 2; ++k) dst[m][k] = *(const LAS bf16x8*)(lds + PG8_SA(b, h) + aoff + m * 2048 + k * 1024); } while (0)
; #define PG8_LDB(dst, b, h) do { _Pragma("unroll") for (int n = 0; n < 2; ++n) _Pragma("unroll") for (int k = 0; k < 2; ++k) dst[n][k] = *(const LAS bf16x8*)(lds + PG8_SB(b, h) + boff + n * 2048 + k * 1024); } while (0)
; #define PG8_MMA(ai, bj, At, Bt) do { __builtin_amdgcn_s_setprio(1); _Pragma("unroll") for (int m = 0; m < 4; ++m) _Pragma("unroll") for (int n = 0; n < 2; ++n) _Pragma("unroll") for (int k = 0; k < 2; ++k) \
;         acc[ai][bj][m][n] = __builtin_amdgcn_mfma_f32_16x16x32_bf16(Bt[n][k], At[m][k], acc[ai][bj][m][n], 0, 0, 0); __builtin_amdgcn_s_setprio(0); } while (0)
; #define PG8_WAIT_L(n) asm volatile("s_waitcnt lgkmcnt(" #n ")" ::: "memory")
; #define PG8_BAR __builtin_amdgcn_s_barrier()
; #define PG8_SCHED __builtin_amdgcn_sched_barrier(0)
; template <class Epi, class Sched>
; DI void gemm_phase(LAS unsigned char* lds, const Gemm g, const Sched& S, const Epi& E) {
;     ...
;             PG8_LDB(B0, 1, 0); PG8_SCHED; PG8_LDA(At, 1, 0); PG8_STAGE(PG8_SA(0, 1), a2 + hstep, voffA);
;             PG8_WAIT_L(8); PG8_BAR; PG8_WAIT_L(0); PG8_MMA(0, 0, At, B0); PG8_BAR; PG8_SCHED;
;             PG8_LDB(B1, 1, 1); PG8_STAGE(PG8_SB(1, 0), b3, voffB);
;             PG8_BAR; PG8_WAIT_L(0); PG8_MMA(0, 1, At, B1); PG8_BAR;
;             PG8_LDA(At, 1, 1); PG8_STAGE(PG8_SA(1, 0), a3, voffA);
	s_setprio 1
	v_mfma_f32_16x16x32_bf16 v[52:55], v[218:221], v[180:183], 0
	v_mfma_f32_16x16x32_bf16 v[48:51], v[226:229], v[180:183], 0
	v_mfma_f32_16x16x32_bf16 v[36:39], v[218:221], v[194:197], 0
	v_mfma_f32_16x16x32_bf16 v[32:35], v[226:229], v[194:197], 0
	v_mfma_f32_16x16x32_bf16 v[20:23], v[218:221], v[202:205], 0
	v_mfma_f32_16x16x32_bf16 v[16:19], v[226:229], v[202:205], 0
	v_mfma_f32_16x16x32_bf16 v[4:7], v[218:221], v[210:213], 0
	v_mfma_f32_16x16x32_bf16 v[0:3], v[226:229], v[210:213], 0
	v_mfma_f32_16x16x32_bf16 v[52:55], v[222:225], v[188:191], v[52:55]
	v_mfma_f32_16x16x32_bf16 v[48:51], v[230:233], v[188:191], v[48:51]
	v_mfma_f32_16x16x32_bf16 v[36:39], v[222:225], v[198:201], v[36:39]
	v_mfma_f32_16x16x32_bf16 v[32:35], v[230:233], v[198:201], v[32:35]
	v_mfma_f32_16x16x32_bf16 v[20:23], v[222:225], v[206:209], v[20:23]
	v_mfma_f32_16x16x32_bf16 v[16:19], v[230:233], v[206:209], v[16:19]
	v_mfma_f32_16x16x32_bf16 v[4:7], v[222:225], v[214:217], v[4:7]
	v_mfma_f32_16x16x32_bf16 v[0:3], v[230:233], v[214:217], v[0:3]
	s_setprio 0
	s_add_i32 s4, 0, 0x18000
	v_add_u32_e32 v148, s4, v164
	s_barrier
	ds_read_b128 v[144:147], v148
	ds_read_b128 v[168:171], v148 offset:1024
	ds_read_b128 v[172:175], v148 offset:2048
	ds_read_b128 v[176:179], v148 offset:3072
	s_add_u32 s0, s38, 0x30000
	s_addc_u32 s1, s39, 0
	s_mov_b32 m0, s53
	ds_read_b128 v[180:183], v166 offset:32768
	ds_read_b128 v[188:191], v166 offset:33792
	ds_read_b128 v[194:197], v166 offset:34816
	ds_read_b128 v[198:201], v166 offset:35840
	ds_read_b128 v[202:205], v166 offset:36864
	ds_read_b128 v[206:209], v166 offset:37888
	ds_read_b128 v[210:213], v166 offset:38912
	global_load_lds_dwordx4 v128, s[0:1]
	s_mov_b32 m0, s54
	ds_read_b128 v[214:217], v166 offset:39936
	global_load_lds_dwordx4 v132, s[0:1]
	s_waitcnt lgkmcnt(8)
	s_barrier
	s_waitcnt lgkmcnt(0)
	s_setprio 1
	v_mfma_f32_16x16x32_bf16 v[124:127], v[144:147], v[180:183], v[124:127]
	v_mfma_f32_16x16x32_bf16 v[120:123], v[172:175], v[180:183], v[120:123]
	v_mfma_f32_16x16x32_bf16 v[108:111], v[144:147], v[194:197], v[108:111]
	v_mfma_f32_16x16x32_bf16 v[104:107], v[172:175], v[194:197], v[104:107]
	v_mfma_f32_16x16x32_bf16 v[92:95], v[144:147], v[202:205], v[92:95]
	v_mfma_f32_16x16x32_bf16 v[88:91], v[172:175], v[202:205], v[88:91]
	v_mfma_f32_16x16x32_bf16 v[76:79], v[144:147], v[210:213], v[76:79]
	v_mfma_f32_16x16x32_bf16 v[72:75], v[172:175], v[210:213], v[72:75]
	v_mfma_f32_16x16x32_bf16 v[124:127], v[168:171], v[188:191], v[124:127]
	v_mfma_f32_16x16x32_bf16 v[120:123], v[176:179], v[188:191], v[120:123]
	v_mfma_f32_16x16x32_bf16 v[108:111], v[168:171], v[198:201], v[108:111]
	v_mfma_f32_16x16x32_bf16 v[104:107], v[176:179], v[198:201], v[104:107]
	v_mfma_f32_16x16x32_bf16 v[92:95], v[168:171], v[206:209], v[92:95]
	v_mfma_f32_16x16x32_bf16 v[88:91], v[176:179], v[206:209], v[88:91]
	v_mfma_f32_16x16x32_bf16 v[76:79], v[168:171], v[214:217], v[76:79]
	v_mfma_f32_16x16x32_bf16 v[72:75], v[176:179], v[214:217], v[72:75]
	s_setprio 0
	s_barrier
	s_add_i32 s5, 0, 0x1c000
	s_add_i32 s0, s4, s50
	s_mov_b32 s75, s0
	v_add_u32_e32 v149, s5, v164
	s_add_i32 m0, s0, 0xffffff80
	ds_read_b128 v[218:221], v149
	ds_read_b128 v[222:225], v149 offset:1024
	ds_read_b128 v[226:229], v149 offset:2048
	global_load_lds_dwordx4 v130, s[36:37] offset:128
	s_add_i32 m0, s0, 0x1f80
	ds_read_b128 v[230:233], v149 offset:3072
	global_load_lds_dwordx4 v134, s[36:37] offset:128
	s_barrier
	s_waitcnt lgkmcnt(0)
	s_setprio 1
	v_mfma_f32_16x16x32_bf16 v[116:119], v[218:221], v[180:183], v[116:119]
	v_mfma_f32_16x16x32_bf16 v[112:115], v[226:229], v[180:183], v[112:115]
	v_mfma_f32_16x16x32_bf16 v[100:103], v[218:221], v[194:197], v[100:103]
	v_mfma_f32_16x16x32_bf16 v[96:99], v[226:229], v[194:197], v[96:99]
	v_mfma_f32_16x16x32_bf16 v[84:87], v[218:221], v[202:205], v[84:87]
	v_mfma_f32_16x16x32_bf16 v[80:83], v[226:229], v[202:205], v[80:83]
	v_mfma_f32_16x16x32_bf16 v[68:71], v[218:221], v[210:213], v[68:71]
	v_mfma_f32_16x16x32_bf16 v[64:67], v[226:229], v[210:213], v[64:67]
	v_mfma_f32_16x16x32_bf16 v[116:119], v[222:225], v[188:191], v[116:119]
	v_mfma_f32_16x16x32_bf16 v[112:115], v[230:233], v[188:191], v[112:115]
	v_mfma_f32_16x16x32_bf16 v[100:103], v[222:225], v[198:201], v[100:103]
	v_mfma_f32_16x16x32_bf16 v[96:99], v[230:233], v[198:201], v[96:99]
	v_mfma_f32_16x16x32_bf16 v[84:87], v[222:225], v[206:209], v[84:87]
	v_mfma_f32_16x16x32_bf16 v[80:83], v[230:233], v[206:209], v[80:83]
	v_mfma_f32_16x16x32_bf16 v[68:71], v[222:225], v[214:217], v[68:71]
	v_mfma_f32_16x16x32_bf16 v[64:67], v[230:233], v[214:217], v[64:67]
	s_setprio 0
	s_add_i32 m0, s57, 0xffffff80
	s_barrier
	ds_read_b128 v[180:183], v166 offset:49152
	ds_read_b128 v[188:191], v166 offset:50176
	ds_read_b128 v[194:197], v166 offset:51200
	ds_read_b128 v[198:201], v166 offset:52224
	ds_read_b128 v[202:205], v166 offset:53248
	ds_read_b128 v[206:209], v166 offset:54272
	ds_read_b128 v[210:213], v166 offset:55296
	global_load_lds_dwordx4 v128, s[38:39] offset:128
	s_add_i32 m0, s58, 0xffffff80
	ds_read_b128 v[214:217], v166 offset:56320
	global_load_lds_dwordx4 v132, s[38:39] offset:128
	s_barrier
; #define PG8_STAGE(bufoff, gbase, voff) do { _Pragma("unroll") for (int _i = 0; _i < 2; ++_i) \
;         __builtin_amdgcn_global_load_lds((const unsigned*)((const char*)(gbase) + (voff)[_i]), (LAS unsigned*)(lds + (bufoff) + ldsw + _i * 8192), 16, 0, 0); } while (0)
; #define PG8_LDA(dst, b, h) do { _Pragma("unroll") for (int m = 0; m < 4; ++m) _Pragma("unroll") for (int k = 0; k < 2; ++k) dst[m][k] = *(const LAS bf16x8*)(lds + PG8_SA(b, h) + aoff + m * 2048 + k * 1024); } while (0)
; #define PG8_LDB(dst, b, h) do { _Pragma("unroll") for (int n = 0; n < 2; ++n) _Pragma("unroll") for (int k = 0; k < 2; ++k) dst[n][k] = *(const LAS bf16x8*)(lds + PG8_SB(b, h) + boff + n * 2048 + k * 1024); } while (0)
; #define PG8_MMA(ai, bj, At, Bt) do { __builtin_amdgcn_s_setprio(1); _Pragma("unroll") for (int m = 0; m < 4; ++m) _Pragma("unroll") for (int n = 0; n < 2; ++n) _Pragma("unroll") for (int k = 0; k < 2; ++k) \
;         acc[ai][bj][m][n] = __builtin_amdgcn_mfma_f32_16x16x32_bf16(Bt[n][k], At[m][k], acc[ai][bj][m][n], 0, 0, 0); __builtin_amdgcn_s_setprio(0); } while (0)
; #define PG8_WAIT_V(n) asm volatile("s_waitcnt vmcnt(" #n ")" ::: "memory")
; #define PG8_WAIT_L(n) asm volatile("s_waitcnt lgkmcnt(" #n ")" ::: "memory")
; #define PG8_BAR __builtin_amdgcn_s_barrier()
; #define PG8_SCHED __builtin_amdgcn_sched_barrier(0)
; template <class Epi, class Sched>
; DI void gemm_phase(LAS unsigned char* lds, const Gemm g, const Sched& S, const Epi& E) {
;     ...
;             PG8_LDB(B0, 0, 0); PG8_SCHED; PG8_LDA(At, 0, 0); PG8_STAGE(PG8_SA(1, 1), a1 + hstep, voffA);
;             PG8_WAIT_L(8); PG8_BAR; PG8_WAIT_L(0); PG8_MMA(0, 0, At, B0); PG8_BAR; PG8_SCHED;
;             PG8_LDB(B1, 0, 1); PG8_STAGE(PG8_SB(0, 0), b2, voffB);
;             PG8_BAR; PG8_WAIT_L(0); PG8_MMA(0, 1, At, B1); PG8_BAR;
;     ...
;             PG8_BAR; PG8_WAIT_L(0); PG8_MMA(1, 0, At, B0); PG8_BAR; PG8_SCHED;
;             PG8_STAGE(PG8_SB(1, 1), b3 + hstep, voffB);
;             PG8_WAIT_V(6); PG8_BAR; PG8_MMA(1, 1, At, B1); PG8_BAR;
;         }
	s_waitcnt lgkmcnt(0)
	s_setprio 1
	v_mfma_f32_16x16x32_bf16 v[60:63], v[144:147], v[180:183], v[60:63]
	v_mfma_f32_16x16x32_bf16 v[56:59], v[172:175], v[180:183], v[56:59]
	v_mfma_f32_16x16x32_bf16 v[44:47], v[144:147], v[194:197], v[44:47]
	v_mfma_f32_16x16x32_bf16 v[40:43], v[172:175], v[194:197], v[40:43]
	v_mfma_f32_16x16x32_bf16 v[28:31], v[144:147], v[202:205], v[28:31]
	v_mfma_f32_16x16x32_bf16 v[24:27], v[172:175], v[202:205], v[24:27]
	v_mfma_f32_16x16x32_bf16 v[12:15], v[144:147], v[210:213], v[12:15]
	v_mfma_f32_16x16x32_bf16 v[8:11], v[172:175], v[210:213], v[8:11]
	v_mfma_f32_16x16x32_bf16 v[60:63], v[168:171], v[188:191], v[60:63]
	v_mfma_f32_16x16x32_bf16 v[56:59], v[176:179], v[188:191], v[56:59]
	v_mfma_f32_16x16x32_bf16 v[44:47], v[168:171], v[198:201], v[44:47]
	v_mfma_f32_16x16x32_bf16 v[40:43], v[176:179], v[198:201], v[40:43]
	v_mfma_f32_16x16x32_bf16 v[28:31], v[168:171], v[206:209], v[28:31]
	v_mfma_f32_16x16x32_bf16 v[24:27], v[176:179], v[206:209], v[24:27]
	v_mfma_f32_16x16x32_bf16 v[12:15], v[168:171], v[214:217], v[12:15]
	v_mfma_f32_16x16x32_bf16 v[8:11], v[176:179], v[214:217], v[8:11]
	s_setprio 0
	s_barrier
	s_add_i32 s4, s5, s50
	s_mov_b32 s76, s4
	s_mov_b32 m0, s4
	s_add_u32 s0, s36, 0x30080
	s_addc_u32 s1, s37, 0
	global_load_lds_dwordx4 v130, s[0:1]
	s_add_i32 m0, s4, 0x2000
	s_nop 0
	global_load_lds_dwordx4 v134, s[0:1]
	s_waitcnt vmcnt(6)
	s_barrier
	s_setprio 1
	v_mfma_f32_16x16x32_bf16 v[52:55], v[218:221], v[180:183], v[52:55]
	v_mfma_f32_16x16x32_bf16 v[48:51], v[226:229], v[180:183], v[48:51]
	v_mfma_f32_16x16x32_bf16 v[36:39], v[218:221], v[194:197], v[36:39]
	v_mfma_f32_16x16x32_bf16 v[32:35], v[226:229], v[194:197], v[32:35]
	v_mfma_f32_16x16x32_bf16 v[20:23], v[218:221], v[202:205], v[20:23]
	v_mfma_f32_16x16x32_bf16 v[16:19], v[226:229], v[202:205], v[16:19]
	v_mfma_f32_16x16x32_bf16 v[4:7], v[218:221], v[210:213], v[4:7]
	v_mfma_f32_16x16x32_bf16 v[0:3], v[226:229], v[210:213], v[0:3]
	v_mfma_f32_16x16x32_bf16 v[52:55], v[222:225], v[188:191], v[52:55]
	v_mfma_f32_16x16x32_bf16 v[48:51], v[230:233], v[188:191], v[48:51]
	v_mfma_f32_16x16x32_bf16 v[36:39], v[222:225], v[198:201], v[36:39]
	v_mfma_f32_16x16x32_bf16 v[32:35], v[230:233], v[198:201], v[32:35]
	v_mfma_f32_16x16x32_bf16 v[20:23], v[222:225], v[206:209], v[20:23]
	v_mfma_f32_16x16x32_bf16 v[16:19], v[230:233], v[206:209], v[16:19]
	v_mfma_f32_16x16x32_bf16 v[4:7], v[222:225], v[214:217], v[4:7]
	v_mfma_f32_16x16x32_bf16 v[0:3], v[230:233], v[214:217], v[0:3]
	s_setprio 0
	s_add_i32 s41, s41, 2
	s_add_u32 s8, s8, 0x100
	s_addc_u32 s9, s9, 0
	s_add_u32 s35, s35, 0x100
	s_addc_u32 s40, s40, 0
	s_cmp_gt_u32 s41, 9
	s_barrier
	s_cbranch_scc0 .LBB0_938
	s_branch .Lpeel_done_938
.LBB0_938:
	ds_read_b128 v[144:147], v165
	ds_read_b128 v[168:171], v165 offset:1024
	ds_read_b128 v[172:175], v165 offset:2048
	ds_read_b128 v[176:179], v165 offset:3072
	s_add_u32 s0, s8, 0xfffd0080
	s_addc_u32 s1, s9, -1
	s_cmp_eq_u32 s41, 8
	s_cselect_b32 s39, s31, s1
	s_cselect_b32 s38, s30, s0
	s_cselect_b32 s37, s11, s40
	s_cselect_b32 s36, s10, s35
	s_add_i32 m0, s51, 0xc000
	ds_read_b128 v[180:183], v166
	ds_read_b128 v[188:191], v166 offset:1024
	ds_read_b128 v[194:197], v166 offset:2048
	ds_read_b128 v[198:201], v166 offset:3072
	ds_read_b128 v[202:205], v166 offset:4096
	ds_read_b128 v[206:209], v166 offset:5120
	ds_read_b128 v[210:213], v166 offset:6144
	global_load_lds_dwordx4 v136, s[8:9]
	s_add_i32 m0, s51, 0xe000
	ds_read_b128 v[214:217], v166 offset:7168
	global_load_lds_dwordx4 v138, s[8:9]
	s_waitcnt lgkmcnt(8)
	s_barrier
	s_waitcnt lgkmcnt(0)
	s_setprio 1
	v_mfma_f32_16x16x32_bf16 v[124:127], v[144:147], v[180:183], v[124:127]
	v_mfma_f32_16x16x32_bf16 v[120:123], v[172:175], v[180:183], v[120:123]
	v_mfma_f32_16x16x32_bf16 v[108:111], v[144:147], v[194:197], v[108:111]
	v_mfma_f32_16x16x32_bf16 v[104:107], v[172:175], v[194:197], v[104:107]
	v_mfma_f32_16x16x32_bf16 v[92:95], v[144:147], v[202:205], v[92:95]
	v_mfma_f32_16x16x32_bf16 v[88:91], v[172:175], v[202:205], v[88:91]
	v_mfma_f32_16x16x32_bf16 v[76:79], v[144:147], v[210:213], v[76:79]
	v_mfma_f32_16x16x32_bf16 v[72:75], v[172:175], v[210:213], v[72:75]
	v_mfma_f32_16x16x32_bf16 v[124:127], v[168:171], v[188:191], v[124:127]
	v_mfma_f32_16x16x32_bf16 v[120:123], v[176:179], v[188:191], v[120:123]
	v_mfma_f32_16x16x32_bf16 v[108:111], v[168:171], v[198:201], v[108:111]
	v_mfma_f32_16x16x32_bf16 v[104:107], v[176:179], v[198:201], v[104:107]
	v_mfma_f32_16x16x32_bf16 v[92:95], v[168:171], v[206:209], v[92:95]
	v_mfma_f32_16x16x32_bf16 v[88:91], v[176:179], v[206:209], v[88:91]
	v_mfma_f32_16x16x32_bf16 v[76:79], v[168:171], v[214:217], v[76:79]
	v_mfma_f32_16x16x32_bf16 v[72:75], v[176:179], v[214:217], v[72:75]
	s_setprio 0
	s_barrier
	s_mov_b32 m0, s32
	ds_read_b128 v[218:221], v167
	ds_read_b128 v[222:225], v167 offset:1024
	ds_read_b128 v[226:229], v167 offset:2048
	global_load_lds_dwordx4 v130, s[36:37]
	s_add_i32 m0, s32, 0x2000
	ds_read_b128 v[230:233], v167 offset:3072
	global_load_lds_dwordx4 v134, s[36:37]
	s_barrier
; #define PG8_STAGE(bufoff, gbase, voff) do { _Pragma("unroll") for (int _i = 0; _i < 2; ++_i) \
;         __builtin_amdgcn_global_load_lds((const unsigned*)((const char*)(gbase) + (voff)[_i]), (LAS unsigned*)(lds + (bufoff) + ldsw + _i * 8192), 16, 0, 0); } while (0)
; #define PG8_LDA(dst, b, h) do { _Pragma("unroll") for (int m = 0; m < 4; ++m) _Pragma("unroll") for (int k = 0; k < 2; ++k) dst[m][k] = *(const LAS bf16x8*)(lds + PG8_SA(b, h) + aoff + m * 2048 + k * 1024); } while (0)
; #define PG8_LDB(dst, b, h) do { _Pragma("unroll") for (int n = 0; n < 2; ++n) _Pragma("unroll") for (int k = 0; k < 2; ++k) dst[n][k] = *(const LAS bf16x8*)(lds + PG8_SB(b, h) + boff + n * 2048 + k * 1024); } while (0)
; #define PG8_MMA(ai, bj, At, Bt) do { __builtin_amdgcn_s_setprio(1); _Pragma("unroll") for (int m = 0; m < 4; ++m) _Pragma("unroll") for (int n = 0; n < 2; ++n) _Pragma("unroll") for (int k = 0; k < 2; ++k) \
;         acc[ai][bj][m][n] = __builtin_amdgcn_mfma_f32_16x16x32_bf16(Bt[n][k], At[m][k], acc[ai][bj][m][n], 0, 0, 0); __builtin_amdgcn_s_setprio(0); } while (0)
; #define PG8_WAIT_V(n) asm volatile("s_waitcnt vmcnt(" #n ")" ::: "memory")
; #define PG8_WAIT_L(n) asm volatile("s_waitcnt lgkmcnt(" #n ")" ::: "memory")
; #define PG8_BAR __builtin_amdgcn_s_barrier()
; #define PG8_SCHED __builtin_amdgcn_sched_barrier(0)
; template <class Epi, class Sched>
; DI void gemm_phase(LAS unsigned char* lds, const Gemm g, const Sched& S, const Epi& E) {
;     ...
;             PG8_BAR; PG8_WAIT_L(0); PG8_MMA(0, 1, At, B1); PG8_BAR;
;             PG8_LDA(At, 0, 1); PG8_STAGE(PG8_SA(0, 0), a2, voffA);
;             PG8_BAR; PG8_WAIT_L(0); PG8_MMA(1, 0, At, B0); PG8_BAR; PG8_SCHED;
;             PG8_STAGE(PG8_SB(0, 1), b2 + hstep, voffB);
;             PG8_WAIT_V(6); PG8_BAR; PG8_MMA(1, 1, At, B1); PG8_BAR;
;             PG8_LDB(B0, 1, 0); PG8_SCHED; PG8_LDA(At, 1, 0); PG8_STAGE(PG8_SA(0, 1), a2 + hstep, voffA);
;             PG8_WAIT_L(8); PG8_BAR; PG8_WAIT_L(0); PG8_MMA(0, 0, At, B0); PG8_BAR; PG8_SCHED;
	s_waitcnt lgkmcnt(0)
	s_setprio 1
	v_mfma_f32_16x16x32_bf16 v[116:119], v[218:221], v[180:183], v[116:119]
	v_mfma_f32_16x16x32_bf16 v[112:115], v[226:229], v[180:183], v[112:115]
	v_mfma_f32_16x16x32_bf16 v[100:103], v[218:221], v[194:197], v[100:103]
	v_mfma_f32_16x16x32_bf16 v[96:99], v[226:229], v[194:197], v[96:99]
	v_mfma_f32_16x16x32_bf16 v[84:87], v[218:221], v[202:205], v[84:87]
	v_mfma_f32_16x16x32_bf16 v[80:83], v[226:229], v[202:205], v[80:83]
	v_mfma_f32_16x16x32_bf16 v[68:71], v[218:221], v[210:213], v[68:71]
	v_mfma_f32_16x16x32_bf16 v[64:67], v[226:229], v[210:213], v[64:67]
	v_mfma_f32_16x16x32_bf16 v[116:119], v[222:225], v[188:191], v[116:119]
	v_mfma_f32_16x16x32_bf16 v[112:115], v[230:233], v[188:191], v[112:115]
	v_mfma_f32_16x16x32_bf16 v[100:103], v[222:225], v[198:201], v[100:103]
	v_mfma_f32_16x16x32_bf16 v[96:99], v[230:233], v[198:201], v[96:99]
	v_mfma_f32_16x16x32_bf16 v[84:87], v[222:225], v[206:209], v[84:87]
	v_mfma_f32_16x16x32_bf16 v[80:83], v[230:233], v[206:209], v[80:83]
	v_mfma_f32_16x16x32_bf16 v[68:71], v[222:225], v[214:217], v[68:71]
	v_mfma_f32_16x16x32_bf16 v[64:67], v[230:233], v[214:217], v[64:67]
	s_setprio 0
	s_mov_b32 m0, s51
	s_barrier
	ds_read_b128 v[180:183], v166 offset:16384
	ds_read_b128 v[188:191], v166 offset:17408
	ds_read_b128 v[194:197], v166 offset:18432
	ds_read_b128 v[198:201], v166 offset:19456
	ds_read_b128 v[202:205], v166 offset:20480
	ds_read_b128 v[206:209], v166 offset:21504
	ds_read_b128 v[210:213], v166 offset:22528
	global_load_lds_dwordx4 v128, s[38:39]
	s_mov_b32 m0, s52
	ds_read_b128 v[214:217], v166 offset:23552
	global_load_lds_dwordx4 v132, s[38:39]
	s_barrier
	s_waitcnt lgkmcnt(0)
	s_setprio 1
	v_mfma_f32_16x16x32_bf16 v[60:63], v[144:147], v[180:183], v[60:63]
	v_mfma_f32_16x16x32_bf16 v[56:59], v[172:175], v[180:183], v[56:59]
	v_mfma_f32_16x16x32_bf16 v[44:47], v[144:147], v[194:197], v[44:47]
	v_mfma_f32_16x16x32_bf16 v[40:43], v[172:175], v[194:197], v[40:43]
	v_mfma_f32_16x16x32_bf16 v[28:31], v[144:147], v[202:205], v[28:31]
	v_mfma_f32_16x16x32_bf16 v[24:27], v[172:175], v[202:205], v[24:27]
	v_mfma_f32_16x16x32_bf16 v[12:15], v[144:147], v[210:213], v[12:15]
	v_mfma_f32_16x16x32_bf16 v[8:11], v[172:175], v[210:213], v[8:11]
	v_mfma_f32_16x16x32_bf16 v[60:63], v[168:171], v[188:191], v[60:63]
	v_mfma_f32_16x16x32_bf16 v[56:59], v[176:179], v[188:191], v[56:59]
	v_mfma_f32_16x16x32_bf16 v[44:47], v[168:171], v[198:201], v[44:47]
	v_mfma_f32_16x16x32_bf16 v[40:43], v[176:179], v[198:201], v[40:43]
	v_mfma_f32_16x16x32_bf16 v[28:31], v[168:171], v[206:209], v[28:31]
	v_mfma_f32_16x16x32_bf16 v[24:27], v[176:179], v[206:209], v[24:27]
	v_mfma_f32_16x16x32_bf16 v[12:15], v[168:171], v[214:217], v[12:15]
	v_mfma_f32_16x16x32_bf16 v[8:11], v[176:179], v[214:217], v[8:11]
	s_setprio 0
	s_barrier
	s_mov_b32 m0, s74
	s_add_u32 s0, s36, 0x30000
	s_addc_u32 s1, s37, 0
	global_load_lds_dwordx4 v130, s[0:1]
	s_add_i32 m0, s74, 0x2000
	s_nop 0
	global_load_lds_dwordx4 v134, s[0:1]
	s_waitcnt vmcnt(6)
	s_barrier
	s_setprio 1
	v_mfma_f32_16x16x32_bf16 v[52:55], v[218:221], v[180:183], v[52:55]
	v_mfma_f32_16x16x32_bf16 v[48:51], v[226:229], v[180:183], v[48:51]
	v_mfma_f32_16x16x32_bf16 v[36:39], v[218:221], v[194:197], v[36:39]
	v_mfma_f32_16x16x32_bf16 v[32:35], v[226:229], v[194:197], v[32:35]
	v_mfma_f32_16x16x32_bf16 v[20:23], v[218:221], v[202:205], v[20:23]
	v_mfma_f32_16x16x32_bf16 v[16:19], v[226:229], v[202:205], v[16:19]
	v_mfma_f32_16x16x32_bf16 v[4:7], v[218:221], v[210:213], v[4:7]
	v_mfma_f32_16x16x32_bf16 v[0:3], v[226:229], v[210:213], v[0:3]
	v_mfma_f32_16x16x32_bf16 v[52:55], v[222:225], v[188:191], v[52:55]
	v_mfma_f32_16x16x32_bf16 v[48:51], v[230:233], v[188:191], v[48:51]
	v_mfma_f32_16x16x32_bf16 v[36:39], v[222:225], v[198:201], v[36:39]
	v_mfma_f32_16x16x32_bf16 v[32:35], v[230:233], v[198:201], v[32:35]
	v_mfma_f32_16x16x32_bf16 v[20:23], v[222:225], v[206:209], v[20:23]
	v_mfma_f32_16x16x32_bf16 v[16:19], v[230:233], v[206:209], v[16:19]
	v_mfma_f32_16x16x32_bf16 v[4:7], v[222:225], v[214:217], v[4:7]
	v_mfma_f32_16x16x32_bf16 v[0:3], v[230:233], v[214:217], v[0:3]
	s_setprio 0
	s_add_i32 s4, 0, 0x18000
	s_barrier
	ds_read_b128 v[144:147], v148
	ds_read_b128 v[168:171], v148 offset:1024
	ds_read_b128 v[172:175], v148 offset:2048
	ds_read_b128 v[176:179], v148 offset:3072
	s_add_u32 s0, s38, 0x30000
	s_addc_u32 s1, s39, 0
	s_mov_b32 m0, s53
	ds_read_b128 v[180:183], v166 offset:32768
	ds_read_b128 v[188:191], v166 offset:33792
	ds_read_b128 v[194:197], v166 offset:34816
	ds_read_b128 v[198:201], v166 offset:35840
	ds_read_b128 v[202:205], v166 offset:36864
	ds_read_b128 v[206:209], v166 offset:37888
	ds_read_b128 v[210:213], v166 offset:38912
	global_load_lds_dwordx4 v128, s[0:1]
	s_mov_b32 m0, s54
	ds_read_b128 v[214:217], v166 offset:39936
	global_load_lds_dwordx4 v132, s[0:1]
	s_waitcnt lgkmcnt(8)
	s_barrier
; #define PG8_STAGE(bufoff, gbase, voff) do { _Pragma("unroll") for (int _i = 0; _i < 2; ++_i) \
;         __builtin_amdgcn_global_load_lds((const unsigned*)((const char*)(gbase) + (voff)[_i]), (LAS unsigned*)(lds + (bufoff) + ldsw + _i * 8192), 16, 0, 0); } while (0)
; #define PG8_LDA(dst, b, h) do { _Pragma("unroll") for (int m = 0; m < 4; ++m) _Pragma("unroll") for (int k = 0; k < 2; ++k) dst[m][k] = *(const LAS bf16x8*)(lds + PG8_SA(b, h) + aoff + m * 2048 + k * 1024); } while (0)
; #define PG8_LDB(dst, b, h) do { _Pragma("unroll") for (int n = 0; n < 2; ++n) _Pragma("unroll") for (int k = 0; k < 2; ++k) dst[n][k] = *(const LAS bf16x8*)(lds + PG8_SB(b, h) + boff + n * 2048 + k * 1024); } while (0)
; #define PG8_MMA(ai, bj, At, Bt) do { __builtin_amdgcn_s_setprio(1); _Pragma("unroll") for (int m = 0; m < 4; ++m) _Pragma("unroll") for (int n = 0; n < 2; ++n) _Pragma("unroll") for (int k = 0; k < 2; ++k) \
;         acc[ai][bj][m][n] = __builtin_amdgcn_mfma_f32_16x16x32_bf16(Bt[n][k], At[m][k], acc[ai][bj][m][n], 0, 0, 0); __builtin_amdgcn_s_setprio(0); } while (0)
; #define PG8_WAIT_V(n) asm volatile("s_waitcnt vmcnt(" #n ")" ::: "memory")
; #define PG8_WAIT_L(n) asm volatile("s_waitcnt lgkmcnt(" #n ")" ::: "memory")
; #define PG8_BAR __builtin_amdgcn_s_barrier()
; #define PG8_SCHED __builtin_amdgcn_sched_barrier(0)
; template <class Epi, class Sched>
; DI void gemm_phase(LAS unsigned char* lds, const Gemm g, const Sched& S, const Epi& E) {
;     ...
;             PG8_WAIT_L(8); PG8_BAR; PG8_WAIT_L(0); PG8_MMA(0, 0, At, B0); PG8_BAR; PG8_SCHED;
;             PG8_LDB(B1, 1, 1); PG8_STAGE(PG8_SB(1, 0), b3, voffB);
;             PG8_BAR; PG8_WAIT_L(0); PG8_MMA(0, 1, At, B1); PG8_BAR;
;             PG8_LDA(At, 1, 1); PG8_STAGE(PG8_SA(1, 0), a3, voffA);
;             PG8_BAR; PG8_WAIT_L(0); PG8_MMA(1, 0, At, B0); PG8_BAR; PG8_SCHED;
;             PG8_STAGE(PG8_SB(1, 1), b3 + hstep, voffB);
;             PG8_WAIT_V(6); PG8_BAR; PG8_MMA(1, 1, At, B1); PG8_BAR;
;         }
	s_waitcnt lgkmcnt(0)
	s_setprio 1
	v_mfma_f32_16x16x32_bf16 v[124:127], v[144:147], v[180:183], v[124:127]
	v_mfma_f32_16x16x32_bf16 v[120:123], v[172:175], v[180:183], v[120:123]
	v_mfma_f32_16x16x32_bf16 v[108:111], v[144:147], v[194:197], v[108:111]
	v_mfma_f32_16x16x32_bf16 v[104:107], v[172:175], v[194:197], v[104:107]
	v_mfma_f32_16x16x32_bf16 v[92:95], v[144:147], v[202:205], v[92:95]
	v_mfma_f32_16x16x32_bf16 v[88:91], v[172:175], v[202:205], v[88:91]
	v_mfma_f32_16x16x32_bf16 v[76:79], v[144:147], v[210:213], v[76:79]
	v_mfma_f32_16x16x32_bf16 v[72:75], v[172:175], v[210:213], v[72:75]
	v_mfma_f32_16x16x32_bf16 v[124:127], v[168:171], v[188:191], v[124:127]
	v_mfma_f32_16x16x32_bf16 v[120:123], v[176:179], v[188:191], v[120:123]
	v_mfma_f32_16x16x32_bf16 v[108:111], v[168:171], v[198:201], v[108:111]
	v_mfma_f32_16x16x32_bf16 v[104:107], v[176:179], v[198:201], v[104:107]
	v_mfma_f32_16x16x32_bf16 v[92:95], v[168:171], v[206:209], v[92:95]
	v_mfma_f32_16x16x32_bf16 v[88:91], v[176:179], v[206:209], v[88:91]
	v_mfma_f32_16x16x32_bf16 v[76:79], v[168:171], v[214:217], v[76:79]
	v_mfma_f32_16x16x32_bf16 v[72:75], v[176:179], v[214:217], v[72:75]
	s_setprio 0
	s_barrier
	s_add_i32 s5, 0, 0x1c000
	s_add_i32 m0, s75, 0xffffff80
	ds_read_b128 v[218:221], v149
	ds_read_b128 v[222:225], v149 offset:1024
	ds_read_b128 v[226:229], v149 offset:2048
	global_load_lds_dwordx4 v130, s[36:37] offset:128
	s_add_i32 m0, s75, 0x1f80
	ds_read_b128 v[230:233], v149 offset:3072
	global_load_lds_dwordx4 v134, s[36:37] offset:128
	s_barrier
	s_waitcnt lgkmcnt(0)
	s_setprio 1
	v_mfma_f32_16x16x32_bf16 v[116:119], v[218:221], v[180:183], v[116:119]
	v_mfma_f32_16x16x32_bf16 v[112:115], v[226:229], v[180:183], v[112:115]
	v_mfma_f32_16x16x32_bf16 v[100:103], v[218:221], v[194:197], v[100:103]
	v_mfma_f32_16x16x32_bf16 v[96:99], v[226:229], v[194:197], v[96:99]
	v_mfma_f32_16x16x32_bf16 v[84:87], v[218:221], v[202:205], v[84:87]
	v_mfma_f32_16x16x32_bf16 v[80:83], v[226:229], v[202:205], v[80:83]
	v_mfma_f32_16x16x32_bf16 v[68:71], v[218:221], v[210:213], v[68:71]
	v_mfma_f32_16x16x32_bf16 v[64:67], v[226:229], v[210:213], v[64:67]
	v_mfma_f32_16x16x32_bf16 v[116:119], v[222:225], v[188:191], v[116:119]
	v_mfma_f32_16x16x32_bf16 v[112:115], v[230:233], v[188:191], v[112:115]
	v_mfma_f32_16x16x32_bf16 v[100:103], v[222:225], v[198:201], v[100:103]
	v_mfma_f32_16x16x32_bf16 v[96:99], v[230:233], v[198:201], v[96:99]
	v_mfma_f32_16x16x32_bf16 v[84:87], v[222:225], v[206:209], v[84:87]
	v_mfma_f32_16x16x32_bf16 v[80:83], v[230:233], v[206:209], v[80:83]
	v_mfma_f32_16x16x32_bf16 v[68:71], v[222:225], v[214:217], v[68:71]
	v_mfma_f32_16x16x32_bf16 v[64:67], v[230:233], v[214:217], v[64:67]
	s_setprio 0
	s_add_i32 m0, s57, 0xffffff80
	s_barrier
	ds_read_b128 v[180:183], v166 offset:49152
	ds_read_b128 v[188:191], v166 offset:50176
	ds_read_b128 v[194:197], v166 offset:51200
	ds_read_b128 v[198:201], v166 offset:52224
	ds_read_b128 v[202:205], v166 offset:53248
	ds_read_b128 v[206:209], v166 offset:54272
	ds_read_b128 v[210:213], v166 offset:55296
	global_load_lds_dwordx4 v128, s[38:39] offset:128
	s_add_i32 m0, s58, 0xffffff80
	ds_read_b128 v[214:217], v166 offset:56320
	global_load_lds_dwordx4 v132, s[38:39] offset:128
	s_barrier
	s_waitcnt lgkmcnt(0)
	s_setprio 1
	v_mfma_f32_16x16x32_bf16 v[60:63], v[144:147], v[180:183], v[60:63]
	v_mfma_f32_16x16x32_bf16 v[56:59], v[172:175], v[180:183], v[56:59]
	v_mfma_f32_16x16x32_bf16 v[44:47], v[144:147], v[194:197], v[44:47]
	v_mfma_f32_16x16x32_bf16 v[40:43], v[172:175], v[194:197], v[40:43]
	v_mfma_f32_16x16x32_bf16 v[28:31], v[144:147], v[202:205], v[28:31]
	v_mfma_f32_16x16x32_bf16 v[24:27], v[172:175], v[202:205], v[24:27]
	v_mfma_f32_16x16x32_bf16 v[12:15], v[144:147], v[210:213], v[12:15]
	v_mfma_f32_16x16x32_bf16 v[8:11], v[172:175], v[210:213], v[8:11]
	v_mfma_f32_16x16x32_bf16 v[60:63], v[168:171], v[188:191], v[60:63]
	v_mfma_f32_16x16x32_bf16 v[56:59], v[176:179], v[188:191], v[56:59]
	v_mfma_f32_16x16x32_bf16 v[44:47], v[168:171], v[198:201], v[44:47]
	v_mfma_f32_16x16x32_bf16 v[40:43], v[176:179], v[198:201], v[40:43]
	v_mfma_f32_16x16x32_bf16 v[28:31], v[168:171], v[206:209], v[28:31]
	v_mfma_f32_16x16x32_bf16 v[24:27], v[176:179], v[206:209], v[24:27]
	v_mfma_f32_16x16x32_bf16 v[12:15], v[168:171], v[214:217], v[12:15]
	v_mfma_f32_16x16x32_bf16 v[8:11], v[176:179], v[214:217], v[8:11]
	s_setprio 0
	s_barrier
	s_mov_b32 m0, s76
	s_add_u32 s0, s36, 0x30080
	s_addc_u32 s1, s37, 0
	global_load_lds_dwordx4 v130, s[0:1]
	s_add_i32 m0, s76, 0x2000
	s_nop 0
	global_load_lds_dwordx4 v134, s[0:1]
	s_waitcnt vmcnt(6)
	s_barrier
	s_setprio 1
	v_mfma_f32_16x16x32_bf16 v[52:55], v[218:221], v[180:183], v[52:55]
	v_mfma_f32_16x16x32_bf16 v[48:51], v[226:229], v[180:183], v[48:51]
	v_mfma_f32_16x16x32_bf16 v[36:39], v[218:221], v[194:197], v[36:39]
	v_mfma_f32_16x16x32_bf16 v[32:35], v[226:229], v[194:197], v[32:35]
	v_mfma_f32_16x16x32_bf16 v[20:23], v[218:221], v[202:205], v[20:23]
	v_mfma_f32_16x16x32_bf16 v[16:19], v[226:229], v[202:205], v[16:19]
	v_mfma_f32_16x16x32_bf16 v[4:7], v[218:221], v[210:213], v[4:7]
	v_mfma_f32_16x16x32_bf16 v[0:3], v[226:229], v[210:213], v[0:3]
	v_mfma_f32_16x16x32_bf16 v[52:55], v[222:225], v[188:191], v[52:55]
	v_mfma_f32_16x16x32_bf16 v[48:51], v[230:233], v[188:191], v[48:51]
	v_mfma_f32_16x16x32_bf16 v[36:39], v[222:225], v[198:201], v[36:39]
	v_mfma_f32_16x16x32_bf16 v[32:35], v[230:233], v[198:201], v[32:35]
	v_mfma_f32_16x16x32_bf16 v[20:23], v[222:225], v[206:209], v[20:23]
	v_mfma_f32_16x16x32_bf16 v[16:19], v[230:233], v[206:209], v[16:19]
	v_mfma_f32_16x16x32_bf16 v[4:7], v[222:225], v[214:217], v[4:7]
	v_mfma_f32_16x16x32_bf16 v[0:3], v[230:233], v[214:217], v[0:3]
	s_setprio 0
	s_add_i32 s41, s41, 2
	s_add_u32 s8, s8, 0x100
	s_addc_u32 s9, s9, 0
	s_add_u32 s35, s35, 0x100
	s_addc_u32 s40, s40, 0
	s_cmp_gt_u32 s41, 9
	s_barrier
	s_cbranch_scc0 .LBB0_938

;     DI size_t aoff(const Unit& u, size_t tstep) const { return (size_t)u.pm * tstep; }
;     DI size_t boff(const Unit& u, size_t tstep) const { return (size_t)u.pn * tstep; }
;     DI bool next(int i, Unit& u) const { const long L = (long)i * G + c; if (L >= np) return false; u.pm = pmv; u.pn = (int)(L % nN); u.ks = (int)(L / nN); return true; }
;     DI size_t aoff(const Unit& u, size_t) const { return (size_t)u.ks * kbytes; }
;     DI size_t boff(const Unit& u, size_t tstep) const { return (size_t)u.pn * tstep + (size_t)u.ks * kbytes; }
;     DI bool next(int i, Unit& u) const { Unit t; if (!S.next(i / 3, t)) return false; u.pm = t.pm; u.pn = t.pn; u.ks = i % 3; return true; }
;     DI size_t aoff(const Unit& u, size_t tstep) const { return (u.ks < 2 ? offU : offOA) + (size_t)u.pm * tstep; }
; #define PG8_WAIT_V(n) asm volatile("s_waitcnt vmcnt(" #n ")" ::: "memory")
; template <class Epi, class Sched>
; DI void gemm_phase(LAS unsigned char* lds, const Gemm g, const Sched& S, const Epi& E) {
;     ...
;         const bool has_next = S.next(ui + 1, nxt);
;         const char* nA = has_next ? (const char*)g.A + S.aoff(nxt, tstep) : cA; const char* nB = has_next ? (const char*)g.Bt + S.boff(nxt, tstep) : cB;
;         for (int t = 0; t < nt; t += 2) {
;             if constexpr (Epi::HAS_MID) { if (t == E.mid_t(nt)) { int fr3 = fr, fq3 = fq; asm volatile("" : "+v"(fr3), "+v"(fq3)); E.mid(acc, cur, wr, wc, fr3, fq3); } }
;             const bool last = (t == nt - 2);
;             const char* a1 = cA + (size_t)(t + 1) * kstep;
;             const char* a2 = last ? nA : cA + (size_t)(t + 2) * kstep; const char* b2 = last ? nB : cB + (size_t)(t + 2) * kstep;
;             const char* a3 = a2 + kstep; const char* b3 = b2 + kstep;
;             PG8_LDB(B0, 0, 0); PG8_SCHED; PG8_LDA(At, 0, 0); PG8_STAGE(PG8_SA(1, 1), a1 + hstep, voffA);
;             PG8_WAIT_L(8); PG8_BAR; PG8_WAIT_L(0); PG8_MMA(0, 0, At, B0); PG8_BAR; PG8_SCHED;
;             PG8_LDB(B1, 0, 1); PG8_STAGE(PG8_SB(0, 0), b2, voffB);
;             PG8_BAR; PG8_WAIT_L(0); PG8_MMA(0, 1, At, B1); PG8_BAR;
;             PG8_LDA(At, 0, 1); PG8_STAGE(PG8_SA(0, 0), a2, voffA);
;             PG8_BAR; PG8_WAIT_L(0); PG8_MMA(1, 0, At, B0); PG8_BAR; PG8_SCHED;
;             PG8_STAGE(PG8_SB(0, 1), b2 + hstep, voffB);
;             PG8_WAIT_V(6); PG8_BAR; PG8_MMA(1, 1, At, B1); PG8_BAR;
.LBB0_983:
	s_ashr_i32 s31, s30, 31
	s_lshl_b64 s[0:1], s[30:31], 18
	v_cmp_lt_i64_e32 vcc, s[36:37], v[142:143]
	s_add_u32 s36, s51, s0
	s_addc_u32 s37, s52, s1
	s_and_b64 s[0:1], vcc, exec
	s_cselect_b32 s9, s37, s43
	s_cselect_b32 s31, s36, s42
	s_ashr_i32 s29, s28, 31
	s_lshl_b64 s[0:1], s[28:29], 18
	s_add_u32 s38, s53, s0
	s_addc_u32 s39, s54, s1
	s_and_b64 s[0:1], vcc, exec
	s_cselect_b32 s29, s39, s45
	s_cselect_b32 s34, s38, s44
	s_add_u32 s42, s42, 0x20080
	s_addc_u32 s43, s43, 0
	s_add_u32 s35, s44, 0x100
	v_mov_b32_e32 v0, 0
	s_addc_u32 s41, s45, 0
	s_mov_b32 s79, -2
	ds_read_b128 v[146:149], v156
	ds_read_b128 v[150:153], v156 offset:1024
	ds_read_b128 v[160:163], v156 offset:2048
	ds_read_b128 v[164:167], v156 offset:3072
	s_add_u32 s0, s42, 0xfffe0080
	s_addc_u32 s1, s43, -1
	s_cmp_eq_u32 s79, 4
	s_cselect_b32 s47, s9, s1
	s_cselect_b32 s46, s31, s0
	s_cselect_b32 s45, s29, s41
	s_cselect_b32 s44, s34, s35
	s_add_i32 m0, s55, 0xc000
	ds_read_b128 v[168:171], v158
	ds_read_b128 v[172:175], v158 offset:1024
	ds_read_b128 v[176:179], v158 offset:2048
	ds_read_b128 v[180:183], v158 offset:3072
	ds_read_b128 v[188:191], v158 offset:4096
	ds_read_b128 v[194:197], v158 offset:5120
	ds_read_b128 v[198:201], v158 offset:6144
	global_load_lds_dwordx4 v138, s[42:43]
	s_add_i32 m0, s55, 0xe000
	ds_read_b128 v[202:205], v158 offset:7168
	global_load_lds_dwordx4 v140, s[42:43]
	s_waitcnt lgkmcnt(8)
	s_barrier
	s_waitcnt lgkmcnt(0)
	s_setprio 1
	v_mfma_f32_16x16x32_bf16 v[124:127], v[146:149], v[168:171], 0
	v_mfma_f32_16x16x32_bf16 v[120:123], v[160:163], v[168:171], 0
	v_mfma_f32_16x16x32_bf16 v[108:111], v[146:149], v[176:179], 0
	v_mfma_f32_16x16x32_bf16 v[104:107], v[160:163], v[176:179], 0
	v_mfma_f32_16x16x32_bf16 v[92:95], v[146:149], v[188:191], 0
	v_mfma_f32_16x16x32_bf16 v[88:91], v[160:163], v[188:191], 0
	v_mfma_f32_16x16x32_bf16 v[76:79], v[146:149], v[198:201], 0
	v_mfma_f32_16x16x32_bf16 v[72:75], v[160:163], v[198:201], 0
	v_mfma_f32_16x16x32_bf16 v[124:127], v[150:153], v[172:175], v[124:127]
	v_mfma_f32_16x16x32_bf16 v[120:123], v[164:167], v[172:175], v[120:123]
	v_mfma_f32_16x16x32_bf16 v[108:111], v[150:153], v[180:183], v[108:111]
	v_mfma_f32_16x16x32_bf16 v[104:107], v[164:167], v[180:183], v[104:107]
	v_mfma_f32_16x16x32_bf16 v[92:95], v[150:153], v[194:197], v[92:95]
	v_mfma_f32_16x16x32_bf16 v[88:91], v[164:167], v[194:197], v[88:91]
	v_mfma_f32_16x16x32_bf16 v[76:79], v[150:153], v[202:205], v[76:79]
	v_mfma_f32_16x16x32_bf16 v[72:75], v[164:167], v[202:205], v[72:75]
	s_setprio 0
	s_barrier
	s_add_i32 s0, s66, s50
	s_mov_b32 s19, s0
	s_mov_b32 m0, s0
	ds_read_b128 v[206:209], v159
	ds_read_b128 v[210:213], v159 offset:1024
	ds_read_b128 v[214:217], v159 offset:2048
	global_load_lds_dwordx4 v130, s[44:45]
	s_add_i32 m0, s0, 0x2000
	ds_read_b128 v[218:221], v159 offset:3072
	global_load_lds_dwordx4 v134, s[44:45]
	s_barrier
	s_waitcnt lgkmcnt(0)
	s_setprio 1
	v_mfma_f32_16x16x32_bf16 v[116:119], v[206:209], v[168:171], 0
	v_mfma_f32_16x16x32_bf16 v[112:115], v[214:217], v[168:171], 0
	v_mfma_f32_16x16x32_bf16 v[100:103], v[206:209], v[176:179], 0
	v_mfma_f32_16x16x32_bf16 v[96:99], v[214:217], v[176:179], 0
	v_mfma_f32_16x16x32_bf16 v[84:87], v[206:209], v[188:191], 0
	v_mfma_f32_16x16x32_bf16 v[80:83], v[214:217], v[188:191], 0
	v_mfma_f32_16x16x32_bf16 v[68:71], v[206:209], v[198:201], 0
	v_mfma_f32_16x16x32_bf16 v[64:67], v[214:217], v[198:201], 0
	v_mfma_f32_16x16x32_bf16 v[116:119], v[210:213], v[172:175], v[116:119]
	v_mfma_f32_16x16x32_bf16 v[112:115], v[218:221], v[172:175], v[112:115]
	v_mfma_f32_16x16x32_bf16 v[100:103], v[210:213], v[180:183], v[100:103]
	v_mfma_f32_16x16x32_bf16 v[96:99], v[218:221], v[180:183], v[96:99]
	v_mfma_f32_16x16x32_bf16 v[84:87], v[210:213], v[194:197], v[84:87]
	v_mfma_f32_16x16x32_bf16 v[80:83], v[218:221], v[194:197], v[80:83]
	v_mfma_f32_16x16x32_bf16 v[68:71], v[210:213], v[202:205], v[68:71]
	v_mfma_f32_16x16x32_bf16 v[64:67], v[218:221], v[202:205], v[64:67]
	s_setprio 0
	s_mov_b32 m0, s55
	s_barrier
	ds_read_b128 v[168:171], v158 offset:16384
	ds_read_b128 v[172:175], v158 offset:17408
	ds_read_b128 v[176:179], v158 offset:18432
	ds_read_b128 v[180:183], v158 offset:19456
	ds_read_b128 v[188:191], v158 offset:20480
	ds_read_b128 v[194:197], v158 offset:21504
	ds_read_b128 v[198:201], v158 offset:22528
	global_load_lds_dwordx4 v128, s[46:47]
	s_mov_b32 m0, s56
	ds_read_b128 v[202:205], v158 offset:23552
	global_load_lds_dwordx4 v132, s[46:47]
	s_barrier
	s_waitcnt lgkmcnt(0)
	s_setprio 1
	v_mfma_f32_16x16x32_bf16 v[60:63], v[146:149], v[168:171], 0
	v_mfma_f32_16x16x32_bf16 v[56:59], v[160:163], v[168:171], 0
	v_mfma_f32_16x16x32_bf16 v[44:47], v[146:149], v[176:179], 0
	v_mfma_f32_16x16x32_bf16 v[40:43], v[160:163], v[176:179], 0
	v_mfma_f32_16x16x32_bf16 v[28:31], v[146:149], v[188:191], 0
	v_mfma_f32_16x16x32_bf16 v[24:27], v[160:163], v[188:191], 0
	v_mfma_f32_16x16x32_bf16 v[12:15], v[146:149], v[198:201], 0
	v_mfma_f32_16x16x32_bf16 v[8:11], v[160:163], v[198:201], 0
	v_mfma_f32_16x16x32_bf16 v[60:63], v[150:153], v[172:175], v[60:63]
	v_mfma_f32_16x16x32_bf16 v[56:59], v[164:167], v[172:175], v[56:59]
	v_mfma_f32_16x16x32_bf16 v[44:47], v[150:153], v[180:183], v[44:47]
	v_mfma_f32_16x16x32_bf16 v[40:43], v[164:167], v[180:183], v[40:43]
	v_mfma_f32_16x16x32_bf16 v[28:31], v[150:153], v[194:197], v[28:31]
	v_mfma_f32_16x16x32_bf16 v[24:27], v[164:167], v[194:197], v[24:27]
	v_mfma_f32_16x16x32_bf16 v[12:15], v[150:153], v[202:205], v[12:15]
	v_mfma_f32_16x16x32_bf16 v[8:11], v[164:167], v[202:205], v[8:11]
	s_setprio 0
	s_barrier
; #define PG8_STAGE(bufoff, gbase, voff) do { _Pragma("unroll") for (int _i = 0; _i < 2; ++_i) \
;         __builtin_amdgcn_global_load_lds((const unsigned*)((const char*)(gbase) + (voff)[_i]), (LAS unsigned*)(lds + (bufoff) + ldsw + _i * 8192), 16, 0, 0); } while (0)
; #define PG8_LDA(dst, b, h) do { _Pragma("unroll") for (int m = 0; m < 4; ++m) _Pragma("unroll") for (int k = 0; k < 2; ++k) dst[m][k] = *(const LAS bf16x8*)(lds + PG8_SA(b, h) + aoff + m * 2048 + k * 1024); } while (0)
; #define PG8_LDB(dst, b, h) do { _Pragma("unroll") for (int n = 0; n < 2; ++n) _Pragma("unroll") for (int k = 0; k < 2; ++k) dst[n][k] = *(const LAS bf16x8*)(lds + PG8_SB(b, h) + boff + n * 2048 + k * 1024); } while (0)
; #define PG8_MMA(ai, bj, At, Bt) do { __builtin_amdgcn_s_setprio(1); _Pragma("unroll") for (int m = 0; m < 4; ++m) _Pragma("unroll") for (int n = 0; n < 2; ++n) _Pragma("unroll") for (int k = 0; k < 2; ++k) \
;         acc[ai][bj][m][n] = __builtin_amdgcn_mfma_f32_16x16x32_bf16(Bt[n][k], At[m][k], acc[ai][bj][m][n], 0, 0, 0); __builtin_amdgcn_s_setprio(0); } while (0)
; #define PG8_WAIT_V(n) asm volatile("s_waitcnt vmcnt(" #n ")" ::: "memory")
; #define PG8_WAIT_L(n) asm volatile("s_waitcnt lgkmcnt(" #n ")" ::: "memory")
; #define PG8_BAR __builtin_amdgcn_s_barrier()
; #define PG8_SCHED __builtin_amdgcn_sched_barrier(0)
; template <class Epi, class Sched>
; DI void gemm_phase(LAS unsigned char* lds, const Gemm g, const Sched& S, const Epi& E) {
;     ...
;             PG8_STAGE(PG8_SB(0, 1), b2 + hstep, voffB);
;             PG8_WAIT_V(6); PG8_BAR; PG8_MMA(1, 1, At, B1); PG8_BAR;
;             PG8_LDB(B0, 1, 0); PG8_SCHED; PG8_LDA(At, 1, 0); PG8_STAGE(PG8_SA(0, 1), a2 + hstep, voffA);
;             PG8_WAIT_L(8); PG8_BAR; PG8_WAIT_L(0); PG8_MMA(0, 0, At, B0); PG8_BAR; PG8_SCHED;
;             PG8_LDB(B1, 1, 1); PG8_STAGE(PG8_SB(1, 0), b3, voffB);
;             PG8_BAR; PG8_WAIT_L(0); PG8_MMA(0, 1, At, B1); PG8_BAR;
;             PG8_LDA(At, 1, 1); PG8_STAGE(PG8_SA(1, 0), a3, voffA);
	s_add_i32 s4, s67, s50
	s_mov_b32 s32, s4
	s_mov_b32 m0, s4
	s_add_u32 s0, s44, 0x20000
	s_addc_u32 s1, s45, 0
	global_load_lds_dwordx4 v130, s[0:1]
	s_add_i32 m0, s4, 0x2000
	s_nop 0
	global_load_lds_dwordx4 v134, s[0:1]
	s_waitcnt vmcnt(6)
	s_barrier
	s_setprio 1
	v_mfma_f32_16x16x32_bf16 v[52:55], v[206:209], v[168:171], 0
	v_mfma_f32_16x16x32_bf16 v[48:51], v[214:217], v[168:171], 0
	v_mfma_f32_16x16x32_bf16 v[36:39], v[206:209], v[176:179], 0
	v_mfma_f32_16x16x32_bf16 v[32:35], v[214:217], v[176:179], 0
	v_mfma_f32_16x16x32_bf16 v[20:23], v[206:209], v[188:191], 0
	v_mfma_f32_16x16x32_bf16 v[16:19], v[214:217], v[188:191], 0
	v_mfma_f32_16x16x32_bf16 v[4:7], v[206:209], v[198:201], 0
	v_mfma_f32_16x16x32_bf16 v[0:3], v[214:217], v[198:201], 0
	v_mfma_f32_16x16x32_bf16 v[52:55], v[210:213], v[172:175], v[52:55]
	v_mfma_f32_16x16x32_bf16 v[48:51], v[218:221], v[172:175], v[48:51]
	v_mfma_f32_16x16x32_bf16 v[36:39], v[210:213], v[180:183], v[36:39]
	v_mfma_f32_16x16x32_bf16 v[32:35], v[218:221], v[180:183], v[32:35]
	v_mfma_f32_16x16x32_bf16 v[20:23], v[210:213], v[194:197], v[20:23]
	v_mfma_f32_16x16x32_bf16 v[16:19], v[218:221], v[194:197], v[16:19]
	v_mfma_f32_16x16x32_bf16 v[4:7], v[210:213], v[202:205], v[4:7]
	v_mfma_f32_16x16x32_bf16 v[0:3], v[218:221], v[202:205], v[0:3]
	s_setprio 0
	s_add_i32 s4, 0, 0x18000
	v_add_u32_e32 v222, s4, v157
	s_barrier
	ds_read_b128 v[146:149], v222
	ds_read_b128 v[150:153], v222 offset:1024
	ds_read_b128 v[160:163], v222 offset:2048
	ds_read_b128 v[164:167], v222 offset:3072
	s_add_u32 s0, s46, 0x20000
	s_addc_u32 s1, s47, 0
	s_mov_b32 m0, s57
	ds_read_b128 v[168:171], v158 offset:32768
	ds_read_b128 v[172:175], v158 offset:33792
	ds_read_b128 v[176:179], v158 offset:34816
	ds_read_b128 v[180:183], v158 offset:35840
	ds_read_b128 v[188:191], v158 offset:36864
	ds_read_b128 v[194:197], v158 offset:37888
	ds_read_b128 v[198:201], v158 offset:38912
	global_load_lds_dwordx4 v128, s[0:1]
	s_mov_b32 m0, s58
	ds_read_b128 v[202:205], v158 offset:39936
	global_load_lds_dwordx4 v132, s[0:1]
	s_waitcnt lgkmcnt(8)
	s_barrier
	s_waitcnt lgkmcnt(0)
	s_setprio 1
	v_mfma_f32_16x16x32_bf16 v[124:127], v[146:149], v[168:171], v[124:127]
	v_mfma_f32_16x16x32_bf16 v[120:123], v[160:163], v[168:171], v[120:123]
	v_mfma_f32_16x16x32_bf16 v[108:111], v[146:149], v[176:179], v[108:111]
	v_mfma_f32_16x16x32_bf16 v[104:107], v[160:163], v[176:179], v[104:107]
	v_mfma_f32_16x16x32_bf16 v[92:95], v[146:149], v[188:191], v[92:95]
	v_mfma_f32_16x16x32_bf16 v[88:91], v[160:163], v[188:191], v[88:91]
	v_mfma_f32_16x16x32_bf16 v[76:79], v[146:149], v[198:201], v[76:79]
	v_mfma_f32_16x16x32_bf16 v[72:75], v[160:163], v[198:201], v[72:75]
	v_mfma_f32_16x16x32_bf16 v[124:127], v[150:153], v[172:175], v[124:127]
	v_mfma_f32_16x16x32_bf16 v[120:123], v[164:167], v[172:175], v[120:123]
	v_mfma_f32_16x16x32_bf16 v[108:111], v[150:153], v[180:183], v[108:111]
	v_mfma_f32_16x16x32_bf16 v[104:107], v[164:167], v[180:183], v[104:107]
	v_mfma_f32_16x16x32_bf16 v[92:95], v[150:153], v[194:197], v[92:95]
	v_mfma_f32_16x16x32_bf16 v[88:91], v[164:167], v[194:197], v[88:91]
	v_mfma_f32_16x16x32_bf16 v[76:79], v[150:153], v[202:205], v[76:79]
	v_mfma_f32_16x16x32_bf16 v[72:75], v[164:167], v[202:205], v[72:75]
	s_setprio 0
	s_barrier
	s_add_i32 s5, 0, 0x1c000
	s_add_i32 s0, s4, s50
	s_mov_b32 s80, s0
	v_add_u32_e32 v223, s5, v157
	s_add_i32 m0, s0, 0xffffff80
	ds_read_b128 v[206:209], v223
	ds_read_b128 v[210:213], v223 offset:1024
	ds_read_b128 v[214:217], v223 offset:2048
	global_load_lds_dwordx4 v130, s[44:45] offset:128
	s_add_i32 m0, s0, 0x1f80
	ds_read_b128 v[218:221], v223 offset:3072
	global_load_lds_dwordx4 v134, s[44:45] offset:128
	s_barrier
	s_waitcnt lgkmcnt(0)
	s_setprio 1
	v_mfma_f32_16x16x32_bf16 v[116:119], v[206:209], v[168:171], v[116:119]
	v_mfma_f32_16x16x32_bf16 v[112:115], v[214:217], v[168:171], v[112:115]
	v_mfma_f32_16x16x32_bf16 v[100:103], v[206:209], v[176:179], v[100:103]
	v_mfma_f32_16x16x32_bf16 v[96:99], v[214:217], v[176:179], v[96:99]
	v_mfma_f32_16x16x32_bf16 v[84:87], v[206:209], v[188:191], v[84:87]
	v_mfma_f32_16x16x32_bf16 v[80:83], v[214:217], v[188:191], v[80:83]
	v_mfma_f32_16x16x32_bf16 v[68:71], v[206:209], v[198:201], v[68:71]
	v_mfma_f32_16x16x32_bf16 v[64:67], v[214:217], v[198:201], v[64:67]
	v_mfma_f32_16x16x32_bf16 v[116:119], v[210:213], v[172:175], v[116:119]
	v_mfma_f32_16x16x32_bf16 v[112:115], v[218:221], v[172:175], v[112:115]
	v_mfma_f32_16x16x32_bf16 v[100:103], v[210:213], v[180:183], v[100:103]
	v_mfma_f32_16x16x32_bf16 v[96:99], v[218:221], v[180:183], v[96:99]
	v_mfma_f32_16x16x32_bf16 v[84:87], v[210:213], v[194:197], v[84:87]
	v_mfma_f32_16x16x32_bf16 v[80:83], v[218:221], v[194:197], v[80:83]
	v_mfma_f32_16x16x32_bf16 v[68:71], v[210:213], v[202:205], v[68:71]
	v_mfma_f32_16x16x32_bf16 v[64:67], v[218:221], v[202:205], v[64:67]
	s_setprio 0
	s_add_i32 m0, s62, 0xffffff80
	s_barrier
	ds_read_b128 v[168:171], v158 offset:49152
	ds_read_b128 v[172:175], v158 offset:50176
	ds_read_b128 v[176:179], v158 offset:51200
	ds_read_b128 v[180:183], v158 offset:52224
	ds_read_b128 v[188:191], v158 offset:53248
	ds_read_b128 v[194:197], v158 offset:54272
	ds_read_b128 v[198:201], v158 offset:55296
	global_load_lds_dwordx4 v128, s[46:47] offset:128
	s_add_i32 m0, s63, 0xffffff80
	ds_read_b128 v[202:205], v158 offset:56320
	global_load_lds_dwordx4 v132, s[46:47] offset:128
	s_barrier
; #define PG8_STAGE(bufoff, gbase, voff) do { _Pragma("unroll") for (int _i = 0; _i < 2; ++_i) \
;         __builtin_amdgcn_global_load_lds((const unsigned*)((const char*)(gbase) + (voff)[_i]), (LAS unsigned*)(lds + (bufoff) + ldsw + _i * 8192), 16, 0, 0); } while (0)
; #define PG8_LDA(dst, b, h) do { _Pragma("unroll") for (int m = 0; m < 4; ++m) _Pragma("unroll") for (int k = 0; k < 2; ++k) dst[m][k] = *(const LAS bf16x8*)(lds + PG8_SA(b, h) + aoff + m * 2048 + k * 1024); } while (0)
; #define PG8_LDB(dst, b, h) do { _Pragma("unroll") for (int n = 0; n < 2; ++n) _Pragma("unroll") for (int k = 0; k < 2; ++k) dst[n][k] = *(const LAS bf16x8*)(lds + PG8_SB(b, h) + boff + n * 2048 + k * 1024); } while (0)
; #define PG8_MMA(ai, bj, At, Bt) do { __builtin_amdgcn_s_setprio(1); _Pragma("unroll") for (int m = 0; m < 4; ++m) _Pragma("unroll") for (int n = 0; n < 2; ++n) _Pragma("unroll") for (int k = 0; k < 2; ++k) \
;         acc[ai][bj][m][n] = __builtin_amdgcn_mfma_f32_16x16x32_bf16(Bt[n][k], At[m][k], acc[ai][bj][m][n], 0, 0, 0); __builtin_amdgcn_s_setprio(0); } while (0)
; #define PG8_WAIT_V(n) asm volatile("s_waitcnt vmcnt(" #n ")" ::: "memory")
; #define PG8_WAIT_L(n) asm volatile("s_waitcnt lgkmcnt(" #n ")" ::: "memory")
; #define PG8_BAR __builtin_amdgcn_s_barrier()
; #define PG8_SCHED __builtin_amdgcn_sched_barrier(0)
; template <class Epi, class Sched>
; DI void gemm_phase(LAS unsigned char* lds, const Gemm g, const Sched& S, const Epi& E) {
;     ...
;             PG8_LDB(B0, 0, 0); PG8_SCHED; PG8_LDA(At, 0, 0); PG8_STAGE(PG8_SA(1, 1), a1 + hstep, voffA);
;             PG8_WAIT_L(8); PG8_BAR; PG8_WAIT_L(0); PG8_MMA(0, 0, At, B0); PG8_BAR; PG8_SCHED;
;             PG8_LDB(B1, 0, 1); PG8_STAGE(PG8_SB(0, 0), b2, voffB);
;             PG8_BAR; PG8_WAIT_L(0); PG8_MMA(0, 1, At, B1); PG8_BAR;
;     ...
;             PG8_BAR; PG8_WAIT_L(0); PG8_MMA(1, 0, At, B0); PG8_BAR; PG8_SCHED;
;             PG8_STAGE(PG8_SB(1, 1), b3 + hstep, voffB);
;             PG8_WAIT_V(6); PG8_BAR; PG8_MMA(1, 1, At, B1); PG8_BAR;
;         }
	s_waitcnt lgkmcnt(0)
	s_setprio 1
	v_mfma_f32_16x16x32_bf16 v[60:63], v[146:149], v[168:171], v[60:63]
	v_mfma_f32_16x16x32_bf16 v[56:59], v[160:163], v[168:171], v[56:59]
	v_mfma_f32_16x16x32_bf16 v[44:47], v[146:149], v[176:179], v[44:47]
	v_mfma_f32_16x16x32_bf16 v[40:43], v[160:163], v[176:179], v[40:43]
	v_mfma_f32_16x16x32_bf16 v[28:31], v[146:149], v[188:191], v[28:31]
	v_mfma_f32_16x16x32_bf16 v[24:27], v[160:163], v[188:191], v[24:27]
	v_mfma_f32_16x16x32_bf16 v[12:15], v[146:149], v[198:201], v[12:15]
	v_mfma_f32_16x16x32_bf16 v[8:11], v[160:163], v[198:201], v[8:11]
	v_mfma_f32_16x16x32_bf16 v[60:63], v[150:153], v[172:175], v[60:63]
	v_mfma_f32_16x16x32_bf16 v[56:59], v[164:167], v[172:175], v[56:59]
	v_mfma_f32_16x16x32_bf16 v[44:47], v[150:153], v[180:183], v[44:47]
	v_mfma_f32_16x16x32_bf16 v[40:43], v[164:167], v[180:183], v[40:43]
	v_mfma_f32_16x16x32_bf16 v[28:31], v[150:153], v[194:197], v[28:31]
	v_mfma_f32_16x16x32_bf16 v[24:27], v[164:167], v[194:197], v[24:27]
	v_mfma_f32_16x16x32_bf16 v[12:15], v[150:153], v[202:205], v[12:15]
	v_mfma_f32_16x16x32_bf16 v[8:11], v[164:167], v[202:205], v[8:11]
	s_setprio 0
	s_barrier
	s_add_i32 s4, s5, s50
	s_mov_b32 s81, s4
	s_mov_b32 m0, s4
	s_add_u32 s0, s44, 0x20080
	s_addc_u32 s1, s45, 0
	global_load_lds_dwordx4 v130, s[0:1]
	v_lshl_add_u64 v[146:147], s[0:1], 0, v[134:135]
	s_add_i32 m0, s4, 0x2000
	s_nop 0
	global_load_lds_dwordx4 v134, s[0:1]
	s_waitcnt vmcnt(6)
	s_barrier
	s_setprio 1
	v_mfma_f32_16x16x32_bf16 v[52:55], v[206:209], v[168:171], v[52:55]
	v_mfma_f32_16x16x32_bf16 v[48:51], v[214:217], v[168:171], v[48:51]
	v_mfma_f32_16x16x32_bf16 v[36:39], v[206:209], v[176:179], v[36:39]
	v_mfma_f32_16x16x32_bf16 v[32:35], v[214:217], v[176:179], v[32:35]
	v_mfma_f32_16x16x32_bf16 v[20:23], v[206:209], v[188:191], v[20:23]
	v_mfma_f32_16x16x32_bf16 v[16:19], v[214:217], v[188:191], v[16:19]
	v_mfma_f32_16x16x32_bf16 v[4:7], v[206:209], v[198:201], v[4:7]
	v_mfma_f32_16x16x32_bf16 v[0:3], v[214:217], v[198:201], v[0:3]
	v_mfma_f32_16x16x32_bf16 v[52:55], v[210:213], v[172:175], v[52:55]
	v_mfma_f32_16x16x32_bf16 v[48:51], v[218:221], v[172:175], v[48:51]
	v_mfma_f32_16x16x32_bf16 v[36:39], v[210:213], v[180:183], v[36:39]
	v_mfma_f32_16x16x32_bf16 v[32:35], v[218:221], v[180:183], v[32:35]
	v_mfma_f32_16x16x32_bf16 v[20:23], v[210:213], v[194:197], v[20:23]
	v_mfma_f32_16x16x32_bf16 v[16:19], v[218:221], v[194:197], v[16:19]
	v_mfma_f32_16x16x32_bf16 v[4:7], v[210:213], v[202:205], v[4:7]
	v_mfma_f32_16x16x32_bf16 v[0:3], v[218:221], v[202:205], v[0:3]
	s_setprio 0
	s_add_i32 s79, s79, 2
	s_add_u32 s42, s42, 0x100
	s_addc_u32 s43, s43, 0
	s_add_u32 s35, s35, 0x100
	s_addc_u32 s41, s41, 0
	s_cmp_gt_u32 s79, 5
	s_barrier
	s_cbranch_scc0 .LBB0_984
	s_branch .Lpeel_done_984
.LBB0_984:
	ds_read_b128 v[146:149], v156
	ds_read_b128 v[150:153], v156 offset:1024
	ds_read_b128 v[160:163], v156 offset:2048
	ds_read_b128 v[164:167], v156 offset:3072
	s_add_u32 s0, s42, 0xfffe0080
	s_addc_u32 s1, s43, -1
	s_cmp_eq_u32 s79, 4
	s_cselect_b32 s47, s9, s1
	s_cselect_b32 s46, s31, s0
	s_cselect_b32 s45, s29, s41
	s_cselect_b32 s44, s34, s35
	s_add_i32 m0, s55, 0xc000
	ds_read_b128 v[168:171], v158
	ds_read_b128 v[172:175], v158 offset:1024
	ds_read_b128 v[176:179], v158 offset:2048
	ds_read_b128 v[180:183], v158 offset:3072
	ds_read_b128 v[188:191], v158 offset:4096
	ds_read_b128 v[194:197], v158 offset:5120
	ds_read_b128 v[198:201], v158 offset:6144
	global_load_lds_dwordx4 v138, s[42:43]
	s_add_i32 m0, s55, 0xe000
	ds_read_b128 v[202:205], v158 offset:7168
	global_load_lds_dwordx4 v140, s[42:43]
	s_waitcnt lgkmcnt(8)
	s_barrier
	s_waitcnt lgkmcnt(0)
	s_setprio 1
	v_mfma_f32_16x16x32_bf16 v[124:127], v[146:149], v[168:171], v[124:127]
	v_mfma_f32_16x16x32_bf16 v[120:123], v[160:163], v[168:171], v[120:123]
	v_mfma_f32_16x16x32_bf16 v[108:111], v[146:149], v[176:179], v[108:111]
	v_mfma_f32_16x16x32_bf16 v[104:107], v[160:163], v[176:179], v[104:107]
	v_mfma_f32_16x16x32_bf16 v[92:95], v[146:149], v[188:191], v[92:95]
	v_mfma_f32_16x16x32_bf16 v[88:91], v[160:163], v[188:191], v[88:91]
	v_mfma_f32_16x16x32_bf16 v[76:79], v[146:149], v[198:201], v[76:79]
	v_mfma_f32_16x16x32_bf16 v[72:75], v[160:163], v[198:201], v[72:75]
	v_mfma_f32_16x16x32_bf16 v[124:127], v[150:153], v[172:175], v[124:127]
	v_mfma_f32_16x16x32_bf16 v[120:123], v[164:167], v[172:175], v[120:123]
	v_mfma_f32_16x16x32_bf16 v[108:111], v[150:153], v[180:183], v[108:111]
	v_mfma_f32_16x16x32_bf16 v[104:107], v[164:167], v[180:183], v[104:107]
	v_mfma_f32_16x16x32_bf16 v[92:95], v[150:153], v[194:197], v[92:95]
	v_mfma_f32_16x16x32_bf16 v[88:91], v[164:167], v[194:197], v[88:91]
	v_mfma_f32_16x16x32_bf16 v[76:79], v[150:153], v[202:205], v[76:79]
	v_mfma_f32_16x16x32_bf16 v[72:75], v[164:167], v[202:205], v[72:75]
	s_setprio 0
	s_barrier
	s_mov_b32 m0, s19
	ds_read_b128 v[206:209], v159
	ds_read_b128 v[210:213], v159 offset:1024
	ds_read_b128 v[214:217], v159 offset:2048
	global_load_lds_dwordx4 v130, s[44:45]
	s_add_i32 m0, s19, 0x2000
	ds_read_b128 v[218:221], v159 offset:3072
	global_load_lds_dwordx4 v134, s[44:45]
	s_barrier
; #define PG8_STAGE(bufoff, gbase, voff) do { _Pragma("unroll") for (int _i = 0; _i < 2; ++_i) \
;         __builtin_amdgcn_global_load_lds((const unsigned*)((const char*)(gbase) + (voff)[_i]), (LAS unsigned*)(lds + (bufoff) + ldsw + _i * 8192), 16, 0, 0); } while (0)
; #define PG8_LDA(dst, b, h) do { _Pragma("unroll") for (int m = 0; m < 4; ++m) _Pragma("unroll") for (int k = 0; k < 2; ++k) dst[m][k] = *(const LAS bf16x8*)(lds + PG8_SA(b, h) + aoff + m * 2048 + k * 1024); } while (0)
; #define PG8_LDB(dst, b, h) do { _Pragma("unroll") for (int n = 0; n < 2; ++n) _Pragma("unroll") for (int k = 0; k < 2; ++k) dst[n][k] = *(const LAS bf16x8*)(lds + PG8_SB(b, h) + boff + n * 2048 + k * 1024); } while (0)
; #define PG8_MMA(ai, bj, At, Bt) do { __builtin_amdgcn_s_setprio(1); _Pragma("unroll") for (int m = 0; m < 4; ++m) _Pragma("unroll") for (int n = 0; n < 2; ++n) _Pragma("unroll") for (int k = 0; k < 2; ++k) \
;         acc[ai][bj][m][n] = __builtin_amdgcn_mfma_f32_16x16x32_bf16(Bt[n][k], At[m][k], acc[ai][bj][m][n], 0, 0, 0); __builtin_amdgcn_s_setprio(0); } while (0)
; #define PG8_WAIT_V(n) asm volatile("s_waitcnt vmcnt(" #n ")" ::: "memory")
; #define PG8_WAIT_L(n) asm volatile("s_waitcnt lgkmcnt(" #n ")" ::: "memory")
; #define PG8_BAR __builtin_amdgcn_s_barrier()
; #define PG8_SCHED __builtin_amdgcn_sched_barrier(0)
; template <class Epi, class Sched>
; DI void gemm_phase(LAS unsigned char* lds, const Gemm g, const Sched& S, const Epi& E) {
;     ...
;             PG8_BAR; PG8_WAIT_L(0); PG8_MMA(0, 1, At, B1); PG8_BAR;
;             PG8_LDA(At, 0, 1); PG8_STAGE(PG8_SA(0, 0), a2, voffA);
;             PG8_BAR; PG8_WAIT_L(0); PG8_MMA(1, 0, At, B0); PG8_BAR; PG8_SCHED;
;             PG8_STAGE(PG8_SB(0, 1), b2 + hstep, voffB);
;             PG8_WAIT_V(6); PG8_BAR; PG8_MMA(1, 1, At, B1); PG8_BAR;
;             PG8_LDB(B0, 1, 0); PG8_SCHED; PG8_LDA(At, 1, 0); PG8_STAGE(PG8_SA(0, 1), a2 + hstep, voffA);
;             PG8_WAIT_L(8); PG8_BAR; PG8_WAIT_L(0); PG8_MMA(0, 0, At, B0); PG8_BAR; PG8_SCHED;
	s_waitcnt lgkmcnt(0)
	s_setprio 1
	v_mfma_f32_16x16x32_bf16 v[116:119], v[206:209], v[168:171], v[116:119]
	v_mfma_f32_16x16x32_bf16 v[112:115], v[214:217], v[168:171], v[112:115]
	v_mfma_f32_16x16x32_bf16 v[100:103], v[206:209], v[176:179], v[100:103]
	v_mfma_f32_16x16x32_bf16 v[96:99], v[214:217], v[176:179], v[96:99]
	v_mfma_f32_16x16x32_bf16 v[84:87], v[206:209], v[188:191], v[84:87]
	v_mfma_f32_16x16x32_bf16 v[80:83], v[214:217], v[188:191], v[80:83]
	v_mfma_f32_16x16x32_bf16 v[68:71], v[206:209], v[198:201], v[68:71]
	v_mfma_f32_16x16x32_bf16 v[64:67], v[214:217], v[198:201], v[64:67]
	v_mfma_f32_16x16x32_bf16 v[116:119], v[210:213], v[172:175], v[116:119]
	v_mfma_f32_16x16x32_bf16 v[112:115], v[218:221], v[172:175], v[112:115]
	v_mfma_f32_16x16x32_bf16 v[100:103], v[210:213], v[180:183], v[100:103]
	v_mfma_f32_16x16x32_bf16 v[96:99], v[218:221], v[180:183], v[96:99]
	v_mfma_f32_16x16x32_bf16 v[84:87], v[210:213], v[194:197], v[84:87]
	v_mfma_f32_16x16x32_bf16 v[80:83], v[218:221], v[194:197], v[80:83]
	v_mfma_f32_16x16x32_bf16 v[68:71], v[210:213], v[202:205], v[68:71]
	v_mfma_f32_16x16x32_bf16 v[64:67], v[218:221], v[202:205], v[64:67]
	s_setprio 0
	s_mov_b32 m0, s55
	s_barrier
	ds_read_b128 v[168:171], v158 offset:16384
	ds_read_b128 v[172:175], v158 offset:17408
	ds_read_b128 v[176:179], v158 offset:18432
	ds_read_b128 v[180:183], v158 offset:19456
	ds_read_b128 v[188:191], v158 offset:20480
	ds_read_b128 v[194:197], v158 offset:21504
	ds_read_b128 v[198:201], v158 offset:22528
	global_load_lds_dwordx4 v128, s[46:47]
	s_mov_b32 m0, s56
	ds_read_b128 v[202:205], v158 offset:23552
	global_load_lds_dwordx4 v132, s[46:47]
	s_barrier
	s_waitcnt lgkmcnt(0)
	s_setprio 1
	v_mfma_f32_16x16x32_bf16 v[60:63], v[146:149], v[168:171], v[60:63]
	v_mfma_f32_16x16x32_bf16 v[56:59], v[160:163], v[168:171], v[56:59]
	v_mfma_f32_16x16x32_bf16 v[44:47], v[146:149], v[176:179], v[44:47]
	v_mfma_f32_16x16x32_bf16 v[40:43], v[160:163], v[176:179], v[40:43]
	v_mfma_f32_16x16x32_bf16 v[28:31], v[146:149], v[188:191], v[28:31]
	v_mfma_f32_16x16x32_bf16 v[24:27], v[160:163], v[188:191], v[24:27]
	v_mfma_f32_16x16x32_bf16 v[12:15], v[146:149], v[198:201], v[12:15]
	v_mfma_f32_16x16x32_bf16 v[8:11], v[160:163], v[198:201], v[8:11]
	v_mfma_f32_16x16x32_bf16 v[60:63], v[150:153], v[172:175], v[60:63]
	v_mfma_f32_16x16x32_bf16 v[56:59], v[164:167], v[172:175], v[56:59]
	v_mfma_f32_16x16x32_bf16 v[44:47], v[150:153], v[180:183], v[44:47]
	v_mfma_f32_16x16x32_bf16 v[40:43], v[164:167], v[180:183], v[40:43]
	v_mfma_f32_16x16x32_bf16 v[28:31], v[150:153], v[194:197], v[28:31]
	v_mfma_f32_16x16x32_bf16 v[24:27], v[164:167], v[194:197], v[24:27]
	v_mfma_f32_16x16x32_bf16 v[12:15], v[150:153], v[202:205], v[12:15]
	v_mfma_f32_16x16x32_bf16 v[8:11], v[164:167], v[202:205], v[8:11]
	s_setprio 0
	s_barrier
	s_mov_b32 m0, s32
	s_add_u32 s0, s44, 0x20000
	s_addc_u32 s1, s45, 0
	global_load_lds_dwordx4 v130, s[0:1]
	s_add_i32 m0, s32, 0x2000
	s_nop 0
	global_load_lds_dwordx4 v134, s[0:1]
	s_waitcnt vmcnt(6)
	s_barrier
	s_setprio 1
	v_mfma_f32_16x16x32_bf16 v[52:55], v[206:209], v[168:171], v[52:55]
	v_mfma_f32_16x16x32_bf16 v[48:51], v[214:217], v[168:171], v[48:51]
	v_mfma_f32_16x16x32_bf16 v[36:39], v[206:209], v[176:179], v[36:39]
	v_mfma_f32_16x16x32_bf16 v[32:35], v[214:217], v[176:179], v[32:35]
	v_mfma_f32_16x16x32_bf16 v[20:23], v[206:209], v[188:191], v[20:23]
	v_mfma_f32_16x16x32_bf16 v[16:19], v[214:217], v[188:191], v[16:19]
	v_mfma_f32_16x16x32_bf16 v[4:7], v[206:209], v[198:201], v[4:7]
	v_mfma_f32_16x16x32_bf16 v[0:3], v[214:217], v[198:201], v[0:3]
	v_mfma_f32_16x16x32_bf16 v[52:55], v[210:213], v[172:175], v[52:55]
	v_mfma_f32_16x16x32_bf16 v[48:51], v[218:221], v[172:175], v[48:51]
	v_mfma_f32_16x16x32_bf16 v[36:39], v[210:213], v[180:183], v[36:39]
	v_mfma_f32_16x16x32_bf16 v[32:35], v[218:221], v[180:183], v[32:35]
	v_mfma_f32_16x16x32_bf16 v[20:23], v[210:213], v[194:197], v[20:23]
	v_mfma_f32_16x16x32_bf16 v[16:19], v[218:221], v[194:197], v[16:19]
	v_mfma_f32_16x16x32_bf16 v[4:7], v[210:213], v[202:205], v[4:7]
	v_mfma_f32_16x16x32_bf16 v[0:3], v[218:221], v[202:205], v[0:3]
	s_setprio 0
	s_add_i32 s4, 0, 0x18000
	s_barrier
	ds_read_b128 v[146:149], v222
	ds_read_b128 v[150:153], v222 offset:1024
	ds_read_b128 v[160:163], v222 offset:2048
	ds_read_b128 v[164:167], v222 offset:3072
	s_add_u32 s0, s46, 0x20000
	s_addc_u32 s1, s47, 0
	s_mov_b32 m0, s57
	ds_read_b128 v[168:171], v158 offset:32768
	ds_read_b128 v[172:175], v158 offset:33792
	ds_read_b128 v[176:179], v158 offset:34816
	ds_read_b128 v[180:183], v158 offset:35840
	ds_read_b128 v[188:191], v158 offset:36864
	ds_read_b128 v[194:197], v158 offset:37888
	ds_read_b128 v[198:201], v158 offset:38912
	global_load_lds_dwordx4 v128, s[0:1]
	s_mov_b32 m0, s58
	ds_read_b128 v[202:205], v158 offset:39936
	global_load_lds_dwordx4 v132, s[0:1]
	s_waitcnt lgkmcnt(8)
	s_barrier
; #define PG8_STAGE(bufoff, gbase, voff) do { _Pragma("unroll") for (int _i = 0; _i < 2; ++_i) \
;         __builtin_amdgcn_global_load_lds((const unsigned*)((const char*)(gbase) + (voff)[_i]), (LAS unsigned*)(lds + (bufoff) + ldsw + _i * 8192), 16, 0, 0); } while (0)
; #define PG8_LDA(dst, b, h) do { _Pragma("unroll") for (int m = 0; m < 4; ++m) _Pragma("unroll") for (int k = 0; k < 2; ++k) dst[m][k] = *(const LAS bf16x8*)(lds + PG8_SA(b, h) + aoff + m * 2048 + k * 1024); } while (0)
; #define PG8_LDB(dst, b, h) do { _Pragma("unroll") for (int n = 0; n < 2; ++n) _Pragma("unroll") for (int k = 0; k < 2; ++k) dst[n][k] = *(const LAS bf16x8*)(lds + PG8_SB(b, h) + boff + n * 2048 + k * 1024); } while (0)
; #define PG8_MMA(ai, bj, At, Bt) do { __builtin_amdgcn_s_setprio(1); _Pragma("unroll") for (int m = 0; m < 4; ++m) _Pragma("unroll") for (int n = 0; n < 2; ++n) _Pragma("unroll") for (int k = 0; k < 2; ++k) \
;         acc[ai][bj][m][n] = __builtin_amdgcn_mfma_f32_16x16x32_bf16(Bt[n][k], At[m][k], acc[ai][bj][m][n], 0, 0, 0); __builtin_amdgcn_s_setprio(0); } while (0)
; #define PG8_WAIT_V(n) asm volatile("s_waitcnt vmcnt(" #n ")" ::: "memory")
; #define PG8_WAIT_L(n) asm volatile("s_waitcnt lgkmcnt(" #n ")" ::: "memory")
; #define PG8_BAR __builtin_amdgcn_s_barrier()
; #define PG8_SCHED __builtin_amdgcn_sched_barrier(0)
; template <class Epi, class Sched>
; DI void gemm_phase(LAS unsigned char* lds, const Gemm g, const Sched& S, const Epi& E) {
;     ...
;             PG8_WAIT_L(8); PG8_BAR; PG8_WAIT_L(0); PG8_MMA(0, 0, At, B0); PG8_BAR; PG8_SCHED;
;             PG8_LDB(B1, 1, 1); PG8_STAGE(PG8_SB(1, 0), b3, voffB);
;             PG8_BAR; PG8_WAIT_L(0); PG8_MMA(0, 1, At, B1); PG8_BAR;
;             PG8_LDA(At, 1, 1); PG8_STAGE(PG8_SA(1, 0), a3, voffA);
;             PG8_BAR; PG8_WAIT_L(0); PG8_MMA(1, 0, At, B0); PG8_BAR; PG8_SCHED;
;             PG8_STAGE(PG8_SB(1, 1), b3 + hstep, voffB);
;             PG8_WAIT_V(6); PG8_BAR; PG8_MMA(1, 1, At, B1); PG8_BAR;
;         }
	s_waitcnt lgkmcnt(0)
	s_setprio 1
	v_mfma_f32_16x16x32_bf16 v[124:127], v[146:149], v[168:171], v[124:127]
	v_mfma_f32_16x16x32_bf16 v[120:123], v[160:163], v[168:171], v[120:123]
	v_mfma_f32_16x16x32_bf16 v[108:111], v[146:149], v[176:179], v[108:111]
	v_mfma_f32_16x16x32_bf16 v[104:107], v[160:163], v[176:179], v[104:107]
	v_mfma_f32_16x16x32_bf16 v[92:95], v[146:149], v[188:191], v[92:95]
	v_mfma_f32_16x16x32_bf16 v[88:91], v[160:163], v[188:191], v[88:91]
	v_mfma_f32_16x16x32_bf16 v[76:79], v[146:149], v[198:201], v[76:79]
	v_mfma_f32_16x16x32_bf16 v[72:75], v[160:163], v[198:201], v[72:75]
	v_mfma_f32_16x16x32_bf16 v[124:127], v[150:153], v[172:175], v[124:127]
	v_mfma_f32_16x16x32_bf16 v[120:123], v[164:167], v[172:175], v[120:123]
	v_mfma_f32_16x16x32_bf16 v[108:111], v[150:153], v[180:183], v[108:111]
	v_mfma_f32_16x16x32_bf16 v[104:107], v[164:167], v[180:183], v[104:107]
	v_mfma_f32_16x16x32_bf16 v[92:95], v[150:153], v[194:197], v[92:95]
	v_mfma_f32_16x16x32_bf16 v[88:91], v[164:167], v[194:197], v[88:91]
	v_mfma_f32_16x16x32_bf16 v[76:79], v[150:153], v[202:205], v[76:79]
	v_mfma_f32_16x16x32_bf16 v[72:75], v[164:167], v[202:205], v[72:75]
	s_setprio 0
	s_barrier
	s_add_i32 s5, 0, 0x1c000
	s_add_i32 m0, s80, 0xffffff80
	ds_read_b128 v[206:209], v223
	ds_read_b128 v[210:213], v223 offset:1024
	ds_read_b128 v[214:217], v223 offset:2048
	global_load_lds_dwordx4 v130, s[44:45] offset:128
	s_add_i32 m0, s80, 0x1f80
	ds_read_b128 v[218:221], v223 offset:3072
	global_load_lds_dwordx4 v134, s[44:45] offset:128
	s_barrier
	s_waitcnt lgkmcnt(0)
	s_setprio 1
	v_mfma_f32_16x16x32_bf16 v[116:119], v[206:209], v[168:171], v[116:119]
	v_mfma_f32_16x16x32_bf16 v[112:115], v[214:217], v[168:171], v[112:115]
	v_mfma_f32_16x16x32_bf16 v[100:103], v[206:209], v[176:179], v[100:103]
	v_mfma_f32_16x16x32_bf16 v[96:99], v[214:217], v[176:179], v[96:99]
	v_mfma_f32_16x16x32_bf16 v[84:87], v[206:209], v[188:191], v[84:87]
	v_mfma_f32_16x16x32_bf16 v[80:83], v[214:217], v[188:191], v[80:83]
	v_mfma_f32_16x16x32_bf16 v[68:71], v[206:209], v[198:201], v[68:71]
	v_mfma_f32_16x16x32_bf16 v[64:67], v[214:217], v[198:201], v[64:67]
	v_mfma_f32_16x16x32_bf16 v[116:119], v[210:213], v[172:175], v[116:119]
	v_mfma_f32_16x16x32_bf16 v[112:115], v[218:221], v[172:175], v[112:115]
	v_mfma_f32_16x16x32_bf16 v[100:103], v[210:213], v[180:183], v[100:103]
	v_mfma_f32_16x16x32_bf16 v[96:99], v[218:221], v[180:183], v[96:99]
	v_mfma_f32_16x16x32_bf16 v[84:87], v[210:213], v[194:197], v[84:87]
	v_mfma_f32_16x16x32_bf16 v[80:83], v[218:221], v[194:197], v[80:83]
	v_mfma_f32_16x16x32_bf16 v[68:71], v[210:213], v[202:205], v[68:71]
	v_mfma_f32_16x16x32_bf16 v[64:67], v[218:221], v[202:205], v[64:67]
	s_setprio 0
	s_add_i32 m0, s62, 0xffffff80
	s_barrier
	ds_read_b128 v[168:171], v158 offset:49152
	ds_read_b128 v[172:175], v158 offset:50176
	ds_read_b128 v[176:179], v158 offset:51200
	ds_read_b128 v[180:183], v158 offset:52224
	ds_read_b128 v[188:191], v158 offset:53248
	ds_read_b128 v[194:197], v158 offset:54272
	ds_read_b128 v[198:201], v158 offset:55296
	global_load_lds_dwordx4 v128, s[46:47] offset:128
	s_add_i32 m0, s63, 0xffffff80
	ds_read_b128 v[202:205], v158 offset:56320
	global_load_lds_dwordx4 v132, s[46:47] offset:128
	s_barrier
	s_waitcnt lgkmcnt(0)
	s_setprio 1
	v_mfma_f32_16x16x32_bf16 v[60:63], v[146:149], v[168:171], v[60:63]
	v_mfma_f32_16x16x32_bf16 v[56:59], v[160:163], v[168:171], v[56:59]
	v_mfma_f32_16x16x32_bf16 v[44:47], v[146:149], v[176:179], v[44:47]
	v_mfma_f32_16x16x32_bf16 v[40:43], v[160:163], v[176:179], v[40:43]
	v_mfma_f32_16x16x32_bf16 v[28:31], v[146:149], v[188:191], v[28:31]
	v_mfma_f32_16x16x32_bf16 v[24:27], v[160:163], v[188:191], v[24:27]
	v_mfma_f32_16x16x32_bf16 v[12:15], v[146:149], v[198:201], v[12:15]
	v_mfma_f32_16x16x32_bf16 v[8:11], v[160:163], v[198:201], v[8:11]
	v_mfma_f32_16x16x32_bf16 v[60:63], v[150:153], v[172:175], v[60:63]
	v_mfma_f32_16x16x32_bf16 v[56:59], v[164:167], v[172:175], v[56:59]
	v_mfma_f32_16x16x32_bf16 v[44:47], v[150:153], v[180:183], v[44:47]
	v_mfma_f32_16x16x32_bf16 v[40:43], v[164:167], v[180:183], v[40:43]
	v_mfma_f32_16x16x32_bf16 v[28:31], v[150:153], v[194:197], v[28:31]
	v_mfma_f32_16x16x32_bf16 v[24:27], v[164:167], v[194:197], v[24:27]
	v_mfma_f32_16x16x32_bf16 v[12:15], v[150:153], v[202:205], v[12:15]
	v_mfma_f32_16x16x32_bf16 v[8:11], v[164:167], v[202:205], v[8:11]
	s_setprio 0
	s_barrier
	s_mov_b32 m0, s81
	s_add_u32 s0, s44, 0x20080
	s_addc_u32 s1, s45, 0
	global_load_lds_dwordx4 v130, s[0:1]
	v_lshl_add_u64 v[146:147], s[0:1], 0, v[134:135]
	s_add_i32 m0, s81, 0x2000
	s_nop 0
	global_load_lds_dwordx4 v134, s[0:1]
	s_waitcnt vmcnt(6)
	s_barrier
	s_setprio 1
	v_mfma_f32_16x16x32_bf16 v[52:55], v[206:209], v[168:171], v[52:55]
	v_mfma_f32_16x16x32_bf16 v[48:51], v[214:217], v[168:171], v[48:51]
	v_mfma_f32_16x16x32_bf16 v[36:39], v[206:209], v[176:179], v[36:39]
	v_mfma_f32_16x16x32_bf16 v[32:35], v[214:217], v[176:179], v[32:35]
	v_mfma_f32_16x16x32_bf16 v[20:23], v[206:209], v[188:191], v[20:23]
	v_mfma_f32_16x16x32_bf16 v[16:19], v[214:217], v[188:191], v[16:19]
	v_mfma_f32_16x16x32_bf16 v[4:7], v[206:209], v[198:201], v[4:7]
	v_mfma_f32_16x16x32_bf16 v[0:3], v[214:217], v[198:201], v[0:3]
	v_mfma_f32_16x16x32_bf16 v[52:55], v[210:213], v[172:175], v[52:55]
	v_mfma_f32_16x16x32_bf16 v[48:51], v[218:221], v[172:175], v[48:51]
	v_mfma_f32_16x16x32_bf16 v[36:39], v[210:213], v[180:183], v[36:39]
	v_mfma_f32_16x16x32_bf16 v[32:35], v[218:221], v[180:183], v[32:35]
	v_mfma_f32_16x16x32_bf16 v[20:23], v[210:213], v[194:197], v[20:23]
	v_mfma_f32_16x16x32_bf16 v[16:19], v[218:221], v[194:197], v[16:19]
	v_mfma_f32_16x16x32_bf16 v[4:7], v[210:213], v[202:205], v[4:7]
	v_mfma_f32_16x16x32_bf16 v[0:3], v[218:221], v[202:205], v[0:3]
	s_setprio 0
	s_add_i32 s79, s79, 2
	s_add_u32 s42, s42, 0x100
	s_addc_u32 s43, s43, 0
	s_add_u32 s35, s35, 0x100
	s_addc_u32 s41, s41, 0
	s_cmp_gt_u32 s79, 5
	s_barrier
	s_cbranch_scc0 .LBB0_984

;     DI size_t aoff(const Unit& u, size_t tstep) const { return (size_t)u.pm * tstep; }
;     DI size_t boff(const Unit& u, size_t tstep) const { return (size_t)u.pn * tstep; }
;     DI bool next(int i, Unit& u) const { const long L = (long)i * G + c; if (L >= np) return false; u.pm = pmv; u.pn = (int)(L % nN); u.ks = (int)(L / nN); return true; }
;     DI size_t aoff(const Unit& u, size_t) const { return (size_t)u.ks * kbytes; }
;     DI size_t boff(const Unit& u, size_t tstep) const { return (size_t)u.pn * tstep + (size_t)u.ks * kbytes; }
;     DI bool next(int i, Unit& u) const { Unit t; if (!S.next(i / 3, t)) return false; u.pm = t.pm; u.pn = t.pn; u.ks = i % 3; return true; }
;     DI size_t aoff(const Unit& u, size_t tstep) const { return (u.ks < 2 ? offU : offOA) + (size_t)u.pm * tstep; }
; #define PG8_LDA(dst, b, h) do { _Pragma("unroll") for (int m = 0; m < 4; ++m) _Pragma("unroll") for (int k = 0; k < 2; ++k) dst[m][k] = *(const LAS bf16x8*)(lds + PG8_SA(b, h) + aoff + m * 2048 + k * 1024); } while (0)
; template <class Epi, class Sched>
; DI void gemm_phase(LAS unsigned char* lds, const Gemm g, const Sched& S, const Epi& E) {
;     ...
;         const bool has_next = S.next(ui + 1, nxt);
;         const char* nA = has_next ? (const char*)g.A + S.aoff(nxt, tstep) : cA; const char* nB = has_next ? (const char*)g.Bt + S.boff(nxt, tstep) : cB;
;         for (int t = 0; t < nt; t += 2) {
;             if constexpr (Epi::HAS_MID) { if (t == E.mid_t(nt)) { int fr3 = fr, fq3 = fq; asm volatile("" : "+v"(fr3), "+v"(fq3)); E.mid(acc, cur, wr, wc, fr3, fq3); } }
;             const bool last = (t == nt - 2);
;             const char* a1 = cA + (size_t)(t + 1) * kstep;
;             const char* a2 = last ? nA : cA + (size_t)(t + 2) * kstep; const char* b2 = last ? nB : cB + (size_t)(t + 2) * kstep;
;             const char* a3 = a2 + kstep; const char* b3 = b2 + kstep;
;             PG8_LDB(B0, 0, 0); PG8_SCHED; PG8_LDA(At, 0, 0); PG8_STAGE(PG8_SA(1, 1), a1 + hstep, voffA);
;             PG8_WAIT_L(8); PG8_BAR; PG8_WAIT_L(0); PG8_MMA(0, 0, At, B0); PG8_BAR; PG8_SCHED;
;             PG8_LDB(B1, 0, 1); PG8_STAGE(PG8_SB(0, 0), b2, voffB);
;             PG8_BAR; PG8_WAIT_L(0); PG8_MMA(0, 1, At, B1); PG8_BAR;
;             PG8_LDA(At, 0, 1); PG8_STAGE(PG8_SA(0, 0), a2, voffA);
;             PG8_BAR; PG8_WAIT_L(0); PG8_MMA(1, 0, At, B0); PG8_BAR; PG8_SCHED;
.LBB0_1507:
	s_ashr_i32 s37, s36, 31
	s_lshl_b64 s[0:1], s[36:37], 20
	v_cmp_lt_i64_e32 vcc, s[38:39], v[140:141]
	s_add_u32 s38, s13, s0
	s_addc_u32 s39, s50, s1
	s_and_b64 s[0:1], vcc, exec
	s_cselect_b32 s34, s39, s45
	s_cselect_b32 s35, s38, s44
	s_ashr_i32 s31, s30, 31
	s_lshl_b64 s[0:1], s[30:31], 20
	s_add_u32 s40, s55, s0
	s_addc_u32 s41, s56, s1
	s_and_b64 s[0:1], vcc, exec
	s_cselect_b32 s31, s41, s47
	s_cselect_b32 s37, s40, s46
	s_add_u32 s44, s44, 0x80080
	s_addc_u32 s45, s45, 0
	s_add_u32 s43, s46, 0x100
	v_mov_b32_e32 v0, 0
	s_addc_u32 s68, s47, 0
	s_mov_b32 s69, -2
	s_waitcnt lgkmcnt(0)
	ds_read_b128 v[144:147], v150
	ds_read_b128 v[154:157], v150 offset:1024
	ds_read_b128 v[158:161], v150 offset:2048
	ds_read_b128 v[162:165], v150 offset:3072
	s_add_u32 s0, s44, 0xfff80080
	s_addc_u32 s1, s45, -1
	s_cmp_eq_u32 s69, 28
	s_cselect_b32 s49, s34, s1
	s_cselect_b32 s48, s35, s0
	s_cselect_b32 s47, s31, s68
	s_cselect_b32 s46, s37, s43
	s_add_i32 m0, s52, 0xc000
	ds_read_b128 v[166:169], v151
	ds_read_b128 v[170:173], v151 offset:1024
	ds_read_b128 v[174:177], v151 offset:2048
	ds_read_b128 v[178:181], v151 offset:3072
	ds_read_b128 v[188:191], v151 offset:4096
	ds_read_b128 v[206:209], v151 offset:5120
	ds_read_b128 v[210:213], v151 offset:6144
	global_load_lds_dwordx4 v136, s[44:45]
	s_add_i32 m0, s52, 0xe000
	ds_read_b128 v[214:217], v151 offset:7168
	global_load_lds_dwordx4 v138, s[44:45]
	s_waitcnt lgkmcnt(8)
	s_barrier
	s_waitcnt lgkmcnt(0)
	s_setprio 1
	v_mfma_f32_16x16x32_bf16 v[124:127], v[144:147], v[166:169], 0
	v_mfma_f32_16x16x32_bf16 v[120:123], v[158:161], v[166:169], 0
	v_mfma_f32_16x16x32_bf16 v[108:111], v[144:147], v[174:177], 0
	v_mfma_f32_16x16x32_bf16 v[104:107], v[158:161], v[174:177], 0
	v_mfma_f32_16x16x32_bf16 v[92:95], v[144:147], v[188:191], 0
	v_mfma_f32_16x16x32_bf16 v[88:91], v[158:161], v[188:191], 0
	v_mfma_f32_16x16x32_bf16 v[76:79], v[144:147], v[210:213], 0
	v_mfma_f32_16x16x32_bf16 v[72:75], v[158:161], v[210:213], 0
	v_mfma_f32_16x16x32_bf16 v[124:127], v[154:157], v[170:173], v[124:127]
	v_mfma_f32_16x16x32_bf16 v[120:123], v[162:165], v[170:173], v[120:123]
	v_mfma_f32_16x16x32_bf16 v[108:111], v[154:157], v[178:181], v[108:111]
	v_mfma_f32_16x16x32_bf16 v[104:107], v[162:165], v[178:181], v[104:107]
	v_mfma_f32_16x16x32_bf16 v[92:95], v[154:157], v[206:209], v[92:95]
	v_mfma_f32_16x16x32_bf16 v[88:91], v[162:165], v[206:209], v[88:91]
	v_mfma_f32_16x16x32_bf16 v[76:79], v[154:157], v[214:217], v[76:79]
	v_mfma_f32_16x16x32_bf16 v[72:75], v[162:165], v[214:217], v[72:75]
	s_setprio 0
	s_barrier
	s_add_i32 s0, s65, s51
	s_mov_b32 s32, s0
	s_mov_b32 m0, s0
	ds_read_b128 v[218:221], v152
	ds_read_b128 v[222:225], v152 offset:1024
	ds_read_b128 v[226:229], v152 offset:2048
	global_load_lds_dwordx4 v132, s[46:47]
	s_add_i32 m0, s0, 0x2000
	ds_read_b128 v[230:233], v152 offset:3072
	global_load_lds_dwordx4 v134, s[46:47]
	s_barrier
	s_waitcnt lgkmcnt(0)
	s_setprio 1
	v_mfma_f32_16x16x32_bf16 v[116:119], v[218:221], v[166:169], 0
	v_mfma_f32_16x16x32_bf16 v[112:115], v[226:229], v[166:169], 0
	v_mfma_f32_16x16x32_bf16 v[100:103], v[218:221], v[174:177], 0
	v_mfma_f32_16x16x32_bf16 v[96:99], v[226:229], v[174:177], 0
	v_mfma_f32_16x16x32_bf16 v[84:87], v[218:221], v[188:191], 0
	v_mfma_f32_16x16x32_bf16 v[80:83], v[226:229], v[188:191], 0
	v_mfma_f32_16x16x32_bf16 v[68:71], v[218:221], v[210:213], 0
	v_mfma_f32_16x16x32_bf16 v[64:67], v[226:229], v[210:213], 0
	v_mfma_f32_16x16x32_bf16 v[116:119], v[222:225], v[170:173], v[116:119]
	v_mfma_f32_16x16x32_bf16 v[112:115], v[230:233], v[170:173], v[112:115]
	v_mfma_f32_16x16x32_bf16 v[100:103], v[222:225], v[178:181], v[100:103]
	v_mfma_f32_16x16x32_bf16 v[96:99], v[230:233], v[178:181], v[96:99]
	v_mfma_f32_16x16x32_bf16 v[84:87], v[222:225], v[206:209], v[84:87]
	v_mfma_f32_16x16x32_bf16 v[80:83], v[230:233], v[206:209], v[80:83]
	v_mfma_f32_16x16x32_bf16 v[68:71], v[222:225], v[214:217], v[68:71]
	v_mfma_f32_16x16x32_bf16 v[64:67], v[230:233], v[214:217], v[64:67]
	s_setprio 0
	s_mov_b32 m0, s52
	s_barrier
	ds_read_b128 v[166:169], v151 offset:16384
	ds_read_b128 v[170:173], v151 offset:17408
	ds_read_b128 v[174:177], v151 offset:18432
	ds_read_b128 v[178:181], v151 offset:19456
	ds_read_b128 v[188:191], v151 offset:20480
	ds_read_b128 v[206:209], v151 offset:21504
	ds_read_b128 v[210:213], v151 offset:22528
	global_load_lds_dwordx4 v128, s[48:49]
	s_mov_b32 m0, s53
	ds_read_b128 v[214:217], v151 offset:23552
	global_load_lds_dwordx4 v130, s[48:49]
	s_barrier
	s_waitcnt lgkmcnt(0)
	s_setprio 1
	v_mfma_f32_16x16x32_bf16 v[60:63], v[144:147], v[166:169], 0
	v_mfma_f32_16x16x32_bf16 v[56:59], v[158:161], v[166:169], 0
	v_mfma_f32_16x16x32_bf16 v[44:47], v[144:147], v[174:177], 0
	v_mfma_f32_16x16x32_bf16 v[40:43], v[158:161], v[174:177], 0
	v_mfma_f32_16x16x32_bf16 v[28:31], v[144:147], v[188:191], 0
	v_mfma_f32_16x16x32_bf16 v[24:27], v[158:161], v[188:191], 0
	v_mfma_f32_16x16x32_bf16 v[12:15], v[144:147], v[210:213], 0
	v_mfma_f32_16x16x32_bf16 v[8:11], v[158:161], v[210:213], 0
	v_mfma_f32_16x16x32_bf16 v[60:63], v[154:157], v[170:173], v[60:63]
	v_mfma_f32_16x16x32_bf16 v[56:59], v[162:165], v[170:173], v[56:59]
	v_mfma_f32_16x16x32_bf16 v[44:47], v[154:157], v[178:181], v[44:47]
	v_mfma_f32_16x16x32_bf16 v[40:43], v[162:165], v[178:181], v[40:43]
	v_mfma_f32_16x16x32_bf16 v[28:31], v[154:157], v[206:209], v[28:31]
	v_mfma_f32_16x16x32_bf16 v[24:27], v[162:165], v[206:209], v[24:27]
	v_mfma_f32_16x16x32_bf16 v[12:15], v[154:157], v[214:217], v[12:15]
	v_mfma_f32_16x16x32_bf16 v[8:11], v[162:165], v[214:217], v[8:11]
	s_setprio 0
	s_barrier
; #define PG8_STAGE(bufoff, gbase, voff) do { _Pragma("unroll") for (int _i = 0; _i < 2; ++_i) \
;         __builtin_amdgcn_global_load_lds((const unsigned*)((const char*)(gbase) + (voff)[_i]), (LAS unsigned*)(lds + (bufoff) + ldsw + _i * 8192), 16, 0, 0); } while (0)
; #define PG8_LDA(dst, b, h) do { _Pragma("unroll") for (int m = 0; m < 4; ++m) _Pragma("unroll") for (int k = 0; k < 2; ++k) dst[m][k] = *(const LAS bf16x8*)(lds + PG8_SA(b, h) + aoff + m * 2048 + k * 1024); } while (0)
; #define PG8_LDB(dst, b, h) do { _Pragma("unroll") for (int n = 0; n < 2; ++n) _Pragma("unroll") for (int k = 0; k < 2; ++k) dst[n][k] = *(const LAS bf16x8*)(lds + PG8_SB(b, h) + boff + n * 2048 + k * 1024); } while (0)
; #define PG8_MMA(ai, bj, At, Bt) do { __builtin_amdgcn_s_setprio(1); _Pragma("unroll") for (int m = 0; m < 4; ++m) _Pragma("unroll") for (int n = 0; n < 2; ++n) _Pragma("unroll") for (int k = 0; k < 2; ++k) \
;         acc[ai][bj][m][n] = __builtin_amdgcn_mfma_f32_16x16x32_bf16(Bt[n][k], At[m][k], acc[ai][bj][m][n], 0, 0, 0); __builtin_amdgcn_s_setprio(0); } while (0)
; #define PG8_WAIT_V(n) asm volatile("s_waitcnt vmcnt(" #n ")" ::: "memory")
; #define PG8_WAIT_L(n) asm volatile("s_waitcnt lgkmcnt(" #n ")" ::: "memory")
; #define PG8_BAR __builtin_amdgcn_s_barrier()
; #define PG8_SCHED __builtin_amdgcn_sched_barrier(0)
; template <class Epi, class Sched>
; DI void gemm_phase(LAS unsigned char* lds, const Gemm g, const Sched& S, const Epi& E) {
;     ...
;             PG8_STAGE(PG8_SB(0, 1), b2 + hstep, voffB);
;             PG8_WAIT_V(6); PG8_BAR; PG8_MMA(1, 1, At, B1); PG8_BAR;
;             PG8_LDB(B0, 1, 0); PG8_SCHED; PG8_LDA(At, 1, 0); PG8_STAGE(PG8_SA(0, 1), a2 + hstep, voffA);
;             PG8_WAIT_L(8); PG8_BAR; PG8_WAIT_L(0); PG8_MMA(0, 0, At, B0); PG8_BAR; PG8_SCHED;
;             PG8_LDB(B1, 1, 1); PG8_STAGE(PG8_SB(1, 0), b3, voffB);
;             PG8_BAR; PG8_WAIT_L(0); PG8_MMA(0, 1, At, B1); PG8_BAR;
;             PG8_LDA(At, 1, 1); PG8_STAGE(PG8_SA(1, 0), a3, voffA);
	s_add_i32 s4, s66, s51
	s_mov_b32 s70, s4
	s_mov_b32 m0, s4
	s_add_u32 s0, s46, 0x80000
	s_addc_u32 s1, s47, 0
	global_load_lds_dwordx4 v132, s[0:1]
	s_add_i32 m0, s4, 0x2000
	s_nop 0
	global_load_lds_dwordx4 v134, s[0:1]
	s_waitcnt vmcnt(6)
	s_barrier
	s_setprio 1
	v_mfma_f32_16x16x32_bf16 v[52:55], v[218:221], v[166:169], 0
	v_mfma_f32_16x16x32_bf16 v[48:51], v[226:229], v[166:169], 0
	v_mfma_f32_16x16x32_bf16 v[36:39], v[218:221], v[174:177], 0
	v_mfma_f32_16x16x32_bf16 v[32:35], v[226:229], v[174:177], 0
	v_mfma_f32_16x16x32_bf16 v[20:23], v[218:221], v[188:191], 0
	v_mfma_f32_16x16x32_bf16 v[16:19], v[226:229], v[188:191], 0
	v_mfma_f32_16x16x32_bf16 v[4:7], v[218:221], v[210:213], 0
	v_mfma_f32_16x16x32_bf16 v[0:3], v[226:229], v[210:213], 0
	v_mfma_f32_16x16x32_bf16 v[52:55], v[222:225], v[170:173], v[52:55]
	v_mfma_f32_16x16x32_bf16 v[48:51], v[230:233], v[170:173], v[48:51]
	v_mfma_f32_16x16x32_bf16 v[36:39], v[222:225], v[178:181], v[36:39]
	v_mfma_f32_16x16x32_bf16 v[32:35], v[230:233], v[178:181], v[32:35]
	v_mfma_f32_16x16x32_bf16 v[20:23], v[222:225], v[206:209], v[20:23]
	v_mfma_f32_16x16x32_bf16 v[16:19], v[230:233], v[206:209], v[16:19]
	v_mfma_f32_16x16x32_bf16 v[4:7], v[222:225], v[214:217], v[4:7]
	v_mfma_f32_16x16x32_bf16 v[0:3], v[230:233], v[214:217], v[0:3]
	s_setprio 0
	s_add_i32 s4, 0, 0x18000
	v_add_u32_e32 v162, s4, v149
	s_barrier
	ds_read_b128 v[144:147], v162
	ds_read_b128 v[154:157], v162 offset:1024
	ds_read_b128 v[158:161], v162 offset:2048
	ds_read_b128 v[162:165], v162 offset:3072
	s_add_u32 s0, s48, 0x80000
	s_addc_u32 s1, s49, 0
	s_mov_b32 m0, s58
	ds_read_b128 v[166:169], v151 offset:32768
	ds_read_b128 v[170:173], v151 offset:33792
	ds_read_b128 v[174:177], v151 offset:34816
	ds_read_b128 v[178:181], v151 offset:35840
	ds_read_b128 v[188:191], v151 offset:36864
	ds_read_b128 v[206:209], v151 offset:37888
	ds_read_b128 v[210:213], v151 offset:38912
	global_load_lds_dwordx4 v128, s[0:1]
	s_mov_b32 m0, s59
	ds_read_b128 v[214:217], v151 offset:39936
	global_load_lds_dwordx4 v130, s[0:1]
	s_waitcnt lgkmcnt(8)
	s_barrier
	s_waitcnt lgkmcnt(0)
	s_setprio 1
	v_mfma_f32_16x16x32_bf16 v[124:127], v[144:147], v[166:169], v[124:127]
	v_mfma_f32_16x16x32_bf16 v[120:123], v[158:161], v[166:169], v[120:123]
	v_mfma_f32_16x16x32_bf16 v[108:111], v[144:147], v[174:177], v[108:111]
	v_mfma_f32_16x16x32_bf16 v[104:107], v[158:161], v[174:177], v[104:107]
	v_mfma_f32_16x16x32_bf16 v[92:95], v[144:147], v[188:191], v[92:95]
	v_mfma_f32_16x16x32_bf16 v[88:91], v[158:161], v[188:191], v[88:91]
	v_mfma_f32_16x16x32_bf16 v[76:79], v[144:147], v[210:213], v[76:79]
	v_mfma_f32_16x16x32_bf16 v[72:75], v[158:161], v[210:213], v[72:75]
	v_mfma_f32_16x16x32_bf16 v[124:127], v[154:157], v[170:173], v[124:127]
	v_mfma_f32_16x16x32_bf16 v[120:123], v[162:165], v[170:173], v[120:123]
	v_mfma_f32_16x16x32_bf16 v[108:111], v[154:157], v[178:181], v[108:111]
	v_mfma_f32_16x16x32_bf16 v[104:107], v[162:165], v[178:181], v[104:107]
	v_mfma_f32_16x16x32_bf16 v[92:95], v[154:157], v[206:209], v[92:95]
	v_mfma_f32_16x16x32_bf16 v[88:91], v[162:165], v[206:209], v[88:91]
	v_mfma_f32_16x16x32_bf16 v[76:79], v[154:157], v[214:217], v[76:79]
	v_mfma_f32_16x16x32_bf16 v[72:75], v[162:165], v[214:217], v[72:75]
	s_setprio 0
	s_barrier
	s_add_i32 s5, 0, 0x1c000
	s_add_i32 s0, s4, s51
	s_mov_b32 s71, s0
	v_add_u32_e32 v201, s5, v149
	s_add_i32 m0, s0, 0xffffff80
	ds_read_b128 v[218:221], v201
	ds_read_b128 v[222:225], v201 offset:1024
	ds_read_b128 v[226:229], v201 offset:2048
	global_load_lds_dwordx4 v132, s[46:47] offset:128
	s_add_i32 m0, s0, 0x1f80
	ds_read_b128 v[230:233], v201 offset:3072
	global_load_lds_dwordx4 v134, s[46:47] offset:128
	s_barrier
	s_waitcnt lgkmcnt(0)
	s_setprio 1
	v_mfma_f32_16x16x32_bf16 v[116:119], v[218:221], v[166:169], v[116:119]
	v_mfma_f32_16x16x32_bf16 v[112:115], v[226:229], v[166:169], v[112:115]
	v_mfma_f32_16x16x32_bf16 v[100:103], v[218:221], v[174:177], v[100:103]
	v_mfma_f32_16x16x32_bf16 v[96:99], v[226:229], v[174:177], v[96:99]
	v_mfma_f32_16x16x32_bf16 v[84:87], v[218:221], v[188:191], v[84:87]
	v_mfma_f32_16x16x32_bf16 v[80:83], v[226:229], v[188:191], v[80:83]
	v_mfma_f32_16x16x32_bf16 v[68:71], v[218:221], v[210:213], v[68:71]
	v_mfma_f32_16x16x32_bf16 v[64:67], v[226:229], v[210:213], v[64:67]
	v_mfma_f32_16x16x32_bf16 v[116:119], v[222:225], v[170:173], v[116:119]
	v_mfma_f32_16x16x32_bf16 v[112:115], v[230:233], v[170:173], v[112:115]
	v_mfma_f32_16x16x32_bf16 v[100:103], v[222:225], v[178:181], v[100:103]
	v_mfma_f32_16x16x32_bf16 v[96:99], v[230:233], v[178:181], v[96:99]
	v_mfma_f32_16x16x32_bf16 v[84:87], v[222:225], v[206:209], v[84:87]
	v_mfma_f32_16x16x32_bf16 v[80:83], v[230:233], v[206:209], v[80:83]
	v_mfma_f32_16x16x32_bf16 v[68:71], v[222:225], v[214:217], v[68:71]
	v_mfma_f32_16x16x32_bf16 v[64:67], v[230:233], v[214:217], v[64:67]
	s_setprio 0
	s_add_i32 m0, s63, 0xffffff80
	s_barrier
	ds_read_b128 v[166:169], v151 offset:49152
	ds_read_b128 v[170:173], v151 offset:50176
	ds_read_b128 v[174:177], v151 offset:51200
	ds_read_b128 v[178:181], v151 offset:52224
	ds_read_b128 v[188:191], v151 offset:53248
	ds_read_b128 v[206:209], v151 offset:54272
	ds_read_b128 v[210:213], v151 offset:55296
	global_load_lds_dwordx4 v128, s[48:49] offset:128
	s_add_i32 m0, s64, 0xffffff80
	ds_read_b128 v[214:217], v151 offset:56320
	global_load_lds_dwordx4 v130, s[48:49] offset:128
	s_barrier
; #define PG8_STAGE(bufoff, gbase, voff) do { _Pragma("unroll") for (int _i = 0; _i < 2; ++_i) \
;         __builtin_amdgcn_global_load_lds((const unsigned*)((const char*)(gbase) + (voff)[_i]), (LAS unsigned*)(lds + (bufoff) + ldsw + _i * 8192), 16, 0, 0); } while (0)
; #define PG8_LDA(dst, b, h) do { _Pragma("unroll") for (int m = 0; m < 4; ++m) _Pragma("unroll") for (int k = 0; k < 2; ++k) dst[m][k] = *(const LAS bf16x8*)(lds + PG8_SA(b, h) + aoff + m * 2048 + k * 1024); } while (0)
; #define PG8_LDB(dst, b, h) do { _Pragma("unroll") for (int n = 0; n < 2; ++n) _Pragma("unroll") for (int k = 0; k < 2; ++k) dst[n][k] = *(const LAS bf16x8*)(lds + PG8_SB(b, h) + boff + n * 2048 + k * 1024); } while (0)
; #define PG8_MMA(ai, bj, At, Bt) do { __builtin_amdgcn_s_setprio(1); _Pragma("unroll") for (int m = 0; m < 4; ++m) _Pragma("unroll") for (int n = 0; n < 2; ++n) _Pragma("unroll") for (int k = 0; k < 2; ++k) \
;         acc[ai][bj][m][n] = __builtin_amdgcn_mfma_f32_16x16x32_bf16(Bt[n][k], At[m][k], acc[ai][bj][m][n], 0, 0, 0); __builtin_amdgcn_s_setprio(0); } while (0)
; #define PG8_WAIT_V(n) asm volatile("s_waitcnt vmcnt(" #n ")" ::: "memory")
; #define PG8_WAIT_L(n) asm volatile("s_waitcnt lgkmcnt(" #n ")" ::: "memory")
; #define PG8_BAR __builtin_amdgcn_s_barrier()
; #define PG8_SCHED __builtin_amdgcn_sched_barrier(0)
; template <class Epi, class Sched>
; DI void gemm_phase(LAS unsigned char* lds, const Gemm g, const Sched& S, const Epi& E) {
;     ...
;             PG8_LDB(B0, 0, 0); PG8_SCHED; PG8_LDA(At, 0, 0); PG8_STAGE(PG8_SA(1, 1), a1 + hstep, voffA);
;             PG8_WAIT_L(8); PG8_BAR; PG8_WAIT_L(0); PG8_MMA(0, 0, At, B0); PG8_BAR; PG8_SCHED;
;             PG8_LDB(B1, 0, 1); PG8_STAGE(PG8_SB(0, 0), b2, voffB);
;     ...
;             PG8_BAR; PG8_WAIT_L(0); PG8_MMA(1, 0, At, B0); PG8_BAR; PG8_SCHED;
;             PG8_STAGE(PG8_SB(1, 1), b3 + hstep, voffB);
;             PG8_WAIT_V(6); PG8_BAR; PG8_MMA(1, 1, At, B1); PG8_BAR;
	s_waitcnt lgkmcnt(0)
	s_setprio 1
	v_mfma_f32_16x16x32_bf16 v[60:63], v[144:147], v[166:169], v[60:63]
	v_mfma_f32_16x16x32_bf16 v[56:59], v[158:161], v[166:169], v[56:59]
	v_mfma_f32_16x16x32_bf16 v[44:47], v[144:147], v[174:177], v[44:47]
	v_mfma_f32_16x16x32_bf16 v[40:43], v[158:161], v[174:177], v[40:43]
	v_mfma_f32_16x16x32_bf16 v[28:31], v[144:147], v[188:191], v[28:31]
	v_mfma_f32_16x16x32_bf16 v[24:27], v[158:161], v[188:191], v[24:27]
	v_mfma_f32_16x16x32_bf16 v[12:15], v[144:147], v[210:213], v[12:15]
	v_mfma_f32_16x16x32_bf16 v[8:11], v[158:161], v[210:213], v[8:11]
	v_mfma_f32_16x16x32_bf16 v[60:63], v[154:157], v[170:173], v[60:63]
	v_mfma_f32_16x16x32_bf16 v[56:59], v[162:165], v[170:173], v[56:59]
	v_mfma_f32_16x16x32_bf16 v[44:47], v[154:157], v[178:181], v[44:47]
	v_mfma_f32_16x16x32_bf16 v[40:43], v[162:165], v[178:181], v[40:43]
	v_mfma_f32_16x16x32_bf16 v[28:31], v[154:157], v[206:209], v[28:31]
	v_mfma_f32_16x16x32_bf16 v[24:27], v[162:165], v[206:209], v[24:27]
	v_mfma_f32_16x16x32_bf16 v[12:15], v[154:157], v[214:217], v[12:15]
	v_mfma_f32_16x16x32_bf16 v[8:11], v[162:165], v[214:217], v[8:11]
	s_setprio 0
	s_barrier
	s_add_i32 s4, s5, s51
	s_mov_b32 s72, s4
	s_mov_b32 m0, s4
	s_add_u32 s0, s46, 0x80080
	s_addc_u32 s1, s47, 0
	global_load_lds_dwordx4 v132, s[0:1]
	s_add_i32 m0, s4, 0x2000
	s_nop 0
	global_load_lds_dwordx4 v134, s[0:1]
	s_waitcnt vmcnt(6)
	s_barrier
	s_setprio 1
	v_mfma_f32_16x16x32_bf16 v[52:55], v[218:221], v[166:169], v[52:55]
	v_mfma_f32_16x16x32_bf16 v[48:51], v[226:229], v[166:169], v[48:51]
	v_mfma_f32_16x16x32_bf16 v[36:39], v[218:221], v[174:177], v[36:39]
	v_mfma_f32_16x16x32_bf16 v[32:35], v[226:229], v[174:177], v[32:35]
	v_mfma_f32_16x16x32_bf16 v[20:23], v[218:221], v[188:191], v[20:23]
	v_mfma_f32_16x16x32_bf16 v[16:19], v[226:229], v[188:191], v[16:19]
	v_mfma_f32_16x16x32_bf16 v[4:7], v[218:221], v[210:213], v[4:7]
	v_mfma_f32_16x16x32_bf16 v[0:3], v[226:229], v[210:213], v[0:3]
	v_mfma_f32_16x16x32_bf16 v[52:55], v[222:225], v[170:173], v[52:55]
	v_mfma_f32_16x16x32_bf16 v[48:51], v[230:233], v[170:173], v[48:51]
	v_mfma_f32_16x16x32_bf16 v[36:39], v[222:225], v[178:181], v[36:39]
	v_mfma_f32_16x16x32_bf16 v[32:35], v[230:233], v[178:181], v[32:35]
	v_mfma_f32_16x16x32_bf16 v[20:23], v[222:225], v[206:209], v[20:23]
	v_mfma_f32_16x16x32_bf16 v[16:19], v[230:233], v[206:209], v[16:19]
	v_mfma_f32_16x16x32_bf16 v[4:7], v[222:225], v[214:217], v[4:7]
	v_mfma_f32_16x16x32_bf16 v[0:3], v[230:233], v[214:217], v[0:3]
	s_setprio 0
	s_add_i32 s69, s69, 2
	s_add_u32 s44, s44, 0x100
	s_addc_u32 s45, s45, 0
	s_add_u32 s43, s43, 0x100
	s_addc_u32 s68, s68, 0
	s_cmp_gt_u32 s69, 29
	s_barrier
	s_cbranch_scc0 .LBB0_1508
	s_branch .Lpeel_done_1508
.LBB0_1508:
	ds_read_b128 v[144:147], v150
	ds_read_b128 v[154:157], v150 offset:1024
	ds_read_b128 v[158:161], v150 offset:2048
	ds_read_b128 v[162:165], v150 offset:3072
	s_add_u32 s0, s44, 0xfff80080
	s_addc_u32 s1, s45, -1
	s_cmp_eq_u32 s69, 28
	s_cselect_b32 s49, s34, s1
	s_cselect_b32 s48, s35, s0
	s_cselect_b32 s47, s31, s68
	s_cselect_b32 s46, s37, s43
	s_add_i32 m0, s52, 0xc000
	ds_read_b128 v[166:169], v151
	ds_read_b128 v[170:173], v151 offset:1024
	ds_read_b128 v[174:177], v151 offset:2048
	ds_read_b128 v[178:181], v151 offset:3072
	ds_read_b128 v[188:191], v151 offset:4096
	ds_read_b128 v[206:209], v151 offset:5120
	ds_read_b128 v[210:213], v151 offset:6144
	global_load_lds_dwordx4 v136, s[44:45]
	s_add_i32 m0, s52, 0xe000
	ds_read_b128 v[214:217], v151 offset:7168
	global_load_lds_dwordx4 v138, s[44:45]
	s_waitcnt lgkmcnt(8)
	s_barrier
	s_waitcnt lgkmcnt(0)
	s_setprio 1
	v_mfma_f32_16x16x32_bf16 v[124:127], v[144:147], v[166:169], v[124:127]
	v_mfma_f32_16x16x32_bf16 v[120:123], v[158:161], v[166:169], v[120:123]
	v_mfma_f32_16x16x32_bf16 v[108:111], v[144:147], v[174:177], v[108:111]
	v_mfma_f32_16x16x32_bf16 v[104:107], v[158:161], v[174:177], v[104:107]
	v_mfma_f32_16x16x32_bf16 v[92:95], v[144:147], v[188:191], v[92:95]
	v_mfma_f32_16x16x32_bf16 v[88:91], v[158:161], v[188:191], v[88:91]
	v_mfma_f32_16x16x32_bf16 v[76:79], v[144:147], v[210:213], v[76:79]
	v_mfma_f32_16x16x32_bf16 v[72:75], v[158:161], v[210:213], v[72:75]
	v_mfma_f32_16x16x32_bf16 v[124:127], v[154:157], v[170:173], v[124:127]
	v_mfma_f32_16x16x32_bf16 v[120:123], v[162:165], v[170:173], v[120:123]
	v_mfma_f32_16x16x32_bf16 v[108:111], v[154:157], v[178:181], v[108:111]
	v_mfma_f32_16x16x32_bf16 v[104:107], v[162:165], v[178:181], v[104:107]
	v_mfma_f32_16x16x32_bf16 v[92:95], v[154:157], v[206:209], v[92:95]
	v_mfma_f32_16x16x32_bf16 v[88:91], v[162:165], v[206:209], v[88:91]
	v_mfma_f32_16x16x32_bf16 v[76:79], v[154:157], v[214:217], v[76:79]
	v_mfma_f32_16x16x32_bf16 v[72:75], v[162:165], v[214:217], v[72:75]
	s_setprio 0
	s_barrier
	s_mov_b32 m0, s32
	ds_read_b128 v[218:221], v152
	ds_read_b128 v[222:225], v152 offset:1024
	ds_read_b128 v[226:229], v152 offset:2048
	global_load_lds_dwordx4 v132, s[46:47]
	s_add_i32 m0, s32, 0x2000
	ds_read_b128 v[230:233], v152 offset:3072
	global_load_lds_dwordx4 v134, s[46:47]
	s_barrier
; #define PG8_STAGE(bufoff, gbase, voff) do { _Pragma("unroll") for (int _i = 0; _i < 2; ++_i) \
;         __builtin_amdgcn_global_load_lds((const unsigned*)((const char*)(gbase) + (voff)[_i]), (LAS unsigned*)(lds + (bufoff) + ldsw + _i * 8192), 16, 0, 0); } while (0)
; #define PG8_LDA(dst, b, h) do { _Pragma("unroll") for (int m = 0; m < 4; ++m) _Pragma("unroll") for (int k = 0; k < 2; ++k) dst[m][k] = *(const LAS bf16x8*)(lds + PG8_SA(b, h) + aoff + m * 2048 + k * 1024); } while (0)
; #define PG8_LDB(dst, b, h) do { _Pragma("unroll") for (int n = 0; n < 2; ++n) _Pragma("unroll") for (int k = 0; k < 2; ++k) dst[n][k] = *(const LAS bf16x8*)(lds + PG8_SB(b, h) + boff + n * 2048 + k * 1024); } while (0)
; #define PG8_MMA(ai, bj, At, Bt) do { __builtin_amdgcn_s_setprio(1); _Pragma("unroll") for (int m = 0; m < 4; ++m) _Pragma("unroll") for (int n = 0; n < 2; ++n) _Pragma("unroll") for (int k = 0; k < 2; ++k) \
;         acc[ai][bj][m][n] = __builtin_amdgcn_mfma_f32_16x16x32_bf16(Bt[n][k], At[m][k], acc[ai][bj][m][n], 0, 0, 0); __builtin_amdgcn_s_setprio(0); } while (0)
; #define PG8_WAIT_V(n) asm volatile("s_waitcnt vmcnt(" #n ")" ::: "memory")
; #define PG8_WAIT_L(n) asm volatile("s_waitcnt lgkmcnt(" #n ")" ::: "memory")
; #define PG8_BAR __builtin_amdgcn_s_barrier()
; #define PG8_SCHED __builtin_amdgcn_sched_barrier(0)
; template <class Epi, class Sched>
; DI void gemm_phase(LAS unsigned char* lds, const Gemm g, const Sched& S, const Epi& E) {
;     ...
;             PG8_BAR; PG8_WAIT_L(0); PG8_MMA(0, 1, At, B1); PG8_BAR;
;             PG8_LDA(At, 0, 1); PG8_STAGE(PG8_SA(0, 0), a2, voffA);
;             PG8_BAR; PG8_WAIT_L(0); PG8_MMA(1, 0, At, B0); PG8_BAR; PG8_SCHED;
;             PG8_STAGE(PG8_SB(0, 1), b2 + hstep, voffB);
;             PG8_WAIT_V(6); PG8_BAR; PG8_MMA(1, 1, At, B1); PG8_BAR;
;             PG8_LDB(B0, 1, 0); PG8_SCHED; PG8_LDA(At, 1, 0); PG8_STAGE(PG8_SA(0, 1), a2 + hstep, voffA);
	s_waitcnt lgkmcnt(0)
	s_setprio 1
	v_mfma_f32_16x16x32_bf16 v[116:119], v[218:221], v[166:169], v[116:119]
	v_mfma_f32_16x16x32_bf16 v[112:115], v[226:229], v[166:169], v[112:115]
	v_mfma_f32_16x16x32_bf16 v[100:103], v[218:221], v[174:177], v[100:103]
	v_mfma_f32_16x16x32_bf16 v[96:99], v[226:229], v[174:177], v[96:99]
	v_mfma_f32_16x16x32_bf16 v[84:87], v[218:221], v[188:191], v[84:87]
	v_mfma_f32_16x16x32_bf16 v[80:83], v[226:229], v[188:191], v[80:83]
	v_mfma_f32_16x16x32_bf16 v[68:71], v[218:221], v[210:213], v[68:71]
	v_mfma_f32_16x16x32_bf16 v[64:67], v[226:229], v[210:213], v[64:67]
	v_mfma_f32_16x16x32_bf16 v[116:119], v[222:225], v[170:173], v[116:119]
	v_mfma_f32_16x16x32_bf16 v[112:115], v[230:233], v[170:173], v[112:115]
	v_mfma_f32_16x16x32_bf16 v[100:103], v[222:225], v[178:181], v[100:103]
	v_mfma_f32_16x16x32_bf16 v[96:99], v[230:233], v[178:181], v[96:99]
	v_mfma_f32_16x16x32_bf16 v[84:87], v[222:225], v[206:209], v[84:87]
	v_mfma_f32_16x16x32_bf16 v[80:83], v[230:233], v[206:209], v[80:83]
	v_mfma_f32_16x16x32_bf16 v[68:71], v[222:225], v[214:217], v[68:71]
	v_mfma_f32_16x16x32_bf16 v[64:67], v[230:233], v[214:217], v[64:67]
	s_setprio 0
	s_mov_b32 m0, s52
	s_barrier
	ds_read_b128 v[166:169], v151 offset:16384
	ds_read_b128 v[170:173], v151 offset:17408
	ds_read_b128 v[174:177], v151 offset:18432
	ds_read_b128 v[178:181], v151 offset:19456
	ds_read_b128 v[188:191], v151 offset:20480
	ds_read_b128 v[206:209], v151 offset:21504
	ds_read_b128 v[210:213], v151 offset:22528
	global_load_lds_dwordx4 v128, s[48:49]
	s_mov_b32 m0, s53
	ds_read_b128 v[214:217], v151 offset:23552
	global_load_lds_dwordx4 v130, s[48:49]
	s_barrier
	s_waitcnt lgkmcnt(0)
	s_setprio 1
	v_mfma_f32_16x16x32_bf16 v[60:63], v[144:147], v[166:169], v[60:63]
	v_mfma_f32_16x16x32_bf16 v[56:59], v[158:161], v[166:169], v[56:59]
	v_mfma_f32_16x16x32_bf16 v[44:47], v[144:147], v[174:177], v[44:47]
	v_mfma_f32_16x16x32_bf16 v[40:43], v[158:161], v[174:177], v[40:43]
	v_mfma_f32_16x16x32_bf16 v[28:31], v[144:147], v[188:191], v[28:31]
	v_mfma_f32_16x16x32_bf16 v[24:27], v[158:161], v[188:191], v[24:27]
	v_mfma_f32_16x16x32_bf16 v[12:15], v[144:147], v[210:213], v[12:15]
	v_mfma_f32_16x16x32_bf16 v[8:11], v[158:161], v[210:213], v[8:11]
	v_mfma_f32_16x16x32_bf16 v[60:63], v[154:157], v[170:173], v[60:63]
	v_mfma_f32_16x16x32_bf16 v[56:59], v[162:165], v[170:173], v[56:59]
	v_mfma_f32_16x16x32_bf16 v[44:47], v[154:157], v[178:181], v[44:47]
	v_mfma_f32_16x16x32_bf16 v[40:43], v[162:165], v[178:181], v[40:43]
	v_mfma_f32_16x16x32_bf16 v[28:31], v[154:157], v[206:209], v[28:31]
	v_mfma_f32_16x16x32_bf16 v[24:27], v[162:165], v[206:209], v[24:27]
	v_mfma_f32_16x16x32_bf16 v[12:15], v[154:157], v[214:217], v[12:15]
	v_mfma_f32_16x16x32_bf16 v[8:11], v[162:165], v[214:217], v[8:11]
	s_setprio 0
	s_barrier
	s_mov_b32 m0, s70
	s_add_u32 s0, s46, 0x80000
	s_addc_u32 s1, s47, 0
	global_load_lds_dwordx4 v132, s[0:1]
	s_add_i32 m0, s70, 0x2000
	s_nop 0
	global_load_lds_dwordx4 v134, s[0:1]
	s_waitcnt vmcnt(6)
	s_barrier
	s_setprio 1
	v_mfma_f32_16x16x32_bf16 v[52:55], v[218:221], v[166:169], v[52:55]
	v_mfma_f32_16x16x32_bf16 v[48:51], v[226:229], v[166:169], v[48:51]
	v_mfma_f32_16x16x32_bf16 v[36:39], v[218:221], v[174:177], v[36:39]
	v_mfma_f32_16x16x32_bf16 v[32:35], v[226:229], v[174:177], v[32:35]
	v_mfma_f32_16x16x32_bf16 v[20:23], v[218:221], v[188:191], v[20:23]
	v_mfma_f32_16x16x32_bf16 v[16:19], v[226:229], v[188:191], v[16:19]
	v_mfma_f32_16x16x32_bf16 v[4:7], v[218:221], v[210:213], v[4:7]
	v_mfma_f32_16x16x32_bf16 v[0:3], v[226:229], v[210:213], v[0:3]
	v_mfma_f32_16x16x32_bf16 v[52:55], v[222:225], v[170:173], v[52:55]
	v_mfma_f32_16x16x32_bf16 v[48:51], v[230:233], v[170:173], v[48:51]
	v_mfma_f32_16x16x32_bf16 v[36:39], v[222:225], v[178:181], v[36:39]
	v_mfma_f32_16x16x32_bf16 v[32:35], v[230:233], v[178:181], v[32:35]
	v_mfma_f32_16x16x32_bf16 v[20:23], v[222:225], v[206:209], v[20:23]
	v_mfma_f32_16x16x32_bf16 v[16:19], v[230:233], v[206:209], v[16:19]
	v_mfma_f32_16x16x32_bf16 v[4:7], v[222:225], v[214:217], v[4:7]
	v_mfma_f32_16x16x32_bf16 v[0:3], v[230:233], v[214:217], v[0:3]
	s_setprio 0
	s_add_i32 s4, 0, 0x18000
	v_add_u32_e32 v162, s4, v149
	s_barrier
	ds_read_b128 v[144:147], v162
	ds_read_b128 v[154:157], v162 offset:1024
	ds_read_b128 v[158:161], v162 offset:2048
	ds_read_b128 v[162:165], v162 offset:3072
	s_add_u32 s0, s48, 0x80000
	s_addc_u32 s1, s49, 0
	s_mov_b32 m0, s58
	ds_read_b128 v[166:169], v151 offset:32768
	ds_read_b128 v[170:173], v151 offset:33792
	ds_read_b128 v[174:177], v151 offset:34816
	ds_read_b128 v[178:181], v151 offset:35840
	ds_read_b128 v[188:191], v151 offset:36864
	ds_read_b128 v[206:209], v151 offset:37888
	ds_read_b128 v[210:213], v151 offset:38912
	global_load_lds_dwordx4 v128, s[0:1]
	s_mov_b32 m0, s59
	ds_read_b128 v[214:217], v151 offset:39936
	global_load_lds_dwordx4 v130, s[0:1]
	s_waitcnt lgkmcnt(8)
	s_barrier
; #define PG8_STAGE(bufoff, gbase, voff) do { _Pragma("unroll") for (int _i = 0; _i < 2; ++_i) \
;         __builtin_amdgcn_global_load_lds((const unsigned*)((const char*)(gbase) + (voff)[_i]), (LAS unsigned*)(lds + (bufoff) + ldsw + _i * 8192), 16, 0, 0); } while (0)
; #define PG8_LDA(dst, b, h) do { _Pragma("unroll") for (int m = 0; m < 4; ++m) _Pragma("unroll") for (int k = 0; k < 2; ++k) dst[m][k] = *(const LAS bf16x8*)(lds + PG8_SA(b, h) + aoff + m * 2048 + k * 1024); } while (0)
; #define PG8_LDB(dst, b, h) do { _Pragma("unroll") for (int n = 0; n < 2; ++n) _Pragma("unroll") for (int k = 0; k < 2; ++k) dst[n][k] = *(const LAS bf16x8*)(lds + PG8_SB(b, h) + boff + n * 2048 + k * 1024); } while (0)
; #define PG8_MMA(ai, bj, At, Bt) do { __builtin_amdgcn_s_setprio(1); _Pragma("unroll") for (int m = 0; m < 4; ++m) _Pragma("unroll") for (int n = 0; n < 2; ++n) _Pragma("unroll") for (int k = 0; k < 2; ++k) \
;         acc[ai][bj][m][n] = __builtin_amdgcn_mfma_f32_16x16x32_bf16(Bt[n][k], At[m][k], acc[ai][bj][m][n], 0, 0, 0); __builtin_amdgcn_s_setprio(0); } while (0)
; #define PG8_WAIT_V(n) asm volatile("s_waitcnt vmcnt(" #n ")" ::: "memory")
; #define PG8_WAIT_L(n) asm volatile("s_waitcnt lgkmcnt(" #n ")" ::: "memory")
; #define PG8_BAR __builtin_amdgcn_s_barrier()
; #define PG8_SCHED __builtin_amdgcn_sched_barrier(0)
; template <class Epi, class Sched>
; DI void gemm_phase(LAS unsigned char* lds, const Gemm g, const Sched& S, const Epi& E) {
;     ...
;             PG8_WAIT_L(8); PG8_BAR; PG8_WAIT_L(0); PG8_MMA(0, 0, At, B0); PG8_BAR; PG8_SCHED;
;             PG8_LDB(B1, 1, 1); PG8_STAGE(PG8_SB(1, 0), b3, voffB);
;             PG8_BAR; PG8_WAIT_L(0); PG8_MMA(0, 1, At, B1); PG8_BAR;
;             PG8_LDA(At, 1, 1); PG8_STAGE(PG8_SA(1, 0), a3, voffA);
;             PG8_BAR; PG8_WAIT_L(0); PG8_MMA(1, 0, At, B0); PG8_BAR; PG8_SCHED;
;             PG8_STAGE(PG8_SB(1, 1), b3 + hstep, voffB);
;             PG8_WAIT_V(6); PG8_BAR; PG8_MMA(1, 1, At, B1); PG8_BAR;
	s_waitcnt lgkmcnt(0)
	s_setprio 1
	v_mfma_f32_16x16x32_bf16 v[124:127], v[144:147], v[166:169], v[124:127]
	v_mfma_f32_16x16x32_bf16 v[120:123], v[158:161], v[166:169], v[120:123]
	v_mfma_f32_16x16x32_bf16 v[108:111], v[144:147], v[174:177], v[108:111]
	v_mfma_f32_16x16x32_bf16 v[104:107], v[158:161], v[174:177], v[104:107]
	v_mfma_f32_16x16x32_bf16 v[92:95], v[144:147], v[188:191], v[92:95]
	v_mfma_f32_16x16x32_bf16 v[88:91], v[158:161], v[188:191], v[88:91]
	v_mfma_f32_16x16x32_bf16 v[76:79], v[144:147], v[210:213], v[76:79]
	v_mfma_f32_16x16x32_bf16 v[72:75], v[158:161], v[210:213], v[72:75]
	v_mfma_f32_16x16x32_bf16 v[124:127], v[154:157], v[170:173], v[124:127]
	v_mfma_f32_16x16x32_bf16 v[120:123], v[162:165], v[170:173], v[120:123]
	v_mfma_f32_16x16x32_bf16 v[108:111], v[154:157], v[178:181], v[108:111]
	v_mfma_f32_16x16x32_bf16 v[104:107], v[162:165], v[178:181], v[104:107]
	v_mfma_f32_16x16x32_bf16 v[92:95], v[154:157], v[206:209], v[92:95]
	v_mfma_f32_16x16x32_bf16 v[88:91], v[162:165], v[206:209], v[88:91]
	v_mfma_f32_16x16x32_bf16 v[76:79], v[154:157], v[214:217], v[76:79]
	v_mfma_f32_16x16x32_bf16 v[72:75], v[162:165], v[214:217], v[72:75]
	s_setprio 0
	s_barrier
	s_add_i32 s5, 0, 0x1c000
	v_add_u32_e32 v201, s5, v149
	s_add_i32 m0, s71, 0xffffff80
	ds_read_b128 v[218:221], v201
	ds_read_b128 v[222:225], v201 offset:1024
	ds_read_b128 v[226:229], v201 offset:2048
	global_load_lds_dwordx4 v132, s[46:47] offset:128
	s_add_i32 m0, s71, 0x1f80
	ds_read_b128 v[230:233], v201 offset:3072
	global_load_lds_dwordx4 v134, s[46:47] offset:128
	s_barrier
	s_waitcnt lgkmcnt(0)
	s_setprio 1
	v_mfma_f32_16x16x32_bf16 v[116:119], v[218:221], v[166:169], v[116:119]
	v_mfma_f32_16x16x32_bf16 v[112:115], v[226:229], v[166:169], v[112:115]
	v_mfma_f32_16x16x32_bf16 v[100:103], v[218:221], v[174:177], v[100:103]
	v_mfma_f32_16x16x32_bf16 v[96:99], v[226:229], v[174:177], v[96:99]
	v_mfma_f32_16x16x32_bf16 v[84:87], v[218:221], v[188:191], v[84:87]
	v_mfma_f32_16x16x32_bf16 v[80:83], v[226:229], v[188:191], v[80:83]
	v_mfma_f32_16x16x32_bf16 v[68:71], v[218:221], v[210:213], v[68:71]
	v_mfma_f32_16x16x32_bf16 v[64:67], v[226:229], v[210:213], v[64:67]
	v_mfma_f32_16x16x32_bf16 v[116:119], v[222:225], v[170:173], v[116:119]
	v_mfma_f32_16x16x32_bf16 v[112:115], v[230:233], v[170:173], v[112:115]
	v_mfma_f32_16x16x32_bf16 v[100:103], v[222:225], v[178:181], v[100:103]
	v_mfma_f32_16x16x32_bf16 v[96:99], v[230:233], v[178:181], v[96:99]
	v_mfma_f32_16x16x32_bf16 v[84:87], v[222:225], v[206:209], v[84:87]
	v_mfma_f32_16x16x32_bf16 v[80:83], v[230:233], v[206:209], v[80:83]
	v_mfma_f32_16x16x32_bf16 v[68:71], v[222:225], v[214:217], v[68:71]
	v_mfma_f32_16x16x32_bf16 v[64:67], v[230:233], v[214:217], v[64:67]
	s_setprio 0
	s_add_i32 m0, s63, 0xffffff80
	s_barrier
	ds_read_b128 v[166:169], v151 offset:49152
	ds_read_b128 v[170:173], v151 offset:50176
	ds_read_b128 v[174:177], v151 offset:51200
	ds_read_b128 v[178:181], v151 offset:52224
	ds_read_b128 v[188:191], v151 offset:53248
	ds_read_b128 v[206:209], v151 offset:54272
	ds_read_b128 v[210:213], v151 offset:55296
	global_load_lds_dwordx4 v128, s[48:49] offset:128
	s_add_i32 m0, s64, 0xffffff80
	ds_read_b128 v[214:217], v151 offset:56320
	global_load_lds_dwordx4 v130, s[48:49] offset:128
	s_barrier
	s_waitcnt lgkmcnt(0)
	s_setprio 1
	v_mfma_f32_16x16x32_bf16 v[60:63], v[144:147], v[166:169], v[60:63]
	v_mfma_f32_16x16x32_bf16 v[56:59], v[158:161], v[166:169], v[56:59]
	v_mfma_f32_16x16x32_bf16 v[44:47], v[144:147], v[174:177], v[44:47]
	v_mfma_f32_16x16x32_bf16 v[40:43], v[158:161], v[174:177], v[40:43]
	v_mfma_f32_16x16x32_bf16 v[28:31], v[144:147], v[188:191], v[28:31]
	v_mfma_f32_16x16x32_bf16 v[24:27], v[158:161], v[188:191], v[24:27]
	v_mfma_f32_16x16x32_bf16 v[12:15], v[144:147], v[210:213], v[12:15]
	v_mfma_f32_16x16x32_bf16 v[8:11], v[158:161], v[210:213], v[8:11]
	v_mfma_f32_16x16x32_bf16 v[60:63], v[154:157], v[170:173], v[60:63]
	v_mfma_f32_16x16x32_bf16 v[56:59], v[162:165], v[170:173], v[56:59]
	v_mfma_f32_16x16x32_bf16 v[44:47], v[154:157], v[178:181], v[44:47]
	v_mfma_f32_16x16x32_bf16 v[40:43], v[162:165], v[178:181], v[40:43]
	v_mfma_f32_16x16x32_bf16 v[28:31], v[154:157], v[206:209], v[28:31]
	v_mfma_f32_16x16x32_bf16 v[24:27], v[162:165], v[206:209], v[24:27]
	v_mfma_f32_16x16x32_bf16 v[12:15], v[154:157], v[214:217], v[12:15]
	v_mfma_f32_16x16x32_bf16 v[8:11], v[162:165], v[214:217], v[8:11]
	s_setprio 0
	s_barrier
	s_mov_b32 m0, s72
	s_add_u32 s0, s46, 0x80080
	s_addc_u32 s1, s47, 0
	global_load_lds_dwordx4 v132, s[0:1]
	s_add_i32 m0, s72, 0x2000
	s_nop 0
	global_load_lds_dwordx4 v134, s[0:1]
	s_waitcnt vmcnt(6)
	s_barrier
	s_setprio 1
	v_mfma_f32_16x16x32_bf16 v[52:55], v[218:221], v[166:169], v[52:55]
	v_mfma_f32_16x16x32_bf16 v[48:51], v[226:229], v[166:169], v[48:51]
	v_mfma_f32_16x16x32_bf16 v[36:39], v[218:221], v[174:177], v[36:39]
	v_mfma_f32_16x16x32_bf16 v[32:35], v[226:229], v[174:177], v[32:35]
	v_mfma_f32_16x16x32_bf16 v[20:23], v[218:221], v[188:191], v[20:23]
	v_mfma_f32_16x16x32_bf16 v[16:19], v[226:229], v[188:191], v[16:19]
	v_mfma_f32_16x16x32_bf16 v[4:7], v[218:221], v[210:213], v[4:7]
	v_mfma_f32_16x16x32_bf16 v[0:3], v[226:229], v[210:213], v[0:3]
	v_mfma_f32_16x16x32_bf16 v[52:55], v[222:225], v[170:173], v[52:55]
	v_mfma_f32_16x16x32_bf16 v[48:51], v[230:233], v[170:173], v[48:51]
	v_mfma_f32_16x16x32_bf16 v[36:39], v[222:225], v[178:181], v[36:39]
	v_mfma_f32_16x16x32_bf16 v[32:35], v[230:233], v[178:181], v[32:35]
	v_mfma_f32_16x16x32_bf16 v[20:23], v[222:225], v[206:209], v[20:23]
	v_mfma_f32_16x16x32_bf16 v[16:19], v[230:233], v[206:209], v[16:19]
	v_mfma_f32_16x16x32_bf16 v[4:7], v[222:225], v[214:217], v[4:7]
	v_mfma_f32_16x16x32_bf16 v[0:3], v[230:233], v[214:217], v[0:3]
	s_setprio 0
	s_add_i32 s69, s69, 2
	s_add_u32 s44, s44, 0x100
	s_addc_u32 s45, s45, 0
	s_add_u32 s43, s43, 0x100
	s_addc_u32 s68, s68, 0
	s_cmp_gt_u32 s69, 29
	s_barrier
	s_cbranch_scc0 .LBB0_1508

;     DI size_t aoff(const Unit& u, size_t tstep) const { return (size_t)u.pm * tstep; }
;     DI size_t boff(const Unit& u, size_t tstep) const { return (size_t)u.pn * tstep; }
;     DI bool next(int i, Unit& u) const { const long L = (long)i * G + c; if (L >= np) return false; u.pm = pmv; u.pn = (int)(L % nN); u.ks = (int)(L / nN); return true; }
;     DI size_t aoff(const Unit& u, size_t) const { return (size_t)u.ks * kbytes; }
;     DI size_t boff(const Unit& u, size_t tstep) const { return (size_t)u.pn * tstep + (size_t)u.ks * kbytes; }
;     DI bool next(int i, Unit& u) const { Unit t; if (!S.next(i / 3, t)) return false; u.pm = t.pm; u.pn = t.pn; u.ks = i % 3; return true; }
;     DI size_t aoff(const Unit& u, size_t tstep) const { return (u.ks < 2 ? offU : offOA) + (size_t)u.pm * tstep; }
; #define PG8_LDA(dst, b, h) do { _Pragma("unroll") for (int m = 0; m < 4; ++m) _Pragma("unroll") for (int k = 0; k < 2; ++k) dst[m][k] = *(const LAS bf16x8*)(lds + PG8_SA(b, h) + aoff + m * 2048 + k * 1024); } while (0)
; template <class Epi, class Sched>
; DI void gemm_phase(LAS unsigned char* lds, const Gemm g, const Sched& S, const Epi& E) {
;     ...
;         const bool has_next = S.next(ui + 1, nxt);
;         const char* nA = has_next ? (const char*)g.A + S.aoff(nxt, tstep) : cA; const char* nB = has_next ? (const char*)g.Bt + S.boff(nxt, tstep) : cB;
;         for (int t = 0; t < nt; t += 2) {
;             if constexpr (Epi::HAS_MID) { if (t == E.mid_t(nt)) { int fr3 = fr, fq3 = fq; asm volatile("" : "+v"(fr3), "+v"(fq3)); E.mid(acc, cur, wr, wc, fr3, fq3); } }
;             const bool last = (t == nt - 2);
;             const char* a1 = cA + (size_t)(t + 1) * kstep;
;             const char* a2 = last ? nA : cA + (size_t)(t + 2) * kstep; const char* b2 = last ? nB : cB + (size_t)(t + 2) * kstep;
;             const char* a3 = a2 + kstep; const char* b3 = b2 + kstep;
;             PG8_LDB(B0, 0, 0); PG8_SCHED; PG8_LDA(At, 0, 0); PG8_STAGE(PG8_SA(1, 1), a1 + hstep, voffA);
;             PG8_WAIT_L(8); PG8_BAR; PG8_WAIT_L(0); PG8_MMA(0, 0, At, B0); PG8_BAR; PG8_SCHED;
;             PG8_LDB(B1, 0, 1); PG8_STAGE(PG8_SB(0, 0), b2, voffB);
;             PG8_BAR; PG8_WAIT_L(0); PG8_MMA(0, 1, At, B1); PG8_BAR;
;             PG8_LDA(At, 0, 1); PG8_STAGE(PG8_SA(0, 0), a2, voffA);
;             PG8_BAR; PG8_WAIT_L(0); PG8_MMA(1, 0, At, B0); PG8_BAR; PG8_SCHED;
.LBB0_1667:
	s_ashr_i32 s29, s28, 31
	s_lshl_b64 s[0:1], s[28:29], 20
	s_add_u32 s30, s45, s0
	v_cmp_lt_i64_e32 vcc, s[8:9], v[140:141]
	s_addc_u32 s31, s46, s1
	s_and_b64 s[0:1], vcc, exec
	s_cselect_b32 s29, s31, s43
	s_cselect_b32 s35, s30, s42
	s_ashr_i32 s19, s18, 31
	s_lshl_b64 s[0:1], s[18:19], 20
	s_add_u32 s36, s47, s0
	s_addc_u32 s37, s48, s1
	s_and_b64 s[0:1], vcc, exec
	s_cselect_b32 s19, s37, s41
	s_cselect_b32 s65, s36, s40
	s_add_u32 s8, s42, 0x80080
	s_addc_u32 s9, s43, 0
	s_add_u32 s66, s40, 0x100
	v_mov_b32_e32 v8, 0
	s_addc_u32 s67, s41, 0
	s_mov_b32 s68, -2
	ds_read_b128 v[144:147], v149
	ds_read_b128 v[156:159], v149 offset:1024
	ds_read_b128 v[160:163], v149 offset:2048
	ds_read_b128 v[164:167], v149 offset:3072
	s_add_u32 s0, s8, 0xfff80080
	s_addc_u32 s1, s9, -1
	s_cmp_eq_u32 s68, 28
	s_cselect_b32 s43, s29, s1
	s_cselect_b32 s42, s35, s0
	s_cselect_b32 s41, s19, s67
	s_cselect_b32 s40, s65, s66
	s_add_i32 m0, s39, 0xc000
	ds_read_b128 v[168:171], v150
	ds_read_b128 v[172:175], v150 offset:1024
	ds_read_b128 v[176:179], v150 offset:2048
	ds_read_b128 v[180:183], v150 offset:3072
	ds_read_b128 v[188:191], v150 offset:4096
	ds_read_b128 v[206:209], v150 offset:5120
	ds_read_b128 v[210:213], v150 offset:6144
	global_load_lds_dwordx4 v136, s[8:9]
	s_add_i32 m0, s39, 0xe000
	ds_read_b128 v[214:217], v150 offset:7168
	global_load_lds_dwordx4 v138, s[8:9]
	s_waitcnt lgkmcnt(8)
	s_barrier
	s_waitcnt lgkmcnt(0)
	s_setprio 1
	v_mfma_f32_16x16x32_bf16 v[116:119], v[144:147], v[168:171], 0
	v_mfma_f32_16x16x32_bf16 v[112:115], v[160:163], v[168:171], 0
	v_mfma_f32_16x16x32_bf16 v[100:103], v[144:147], v[176:179], 0
	v_mfma_f32_16x16x32_bf16 v[96:99], v[160:163], v[176:179], 0
	v_mfma_f32_16x16x32_bf16 v[84:87], v[144:147], v[188:191], 0
	v_mfma_f32_16x16x32_bf16 v[80:83], v[160:163], v[188:191], 0
	v_mfma_f32_16x16x32_bf16 v[68:71], v[144:147], v[210:213], 0
	v_mfma_f32_16x16x32_bf16 v[64:67], v[160:163], v[210:213], 0
	v_mfma_f32_16x16x32_bf16 v[116:119], v[156:159], v[172:175], v[116:119]
	v_mfma_f32_16x16x32_bf16 v[112:115], v[164:167], v[172:175], v[112:115]
	v_mfma_f32_16x16x32_bf16 v[100:103], v[156:159], v[180:183], v[100:103]
	v_mfma_f32_16x16x32_bf16 v[96:99], v[164:167], v[180:183], v[96:99]
	v_mfma_f32_16x16x32_bf16 v[84:87], v[156:159], v[206:209], v[84:87]
	v_mfma_f32_16x16x32_bf16 v[80:83], v[164:167], v[206:209], v[80:83]
	v_mfma_f32_16x16x32_bf16 v[68:71], v[156:159], v[214:217], v[68:71]
	v_mfma_f32_16x16x32_bf16 v[64:67], v[164:167], v[214:217], v[64:67]
	s_setprio 0
	s_barrier
	s_add_i32 s0, s61, s50
	s_mov_b32 s17, s0
	s_mov_b32 m0, s0
	ds_read_b128 v[218:221], v151
	ds_read_b128 v[222:225], v151 offset:1024
	ds_read_b128 v[226:229], v151 offset:2048
	global_load_lds_dwordx4 v130, s[40:41]
	s_add_i32 m0, s0, 0x2000
	ds_read_b128 v[230:233], v151 offset:3072
	global_load_lds_dwordx4 v134, s[40:41]
	s_barrier
	s_waitcnt lgkmcnt(0)
	s_setprio 1
	v_mfma_f32_16x16x32_bf16 v[124:127], v[218:221], v[168:171], 0
	v_mfma_f32_16x16x32_bf16 v[120:123], v[226:229], v[168:171], 0
	v_mfma_f32_16x16x32_bf16 v[108:111], v[218:221], v[176:179], 0
	v_mfma_f32_16x16x32_bf16 v[104:107], v[226:229], v[176:179], 0
	v_mfma_f32_16x16x32_bf16 v[92:95], v[218:221], v[188:191], 0
	v_mfma_f32_16x16x32_bf16 v[88:91], v[226:229], v[188:191], 0
	v_mfma_f32_16x16x32_bf16 v[76:79], v[218:221], v[210:213], 0
	v_mfma_f32_16x16x32_bf16 v[72:75], v[226:229], v[210:213], 0
	v_mfma_f32_16x16x32_bf16 v[124:127], v[222:225], v[172:175], v[124:127]
	v_mfma_f32_16x16x32_bf16 v[120:123], v[230:233], v[172:175], v[120:123]
	v_mfma_f32_16x16x32_bf16 v[108:111], v[222:225], v[180:183], v[108:111]
	v_mfma_f32_16x16x32_bf16 v[104:107], v[230:233], v[180:183], v[104:107]
	v_mfma_f32_16x16x32_bf16 v[92:95], v[222:225], v[206:209], v[92:95]
	v_mfma_f32_16x16x32_bf16 v[88:91], v[230:233], v[206:209], v[88:91]
	v_mfma_f32_16x16x32_bf16 v[76:79], v[222:225], v[214:217], v[76:79]
	v_mfma_f32_16x16x32_bf16 v[72:75], v[230:233], v[214:217], v[72:75]
	s_setprio 0
	s_mov_b32 m0, s39
	s_barrier
	ds_read_b128 v[168:171], v150 offset:16384
	ds_read_b128 v[172:175], v150 offset:17408
	ds_read_b128 v[176:179], v150 offset:18432
	ds_read_b128 v[180:183], v150 offset:19456
	ds_read_b128 v[188:191], v150 offset:20480
	ds_read_b128 v[206:209], v150 offset:21504
	ds_read_b128 v[210:213], v150 offset:22528
	global_load_lds_dwordx4 v128, s[42:43]
	s_mov_b32 m0, s51
	ds_read_b128 v[214:217], v150 offset:23552
	global_load_lds_dwordx4 v132, s[42:43]
	s_barrier
	s_waitcnt lgkmcnt(0)
	s_setprio 1
	v_mfma_f32_16x16x32_bf16 v[52:55], v[144:147], v[168:171], 0
	v_mfma_f32_16x16x32_bf16 v[48:51], v[160:163], v[168:171], 0
	v_mfma_f32_16x16x32_bf16 v[36:39], v[144:147], v[176:179], 0
	v_mfma_f32_16x16x32_bf16 v[32:35], v[160:163], v[176:179], 0
	v_mfma_f32_16x16x32_bf16 v[20:23], v[144:147], v[188:191], 0
	v_mfma_f32_16x16x32_bf16 v[16:19], v[160:163], v[188:191], 0
	v_mfma_f32_16x16x32_bf16 v[4:7], v[144:147], v[210:213], 0
	v_mfma_f32_16x16x32_bf16 v[0:3], v[160:163], v[210:213], 0
	v_mfma_f32_16x16x32_bf16 v[52:55], v[156:159], v[172:175], v[52:55]
	v_mfma_f32_16x16x32_bf16 v[48:51], v[164:167], v[172:175], v[48:51]
	v_mfma_f32_16x16x32_bf16 v[36:39], v[156:159], v[180:183], v[36:39]
	v_mfma_f32_16x16x32_bf16 v[32:35], v[164:167], v[180:183], v[32:35]
	v_mfma_f32_16x16x32_bf16 v[20:23], v[156:159], v[206:209], v[20:23]
	v_mfma_f32_16x16x32_bf16 v[16:19], v[164:167], v[206:209], v[16:19]
	v_mfma_f32_16x16x32_bf16 v[4:7], v[156:159], v[214:217], v[4:7]
	v_mfma_f32_16x16x32_bf16 v[0:3], v[164:167], v[214:217], v[0:3]
	s_setprio 0
	s_barrier
; #define PG8_STAGE(bufoff, gbase, voff) do { _Pragma("unroll") for (int _i = 0; _i < 2; ++_i) \
;         __builtin_amdgcn_global_load_lds((const unsigned*)((const char*)(gbase) + (voff)[_i]), (LAS unsigned*)(lds + (bufoff) + ldsw + _i * 8192), 16, 0, 0); } while (0)
; #define PG8_LDA(dst, b, h) do { _Pragma("unroll") for (int m = 0; m < 4; ++m) _Pragma("unroll") for (int k = 0; k < 2; ++k) dst[m][k] = *(const LAS bf16x8*)(lds + PG8_SA(b, h) + aoff + m * 2048 + k * 1024); } while (0)
; #define PG8_LDB(dst, b, h) do { _Pragma("unroll") for (int n = 0; n < 2; ++n) _Pragma("unroll") for (int k = 0; k < 2; ++k) dst[n][k] = *(const LAS bf16x8*)(lds + PG8_SB(b, h) + boff + n * 2048 + k * 1024); } while (0)
; #define PG8_MMA(ai, bj, At, Bt) do { __builtin_amdgcn_s_setprio(1); _Pragma("unroll") for (int m = 0; m < 4; ++m) _Pragma("unroll") for (int n = 0; n < 2; ++n) _Pragma("unroll") for (int k = 0; k < 2; ++k) \
;         acc[ai][bj][m][n] = __builtin_amdgcn_mfma_f32_16x16x32_bf16(Bt[n][k], At[m][k], acc[ai][bj][m][n], 0, 0, 0); __builtin_amdgcn_s_setprio(0); } while (0)
; #define PG8_WAIT_V(n) asm volatile("s_waitcnt vmcnt(" #n ")" ::: "memory")
; #define PG8_WAIT_L(n) asm volatile("s_waitcnt lgkmcnt(" #n ")" ::: "memory")
; #define PG8_BAR __builtin_amdgcn_s_barrier()
; #define PG8_SCHED __builtin_amdgcn_sched_barrier(0)
; template <class Epi, class Sched>
; DI void gemm_phase(LAS unsigned char* lds, const Gemm g, const Sched& S, const Epi& E) {
;     ...
;             PG8_STAGE(PG8_SB(0, 1), b2 + hstep, voffB);
;             PG8_WAIT_V(6); PG8_BAR; PG8_MMA(1, 1, At, B1); PG8_BAR;
;             PG8_LDB(B0, 1, 0); PG8_SCHED; PG8_LDA(At, 1, 0); PG8_STAGE(PG8_SA(0, 1), a2 + hstep, voffA);
;             PG8_WAIT_L(8); PG8_BAR; PG8_WAIT_L(0); PG8_MMA(0, 0, At, B0); PG8_BAR; PG8_SCHED;
;             PG8_LDB(B1, 1, 1); PG8_STAGE(PG8_SB(1, 0), b3, voffB);
;             PG8_BAR; PG8_WAIT_L(0); PG8_MMA(0, 1, At, B1); PG8_BAR;
;             PG8_LDA(At, 1, 1); PG8_STAGE(PG8_SA(1, 0), a3, voffA);
	s_add_i32 s4, s62, s50
	s_mov_b32 s32, s4
	s_mov_b32 m0, s4
	s_add_u32 s0, s40, 0x80000
	s_addc_u32 s1, s41, 0
	global_load_lds_dwordx4 v130, s[0:1]
	s_add_i32 m0, s4, 0x2000
	s_nop 0
	global_load_lds_dwordx4 v134, s[0:1]
	s_waitcnt vmcnt(6)
	s_barrier
	s_setprio 1
	v_mfma_f32_16x16x32_bf16 v[60:63], v[218:221], v[168:171], 0
	v_mfma_f32_16x16x32_bf16 v[56:59], v[226:229], v[168:171], 0
	v_mfma_f32_16x16x32_bf16 v[44:47], v[218:221], v[176:179], 0
	v_mfma_f32_16x16x32_bf16 v[40:43], v[226:229], v[176:179], 0
	v_mfma_f32_16x16x32_bf16 v[28:31], v[218:221], v[188:191], 0
	v_mfma_f32_16x16x32_bf16 v[24:27], v[226:229], v[188:191], 0
	v_mfma_f32_16x16x32_bf16 v[12:15], v[218:221], v[210:213], 0
	v_mfma_f32_16x16x32_bf16 v[8:11], v[226:229], v[210:213], 0
	v_mfma_f32_16x16x32_bf16 v[60:63], v[222:225], v[172:175], v[60:63]
	v_mfma_f32_16x16x32_bf16 v[56:59], v[230:233], v[172:175], v[56:59]
	v_mfma_f32_16x16x32_bf16 v[44:47], v[222:225], v[180:183], v[44:47]
	v_mfma_f32_16x16x32_bf16 v[40:43], v[230:233], v[180:183], v[40:43]
	v_mfma_f32_16x16x32_bf16 v[28:31], v[222:225], v[206:209], v[28:31]
	v_mfma_f32_16x16x32_bf16 v[24:27], v[230:233], v[206:209], v[24:27]
	v_mfma_f32_16x16x32_bf16 v[12:15], v[222:225], v[214:217], v[12:15]
	v_mfma_f32_16x16x32_bf16 v[8:11], v[230:233], v[214:217], v[8:11]
	s_setprio 0
	s_add_i32 s4, 0, 0x18000
	v_add_u32_e32 v202, s4, v148
	s_barrier
	ds_read_b128 v[144:147], v202
	ds_read_b128 v[156:159], v202 offset:1024
	ds_read_b128 v[160:163], v202 offset:2048
	ds_read_b128 v[164:167], v202 offset:3072
	s_add_u32 s0, s42, 0x80000
	s_addc_u32 s1, s43, 0
	s_mov_b32 m0, s52
	ds_read_b128 v[168:171], v150 offset:32768
	ds_read_b128 v[172:175], v150 offset:33792
	ds_read_b128 v[176:179], v150 offset:34816
	ds_read_b128 v[180:183], v150 offset:35840
	ds_read_b128 v[188:191], v150 offset:36864
	ds_read_b128 v[206:209], v150 offset:37888
	ds_read_b128 v[210:213], v150 offset:38912
	global_load_lds_dwordx4 v128, s[0:1]
	s_mov_b32 m0, s53
	ds_read_b128 v[214:217], v150 offset:39936
	global_load_lds_dwordx4 v132, s[0:1]
	s_waitcnt lgkmcnt(8)
	s_barrier
	s_waitcnt lgkmcnt(0)
	s_setprio 1
	v_mfma_f32_16x16x32_bf16 v[116:119], v[144:147], v[168:171], v[116:119]
	v_mfma_f32_16x16x32_bf16 v[112:115], v[160:163], v[168:171], v[112:115]
	v_mfma_f32_16x16x32_bf16 v[100:103], v[144:147], v[176:179], v[100:103]
	v_mfma_f32_16x16x32_bf16 v[96:99], v[160:163], v[176:179], v[96:99]
	v_mfma_f32_16x16x32_bf16 v[84:87], v[144:147], v[188:191], v[84:87]
	v_mfma_f32_16x16x32_bf16 v[80:83], v[160:163], v[188:191], v[80:83]
	v_mfma_f32_16x16x32_bf16 v[68:71], v[144:147], v[210:213], v[68:71]
	v_mfma_f32_16x16x32_bf16 v[64:67], v[160:163], v[210:213], v[64:67]
	v_mfma_f32_16x16x32_bf16 v[116:119], v[156:159], v[172:175], v[116:119]
	v_mfma_f32_16x16x32_bf16 v[112:115], v[164:167], v[172:175], v[112:115]
	v_mfma_f32_16x16x32_bf16 v[100:103], v[156:159], v[180:183], v[100:103]
	v_mfma_f32_16x16x32_bf16 v[96:99], v[164:167], v[180:183], v[96:99]
	v_mfma_f32_16x16x32_bf16 v[84:87], v[156:159], v[206:209], v[84:87]
	v_mfma_f32_16x16x32_bf16 v[80:83], v[164:167], v[206:209], v[80:83]
	v_mfma_f32_16x16x32_bf16 v[68:71], v[156:159], v[214:217], v[68:71]
	v_mfma_f32_16x16x32_bf16 v[64:67], v[164:167], v[214:217], v[64:67]
	s_setprio 0
	s_barrier
	s_add_i32 s5, 0, 0x1c000
	s_add_i32 s0, s4, s50
	s_mov_b32 s69, s0
	v_add_u32_e32 v203, s5, v148
	s_add_i32 m0, s0, 0xffffff80
	ds_read_b128 v[218:221], v203
	ds_read_b128 v[222:225], v203 offset:1024
	ds_read_b128 v[226:229], v203 offset:2048
	global_load_lds_dwordx4 v130, s[40:41] offset:128
	s_add_i32 m0, s0, 0x1f80
	ds_read_b128 v[230:233], v203 offset:3072
	global_load_lds_dwordx4 v134, s[40:41] offset:128
	s_barrier
	s_waitcnt lgkmcnt(0)
	s_setprio 1
	v_mfma_f32_16x16x32_bf16 v[124:127], v[218:221], v[168:171], v[124:127]
	v_mfma_f32_16x16x32_bf16 v[120:123], v[226:229], v[168:171], v[120:123]
	v_mfma_f32_16x16x32_bf16 v[108:111], v[218:221], v[176:179], v[108:111]
	v_mfma_f32_16x16x32_bf16 v[104:107], v[226:229], v[176:179], v[104:107]
	v_mfma_f32_16x16x32_bf16 v[92:95], v[218:221], v[188:191], v[92:95]
	v_mfma_f32_16x16x32_bf16 v[88:91], v[226:229], v[188:191], v[88:91]
	v_mfma_f32_16x16x32_bf16 v[76:79], v[218:221], v[210:213], v[76:79]
	v_mfma_f32_16x16x32_bf16 v[72:75], v[226:229], v[210:213], v[72:75]
	v_mfma_f32_16x16x32_bf16 v[124:127], v[222:225], v[172:175], v[124:127]
	v_mfma_f32_16x16x32_bf16 v[120:123], v[230:233], v[172:175], v[120:123]
	v_mfma_f32_16x16x32_bf16 v[108:111], v[222:225], v[180:183], v[108:111]
	v_mfma_f32_16x16x32_bf16 v[104:107], v[230:233], v[180:183], v[104:107]
	v_mfma_f32_16x16x32_bf16 v[92:95], v[222:225], v[206:209], v[92:95]
	v_mfma_f32_16x16x32_bf16 v[88:91], v[230:233], v[206:209], v[88:91]
	v_mfma_f32_16x16x32_bf16 v[76:79], v[222:225], v[214:217], v[76:79]
	v_mfma_f32_16x16x32_bf16 v[72:75], v[230:233], v[214:217], v[72:75]
	s_setprio 0
	s_add_i32 m0, s57, 0xffffff80
	s_barrier
	ds_read_b128 v[168:171], v150 offset:49152
	ds_read_b128 v[172:175], v150 offset:50176
	ds_read_b128 v[176:179], v150 offset:51200
	ds_read_b128 v[180:183], v150 offset:52224
	ds_read_b128 v[188:191], v150 offset:53248
	ds_read_b128 v[206:209], v150 offset:54272
	ds_read_b128 v[210:213], v150 offset:55296
	global_load_lds_dwordx4 v128, s[42:43] offset:128
	s_add_i32 m0, s58, 0xffffff80
	ds_read_b128 v[214:217], v150 offset:56320
	global_load_lds_dwordx4 v132, s[42:43] offset:128
	s_barrier
; #define PG8_STAGE(bufoff, gbase, voff) do { _Pragma("unroll") for (int _i = 0; _i < 2; ++_i) \
;         __builtin_amdgcn_global_load_lds((const unsigned*)((const char*)(gbase) + (voff)[_i]), (LAS unsigned*)(lds + (bufoff) + ldsw + _i * 8192), 16, 0, 0); } while (0)
; #define PG8_LDA(dst, b, h) do { _Pragma("unroll") for (int m = 0; m < 4; ++m) _Pragma("unroll") for (int k = 0; k < 2; ++k) dst[m][k] = *(const LAS bf16x8*)(lds + PG8_SA(b, h) + aoff + m * 2048 + k * 1024); } while (0)
; #define PG8_LDB(dst, b, h) do { _Pragma("unroll") for (int n = 0; n < 2; ++n) _Pragma("unroll") for (int k = 0; k < 2; ++k) dst[n][k] = *(const LAS bf16x8*)(lds + PG8_SB(b, h) + boff + n * 2048 + k * 1024); } while (0)
; #define PG8_MMA(ai, bj, At, Bt) do { __builtin_amdgcn_s_setprio(1); _Pragma("unroll") for (int m = 0; m < 4; ++m) _Pragma("unroll") for (int n = 0; n < 2; ++n) _Pragma("unroll") for (int k = 0; k < 2; ++k) \
;         acc[ai][bj][m][n] = __builtin_amdgcn_mfma_f32_16x16x32_bf16(Bt[n][k], At[m][k], acc[ai][bj][m][n], 0, 0, 0); __builtin_amdgcn_s_setprio(0); } while (0)
; #define PG8_WAIT_V(n) asm volatile("s_waitcnt vmcnt(" #n ")" ::: "memory")
; #define PG8_WAIT_L(n) asm volatile("s_waitcnt lgkmcnt(" #n ")" ::: "memory")
; #define PG8_BAR __builtin_amdgcn_s_barrier()
; #define PG8_SCHED __builtin_amdgcn_sched_barrier(0)
; template <class Epi, class Sched>
; DI void gemm_phase(LAS unsigned char* lds, const Gemm g, const Sched& S, const Epi& E) {
;     ...
;             PG8_LDB(B0, 0, 0); PG8_SCHED; PG8_LDA(At, 0, 0); PG8_STAGE(PG8_SA(1, 1), a1 + hstep, voffA);
;             PG8_WAIT_L(8); PG8_BAR; PG8_WAIT_L(0); PG8_MMA(0, 0, At, B0); PG8_BAR; PG8_SCHED;
;             PG8_LDB(B1, 0, 1); PG8_STAGE(PG8_SB(0, 0), b2, voffB);
;     ...
;             PG8_BAR; PG8_WAIT_L(0); PG8_MMA(1, 0, At, B0); PG8_BAR; PG8_SCHED;
;             PG8_STAGE(PG8_SB(1, 1), b3 + hstep, voffB);
;             PG8_WAIT_V(6); PG8_BAR; PG8_MMA(1, 1, At, B1); PG8_BAR;
	s_waitcnt lgkmcnt(0)
	s_setprio 1
	v_mfma_f32_16x16x32_bf16 v[52:55], v[144:147], v[168:171], v[52:55]
	v_mfma_f32_16x16x32_bf16 v[48:51], v[160:163], v[168:171], v[48:51]
	v_mfma_f32_16x16x32_bf16 v[36:39], v[144:147], v[176:179], v[36:39]
	v_mfma_f32_16x16x32_bf16 v[32:35], v[160:163], v[176:179], v[32:35]
	v_mfma_f32_16x16x32_bf16 v[20:23], v[144:147], v[188:191], v[20:23]
	v_mfma_f32_16x16x32_bf16 v[16:19], v[160:163], v[188:191], v[16:19]
	v_mfma_f32_16x16x32_bf16 v[4:7], v[144:147], v[210:213], v[4:7]
	v_mfma_f32_16x16x32_bf16 v[0:3], v[160:163], v[210:213], v[0:3]
	v_mfma_f32_16x16x32_bf16 v[52:55], v[156:159], v[172:175], v[52:55]
	v_mfma_f32_16x16x32_bf16 v[48:51], v[164:167], v[172:175], v[48:51]
	v_mfma_f32_16x16x32_bf16 v[36:39], v[156:159], v[180:183], v[36:39]
	v_mfma_f32_16x16x32_bf16 v[32:35], v[164:167], v[180:183], v[32:35]
	v_mfma_f32_16x16x32_bf16 v[20:23], v[156:159], v[206:209], v[20:23]
	v_mfma_f32_16x16x32_bf16 v[16:19], v[164:167], v[206:209], v[16:19]
	v_mfma_f32_16x16x32_bf16 v[4:7], v[156:159], v[214:217], v[4:7]
	v_mfma_f32_16x16x32_bf16 v[0:3], v[164:167], v[214:217], v[0:3]
	s_setprio 0
	s_barrier
	s_add_i32 s4, s5, s50
	s_mov_b32 s70, s4
	s_mov_b32 m0, s4
	s_add_u32 s0, s40, 0x80080
	s_addc_u32 s1, s41, 0
	global_load_lds_dwordx4 v130, s[0:1]
	s_add_i32 m0, s4, 0x2000
	s_nop 0
	global_load_lds_dwordx4 v134, s[0:1]
	s_waitcnt vmcnt(6)
	s_barrier
	s_setprio 1
	v_mfma_f32_16x16x32_bf16 v[60:63], v[218:221], v[168:171], v[60:63]
	v_mfma_f32_16x16x32_bf16 v[56:59], v[226:229], v[168:171], v[56:59]
	v_mfma_f32_16x16x32_bf16 v[44:47], v[218:221], v[176:179], v[44:47]
	v_mfma_f32_16x16x32_bf16 v[40:43], v[226:229], v[176:179], v[40:43]
	v_mfma_f32_16x16x32_bf16 v[28:31], v[218:221], v[188:191], v[28:31]
	v_mfma_f32_16x16x32_bf16 v[24:27], v[226:229], v[188:191], v[24:27]
	v_mfma_f32_16x16x32_bf16 v[12:15], v[218:221], v[210:213], v[12:15]
	v_mfma_f32_16x16x32_bf16 v[8:11], v[226:229], v[210:213], v[8:11]
	v_mfma_f32_16x16x32_bf16 v[60:63], v[222:225], v[172:175], v[60:63]
	v_mfma_f32_16x16x32_bf16 v[56:59], v[230:233], v[172:175], v[56:59]
	v_mfma_f32_16x16x32_bf16 v[44:47], v[222:225], v[180:183], v[44:47]
	v_mfma_f32_16x16x32_bf16 v[40:43], v[230:233], v[180:183], v[40:43]
	v_mfma_f32_16x16x32_bf16 v[28:31], v[222:225], v[206:209], v[28:31]
	v_mfma_f32_16x16x32_bf16 v[24:27], v[230:233], v[206:209], v[24:27]
	v_mfma_f32_16x16x32_bf16 v[12:15], v[222:225], v[214:217], v[12:15]
	v_mfma_f32_16x16x32_bf16 v[8:11], v[230:233], v[214:217], v[8:11]
	s_setprio 0
	s_add_i32 s68, s68, 2
	s_add_u32 s8, s8, 0x100
	s_addc_u32 s9, s9, 0
	s_add_u32 s66, s66, 0x100
	s_addc_u32 s67, s67, 0
	s_cmp_gt_u32 s68, 29
	s_barrier
	s_cbranch_scc0 .LBB0_1668
	s_branch .Lpeel_done_1668
.LBB0_1668:
	ds_read_b128 v[144:147], v149
	ds_read_b128 v[156:159], v149 offset:1024
	ds_read_b128 v[160:163], v149 offset:2048
	ds_read_b128 v[164:167], v149 offset:3072
	s_add_u32 s0, s8, 0xfff80080
	s_addc_u32 s1, s9, -1
	s_cmp_eq_u32 s68, 28
	s_cselect_b32 s43, s29, s1
	s_cselect_b32 s42, s35, s0
	s_cselect_b32 s41, s19, s67
	s_cselect_b32 s40, s65, s66
	s_add_i32 m0, s39, 0xc000
	ds_read_b128 v[168:171], v150
	ds_read_b128 v[172:175], v150 offset:1024
	ds_read_b128 v[176:179], v150 offset:2048
	ds_read_b128 v[180:183], v150 offset:3072
	ds_read_b128 v[188:191], v150 offset:4096
	ds_read_b128 v[206:209], v150 offset:5120
	ds_read_b128 v[210:213], v150 offset:6144
	global_load_lds_dwordx4 v136, s[8:9]
	s_add_i32 m0, s39, 0xe000
	ds_read_b128 v[214:217], v150 offset:7168
	global_load_lds_dwordx4 v138, s[8:9]
	s_waitcnt lgkmcnt(8)
	s_barrier
	s_waitcnt lgkmcnt(0)
	s_setprio 1
	v_mfma_f32_16x16x32_bf16 v[116:119], v[144:147], v[168:171], v[116:119]
	v_mfma_f32_16x16x32_bf16 v[112:115], v[160:163], v[168:171], v[112:115]
	v_mfma_f32_16x16x32_bf16 v[100:103], v[144:147], v[176:179], v[100:103]
	v_mfma_f32_16x16x32_bf16 v[96:99], v[160:163], v[176:179], v[96:99]
	v_mfma_f32_16x16x32_bf16 v[84:87], v[144:147], v[188:191], v[84:87]
	v_mfma_f32_16x16x32_bf16 v[80:83], v[160:163], v[188:191], v[80:83]
	v_mfma_f32_16x16x32_bf16 v[68:71], v[144:147], v[210:213], v[68:71]
	v_mfma_f32_16x16x32_bf16 v[64:67], v[160:163], v[210:213], v[64:67]
	v_mfma_f32_16x16x32_bf16 v[116:119], v[156:159], v[172:175], v[116:119]
	v_mfma_f32_16x16x32_bf16 v[112:115], v[164:167], v[172:175], v[112:115]
	v_mfma_f32_16x16x32_bf16 v[100:103], v[156:159], v[180:183], v[100:103]
	v_mfma_f32_16x16x32_bf16 v[96:99], v[164:167], v[180:183], v[96:99]
	v_mfma_f32_16x16x32_bf16 v[84:87], v[156:159], v[206:209], v[84:87]
	v_mfma_f32_16x16x32_bf16 v[80:83], v[164:167], v[206:209], v[80:83]
	v_mfma_f32_16x16x32_bf16 v[68:71], v[156:159], v[214:217], v[68:71]
	v_mfma_f32_16x16x32_bf16 v[64:67], v[164:167], v[214:217], v[64:67]
	s_setprio 0
	s_barrier
	s_mov_b32 m0, s17
	ds_read_b128 v[218:221], v151
	ds_read_b128 v[222:225], v151 offset:1024
	ds_read_b128 v[226:229], v151 offset:2048
	global_load_lds_dwordx4 v130, s[40:41]
	s_add_i32 m0, s17, 0x2000
	ds_read_b128 v[230:233], v151 offset:3072
	global_load_lds_dwordx4 v134, s[40:41]
	s_barrier
; #define PG8_STAGE(bufoff, gbase, voff) do { _Pragma("unroll") for (int _i = 0; _i < 2; ++_i) \
;         __builtin_amdgcn_global_load_lds((const unsigned*)((const char*)(gbase) + (voff)[_i]), (LAS unsigned*)(lds + (bufoff) + ldsw + _i * 8192), 16, 0, 0); } while (0)
; #define PG8_LDA(dst, b, h) do { _Pragma("unroll") for (int m = 0; m < 4; ++m) _Pragma("unroll") for (int k = 0; k < 2; ++k) dst[m][k] = *(const LAS bf16x8*)(lds + PG8_SA(b, h) + aoff + m * 2048 + k * 1024); } while (0)
; #define PG8_LDB(dst, b, h) do { _Pragma("unroll") for (int n = 0; n < 2; ++n) _Pragma("unroll") for (int k = 0; k < 2; ++k) dst[n][k] = *(const LAS bf16x8*)(lds + PG8_SB(b, h) + boff + n * 2048 + k * 1024); } while (0)
; #define PG8_MMA(ai, bj, At, Bt) do { __builtin_amdgcn_s_setprio(1); _Pragma("unroll") for (int m = 0; m < 4; ++m) _Pragma("unroll") for (int n = 0; n < 2; ++n) _Pragma("unroll") for (int k = 0; k < 2; ++k) \
;         acc[ai][bj][m][n] = __builtin_amdgcn_mfma_f32_16x16x32_bf16(Bt[n][k], At[m][k], acc[ai][bj][m][n], 0, 0, 0); __builtin_amdgcn_s_setprio(0); } while (0)
; #define PG8_WAIT_V(n) asm volatile("s_waitcnt vmcnt(" #n ")" ::: "memory")
; #define PG8_WAIT_L(n) asm volatile("s_waitcnt lgkmcnt(" #n ")" ::: "memory")
; #define PG8_BAR __builtin_amdgcn_s_barrier()
; #define PG8_SCHED __builtin_amdgcn_sched_barrier(0)
; template <class Epi, class Sched>
; DI void gemm_phase(LAS unsigned char* lds, const Gemm g, const Sched& S, const Epi& E) {
;     ...
;             PG8_BAR; PG8_WAIT_L(0); PG8_MMA(0, 1, At, B1); PG8_BAR;
;             PG8_LDA(At, 0, 1); PG8_STAGE(PG8_SA(0, 0), a2, voffA);
;             PG8_BAR; PG8_WAIT_L(0); PG8_MMA(1, 0, At, B0); PG8_BAR; PG8_SCHED;
;             PG8_STAGE(PG8_SB(0, 1), b2 + hstep, voffB);
;             PG8_WAIT_V(6); PG8_BAR; PG8_MMA(1, 1, At, B1); PG8_BAR;
;             PG8_LDB(B0, 1, 0); PG8_SCHED; PG8_LDA(At, 1, 0); PG8_STAGE(PG8_SA(0, 1), a2 + hstep, voffA);
	s_waitcnt lgkmcnt(0)
	s_setprio 1
	v_mfma_f32_16x16x32_bf16 v[124:127], v[218:221], v[168:171], v[124:127]
	v_mfma_f32_16x16x32_bf16 v[120:123], v[226:229], v[168:171], v[120:123]
	v_mfma_f32_16x16x32_bf16 v[108:111], v[218:221], v[176:179], v[108:111]
	v_mfma_f32_16x16x32_bf16 v[104:107], v[226:229], v[176:179], v[104:107]
	v_mfma_f32_16x16x32_bf16 v[92:95], v[218:221], v[188:191], v[92:95]
	v_mfma_f32_16x16x32_bf16 v[88:91], v[226:229], v[188:191], v[88:91]
	v_mfma_f32_16x16x32_bf16 v[76:79], v[218:221], v[210:213], v[76:79]
	v_mfma_f32_16x16x32_bf16 v[72:75], v[226:229], v[210:213], v[72:75]
	v_mfma_f32_16x16x32_bf16 v[124:127], v[222:225], v[172:175], v[124:127]
	v_mfma_f32_16x16x32_bf16 v[120:123], v[230:233], v[172:175], v[120:123]
	v_mfma_f32_16x16x32_bf16 v[108:111], v[222:225], v[180:183], v[108:111]
	v_mfma_f32_16x16x32_bf16 v[104:107], v[230:233], v[180:183], v[104:107]
	v_mfma_f32_16x16x32_bf16 v[92:95], v[222:225], v[206:209], v[92:95]
	v_mfma_f32_16x16x32_bf16 v[88:91], v[230:233], v[206:209], v[88:91]
	v_mfma_f32_16x16x32_bf16 v[76:79], v[222:225], v[214:217], v[76:79]
	v_mfma_f32_16x16x32_bf16 v[72:75], v[230:233], v[214:217], v[72:75]
	s_setprio 0
	s_mov_b32 m0, s39
	s_barrier
	ds_read_b128 v[168:171], v150 offset:16384
	ds_read_b128 v[172:175], v150 offset:17408
	ds_read_b128 v[176:179], v150 offset:18432
	ds_read_b128 v[180:183], v150 offset:19456
	ds_read_b128 v[188:191], v150 offset:20480
	ds_read_b128 v[206:209], v150 offset:21504
	ds_read_b128 v[210:213], v150 offset:22528
	global_load_lds_dwordx4 v128, s[42:43]
	s_mov_b32 m0, s51
	ds_read_b128 v[214:217], v150 offset:23552
	global_load_lds_dwordx4 v132, s[42:43]
	s_barrier
	s_waitcnt lgkmcnt(0)
	s_setprio 1
	v_mfma_f32_16x16x32_bf16 v[52:55], v[144:147], v[168:171], v[52:55]
	v_mfma_f32_16x16x32_bf16 v[48:51], v[160:163], v[168:171], v[48:51]
	v_mfma_f32_16x16x32_bf16 v[36:39], v[144:147], v[176:179], v[36:39]
	v_mfma_f32_16x16x32_bf16 v[32:35], v[160:163], v[176:179], v[32:35]
	v_mfma_f32_16x16x32_bf16 v[20:23], v[144:147], v[188:191], v[20:23]
	v_mfma_f32_16x16x32_bf16 v[16:19], v[160:163], v[188:191], v[16:19]
	v_mfma_f32_16x16x32_bf16 v[4:7], v[144:147], v[210:213], v[4:7]
	v_mfma_f32_16x16x32_bf16 v[0:3], v[160:163], v[210:213], v[0:3]
	v_mfma_f32_16x16x32_bf16 v[52:55], v[156:159], v[172:175], v[52:55]
	v_mfma_f32_16x16x32_bf16 v[48:51], v[164:167], v[172:175], v[48:51]
	v_mfma_f32_16x16x32_bf16 v[36:39], v[156:159], v[180:183], v[36:39]
	v_mfma_f32_16x16x32_bf16 v[32:35], v[164:167], v[180:183], v[32:35]
	v_mfma_f32_16x16x32_bf16 v[20:23], v[156:159], v[206:209], v[20:23]
	v_mfma_f32_16x16x32_bf16 v[16:19], v[164:167], v[206:209], v[16:19]
	v_mfma_f32_16x16x32_bf16 v[4:7], v[156:159], v[214:217], v[4:7]
	v_mfma_f32_16x16x32_bf16 v[0:3], v[164:167], v[214:217], v[0:3]
	s_setprio 0
	s_barrier
	s_mov_b32 m0, s32
	s_add_u32 s0, s40, 0x80000
	s_addc_u32 s1, s41, 0
	global_load_lds_dwordx4 v130, s[0:1]
	s_add_i32 m0, s32, 0x2000
	s_nop 0
	global_load_lds_dwordx4 v134, s[0:1]
	s_waitcnt vmcnt(6)
	s_barrier
	s_setprio 1
	v_mfma_f32_16x16x32_bf16 v[60:63], v[218:221], v[168:171], v[60:63]
	v_mfma_f32_16x16x32_bf16 v[56:59], v[226:229], v[168:171], v[56:59]
	v_mfma_f32_16x16x32_bf16 v[44:47], v[218:221], v[176:179], v[44:47]
	v_mfma_f32_16x16x32_bf16 v[40:43], v[226:229], v[176:179], v[40:43]
	v_mfma_f32_16x16x32_bf16 v[28:31], v[218:221], v[188:191], v[28:31]
	v_mfma_f32_16x16x32_bf16 v[24:27], v[226:229], v[188:191], v[24:27]
	v_mfma_f32_16x16x32_bf16 v[12:15], v[218:221], v[210:213], v[12:15]
	v_mfma_f32_16x16x32_bf16 v[8:11], v[226:229], v[210:213], v[8:11]
	v_mfma_f32_16x16x32_bf16 v[60:63], v[222:225], v[172:175], v[60:63]
	v_mfma_f32_16x16x32_bf16 v[56:59], v[230:233], v[172:175], v[56:59]
	v_mfma_f32_16x16x32_bf16 v[44:47], v[222:225], v[180:183], v[44:47]
	v_mfma_f32_16x16x32_bf16 v[40:43], v[230:233], v[180:183], v[40:43]
	v_mfma_f32_16x16x32_bf16 v[28:31], v[222:225], v[206:209], v[28:31]
	v_mfma_f32_16x16x32_bf16 v[24:27], v[230:233], v[206:209], v[24:27]
	v_mfma_f32_16x16x32_bf16 v[12:15], v[222:225], v[214:217], v[12:15]
	v_mfma_f32_16x16x32_bf16 v[8:11], v[230:233], v[214:217], v[8:11]
	s_setprio 0
	s_add_i32 s4, 0, 0x18000
	s_barrier
	ds_read_b128 v[144:147], v202
	ds_read_b128 v[156:159], v202 offset:1024
	ds_read_b128 v[160:163], v202 offset:2048
	ds_read_b128 v[164:167], v202 offset:3072
	s_add_u32 s0, s42, 0x80000
	s_addc_u32 s1, s43, 0
	s_mov_b32 m0, s52
	ds_read_b128 v[168:171], v150 offset:32768
	ds_read_b128 v[172:175], v150 offset:33792
	ds_read_b128 v[176:179], v150 offset:34816
	ds_read_b128 v[180:183], v150 offset:35840
	ds_read_b128 v[188:191], v150 offset:36864
	ds_read_b128 v[206:209], v150 offset:37888
	ds_read_b128 v[210:213], v150 offset:38912
	global_load_lds_dwordx4 v128, s[0:1]
	s_mov_b32 m0, s53
	ds_read_b128 v[214:217], v150 offset:39936
	global_load_lds_dwordx4 v132, s[0:1]
	s_waitcnt lgkmcnt(8)
	s_barrier
; #define PG8_STAGE(bufoff, gbase, voff) do { _Pragma("unroll") for (int _i = 0; _i < 2; ++_i) \
;         __builtin_amdgcn_global_load_lds((const unsigned*)((const char*)(gbase) + (voff)[_i]), (LAS unsigned*)(lds + (bufoff) + ldsw + _i * 8192), 16, 0, 0); } while (0)
; #define PG8_LDA(dst, b, h) do { _Pragma("unroll") for (int m = 0; m < 4; ++m) _Pragma("unroll") for (int k = 0; k < 2; ++k) dst[m][k] = *(const LAS bf16x8*)(lds + PG8_SA(b, h) + aoff + m * 2048 + k * 1024); } while (0)
; #define PG8_LDB(dst, b, h) do { _Pragma("unroll") for (int n = 0; n < 2; ++n) _Pragma("unroll") for (int k = 0; k < 2; ++k) dst[n][k] = *(const LAS bf16x8*)(lds + PG8_SB(b, h) + boff + n * 2048 + k * 1024); } while (0)
; #define PG8_MMA(ai, bj, At, Bt) do { __builtin_amdgcn_s_setprio(1); _Pragma("unroll") for (int m = 0; m < 4; ++m) _Pragma("unroll") for (int n = 0; n < 2; ++n) _Pragma("unroll") for (int k = 0; k < 2; ++k) \
;         acc[ai][bj][m][n] = __builtin_amdgcn_mfma_f32_16x16x32_bf16(Bt[n][k], At[m][k], acc[ai][bj][m][n], 0, 0, 0); __builtin_amdgcn_s_setprio(0); } while (0)
; #define PG8_WAIT_V(n) asm volatile("s_waitcnt vmcnt(" #n ")" ::: "memory")
; #define PG8_WAIT_L(n) asm volatile("s_waitcnt lgkmcnt(" #n ")" ::: "memory")
; #define PG8_BAR __builtin_amdgcn_s_barrier()
; #define PG8_SCHED __builtin_amdgcn_sched_barrier(0)
; template <class Epi, class Sched>
; DI void gemm_phase(LAS unsigned char* lds, const Gemm g, const Sched& S, const Epi& E) {
;     ...
;             PG8_WAIT_L(8); PG8_BAR; PG8_WAIT_L(0); PG8_MMA(0, 0, At, B0); PG8_BAR; PG8_SCHED;
;             PG8_LDB(B1, 1, 1); PG8_STAGE(PG8_SB(1, 0), b3, voffB);
;             PG8_BAR; PG8_WAIT_L(0); PG8_MMA(0, 1, At, B1); PG8_BAR;
;             PG8_LDA(At, 1, 1); PG8_STAGE(PG8_SA(1, 0), a3, voffA);
;             PG8_BAR; PG8_WAIT_L(0); PG8_MMA(1, 0, At, B0); PG8_BAR; PG8_SCHED;
;             PG8_STAGE(PG8_SB(1, 1), b3 + hstep, voffB);
;             PG8_WAIT_V(6); PG8_BAR; PG8_MMA(1, 1, At, B1); PG8_BAR;
	s_waitcnt lgkmcnt(0)
	s_setprio 1
	v_mfma_f32_16x16x32_bf16 v[116:119], v[144:147], v[168:171], v[116:119]
	v_mfma_f32_16x16x32_bf16 v[112:115], v[160:163], v[168:171], v[112:115]
	v_mfma_f32_16x16x32_bf16 v[100:103], v[144:147], v[176:179], v[100:103]
	v_mfma_f32_16x16x32_bf16 v[96:99], v[160:163], v[176:179], v[96:99]
	v_mfma_f32_16x16x32_bf16 v[84:87], v[144:147], v[188:191], v[84:87]
	v_mfma_f32_16x16x32_bf16 v[80:83], v[160:163], v[188:191], v[80:83]
	v_mfma_f32_16x16x32_bf16 v[68:71], v[144:147], v[210:213], v[68:71]
	v_mfma_f32_16x16x32_bf16 v[64:67], v[160:163], v[210:213], v[64:67]
	v_mfma_f32_16x16x32_bf16 v[116:119], v[156:159], v[172:175], v[116:119]
	v_mfma_f32_16x16x32_bf16 v[112:115], v[164:167], v[172:175], v[112:115]
	v_mfma_f32_16x16x32_bf16 v[100:103], v[156:159], v[180:183], v[100:103]
	v_mfma_f32_16x16x32_bf16 v[96:99], v[164:167], v[180:183], v[96:99]
	v_mfma_f32_16x16x32_bf16 v[84:87], v[156:159], v[206:209], v[84:87]
	v_mfma_f32_16x16x32_bf16 v[80:83], v[164:167], v[206:209], v[80:83]
	v_mfma_f32_16x16x32_bf16 v[68:71], v[156:159], v[214:217], v[68:71]
	v_mfma_f32_16x16x32_bf16 v[64:67], v[164:167], v[214:217], v[64:67]
	s_setprio 0
	s_barrier
	s_add_i32 s5, 0, 0x1c000
	s_add_i32 m0, s69, 0xffffff80
	ds_read_b128 v[218:221], v203
	ds_read_b128 v[222:225], v203 offset:1024
	ds_read_b128 v[226:229], v203 offset:2048
	global_load_lds_dwordx4 v130, s[40:41] offset:128
	s_add_i32 m0, s69, 0x1f80
	ds_read_b128 v[230:233], v203 offset:3072
	global_load_lds_dwordx4 v134, s[40:41] offset:128
	s_barrier
	s_waitcnt lgkmcnt(0)
	s_setprio 1
	v_mfma_f32_16x16x32_bf16 v[124:127], v[218:221], v[168:171], v[124:127]
	v_mfma_f32_16x16x32_bf16 v[120:123], v[226:229], v[168:171], v[120:123]
	v_mfma_f32_16x16x32_bf16 v[108:111], v[218:221], v[176:179], v[108:111]
	v_mfma_f32_16x16x32_bf16 v[104:107], v[226:229], v[176:179], v[104:107]
	v_mfma_f32_16x16x32_bf16 v[92:95], v[218:221], v[188:191], v[92:95]
	v_mfma_f32_16x16x32_bf16 v[88:91], v[226:229], v[188:191], v[88:91]
	v_mfma_f32_16x16x32_bf16 v[76:79], v[218:221], v[210:213], v[76:79]
	v_mfma_f32_16x16x32_bf16 v[72:75], v[226:229], v[210:213], v[72:75]
	v_mfma_f32_16x16x32_bf16 v[124:127], v[222:225], v[172:175], v[124:127]
	v_mfma_f32_16x16x32_bf16 v[120:123], v[230:233], v[172:175], v[120:123]
	v_mfma_f32_16x16x32_bf16 v[108:111], v[222:225], v[180:183], v[108:111]
	v_mfma_f32_16x16x32_bf16 v[104:107], v[230:233], v[180:183], v[104:107]
	v_mfma_f32_16x16x32_bf16 v[92:95], v[222:225], v[206:209], v[92:95]
	v_mfma_f32_16x16x32_bf16 v[88:91], v[230:233], v[206:209], v[88:91]
	v_mfma_f32_16x16x32_bf16 v[76:79], v[222:225], v[214:217], v[76:79]
	v_mfma_f32_16x16x32_bf16 v[72:75], v[230:233], v[214:217], v[72:75]
	s_setprio 0
	s_add_i32 m0, s57, 0xffffff80
	s_barrier
	ds_read_b128 v[168:171], v150 offset:49152
	ds_read_b128 v[172:175], v150 offset:50176
	ds_read_b128 v[176:179], v150 offset:51200
	ds_read_b128 v[180:183], v150 offset:52224
	ds_read_b128 v[188:191], v150 offset:53248
	ds_read_b128 v[206:209], v150 offset:54272
	ds_read_b128 v[210:213], v150 offset:55296
	global_load_lds_dwordx4 v128, s[42:43] offset:128
	s_add_i32 m0, s58, 0xffffff80
	ds_read_b128 v[214:217], v150 offset:56320
	global_load_lds_dwordx4 v132, s[42:43] offset:128
	s_barrier
	s_waitcnt lgkmcnt(0)
	s_setprio 1
	v_mfma_f32_16x16x32_bf16 v[52:55], v[144:147], v[168:171], v[52:55]
	v_mfma_f32_16x16x32_bf16 v[48:51], v[160:163], v[168:171], v[48:51]
	v_mfma_f32_16x16x32_bf16 v[36:39], v[144:147], v[176:179], v[36:39]
	v_mfma_f32_16x16x32_bf16 v[32:35], v[160:163], v[176:179], v[32:35]
	v_mfma_f32_16x16x32_bf16 v[20:23], v[144:147], v[188:191], v[20:23]
	v_mfma_f32_16x16x32_bf16 v[16:19], v[160:163], v[188:191], v[16:19]
	v_mfma_f32_16x16x32_bf16 v[4:7], v[144:147], v[210:213], v[4:7]
	v_mfma_f32_16x16x32_bf16 v[0:3], v[160:163], v[210:213], v[0:3]
	v_mfma_f32_16x16x32_bf16 v[52:55], v[156:159], v[172:175], v[52:55]
	v_mfma_f32_16x16x32_bf16 v[48:51], v[164:167], v[172:175], v[48:51]
	v_mfma_f32_16x16x32_bf16 v[36:39], v[156:159], v[180:183], v[36:39]
	v_mfma_f32_16x16x32_bf16 v[32:35], v[164:167], v[180:183], v[32:35]
	v_mfma_f32_16x16x32_bf16 v[20:23], v[156:159], v[206:209], v[20:23]
	v_mfma_f32_16x16x32_bf16 v[16:19], v[164:167], v[206:209], v[16:19]
	v_mfma_f32_16x16x32_bf16 v[4:7], v[156:159], v[214:217], v[4:7]
	v_mfma_f32_16x16x32_bf16 v[0:3], v[164:167], v[214:217], v[0:3]
	s_setprio 0
	s_barrier
	s_mov_b32 m0, s70
	s_add_u32 s0, s40, 0x80080
	s_addc_u32 s1, s41, 0
	global_load_lds_dwordx4 v130, s[0:1]
	s_add_i32 m0, s70, 0x2000
	s_nop 0
	global_load_lds_dwordx4 v134, s[0:1]
	s_waitcnt vmcnt(6)
	s_barrier
	s_setprio 1
	v_mfma_f32_16x16x32_bf16 v[60:63], v[218:221], v[168:171], v[60:63]
	v_mfma_f32_16x16x32_bf16 v[56:59], v[226:229], v[168:171], v[56:59]
	v_mfma_f32_16x16x32_bf16 v[44:47], v[218:221], v[176:179], v[44:47]
	v_mfma_f32_16x16x32_bf16 v[40:43], v[226:229], v[176:179], v[40:43]
	v_mfma_f32_16x16x32_bf16 v[28:31], v[218:221], v[188:191], v[28:31]
	v_mfma_f32_16x16x32_bf16 v[24:27], v[226:229], v[188:191], v[24:27]
	v_mfma_f32_16x16x32_bf16 v[12:15], v[218:221], v[210:213], v[12:15]
	v_mfma_f32_16x16x32_bf16 v[8:11], v[226:229], v[210:213], v[8:11]
	v_mfma_f32_16x16x32_bf16 v[60:63], v[222:225], v[172:175], v[60:63]
	v_mfma_f32_16x16x32_bf16 v[56:59], v[230:233], v[172:175], v[56:59]
	v_mfma_f32_16x16x32_bf16 v[44:47], v[222:225], v[180:183], v[44:47]
	v_mfma_f32_16x16x32_bf16 v[40:43], v[230:233], v[180:183], v[40:43]
	v_mfma_f32_16x16x32_bf16 v[28:31], v[222:225], v[206:209], v[28:31]
	v_mfma_f32_16x16x32_bf16 v[24:27], v[230:233], v[206:209], v[24:27]
	v_mfma_f32_16x16x32_bf16 v[12:15], v[222:225], v[214:217], v[12:15]
	v_mfma_f32_16x16x32_bf16 v[8:11], v[230:233], v[214:217], v[8:11]
	s_setprio 0
	s_add_i32 s68, s68, 2
	s_add_u32 s8, s8, 0x100
	s_addc_u32 s9, s9, 0
	s_add_u32 s66, s66, 0x100
	s_addc_u32 s67, s67, 0
	s_cmp_gt_u32 s68, 29
	s_barrier
	s_cbranch_scc0 .LBB0_1668

; #define PG8_STAGE(bufoff, gbase, voff) do { _Pragma("unroll") for (int _i = 0; _i < 2; ++_i) \
;         __builtin_amdgcn_global_load_lds((const unsigned*)((const char*)(gbase) + (voff)[_i]), (LAS unsigned*)(lds + (bufoff) + ldsw + _i * 8192), 16, 0, 0); } while (0)
; #define PG8_LDA(dst, b, h) do { _Pragma("unroll") for (int m = 0; m < 4; ++m) _Pragma("unroll") for (int k = 0; k < 2; ++k) dst[m][k] = *(const LAS bf16x8*)(lds + PG8_SA(b, h) + aoff + m * 2048 + k * 1024); } while (0)
; #define PG8_LDB(dst, b, h) do { _Pragma("unroll") for (int n = 0; n < 2; ++n) _Pragma("unroll") for (int k = 0; k < 2; ++k) dst[n][k] = *(const LAS bf16x8*)(lds + PG8_SB(b, h) + boff + n * 2048 + k * 1024); } while (0)
; #define PG8_MMA(ai, bj, At, Bt) do { __builtin_amdgcn_s_setprio(1); _Pragma("unroll") for (int m = 0; m < 4; ++m) _Pragma("unroll") for (int n = 0; n < 2; ++n) _Pragma("unroll") for (int k = 0; k < 2; ++k) \
;         acc[ai][bj][m][n] = __builtin_amdgcn_mfma_f32_16x16x32_bf16(Bt[n][k], At[m][k], acc[ai][bj][m][n], 0, 0, 0); __builtin_amdgcn_s_setprio(0); } while (0)
; #define PG8_WAIT_V(n) asm volatile("s_waitcnt vmcnt(" #n ")" ::: "memory")
; #define PG8_WAIT_L(n) asm volatile("s_waitcnt lgkmcnt(" #n ")" ::: "memory")
; #define PG8_BAR __builtin_amdgcn_s_barrier()
; #define PG8_SCHED __builtin_amdgcn_sched_barrier(0)
; template <class Epi, class Sched>
; DI void gemm_phase(LAS unsigned char* lds, const Gemm g, const Sched& S, const Epi& E) {
;     ...
;             const char* a2 = last ? nA : cA + (size_t)(t + 2) * kstep; const char* b2 = last ? nB : cB + (size_t)(t + 2) * kstep;
;             const char* a3 = a2 + kstep; const char* b3 = b2 + kstep;
;             PG8_LDB(B0, 0, 0); PG8_SCHED; PG8_LDA(At, 0, 0); PG8_STAGE(PG8_SA(1, 1), a1 + hstep, voffA);
;             PG8_WAIT_L(8); PG8_BAR; PG8_WAIT_L(0); PG8_MMA(0, 0, At, B0); PG8_BAR; PG8_SCHED;
;             PG8_LDB(B1, 0, 1); PG8_STAGE(PG8_SB(0, 0), b2, voffB);
;             PG8_BAR; PG8_WAIT_L(0); PG8_MMA(0, 1, At, B1); PG8_BAR;
;             PG8_LDA(At, 0, 1); PG8_STAGE(PG8_SA(0, 0), a2, voffA);
;             PG8_BAR; PG8_WAIT_L(0); PG8_MMA(1, 0, At, B0); PG8_BAR; PG8_SCHED;
;             PG8_STAGE(PG8_SB(0, 1), b2 + hstep, voffB);
;             PG8_WAIT_V(6); PG8_BAR; PG8_MMA(1, 1, At, B1); PG8_BAR;
.LBB0_1745:
	s_add_u32 s38, s38, 0x160080
	s_addc_u32 s39, s39, 0
	s_add_u32 s35, s40, 0x100
	v_mov_b32_e32 v0, 0
	s_addc_u32 s67, s41, 0
	s_mov_b32 s68, -2
	s_waitcnt lgkmcnt(0)
	ds_read_b128 v[144:147], v155
	ds_read_b128 v[160:163], v155 offset:1024
	ds_read_b128 v[164:167], v155 offset:2048
	ds_read_b128 v[168:171], v155 offset:3072
	s_add_u32 s0, s38, 0xffea0080
	s_addc_u32 s1, s39, -1
	s_cmpk_eq_i32 s68, 0x54
	s_cselect_b32 s43, s9, s1
	s_cselect_b32 s42, s8, s0
	s_cselect_b32 s41, s11, s67
	s_cselect_b32 s40, s10, s35
	s_add_i32 m0, s52, 0xc000
	ds_read_b128 v[172:175], v156
	ds_read_b128 v[176:179], v156 offset:1024
	ds_read_b128 v[180:183], v156 offset:2048
	ds_read_b128 v[188:191], v156 offset:3072
	ds_read_b128 v[206:209], v156 offset:4096
	ds_read_b128 v[210:213], v156 offset:5120
	ds_read_b128 v[214:217], v156 offset:6144
	global_load_lds_dwordx4 v136, s[38:39]
	s_add_i32 m0, s52, 0xe000
	ds_read_b128 v[218:221], v156 offset:7168
	global_load_lds_dwordx4 v138, s[38:39]
	s_waitcnt lgkmcnt(8)
	s_barrier
	s_waitcnt lgkmcnt(0)
	s_setprio 1
	v_mfma_f32_16x16x32_bf16 v[124:127], v[144:147], v[172:175], 0
	v_mfma_f32_16x16x32_bf16 v[120:123], v[164:167], v[172:175], 0
	v_mfma_f32_16x16x32_bf16 v[108:111], v[144:147], v[180:183], 0
	v_mfma_f32_16x16x32_bf16 v[104:107], v[164:167], v[180:183], 0
	v_mfma_f32_16x16x32_bf16 v[92:95], v[144:147], v[206:209], 0
	v_mfma_f32_16x16x32_bf16 v[88:91], v[164:167], v[206:209], 0
	v_mfma_f32_16x16x32_bf16 v[76:79], v[144:147], v[214:217], 0
	v_mfma_f32_16x16x32_bf16 v[72:75], v[164:167], v[214:217], 0
	v_mfma_f32_16x16x32_bf16 v[124:127], v[160:163], v[176:179], v[124:127]
	v_mfma_f32_16x16x32_bf16 v[120:123], v[168:171], v[176:179], v[120:123]
	v_mfma_f32_16x16x32_bf16 v[108:111], v[160:163], v[188:191], v[108:111]
	v_mfma_f32_16x16x32_bf16 v[104:107], v[168:171], v[188:191], v[104:107]
	v_mfma_f32_16x16x32_bf16 v[92:95], v[160:163], v[210:213], v[92:95]
	v_mfma_f32_16x16x32_bf16 v[88:91], v[168:171], v[210:213], v[88:91]
	v_mfma_f32_16x16x32_bf16 v[76:79], v[160:163], v[218:221], v[76:79]
	v_mfma_f32_16x16x32_bf16 v[72:75], v[168:171], v[218:221], v[72:75]
	s_setprio 0
	s_barrier
	s_add_i32 s0, s61, s51
	s_mov_b32 s32, s0
	s_mov_b32 m0, s0
	ds_read_b128 v[222:225], v157
	ds_read_b128 v[226:229], v157 offset:1024
	ds_read_b128 v[230:233], v157 offset:2048
	global_load_lds_dwordx4 v130, s[40:41]
	s_add_i32 m0, s0, 0x2000
	ds_read_b128 v[234:237], v157 offset:3072
	global_load_lds_dwordx4 v134, s[40:41]
	s_barrier
	s_waitcnt lgkmcnt(0)
	s_setprio 1
	v_mfma_f32_16x16x32_bf16 v[116:119], v[222:225], v[172:175], 0
	v_mfma_f32_16x16x32_bf16 v[112:115], v[230:233], v[172:175], 0
	v_mfma_f32_16x16x32_bf16 v[100:103], v[222:225], v[180:183], 0
	v_mfma_f32_16x16x32_bf16 v[96:99], v[230:233], v[180:183], 0
	v_mfma_f32_16x16x32_bf16 v[84:87], v[222:225], v[206:209], 0
	v_mfma_f32_16x16x32_bf16 v[80:83], v[230:233], v[206:209], 0
	v_mfma_f32_16x16x32_bf16 v[68:71], v[222:225], v[214:217], 0
	v_mfma_f32_16x16x32_bf16 v[64:67], v[230:233], v[214:217], 0
	v_mfma_f32_16x16x32_bf16 v[116:119], v[226:229], v[176:179], v[116:119]
	v_mfma_f32_16x16x32_bf16 v[112:115], v[234:237], v[176:179], v[112:115]
	v_mfma_f32_16x16x32_bf16 v[100:103], v[226:229], v[188:191], v[100:103]
	v_mfma_f32_16x16x32_bf16 v[96:99], v[234:237], v[188:191], v[96:99]
	v_mfma_f32_16x16x32_bf16 v[84:87], v[226:229], v[210:213], v[84:87]
	v_mfma_f32_16x16x32_bf16 v[80:83], v[234:237], v[210:213], v[80:83]
	v_mfma_f32_16x16x32_bf16 v[68:71], v[226:229], v[218:221], v[68:71]
	v_mfma_f32_16x16x32_bf16 v[64:67], v[234:237], v[218:221], v[64:67]
	s_setprio 0
	s_mov_b32 m0, s52
	s_barrier
	ds_read_b128 v[172:175], v156 offset:16384
	ds_read_b128 v[176:179], v156 offset:17408
	ds_read_b128 v[180:183], v156 offset:18432
	ds_read_b128 v[188:191], v156 offset:19456
	ds_read_b128 v[206:209], v156 offset:20480
	ds_read_b128 v[210:213], v156 offset:21504
	ds_read_b128 v[214:217], v156 offset:22528
	global_load_lds_dwordx4 v128, s[42:43]
	s_mov_b32 m0, s53
	ds_read_b128 v[218:221], v156 offset:23552
	global_load_lds_dwordx4 v132, s[42:43]
	s_barrier
	s_waitcnt lgkmcnt(0)
	s_setprio 1
	v_mfma_f32_16x16x32_bf16 v[60:63], v[144:147], v[172:175], 0
	v_mfma_f32_16x16x32_bf16 v[56:59], v[164:167], v[172:175], 0
	v_mfma_f32_16x16x32_bf16 v[44:47], v[144:147], v[180:183], 0
	v_mfma_f32_16x16x32_bf16 v[40:43], v[164:167], v[180:183], 0
	v_mfma_f32_16x16x32_bf16 v[28:31], v[144:147], v[206:209], 0
	v_mfma_f32_16x16x32_bf16 v[24:27], v[164:167], v[206:209], 0
	v_mfma_f32_16x16x32_bf16 v[12:15], v[144:147], v[214:217], 0
	v_mfma_f32_16x16x32_bf16 v[8:11], v[164:167], v[214:217], 0
	v_mfma_f32_16x16x32_bf16 v[60:63], v[160:163], v[176:179], v[60:63]
	v_mfma_f32_16x16x32_bf16 v[56:59], v[168:171], v[176:179], v[56:59]
	v_mfma_f32_16x16x32_bf16 v[44:47], v[160:163], v[188:191], v[44:47]
	v_mfma_f32_16x16x32_bf16 v[40:43], v[168:171], v[188:191], v[40:43]
	v_mfma_f32_16x16x32_bf16 v[28:31], v[160:163], v[210:213], v[28:31]
	v_mfma_f32_16x16x32_bf16 v[24:27], v[168:171], v[210:213], v[24:27]
	v_mfma_f32_16x16x32_bf16 v[12:15], v[160:163], v[218:221], v[12:15]
	v_mfma_f32_16x16x32_bf16 v[8:11], v[168:171], v[218:221], v[8:11]
	s_setprio 0
	s_barrier
	s_add_i32 s4, s62, s51
	s_mov_b32 s69, s4
	s_mov_b32 m0, s4
	s_add_u32 s0, s40, 0x160000
	s_addc_u32 s1, s41, 0
	global_load_lds_dwordx4 v130, s[0:1]
	s_add_i32 m0, s4, 0x2000
	s_nop 0
	global_load_lds_dwordx4 v134, s[0:1]
	s_waitcnt vmcnt(6)
	s_barrier
; #define PG8_STAGE(bufoff, gbase, voff) do { _Pragma("unroll") for (int _i = 0; _i < 2; ++_i) \
;         __builtin_amdgcn_global_load_lds((const unsigned*)((const char*)(gbase) + (voff)[_i]), (LAS unsigned*)(lds + (bufoff) + ldsw + _i * 8192), 16, 0, 0); } while (0)
; #define PG8_LDA(dst, b, h) do { _Pragma("unroll") for (int m = 0; m < 4; ++m) _Pragma("unroll") for (int k = 0; k < 2; ++k) dst[m][k] = *(const LAS bf16x8*)(lds + PG8_SA(b, h) + aoff + m * 2048 + k * 1024); } while (0)
; #define PG8_LDB(dst, b, h) do { _Pragma("unroll") for (int n = 0; n < 2; ++n) _Pragma("unroll") for (int k = 0; k < 2; ++k) dst[n][k] = *(const LAS bf16x8*)(lds + PG8_SB(b, h) + boff + n * 2048 + k * 1024); } while (0)
; #define PG8_MMA(ai, bj, At, Bt) do { __builtin_amdgcn_s_setprio(1); _Pragma("unroll") for (int m = 0; m < 4; ++m) _Pragma("unroll") for (int n = 0; n < 2; ++n) _Pragma("unroll") for (int k = 0; k < 2; ++k) \
;         acc[ai][bj][m][n] = __builtin_amdgcn_mfma_f32_16x16x32_bf16(Bt[n][k], At[m][k], acc[ai][bj][m][n], 0, 0, 0); __builtin_amdgcn_s_setprio(0); } while (0)
; #define PG8_WAIT_V(n) asm volatile("s_waitcnt vmcnt(" #n ")" ::: "memory")
; #define PG8_WAIT_L(n) asm volatile("s_waitcnt lgkmcnt(" #n ")" ::: "memory")
; #define PG8_BAR __builtin_amdgcn_s_barrier()
; #define PG8_SCHED __builtin_amdgcn_sched_barrier(0)
; template <class Epi, class Sched>
; DI void gemm_phase(LAS unsigned char* lds, const Gemm g, const Sched& S, const Epi& E) {
;     ...
;             PG8_WAIT_V(6); PG8_BAR; PG8_MMA(1, 1, At, B1); PG8_BAR;
;             PG8_LDB(B0, 1, 0); PG8_SCHED; PG8_LDA(At, 1, 0); PG8_STAGE(PG8_SA(0, 1), a2 + hstep, voffA);
;             PG8_WAIT_L(8); PG8_BAR; PG8_WAIT_L(0); PG8_MMA(0, 0, At, B0); PG8_BAR; PG8_SCHED;
;             PG8_LDB(B1, 1, 1); PG8_STAGE(PG8_SB(1, 0), b3, voffB);
;             PG8_BAR; PG8_WAIT_L(0); PG8_MMA(0, 1, At, B1); PG8_BAR;
;             PG8_LDA(At, 1, 1); PG8_STAGE(PG8_SA(1, 0), a3, voffA);
	s_setprio 1
	v_mfma_f32_16x16x32_bf16 v[52:55], v[222:225], v[172:175], 0
	v_mfma_f32_16x16x32_bf16 v[48:51], v[230:233], v[172:175], 0
	v_mfma_f32_16x16x32_bf16 v[36:39], v[222:225], v[180:183], 0
	v_mfma_f32_16x16x32_bf16 v[32:35], v[230:233], v[180:183], 0
	v_mfma_f32_16x16x32_bf16 v[20:23], v[222:225], v[206:209], 0
	v_mfma_f32_16x16x32_bf16 v[16:19], v[230:233], v[206:209], 0
	v_mfma_f32_16x16x32_bf16 v[4:7], v[222:225], v[214:217], 0
	v_mfma_f32_16x16x32_bf16 v[0:3], v[230:233], v[214:217], 0
	v_mfma_f32_16x16x32_bf16 v[52:55], v[226:229], v[176:179], v[52:55]
	v_mfma_f32_16x16x32_bf16 v[48:51], v[234:237], v[176:179], v[48:51]
	v_mfma_f32_16x16x32_bf16 v[36:39], v[226:229], v[188:191], v[36:39]
	v_mfma_f32_16x16x32_bf16 v[32:35], v[234:237], v[188:191], v[32:35]
	v_mfma_f32_16x16x32_bf16 v[20:23], v[226:229], v[210:213], v[20:23]
	v_mfma_f32_16x16x32_bf16 v[16:19], v[234:237], v[210:213], v[16:19]
	v_mfma_f32_16x16x32_bf16 v[4:7], v[226:229], v[218:221], v[4:7]
	v_mfma_f32_16x16x32_bf16 v[0:3], v[234:237], v[218:221], v[0:3]
	s_setprio 0
	s_add_i32 s4, 0, 0x18000
	v_add_u32_e32 v202, s4, v154
	s_barrier
	ds_read_b128 v[144:147], v202
	ds_read_b128 v[160:163], v202 offset:1024
	ds_read_b128 v[164:167], v202 offset:2048
	ds_read_b128 v[168:171], v202 offset:3072
	s_add_u32 s0, s42, 0x160000
	s_addc_u32 s1, s43, 0
	s_mov_b32 m0, s54
	ds_read_b128 v[172:175], v156 offset:32768
	ds_read_b128 v[176:179], v156 offset:33792
	ds_read_b128 v[180:183], v156 offset:34816
	ds_read_b128 v[188:191], v156 offset:35840
	ds_read_b128 v[206:209], v156 offset:36864
	ds_read_b128 v[210:213], v156 offset:37888
	ds_read_b128 v[214:217], v156 offset:38912
	global_load_lds_dwordx4 v128, s[0:1]
	s_mov_b32 m0, s55
	ds_read_b128 v[218:221], v156 offset:39936
	global_load_lds_dwordx4 v132, s[0:1]
	s_waitcnt lgkmcnt(8)
	s_barrier
	s_waitcnt lgkmcnt(0)
	s_setprio 1
	v_mfma_f32_16x16x32_bf16 v[124:127], v[144:147], v[172:175], v[124:127]
	v_mfma_f32_16x16x32_bf16 v[120:123], v[164:167], v[172:175], v[120:123]
	v_mfma_f32_16x16x32_bf16 v[108:111], v[144:147], v[180:183], v[108:111]
	v_mfma_f32_16x16x32_bf16 v[104:107], v[164:167], v[180:183], v[104:107]
	v_mfma_f32_16x16x32_bf16 v[92:95], v[144:147], v[206:209], v[92:95]
	v_mfma_f32_16x16x32_bf16 v[88:91], v[164:167], v[206:209], v[88:91]
	v_mfma_f32_16x16x32_bf16 v[76:79], v[144:147], v[214:217], v[76:79]
	v_mfma_f32_16x16x32_bf16 v[72:75], v[164:167], v[214:217], v[72:75]
	v_mfma_f32_16x16x32_bf16 v[124:127], v[160:163], v[176:179], v[124:127]
	v_mfma_f32_16x16x32_bf16 v[120:123], v[168:171], v[176:179], v[120:123]
	v_mfma_f32_16x16x32_bf16 v[108:111], v[160:163], v[188:191], v[108:111]
	v_mfma_f32_16x16x32_bf16 v[104:107], v[168:171], v[188:191], v[104:107]
	v_mfma_f32_16x16x32_bf16 v[92:95], v[160:163], v[210:213], v[92:95]
	v_mfma_f32_16x16x32_bf16 v[88:91], v[168:171], v[210:213], v[88:91]
	v_mfma_f32_16x16x32_bf16 v[76:79], v[160:163], v[218:221], v[76:79]
	v_mfma_f32_16x16x32_bf16 v[72:75], v[168:171], v[218:221], v[72:75]
	s_setprio 0
	s_barrier
	s_add_i32 s5, 0, 0x1c000
	s_add_i32 s0, s4, s51
	s_mov_b32 s70, s0
	v_add_u32_e32 v203, s5, v154
	s_add_i32 m0, s0, 0xffffff80
	ds_read_b128 v[222:225], v203
	ds_read_b128 v[226:229], v203 offset:1024
	ds_read_b128 v[230:233], v203 offset:2048
	global_load_lds_dwordx4 v130, s[40:41] offset:128
	s_add_i32 m0, s0, 0x1f80
	ds_read_b128 v[234:237], v203 offset:3072
	global_load_lds_dwordx4 v134, s[40:41] offset:128
	s_barrier
	s_waitcnt lgkmcnt(0)
	s_setprio 1
	v_mfma_f32_16x16x32_bf16 v[116:119], v[222:225], v[172:175], v[116:119]
	v_mfma_f32_16x16x32_bf16 v[112:115], v[230:233], v[172:175], v[112:115]
	v_mfma_f32_16x16x32_bf16 v[100:103], v[222:225], v[180:183], v[100:103]
	v_mfma_f32_16x16x32_bf16 v[96:99], v[230:233], v[180:183], v[96:99]
	v_mfma_f32_16x16x32_bf16 v[84:87], v[222:225], v[206:209], v[84:87]
	v_mfma_f32_16x16x32_bf16 v[80:83], v[230:233], v[206:209], v[80:83]
	v_mfma_f32_16x16x32_bf16 v[68:71], v[222:225], v[214:217], v[68:71]
	v_mfma_f32_16x16x32_bf16 v[64:67], v[230:233], v[214:217], v[64:67]
	v_mfma_f32_16x16x32_bf16 v[116:119], v[226:229], v[176:179], v[116:119]
	v_mfma_f32_16x16x32_bf16 v[112:115], v[234:237], v[176:179], v[112:115]
	v_mfma_f32_16x16x32_bf16 v[100:103], v[226:229], v[188:191], v[100:103]
	v_mfma_f32_16x16x32_bf16 v[96:99], v[234:237], v[188:191], v[96:99]
	v_mfma_f32_16x16x32_bf16 v[84:87], v[226:229], v[210:213], v[84:87]
	v_mfma_f32_16x16x32_bf16 v[80:83], v[234:237], v[210:213], v[80:83]
	v_mfma_f32_16x16x32_bf16 v[68:71], v[226:229], v[218:221], v[68:71]
	v_mfma_f32_16x16x32_bf16 v[64:67], v[234:237], v[218:221], v[64:67]
	s_setprio 0
	s_add_i32 m0, s59, 0xffffff80
	s_barrier
	ds_read_b128 v[172:175], v156 offset:49152
	ds_read_b128 v[176:179], v156 offset:50176
	ds_read_b128 v[180:183], v156 offset:51200
	ds_read_b128 v[188:191], v156 offset:52224
	ds_read_b128 v[206:209], v156 offset:53248
	ds_read_b128 v[210:213], v156 offset:54272
	ds_read_b128 v[214:217], v156 offset:55296
	global_load_lds_dwordx4 v128, s[42:43] offset:128
	s_add_i32 m0, s60, 0xffffff80
	ds_read_b128 v[218:221], v156 offset:56320
	global_load_lds_dwordx4 v132, s[42:43] offset:128
	s_barrier
; #define PG8_STAGE(bufoff, gbase, voff) do { _Pragma("unroll") for (int _i = 0; _i < 2; ++_i) \
;         __builtin_amdgcn_global_load_lds((const unsigned*)((const char*)(gbase) + (voff)[_i]), (LAS unsigned*)(lds + (bufoff) + ldsw + _i * 8192), 16, 0, 0); } while (0)
; #define PG8_LDA(dst, b, h) do { _Pragma("unroll") for (int m = 0; m < 4; ++m) _Pragma("unroll") for (int k = 0; k < 2; ++k) dst[m][k] = *(const LAS bf16x8*)(lds + PG8_SA(b, h) + aoff + m * 2048 + k * 1024); } while (0)
; #define PG8_LDB(dst, b, h) do { _Pragma("unroll") for (int n = 0; n < 2; ++n) _Pragma("unroll") for (int k = 0; k < 2; ++k) dst[n][k] = *(const LAS bf16x8*)(lds + PG8_SB(b, h) + boff + n * 2048 + k * 1024); } while (0)
; #define PG8_MMA(ai, bj, At, Bt) do { __builtin_amdgcn_s_setprio(1); _Pragma("unroll") for (int m = 0; m < 4; ++m) _Pragma("unroll") for (int n = 0; n < 2; ++n) _Pragma("unroll") for (int k = 0; k < 2; ++k) \
;         acc[ai][bj][m][n] = __builtin_amdgcn_mfma_f32_16x16x32_bf16(Bt[n][k], At[m][k], acc[ai][bj][m][n], 0, 0, 0); __builtin_amdgcn_s_setprio(0); } while (0)
; #define PG8_WAIT_V(n) asm volatile("s_waitcnt vmcnt(" #n ")" ::: "memory")
; #define PG8_WAIT_L(n) asm volatile("s_waitcnt lgkmcnt(" #n ")" ::: "memory")
; #define PG8_BAR __builtin_amdgcn_s_barrier()
; #define PG8_SCHED __builtin_amdgcn_sched_barrier(0)
; template <class Epi, class Sched>
; DI void gemm_phase(LAS unsigned char* lds, const Gemm g, const Sched& S, const Epi& E) {
;     ...
;             PG8_LDB(B0, 0, 0); PG8_SCHED; PG8_LDA(At, 0, 0); PG8_STAGE(PG8_SA(1, 1), a1 + hstep, voffA);
;             PG8_WAIT_L(8); PG8_BAR; PG8_WAIT_L(0); PG8_MMA(0, 0, At, B0); PG8_BAR; PG8_SCHED;
;             PG8_LDB(B1, 0, 1); PG8_STAGE(PG8_SB(0, 0), b2, voffB);
;     ...
;             PG8_BAR; PG8_WAIT_L(0); PG8_MMA(1, 0, At, B0); PG8_BAR; PG8_SCHED;
;             PG8_STAGE(PG8_SB(1, 1), b3 + hstep, voffB);
;             PG8_WAIT_V(6); PG8_BAR; PG8_MMA(1, 1, At, B1); PG8_BAR;
	s_waitcnt lgkmcnt(0)
	s_setprio 1
	v_mfma_f32_16x16x32_bf16 v[60:63], v[144:147], v[172:175], v[60:63]
	v_mfma_f32_16x16x32_bf16 v[56:59], v[164:167], v[172:175], v[56:59]
	v_mfma_f32_16x16x32_bf16 v[44:47], v[144:147], v[180:183], v[44:47]
	v_mfma_f32_16x16x32_bf16 v[40:43], v[164:167], v[180:183], v[40:43]
	v_mfma_f32_16x16x32_bf16 v[28:31], v[144:147], v[206:209], v[28:31]
	v_mfma_f32_16x16x32_bf16 v[24:27], v[164:167], v[206:209], v[24:27]
	v_mfma_f32_16x16x32_bf16 v[12:15], v[144:147], v[214:217], v[12:15]
	v_mfma_f32_16x16x32_bf16 v[8:11], v[164:167], v[214:217], v[8:11]
	v_mfma_f32_16x16x32_bf16 v[60:63], v[160:163], v[176:179], v[60:63]
	v_mfma_f32_16x16x32_bf16 v[56:59], v[168:171], v[176:179], v[56:59]
	v_mfma_f32_16x16x32_bf16 v[44:47], v[160:163], v[188:191], v[44:47]
	v_mfma_f32_16x16x32_bf16 v[40:43], v[168:171], v[188:191], v[40:43]
	v_mfma_f32_16x16x32_bf16 v[28:31], v[160:163], v[210:213], v[28:31]
	v_mfma_f32_16x16x32_bf16 v[24:27], v[168:171], v[210:213], v[24:27]
	v_mfma_f32_16x16x32_bf16 v[12:15], v[160:163], v[218:221], v[12:15]
	v_mfma_f32_16x16x32_bf16 v[8:11], v[168:171], v[218:221], v[8:11]
	s_setprio 0
	s_barrier
	s_add_i32 s4, s5, s51
	s_mov_b32 s71, s4
	s_mov_b32 m0, s4
	s_add_u32 s0, s40, 0x160080
	s_addc_u32 s1, s41, 0
	global_load_lds_dwordx4 v130, s[0:1]
	s_add_i32 m0, s4, 0x2000
	s_nop 0
	global_load_lds_dwordx4 v134, s[0:1]
	s_waitcnt vmcnt(6)
	s_barrier
	s_setprio 1
	v_mfma_f32_16x16x32_bf16 v[52:55], v[222:225], v[172:175], v[52:55]
	v_mfma_f32_16x16x32_bf16 v[48:51], v[230:233], v[172:175], v[48:51]
	v_mfma_f32_16x16x32_bf16 v[36:39], v[222:225], v[180:183], v[36:39]
	v_mfma_f32_16x16x32_bf16 v[32:35], v[230:233], v[180:183], v[32:35]
	v_mfma_f32_16x16x32_bf16 v[20:23], v[222:225], v[206:209], v[20:23]
	v_mfma_f32_16x16x32_bf16 v[16:19], v[230:233], v[206:209], v[16:19]
	v_mfma_f32_16x16x32_bf16 v[4:7], v[222:225], v[214:217], v[4:7]
	v_mfma_f32_16x16x32_bf16 v[0:3], v[230:233], v[214:217], v[0:3]
	v_mfma_f32_16x16x32_bf16 v[52:55], v[226:229], v[176:179], v[52:55]
	v_mfma_f32_16x16x32_bf16 v[48:51], v[234:237], v[176:179], v[48:51]
	v_mfma_f32_16x16x32_bf16 v[36:39], v[226:229], v[188:191], v[36:39]
	v_mfma_f32_16x16x32_bf16 v[32:35], v[234:237], v[188:191], v[32:35]
	v_mfma_f32_16x16x32_bf16 v[20:23], v[226:229], v[210:213], v[20:23]
	v_mfma_f32_16x16x32_bf16 v[16:19], v[234:237], v[210:213], v[16:19]
	v_mfma_f32_16x16x32_bf16 v[4:7], v[226:229], v[218:221], v[4:7]
	v_mfma_f32_16x16x32_bf16 v[0:3], v[234:237], v[218:221], v[0:3]
	s_setprio 0
	s_add_i32 s68, s68, 2
	s_add_u32 s38, s38, 0x100
	s_addc_u32 s39, s39, 0
	s_add_u32 s35, s35, 0x100
	s_addc_u32 s67, s67, 0
	s_cmpk_gt_u32 s68, 0x55
	s_barrier
	s_cbranch_scc0 .LBB0_1746
	s_branch .Lpeel_done_1746
.LBB0_1746:
	ds_read_b128 v[144:147], v155
	ds_read_b128 v[160:163], v155 offset:1024
	ds_read_b128 v[164:167], v155 offset:2048
	ds_read_b128 v[168:171], v155 offset:3072
	s_add_u32 s0, s38, 0xffea0080
	s_addc_u32 s1, s39, -1
	s_cmpk_eq_i32 s68, 0x54
	s_cselect_b32 s43, s9, s1
	s_cselect_b32 s42, s8, s0
	s_cselect_b32 s41, s11, s67
	s_cselect_b32 s40, s10, s35
	s_add_i32 m0, s52, 0xc000
	ds_read_b128 v[172:175], v156
	ds_read_b128 v[176:179], v156 offset:1024
	ds_read_b128 v[180:183], v156 offset:2048
	ds_read_b128 v[188:191], v156 offset:3072
	ds_read_b128 v[206:209], v156 offset:4096
	ds_read_b128 v[210:213], v156 offset:5120
	ds_read_b128 v[214:217], v156 offset:6144
	global_load_lds_dwordx4 v136, s[38:39]
	s_add_i32 m0, s52, 0xe000
	ds_read_b128 v[218:221], v156 offset:7168
	global_load_lds_dwordx4 v138, s[38:39]
	s_waitcnt lgkmcnt(8)
	s_barrier
	s_waitcnt lgkmcnt(0)
	s_setprio 1
	v_mfma_f32_16x16x32_bf16 v[124:127], v[144:147], v[172:175], v[124:127]
	v_mfma_f32_16x16x32_bf16 v[120:123], v[164:167], v[172:175], v[120:123]
	v_mfma_f32_16x16x32_bf16 v[108:111], v[144:147], v[180:183], v[108:111]
	v_mfma_f32_16x16x32_bf16 v[104:107], v[164:167], v[180:183], v[104:107]
	v_mfma_f32_16x16x32_bf16 v[92:95], v[144:147], v[206:209], v[92:95]
	v_mfma_f32_16x16x32_bf16 v[88:91], v[164:167], v[206:209], v[88:91]
	v_mfma_f32_16x16x32_bf16 v[76:79], v[144:147], v[214:217], v[76:79]
	v_mfma_f32_16x16x32_bf16 v[72:75], v[164:167], v[214:217], v[72:75]
	v_mfma_f32_16x16x32_bf16 v[124:127], v[160:163], v[176:179], v[124:127]
	v_mfma_f32_16x16x32_bf16 v[120:123], v[168:171], v[176:179], v[120:123]
	v_mfma_f32_16x16x32_bf16 v[108:111], v[160:163], v[188:191], v[108:111]
	v_mfma_f32_16x16x32_bf16 v[104:107], v[168:171], v[188:191], v[104:107]
	v_mfma_f32_16x16x32_bf16 v[92:95], v[160:163], v[210:213], v[92:95]
	v_mfma_f32_16x16x32_bf16 v[88:91], v[168:171], v[210:213], v[88:91]
	v_mfma_f32_16x16x32_bf16 v[76:79], v[160:163], v[218:221], v[76:79]
	v_mfma_f32_16x16x32_bf16 v[72:75], v[168:171], v[218:221], v[72:75]
	s_setprio 0
	s_barrier
	s_mov_b32 m0, s32
	ds_read_b128 v[222:225], v157
	ds_read_b128 v[226:229], v157 offset:1024
	ds_read_b128 v[230:233], v157 offset:2048
	global_load_lds_dwordx4 v130, s[40:41]
	s_add_i32 m0, s32, 0x2000
	ds_read_b128 v[234:237], v157 offset:3072
	global_load_lds_dwordx4 v134, s[40:41]
	s_barrier
; #define PG8_STAGE(bufoff, gbase, voff) do { _Pragma("unroll") for (int _i = 0; _i < 2; ++_i) \
;         __builtin_amdgcn_global_load_lds((const unsigned*)((const char*)(gbase) + (voff)[_i]), (LAS unsigned*)(lds + (bufoff) + ldsw + _i * 8192), 16, 0, 0); } while (0)
; #define PG8_LDA(dst, b, h) do { _Pragma("unroll") for (int m = 0; m < 4; ++m) _Pragma("unroll") for (int k = 0; k < 2; ++k) dst[m][k] = *(const LAS bf16x8*)(lds + PG8_SA(b, h) + aoff + m * 2048 + k * 1024); } while (0)
; #define PG8_LDB(dst, b, h) do { _Pragma("unroll") for (int n = 0; n < 2; ++n) _Pragma("unroll") for (int k = 0; k < 2; ++k) dst[n][k] = *(const LAS bf16x8*)(lds + PG8_SB(b, h) + boff + n * 2048 + k * 1024); } while (0)
; #define PG8_MMA(ai, bj, At, Bt) do { __builtin_amdgcn_s_setprio(1); _Pragma("unroll") for (int m = 0; m < 4; ++m) _Pragma("unroll") for (int n = 0; n < 2; ++n) _Pragma("unroll") for (int k = 0; k < 2; ++k) \
;         acc[ai][bj][m][n] = __builtin_amdgcn_mfma_f32_16x16x32_bf16(Bt[n][k], At[m][k], acc[ai][bj][m][n], 0, 0, 0); __builtin_amdgcn_s_setprio(0); } while (0)
; #define PG8_WAIT_V(n) asm volatile("s_waitcnt vmcnt(" #n ")" ::: "memory")
; #define PG8_WAIT_L(n) asm volatile("s_waitcnt lgkmcnt(" #n ")" ::: "memory")
; #define PG8_BAR __builtin_amdgcn_s_barrier()
; #define PG8_SCHED __builtin_amdgcn_sched_barrier(0)
; template <class Epi, class Sched>
; DI void gemm_phase(LAS unsigned char* lds, const Gemm g, const Sched& S, const Epi& E) {
;     ...
;             PG8_BAR; PG8_WAIT_L(0); PG8_MMA(0, 1, At, B1); PG8_BAR;
;             PG8_LDA(At, 0, 1); PG8_STAGE(PG8_SA(0, 0), a2, voffA);
;             PG8_BAR; PG8_WAIT_L(0); PG8_MMA(1, 0, At, B0); PG8_BAR; PG8_SCHED;
;             PG8_STAGE(PG8_SB(0, 1), b2 + hstep, voffB);
;             PG8_WAIT_V(6); PG8_BAR; PG8_MMA(1, 1, At, B1); PG8_BAR;
;             PG8_LDB(B0, 1, 0); PG8_SCHED; PG8_LDA(At, 1, 0); PG8_STAGE(PG8_SA(0, 1), a2 + hstep, voffA);
	s_waitcnt lgkmcnt(0)
	s_setprio 1
	v_mfma_f32_16x16x32_bf16 v[116:119], v[222:225], v[172:175], v[116:119]
	v_mfma_f32_16x16x32_bf16 v[112:115], v[230:233], v[172:175], v[112:115]
	v_mfma_f32_16x16x32_bf16 v[100:103], v[222:225], v[180:183], v[100:103]
	v_mfma_f32_16x16x32_bf16 v[96:99], v[230:233], v[180:183], v[96:99]
	v_mfma_f32_16x16x32_bf16 v[84:87], v[222:225], v[206:209], v[84:87]
	v_mfma_f32_16x16x32_bf16 v[80:83], v[230:233], v[206:209], v[80:83]
	v_mfma_f32_16x16x32_bf16 v[68:71], v[222:225], v[214:217], v[68:71]
	v_mfma_f32_16x16x32_bf16 v[64:67], v[230:233], v[214:217], v[64:67]
	v_mfma_f32_16x16x32_bf16 v[116:119], v[226:229], v[176:179], v[116:119]
	v_mfma_f32_16x16x32_bf16 v[112:115], v[234:237], v[176:179], v[112:115]
	v_mfma_f32_16x16x32_bf16 v[100:103], v[226:229], v[188:191], v[100:103]
	v_mfma_f32_16x16x32_bf16 v[96:99], v[234:237], v[188:191], v[96:99]
	v_mfma_f32_16x16x32_bf16 v[84:87], v[226:229], v[210:213], v[84:87]
	v_mfma_f32_16x16x32_bf16 v[80:83], v[234:237], v[210:213], v[80:83]
	v_mfma_f32_16x16x32_bf16 v[68:71], v[226:229], v[218:221], v[68:71]
	v_mfma_f32_16x16x32_bf16 v[64:67], v[234:237], v[218:221], v[64:67]
	s_setprio 0
	s_mov_b32 m0, s52
	s_barrier
	ds_read_b128 v[172:175], v156 offset:16384
	ds_read_b128 v[176:179], v156 offset:17408
	ds_read_b128 v[180:183], v156 offset:18432
	ds_read_b128 v[188:191], v156 offset:19456
	ds_read_b128 v[206:209], v156 offset:20480
	ds_read_b128 v[210:213], v156 offset:21504
	ds_read_b128 v[214:217], v156 offset:22528
	global_load_lds_dwordx4 v128, s[42:43]
	s_mov_b32 m0, s53
	ds_read_b128 v[218:221], v156 offset:23552
	global_load_lds_dwordx4 v132, s[42:43]
	s_barrier
	s_waitcnt lgkmcnt(0)
	s_setprio 1
	v_mfma_f32_16x16x32_bf16 v[60:63], v[144:147], v[172:175], v[60:63]
	v_mfma_f32_16x16x32_bf16 v[56:59], v[164:167], v[172:175], v[56:59]
	v_mfma_f32_16x16x32_bf16 v[44:47], v[144:147], v[180:183], v[44:47]
	v_mfma_f32_16x16x32_bf16 v[40:43], v[164:167], v[180:183], v[40:43]
	v_mfma_f32_16x16x32_bf16 v[28:31], v[144:147], v[206:209], v[28:31]
	v_mfma_f32_16x16x32_bf16 v[24:27], v[164:167], v[206:209], v[24:27]
	v_mfma_f32_16x16x32_bf16 v[12:15], v[144:147], v[214:217], v[12:15]
	v_mfma_f32_16x16x32_bf16 v[8:11], v[164:167], v[214:217], v[8:11]
	v_mfma_f32_16x16x32_bf16 v[60:63], v[160:163], v[176:179], v[60:63]
	v_mfma_f32_16x16x32_bf16 v[56:59], v[168:171], v[176:179], v[56:59]
	v_mfma_f32_16x16x32_bf16 v[44:47], v[160:163], v[188:191], v[44:47]
	v_mfma_f32_16x16x32_bf16 v[40:43], v[168:171], v[188:191], v[40:43]
	v_mfma_f32_16x16x32_bf16 v[28:31], v[160:163], v[210:213], v[28:31]
	v_mfma_f32_16x16x32_bf16 v[24:27], v[168:171], v[210:213], v[24:27]
	v_mfma_f32_16x16x32_bf16 v[12:15], v[160:163], v[218:221], v[12:15]
	v_mfma_f32_16x16x32_bf16 v[8:11], v[168:171], v[218:221], v[8:11]
	s_setprio 0
	s_barrier
	s_mov_b32 m0, s69
	s_add_u32 s0, s40, 0x160000
	s_addc_u32 s1, s41, 0
	global_load_lds_dwordx4 v130, s[0:1]
	s_add_i32 m0, s69, 0x2000
	s_nop 0
	global_load_lds_dwordx4 v134, s[0:1]
	s_waitcnt vmcnt(6)
	s_barrier
	s_setprio 1
	v_mfma_f32_16x16x32_bf16 v[52:55], v[222:225], v[172:175], v[52:55]
	v_mfma_f32_16x16x32_bf16 v[48:51], v[230:233], v[172:175], v[48:51]
	v_mfma_f32_16x16x32_bf16 v[36:39], v[222:225], v[180:183], v[36:39]
	v_mfma_f32_16x16x32_bf16 v[32:35], v[230:233], v[180:183], v[32:35]
	v_mfma_f32_16x16x32_bf16 v[20:23], v[222:225], v[206:209], v[20:23]
	v_mfma_f32_16x16x32_bf16 v[16:19], v[230:233], v[206:209], v[16:19]
	v_mfma_f32_16x16x32_bf16 v[4:7], v[222:225], v[214:217], v[4:7]
	v_mfma_f32_16x16x32_bf16 v[0:3], v[230:233], v[214:217], v[0:3]
	v_mfma_f32_16x16x32_bf16 v[52:55], v[226:229], v[176:179], v[52:55]
	v_mfma_f32_16x16x32_bf16 v[48:51], v[234:237], v[176:179], v[48:51]
	v_mfma_f32_16x16x32_bf16 v[36:39], v[226:229], v[188:191], v[36:39]
	v_mfma_f32_16x16x32_bf16 v[32:35], v[234:237], v[188:191], v[32:35]
	v_mfma_f32_16x16x32_bf16 v[20:23], v[226:229], v[210:213], v[20:23]
	v_mfma_f32_16x16x32_bf16 v[16:19], v[234:237], v[210:213], v[16:19]
	v_mfma_f32_16x16x32_bf16 v[4:7], v[226:229], v[218:221], v[4:7]
	v_mfma_f32_16x16x32_bf16 v[0:3], v[234:237], v[218:221], v[0:3]
	s_setprio 0
	s_add_i32 s4, 0, 0x18000
	s_barrier
	ds_read_b128 v[144:147], v202
	ds_read_b128 v[160:163], v202 offset:1024
	ds_read_b128 v[164:167], v202 offset:2048
	ds_read_b128 v[168:171], v202 offset:3072
	s_add_u32 s0, s42, 0x160000
	s_addc_u32 s1, s43, 0
	s_mov_b32 m0, s54
	ds_read_b128 v[172:175], v156 offset:32768
	ds_read_b128 v[176:179], v156 offset:33792
	ds_read_b128 v[180:183], v156 offset:34816
	ds_read_b128 v[188:191], v156 offset:35840
	ds_read_b128 v[206:209], v156 offset:36864
	ds_read_b128 v[210:213], v156 offset:37888
	ds_read_b128 v[214:217], v156 offset:38912
	global_load_lds_dwordx4 v128, s[0:1]
	s_mov_b32 m0, s55
	ds_read_b128 v[218:221], v156 offset:39936
	global_load_lds_dwordx4 v132, s[0:1]
	s_waitcnt lgkmcnt(8)
	s_barrier
; #define PG8_STAGE(bufoff, gbase, voff) do { _Pragma("unroll") for (int _i = 0; _i < 2; ++_i) \
;         __builtin_amdgcn_global_load_lds((const unsigned*)((const char*)(gbase) + (voff)[_i]), (LAS unsigned*)(lds + (bufoff) + ldsw + _i * 8192), 16, 0, 0); } while (0)
; #define PG8_LDA(dst, b, h) do { _Pragma("unroll") for (int m = 0; m < 4; ++m) _Pragma("unroll") for (int k = 0; k < 2; ++k) dst[m][k] = *(const LAS bf16x8*)(lds + PG8_SA(b, h) + aoff + m * 2048 + k * 1024); } while (0)
; #define PG8_LDB(dst, b, h) do { _Pragma("unroll") for (int n = 0; n < 2; ++n) _Pragma("unroll") for (int k = 0; k < 2; ++k) dst[n][k] = *(const LAS bf16x8*)(lds + PG8_SB(b, h) + boff + n * 2048 + k * 1024); } while (0)
; #define PG8_MMA(ai, bj, At, Bt) do { __builtin_amdgcn_s_setprio(1); _Pragma("unroll") for (int m = 0; m < 4; ++m) _Pragma("unroll") for (int n = 0; n < 2; ++n) _Pragma("unroll") for (int k = 0; k < 2; ++k) \
;         acc[ai][bj][m][n] = __builtin_amdgcn_mfma_f32_16x16x32_bf16(Bt[n][k], At[m][k], acc[ai][bj][m][n], 0, 0, 0); __builtin_amdgcn_s_setprio(0); } while (0)
; #define PG8_WAIT_V(n) asm volatile("s_waitcnt vmcnt(" #n ")" ::: "memory")
; #define PG8_WAIT_L(n) asm volatile("s_waitcnt lgkmcnt(" #n ")" ::: "memory")
; #define PG8_BAR __builtin_amdgcn_s_barrier()
; #define PG8_SCHED __builtin_amdgcn_sched_barrier(0)
; template <class Epi, class Sched>
; DI void gemm_phase(LAS unsigned char* lds, const Gemm g, const Sched& S, const Epi& E) {
;     ...
;             PG8_WAIT_L(8); PG8_BAR; PG8_WAIT_L(0); PG8_MMA(0, 0, At, B0); PG8_BAR; PG8_SCHED;
;             PG8_LDB(B1, 1, 1); PG8_STAGE(PG8_SB(1, 0), b3, voffB);
;             PG8_BAR; PG8_WAIT_L(0); PG8_MMA(0, 1, At, B1); PG8_BAR;
;             PG8_LDA(At, 1, 1); PG8_STAGE(PG8_SA(1, 0), a3, voffA);
;             PG8_BAR; PG8_WAIT_L(0); PG8_MMA(1, 0, At, B0); PG8_BAR; PG8_SCHED;
;             PG8_STAGE(PG8_SB(1, 1), b3 + hstep, voffB);
;             PG8_WAIT_V(6); PG8_BAR; PG8_MMA(1, 1, At, B1); PG8_BAR;
	s_waitcnt lgkmcnt(0)
	s_setprio 1
	v_mfma_f32_16x16x32_bf16 v[124:127], v[144:147], v[172:175], v[124:127]
	v_mfma_f32_16x16x32_bf16 v[120:123], v[164:167], v[172:175], v[120:123]
	v_mfma_f32_16x16x32_bf16 v[108:111], v[144:147], v[180:183], v[108:111]
	v_mfma_f32_16x16x32_bf16 v[104:107], v[164:167], v[180:183], v[104:107]
	v_mfma_f32_16x16x32_bf16 v[92:95], v[144:147], v[206:209], v[92:95]
	v_mfma_f32_16x16x32_bf16 v[88:91], v[164:167], v[206:209], v[88:91]
	v_mfma_f32_16x16x32_bf16 v[76:79], v[144:147], v[214:217], v[76:79]
	v_mfma_f32_16x16x32_bf16 v[72:75], v[164:167], v[214:217], v[72:75]
	v_mfma_f32_16x16x32_bf16 v[124:127], v[160:163], v[176:179], v[124:127]
	v_mfma_f32_16x16x32_bf16 v[120:123], v[168:171], v[176:179], v[120:123]
	v_mfma_f32_16x16x32_bf16 v[108:111], v[160:163], v[188:191], v[108:111]
	v_mfma_f32_16x16x32_bf16 v[104:107], v[168:171], v[188:191], v[104:107]
	v_mfma_f32_16x16x32_bf16 v[92:95], v[160:163], v[210:213], v[92:95]
	v_mfma_f32_16x16x32_bf16 v[88:91], v[168:171], v[210:213], v[88:91]
	v_mfma_f32_16x16x32_bf16 v[76:79], v[160:163], v[218:221], v[76:79]
	v_mfma_f32_16x16x32_bf16 v[72:75], v[168:171], v[218:221], v[72:75]
	s_setprio 0
	s_barrier
	s_add_i32 s5, 0, 0x1c000
	s_add_i32 m0, s70, 0xffffff80
	ds_read_b128 v[222:225], v203
	ds_read_b128 v[226:229], v203 offset:1024
	ds_read_b128 v[230:233], v203 offset:2048
	global_load_lds_dwordx4 v130, s[40:41] offset:128
	s_add_i32 m0, s70, 0x1f80
	ds_read_b128 v[234:237], v203 offset:3072
	global_load_lds_dwordx4 v134, s[40:41] offset:128
	s_barrier
	s_waitcnt lgkmcnt(0)
	s_setprio 1
	v_mfma_f32_16x16x32_bf16 v[116:119], v[222:225], v[172:175], v[116:119]
	v_mfma_f32_16x16x32_bf16 v[112:115], v[230:233], v[172:175], v[112:115]
	v_mfma_f32_16x16x32_bf16 v[100:103], v[222:225], v[180:183], v[100:103]
	v_mfma_f32_16x16x32_bf16 v[96:99], v[230:233], v[180:183], v[96:99]
	v_mfma_f32_16x16x32_bf16 v[84:87], v[222:225], v[206:209], v[84:87]
	v_mfma_f32_16x16x32_bf16 v[80:83], v[230:233], v[206:209], v[80:83]
	v_mfma_f32_16x16x32_bf16 v[68:71], v[222:225], v[214:217], v[68:71]
	v_mfma_f32_16x16x32_bf16 v[64:67], v[230:233], v[214:217], v[64:67]
	v_mfma_f32_16x16x32_bf16 v[116:119], v[226:229], v[176:179], v[116:119]
	v_mfma_f32_16x16x32_bf16 v[112:115], v[234:237], v[176:179], v[112:115]
	v_mfma_f32_16x16x32_bf16 v[100:103], v[226:229], v[188:191], v[100:103]
	v_mfma_f32_16x16x32_bf16 v[96:99], v[234:237], v[188:191], v[96:99]
	v_mfma_f32_16x16x32_bf16 v[84:87], v[226:229], v[210:213], v[84:87]
	v_mfma_f32_16x16x32_bf16 v[80:83], v[234:237], v[210:213], v[80:83]
	v_mfma_f32_16x16x32_bf16 v[68:71], v[226:229], v[218:221], v[68:71]
	v_mfma_f32_16x16x32_bf16 v[64:67], v[234:237], v[218:221], v[64:67]
	s_setprio 0
	s_add_i32 m0, s59, 0xffffff80
	s_barrier
	ds_read_b128 v[172:175], v156 offset:49152
	ds_read_b128 v[176:179], v156 offset:50176
	ds_read_b128 v[180:183], v156 offset:51200
	ds_read_b128 v[188:191], v156 offset:52224
	ds_read_b128 v[206:209], v156 offset:53248
	ds_read_b128 v[210:213], v156 offset:54272
	ds_read_b128 v[214:217], v156 offset:55296
	global_load_lds_dwordx4 v128, s[42:43] offset:128
	s_add_i32 m0, s60, 0xffffff80
	ds_read_b128 v[218:221], v156 offset:56320
	global_load_lds_dwordx4 v132, s[42:43] offset:128
	s_barrier
	s_waitcnt lgkmcnt(0)
	s_setprio 1
	v_mfma_f32_16x16x32_bf16 v[60:63], v[144:147], v[172:175], v[60:63]
	v_mfma_f32_16x16x32_bf16 v[56:59], v[164:167], v[172:175], v[56:59]
	v_mfma_f32_16x16x32_bf16 v[44:47], v[144:147], v[180:183], v[44:47]
	v_mfma_f32_16x16x32_bf16 v[40:43], v[164:167], v[180:183], v[40:43]
	v_mfma_f32_16x16x32_bf16 v[28:31], v[144:147], v[206:209], v[28:31]
	v_mfma_f32_16x16x32_bf16 v[24:27], v[164:167], v[206:209], v[24:27]
	v_mfma_f32_16x16x32_bf16 v[12:15], v[144:147], v[214:217], v[12:15]
	v_mfma_f32_16x16x32_bf16 v[8:11], v[164:167], v[214:217], v[8:11]
	v_mfma_f32_16x16x32_bf16 v[60:63], v[160:163], v[176:179], v[60:63]
	v_mfma_f32_16x16x32_bf16 v[56:59], v[168:171], v[176:179], v[56:59]
	v_mfma_f32_16x16x32_bf16 v[44:47], v[160:163], v[188:191], v[44:47]
	v_mfma_f32_16x16x32_bf16 v[40:43], v[168:171], v[188:191], v[40:43]
	v_mfma_f32_16x16x32_bf16 v[28:31], v[160:163], v[210:213], v[28:31]
	v_mfma_f32_16x16x32_bf16 v[24:27], v[168:171], v[210:213], v[24:27]
	v_mfma_f32_16x16x32_bf16 v[12:15], v[160:163], v[218:221], v[12:15]
	v_mfma_f32_16x16x32_bf16 v[8:11], v[168:171], v[218:221], v[8:11]
	s_setprio 0
	s_barrier
	s_mov_b32 m0, s71
	s_add_u32 s0, s40, 0x160080
	s_addc_u32 s1, s41, 0
	global_load_lds_dwordx4 v130, s[0:1]
	s_add_i32 m0, s71, 0x2000
	s_nop 0
	global_load_lds_dwordx4 v134, s[0:1]
	s_waitcnt vmcnt(6)
	s_barrier
	s_setprio 1
	v_mfma_f32_16x16x32_bf16 v[52:55], v[222:225], v[172:175], v[52:55]
	v_mfma_f32_16x16x32_bf16 v[48:51], v[230:233], v[172:175], v[48:51]
	v_mfma_f32_16x16x32_bf16 v[36:39], v[222:225], v[180:183], v[36:39]
	v_mfma_f32_16x16x32_bf16 v[32:35], v[230:233], v[180:183], v[32:35]
	v_mfma_f32_16x16x32_bf16 v[20:23], v[222:225], v[206:209], v[20:23]
	v_mfma_f32_16x16x32_bf16 v[16:19], v[230:233], v[206:209], v[16:19]
	v_mfma_f32_16x16x32_bf16 v[4:7], v[222:225], v[214:217], v[4:7]
	v_mfma_f32_16x16x32_bf16 v[0:3], v[230:233], v[214:217], v[0:3]
	v_mfma_f32_16x16x32_bf16 v[52:55], v[226:229], v[176:179], v[52:55]
	v_mfma_f32_16x16x32_bf16 v[48:51], v[234:237], v[176:179], v[48:51]
	v_mfma_f32_16x16x32_bf16 v[36:39], v[226:229], v[188:191], v[36:39]
	v_mfma_f32_16x16x32_bf16 v[32:35], v[234:237], v[188:191], v[32:35]
	v_mfma_f32_16x16x32_bf16 v[20:23], v[226:229], v[210:213], v[20:23]
	v_mfma_f32_16x16x32_bf16 v[16:19], v[234:237], v[210:213], v[16:19]
	v_mfma_f32_16x16x32_bf16 v[4:7], v[226:229], v[218:221], v[4:7]
	v_mfma_f32_16x16x32_bf16 v[0:3], v[234:237], v[218:221], v[0:3]
	s_setprio 0
	s_add_i32 s68, s68, 2
	s_add_u32 s38, s38, 0x100
	s_addc_u32 s39, s39, 0
	s_add_u32 s35, s35, 0x100
	s_addc_u32 s67, s67, 0
	s_cmpk_gt_u32 s68, 0x55
	s_barrier
	s_cbranch_scc0 .LBB0_1746

;     DI size_t aoff(const Unit& u, size_t tstep) const { return (size_t)u.pm * tstep; }
;     DI size_t boff(const Unit& u, size_t tstep) const { return (size_t)u.pn * tstep; }
;     DI size_t aoff(const Unit& u, size_t) const { return (size_t)u.ks * kbytes; }
;     DI size_t boff(const Unit& u, size_t tstep) const { return (size_t)u.pn * tstep + (size_t)u.ks * kbytes; }
;     DI size_t aoff(const Unit& u, size_t tstep) const { return (u.ks < 2 ? offU : offOA) + (size_t)u.pm * tstep; }
; #define PG8_STAGE(bufoff, gbase, voff) do { _Pragma("unroll") for (int _i = 0; _i < 2; ++_i) \
;         __builtin_amdgcn_global_load_lds((const unsigned*)((const char*)(gbase) + (voff)[_i]), (LAS unsigned*)(lds + (bufoff) + ldsw + _i * 8192), 16, 0, 0); } while (0)
; #define PG8_WAIT_V(n) asm volatile("s_waitcnt vmcnt(" #n ")" ::: "memory")
; #define PG8_WAIT_L(n) asm volatile("s_waitcnt lgkmcnt(" #n ")" ::: "memory")
; #define PG8_BAR __builtin_amdgcn_s_barrier()
; template <class Epi, class Sched>
; DI void gemm_phase(LAS unsigned char* lds, const Gemm g, const Sched& S, const Epi& E) {
;     ...
;         const char* nA = has_next ? (const char*)g.A + S.aoff(nxt, tstep) : cA; const char* nB = has_next ? (const char*)g.Bt + S.boff(nxt, tstep) : cB;
;         for (int t = 0; t < nt; t += 2) {
;             if constexpr (Epi::HAS_MID) { if (t == E.mid_t(nt)) { int fr3 = fr, fq3 = fq; asm volatile("" : "+v"(fr3), "+v"(fq3)); E.mid(acc, cur, wr, wc, fr3, fq3); } }
;             const bool last = (t == nt - 2);
;             const char* a1 = cA + (size_t)(t + 1) * kstep;
;             const char* a2 = last ? nA : cA + (size_t)(t + 2) * kstep; const char* b2 = last ? nB : cB + (size_t)(t + 2) * kstep;
;             const char* a3 = a2 + kstep; const char* b3 = b2 + kstep;
;             PG8_LDB(B0, 0, 0); PG8_SCHED; PG8_LDA(At, 0, 0); PG8_STAGE(PG8_SA(1, 1), a1 + hstep, voffA);
;             PG8_WAIT_L(8); PG8_BAR; PG8_WAIT_L(0); PG8_MMA(0, 0, At, B0); PG8_BAR; PG8_SCHED;
;             PG8_LDB(B1, 0, 1); PG8_STAGE(PG8_SB(0, 0), b2, voffB);
;             PG8_BAR; PG8_WAIT_L(0); PG8_MMA(0, 1, At, B1); PG8_BAR;
;             PG8_LDA(At, 0, 1); PG8_STAGE(PG8_SA(0, 0), a2, voffA);
;             PG8_BAR; PG8_WAIT_L(0); PG8_MMA(1, 0, At, B0); PG8_BAR; PG8_SCHED;
;             PG8_STAGE(PG8_SB(0, 1), b2 + hstep, voffB);
;             PG8_WAIT_V(6); PG8_BAR; PG8_MMA(1, 1, At, B1); PG8_BAR;
.LBB0_1774:
	s_add_u32 s28, s38, s28
	s_addc_u32 s29, s39, s29
	s_and_b64 s[0:1], s[8:9], exec
	s_cselect_b32 s15, s29, s37
	s_cselect_b32 s17, s28, s36
	s_add_u32 s8, s36, 0x160080
	s_addc_u32 s9, s37, 0
	s_add_u32 s64, s30, 0x100
	v_mov_b32_e32 v0, 0
	s_addc_u32 s65, s31, 0
	s_mov_b32 s66, -2
	ds_read_b128 v[146:149], v141
	ds_read_b128 v[154:157], v141 offset:1024
	ds_read_b128 v[158:161], v141 offset:2048
	ds_read_b128 v[162:165], v141 offset:3072
	s_add_u32 s0, s8, 0xffea0080
	s_addc_u32 s1, s9, -1
	s_cmp_eq_u32 s66, 4
	s_cselect_b32 s37, s15, s1
	s_cselect_b32 s36, s17, s0
	s_cselect_b32 s31, s19, s65
	s_cselect_b32 s30, s18, s64
	s_mov_b32 m0, s56
	ds_read_b128 v[166:169], v142
	ds_read_b128 v[170:173], v142 offset:1024
	ds_read_b128 v[174:177], v142 offset:2048
	ds_read_b128 v[178:181], v142 offset:3072
	ds_read_b128 v[188:191], v142 offset:4096
	ds_read_b128 v[206:209], v142 offset:5120
	ds_read_b128 v[210:213], v142 offset:6144
	global_load_lds_dwordx4 v132, s[8:9]
	s_mov_b32 m0, s57
	ds_read_b128 v[214:217], v142 offset:7168
	global_load_lds_dwordx4 v134, s[8:9]
	s_waitcnt lgkmcnt(8)
	s_barrier
	s_waitcnt lgkmcnt(0)
	s_setprio 1
	v_mfma_f32_16x16x32_bf16 v[124:127], v[146:149], v[166:169], 0
	v_mfma_f32_16x16x32_bf16 v[120:123], v[158:161], v[166:169], 0
	v_mfma_f32_16x16x32_bf16 v[116:119], v[146:149], v[174:177], 0
	v_mfma_f32_16x16x32_bf16 v[112:115], v[158:161], v[174:177], 0
	v_mfma_f32_16x16x32_bf16 v[104:107], v[146:149], v[188:191], 0
	v_mfma_f32_16x16x32_bf16 v[96:99], v[158:161], v[188:191], 0
	v_mfma_f32_16x16x32_bf16 v[88:91], v[146:149], v[210:213], 0
	v_mfma_f32_16x16x32_bf16 v[80:83], v[158:161], v[210:213], 0
	v_mfma_f32_16x16x32_bf16 v[124:127], v[154:157], v[170:173], v[124:127]
	v_mfma_f32_16x16x32_bf16 v[120:123], v[162:165], v[170:173], v[120:123]
	v_mfma_f32_16x16x32_bf16 v[116:119], v[154:157], v[178:181], v[116:119]
	v_mfma_f32_16x16x32_bf16 v[112:115], v[162:165], v[178:181], v[112:115]
	v_mfma_f32_16x16x32_bf16 v[104:107], v[154:157], v[206:209], v[104:107]
	v_mfma_f32_16x16x32_bf16 v[96:99], v[162:165], v[206:209], v[96:99]
	v_mfma_f32_16x16x32_bf16 v[88:91], v[154:157], v[214:217], v[88:91]
	v_mfma_f32_16x16x32_bf16 v[80:83], v[162:165], v[214:217], v[80:83]
	s_setprio 0
	s_barrier
	s_mov_b32 m0, s58
	ds_read_b128 v[218:221], v143
	ds_read_b128 v[222:225], v143 offset:1024
	ds_read_b128 v[226:229], v143 offset:2048
	global_load_lds_dwordx4 v130, s[30:31]
	s_mov_b32 m0, s59
	ds_read_b128 v[230:233], v143 offset:3072
	global_load_lds_dwordx4 v128, s[30:31]
	s_barrier
	s_waitcnt lgkmcnt(0)
	s_setprio 1
	v_mfma_f32_16x16x32_bf16 v[108:111], v[218:221], v[166:169], 0
	v_mfma_f32_16x16x32_bf16 v[100:103], v[226:229], v[166:169], 0
	v_mfma_f32_16x16x32_bf16 v[92:95], v[218:221], v[174:177], 0
	v_mfma_f32_16x16x32_bf16 v[84:87], v[226:229], v[174:177], 0
	v_mfma_f32_16x16x32_bf16 v[76:79], v[218:221], v[188:191], 0
	v_mfma_f32_16x16x32_bf16 v[72:75], v[226:229], v[188:191], 0
	v_mfma_f32_16x16x32_bf16 v[68:71], v[218:221], v[210:213], 0
	v_mfma_f32_16x16x32_bf16 v[64:67], v[226:229], v[210:213], 0
	v_mfma_f32_16x16x32_bf16 v[108:111], v[222:225], v[170:173], v[108:111]
	v_mfma_f32_16x16x32_bf16 v[100:103], v[230:233], v[170:173], v[100:103]
	v_mfma_f32_16x16x32_bf16 v[92:95], v[222:225], v[178:181], v[92:95]
	v_mfma_f32_16x16x32_bf16 v[84:87], v[230:233], v[178:181], v[84:87]
	v_mfma_f32_16x16x32_bf16 v[76:79], v[222:225], v[206:209], v[76:79]
	v_mfma_f32_16x16x32_bf16 v[72:75], v[230:233], v[206:209], v[72:75]
	v_mfma_f32_16x16x32_bf16 v[68:71], v[222:225], v[214:217], v[68:71]
	v_mfma_f32_16x16x32_bf16 v[64:67], v[230:233], v[214:217], v[64:67]
	s_setprio 0
	s_mov_b32 m0, s40
	s_barrier
	ds_read_b128 v[166:169], v142 offset:16384
	ds_read_b128 v[170:173], v142 offset:17408
	ds_read_b128 v[174:177], v142 offset:18432
	ds_read_b128 v[178:181], v142 offset:19456
	ds_read_b128 v[188:191], v142 offset:20480
	ds_read_b128 v[206:209], v142 offset:21504
	ds_read_b128 v[210:213], v142 offset:22528
	global_load_lds_dwordx4 v130, s[36:37]
	s_mov_b32 m0, s41
	ds_read_b128 v[214:217], v142 offset:23552
	global_load_lds_dwordx4 v128, s[36:37]
	s_barrier
	s_waitcnt lgkmcnt(0)
	s_setprio 1
	v_mfma_f32_16x16x32_bf16 v[60:63], v[146:149], v[166:169], 0
	v_mfma_f32_16x16x32_bf16 v[56:59], v[158:161], v[166:169], 0
	v_mfma_f32_16x16x32_bf16 v[52:55], v[146:149], v[174:177], 0
	v_mfma_f32_16x16x32_bf16 v[48:51], v[158:161], v[174:177], 0
	v_mfma_f32_16x16x32_bf16 v[40:43], v[146:149], v[188:191], 0
	v_mfma_f32_16x16x32_bf16 v[32:35], v[158:161], v[188:191], 0
	v_mfma_f32_16x16x32_bf16 v[24:27], v[146:149], v[210:213], 0
	v_mfma_f32_16x16x32_bf16 v[16:19], v[158:161], v[210:213], 0
	v_mfma_f32_16x16x32_bf16 v[60:63], v[154:157], v[170:173], v[60:63]
	v_mfma_f32_16x16x32_bf16 v[56:59], v[162:165], v[170:173], v[56:59]
	v_mfma_f32_16x16x32_bf16 v[52:55], v[154:157], v[178:181], v[52:55]
	v_mfma_f32_16x16x32_bf16 v[48:51], v[162:165], v[178:181], v[48:51]
	v_mfma_f32_16x16x32_bf16 v[40:43], v[154:157], v[206:209], v[40:43]
	v_mfma_f32_16x16x32_bf16 v[32:35], v[162:165], v[206:209], v[32:35]
	v_mfma_f32_16x16x32_bf16 v[24:27], v[154:157], v[214:217], v[24:27]
	v_mfma_f32_16x16x32_bf16 v[16:19], v[162:165], v[214:217], v[16:19]
	s_setprio 0
	s_barrier
	s_add_u32 s0, s30, 0x160000
	s_addc_u32 s1, s31, 0
	s_mov_b32 m0, s60
	s_nop 0
	global_load_lds_dwordx4 v130, s[0:1]
	s_mov_b32 m0, s61
	s_nop 0
	global_load_lds_dwordx4 v128, s[0:1]
	s_waitcnt vmcnt(6)
	s_barrier
; #define PG8_STAGE(bufoff, gbase, voff) do { _Pragma("unroll") for (int _i = 0; _i < 2; ++_i) \
;         __builtin_amdgcn_global_load_lds((const unsigned*)((const char*)(gbase) + (voff)[_i]), (LAS unsigned*)(lds + (bufoff) + ldsw + _i * 8192), 16, 0, 0); } while (0)
; #define PG8_LDA(dst, b, h) do { _Pragma("unroll") for (int m = 0; m < 4; ++m) _Pragma("unroll") for (int k = 0; k < 2; ++k) dst[m][k] = *(const LAS bf16x8*)(lds + PG8_SA(b, h) + aoff + m * 2048 + k * 1024); } while (0)
; #define PG8_LDB(dst, b, h) do { _Pragma("unroll") for (int n = 0; n < 2; ++n) _Pragma("unroll") for (int k = 0; k < 2; ++k) dst[n][k] = *(const LAS bf16x8*)(lds + PG8_SB(b, h) + boff + n * 2048 + k * 1024); } while (0)
; #define PG8_MMA(ai, bj, At, Bt) do { __builtin_amdgcn_s_setprio(1); _Pragma("unroll") for (int m = 0; m < 4; ++m) _Pragma("unroll") for (int n = 0; n < 2; ++n) _Pragma("unroll") for (int k = 0; k < 2; ++k) \
;         acc[ai][bj][m][n] = __builtin_amdgcn_mfma_f32_16x16x32_bf16(Bt[n][k], At[m][k], acc[ai][bj][m][n], 0, 0, 0); __builtin_amdgcn_s_setprio(0); } while (0)
; #define PG8_WAIT_V(n) asm volatile("s_waitcnt vmcnt(" #n ")" ::: "memory")
; #define PG8_WAIT_L(n) asm volatile("s_waitcnt lgkmcnt(" #n ")" ::: "memory")
; #define PG8_BAR __builtin_amdgcn_s_barrier()
; #define PG8_SCHED __builtin_amdgcn_sched_barrier(0)
; template <class Epi, class Sched>
; DI void gemm_phase(LAS unsigned char* lds, const Gemm g, const Sched& S, const Epi& E) {
;     ...
;             PG8_WAIT_V(6); PG8_BAR; PG8_MMA(1, 1, At, B1); PG8_BAR;
;             PG8_LDB(B0, 1, 0); PG8_SCHED; PG8_LDA(At, 1, 0); PG8_STAGE(PG8_SA(0, 1), a2 + hstep, voffA);
;             PG8_WAIT_L(8); PG8_BAR; PG8_WAIT_L(0); PG8_MMA(0, 0, At, B0); PG8_BAR; PG8_SCHED;
;             PG8_LDB(B1, 1, 1); PG8_STAGE(PG8_SB(1, 0), b3, voffB);
;             PG8_BAR; PG8_WAIT_L(0); PG8_MMA(0, 1, At, B1); PG8_BAR;
;             PG8_LDA(At, 1, 1); PG8_STAGE(PG8_SA(1, 0), a3, voffA);
	s_setprio 1
	v_mfma_f32_16x16x32_bf16 v[44:47], v[218:221], v[166:169], 0
	v_mfma_f32_16x16x32_bf16 v[36:39], v[226:229], v[166:169], 0
	v_mfma_f32_16x16x32_bf16 v[28:31], v[218:221], v[174:177], 0
	v_mfma_f32_16x16x32_bf16 v[20:23], v[226:229], v[174:177], 0
	v_mfma_f32_16x16x32_bf16 v[12:15], v[218:221], v[188:191], 0
	v_mfma_f32_16x16x32_bf16 v[8:11], v[226:229], v[188:191], 0
	v_mfma_f32_16x16x32_bf16 v[4:7], v[218:221], v[210:213], 0
	v_mfma_f32_16x16x32_bf16 v[0:3], v[226:229], v[210:213], 0
	v_mfma_f32_16x16x32_bf16 v[44:47], v[222:225], v[170:173], v[44:47]
	v_mfma_f32_16x16x32_bf16 v[36:39], v[230:233], v[170:173], v[36:39]
	v_mfma_f32_16x16x32_bf16 v[28:31], v[222:225], v[178:181], v[28:31]
	v_mfma_f32_16x16x32_bf16 v[20:23], v[230:233], v[178:181], v[20:23]
	v_mfma_f32_16x16x32_bf16 v[12:15], v[222:225], v[206:209], v[12:15]
	v_mfma_f32_16x16x32_bf16 v[8:11], v[230:233], v[206:209], v[8:11]
	v_mfma_f32_16x16x32_bf16 v[4:7], v[222:225], v[214:217], v[4:7]
	v_mfma_f32_16x16x32_bf16 v[0:3], v[230:233], v[214:217], v[0:3]
	s_setprio 0
	s_barrier
	ds_read_b128 v[146:149], v144
	ds_read_b128 v[154:157], v144 offset:1024
	ds_read_b128 v[158:161], v144 offset:2048
	ds_read_b128 v[162:165], v144 offset:3072
	s_add_u32 s0, s36, 0x160000
	s_addc_u32 s1, s37, 0
	s_mov_b32 m0, s42
	ds_read_b128 v[166:169], v142 offset:32768
	ds_read_b128 v[170:173], v142 offset:33792
	ds_read_b128 v[174:177], v142 offset:34816
	ds_read_b128 v[178:181], v142 offset:35840
	ds_read_b128 v[188:191], v142 offset:36864
	ds_read_b128 v[206:209], v142 offset:37888
	ds_read_b128 v[210:213], v142 offset:38912
	global_load_lds_dwordx4 v130, s[0:1]
	s_mov_b32 m0, s43
	ds_read_b128 v[214:217], v142 offset:39936
	global_load_lds_dwordx4 v128, s[0:1]
	s_waitcnt lgkmcnt(8)
	s_barrier
	s_waitcnt lgkmcnt(0)
	s_setprio 1
	v_mfma_f32_16x16x32_bf16 v[124:127], v[146:149], v[166:169], v[124:127]
	v_mfma_f32_16x16x32_bf16 v[120:123], v[158:161], v[166:169], v[120:123]
	v_mfma_f32_16x16x32_bf16 v[116:119], v[146:149], v[174:177], v[116:119]
	v_mfma_f32_16x16x32_bf16 v[112:115], v[158:161], v[174:177], v[112:115]
	v_mfma_f32_16x16x32_bf16 v[104:107], v[146:149], v[188:191], v[104:107]
	v_mfma_f32_16x16x32_bf16 v[96:99], v[158:161], v[188:191], v[96:99]
	v_mfma_f32_16x16x32_bf16 v[88:91], v[146:149], v[210:213], v[88:91]
	v_mfma_f32_16x16x32_bf16 v[80:83], v[158:161], v[210:213], v[80:83]
	v_mfma_f32_16x16x32_bf16 v[124:127], v[154:157], v[170:173], v[124:127]
	v_mfma_f32_16x16x32_bf16 v[120:123], v[162:165], v[170:173], v[120:123]
	v_mfma_f32_16x16x32_bf16 v[116:119], v[154:157], v[178:181], v[116:119]
	v_mfma_f32_16x16x32_bf16 v[112:115], v[162:165], v[178:181], v[112:115]
	v_mfma_f32_16x16x32_bf16 v[104:107], v[154:157], v[206:209], v[104:107]
	v_mfma_f32_16x16x32_bf16 v[96:99], v[162:165], v[206:209], v[96:99]
	v_mfma_f32_16x16x32_bf16 v[88:91], v[154:157], v[214:217], v[88:91]
	v_mfma_f32_16x16x32_bf16 v[80:83], v[162:165], v[214:217], v[80:83]
	s_setprio 0
	s_barrier
	s_add_i32 s4, 0, 0x1c000
	s_add_i32 s0, s62, s35
	s_mov_b32 s5, s0
	v_add_u32_e32 v145, s4, v140
	s_add_i32 m0, s0, 0xffffff80
	ds_read_b128 v[218:221], v145
	ds_read_b128 v[222:225], v145 offset:1024
	ds_read_b128 v[226:229], v145 offset:2048
	global_load_lds_dwordx4 v130, s[30:31] offset:128
	s_add_i32 m0, s0, 0x1f80
	ds_read_b128 v[230:233], v145 offset:3072
	global_load_lds_dwordx4 v128, s[30:31] offset:128
	s_barrier
	s_waitcnt lgkmcnt(0)
	s_setprio 1
	v_mfma_f32_16x16x32_bf16 v[108:111], v[218:221], v[166:169], v[108:111]
	v_mfma_f32_16x16x32_bf16 v[100:103], v[226:229], v[166:169], v[100:103]
	v_mfma_f32_16x16x32_bf16 v[92:95], v[218:221], v[174:177], v[92:95]
	v_mfma_f32_16x16x32_bf16 v[84:87], v[226:229], v[174:177], v[84:87]
	v_mfma_f32_16x16x32_bf16 v[76:79], v[218:221], v[188:191], v[76:79]
	v_mfma_f32_16x16x32_bf16 v[72:75], v[226:229], v[188:191], v[72:75]
	v_mfma_f32_16x16x32_bf16 v[68:71], v[218:221], v[210:213], v[68:71]
	v_mfma_f32_16x16x32_bf16 v[64:67], v[226:229], v[210:213], v[64:67]
	v_mfma_f32_16x16x32_bf16 v[108:111], v[222:225], v[170:173], v[108:111]
	v_mfma_f32_16x16x32_bf16 v[100:103], v[230:233], v[170:173], v[100:103]
	v_mfma_f32_16x16x32_bf16 v[92:95], v[222:225], v[178:181], v[92:95]
	v_mfma_f32_16x16x32_bf16 v[84:87], v[230:233], v[178:181], v[84:87]
	v_mfma_f32_16x16x32_bf16 v[76:79], v[222:225], v[206:209], v[76:79]
	v_mfma_f32_16x16x32_bf16 v[72:75], v[230:233], v[206:209], v[72:75]
	v_mfma_f32_16x16x32_bf16 v[68:71], v[222:225], v[214:217], v[68:71]
	v_mfma_f32_16x16x32_bf16 v[64:67], v[230:233], v[214:217], v[64:67]
	s_setprio 0
	s_add_i32 m0, s54, 0xffffff80
	s_barrier
	ds_read_b128 v[166:169], v142 offset:49152
	ds_read_b128 v[170:173], v142 offset:50176
	ds_read_b128 v[174:177], v142 offset:51200
	ds_read_b128 v[178:181], v142 offset:52224
	ds_read_b128 v[188:191], v142 offset:53248
	ds_read_b128 v[206:209], v142 offset:54272
	ds_read_b128 v[210:213], v142 offset:55296
	global_load_lds_dwordx4 v130, s[36:37] offset:128
	s_add_i32 m0, s55, 0xffffff80
	ds_read_b128 v[214:217], v142 offset:56320
	global_load_lds_dwordx4 v128, s[36:37] offset:128
	s_barrier
; #define PG8_STAGE(bufoff, gbase, voff) do { _Pragma("unroll") for (int _i = 0; _i < 2; ++_i) \
;         __builtin_amdgcn_global_load_lds((const unsigned*)((const char*)(gbase) + (voff)[_i]), (LAS unsigned*)(lds + (bufoff) + ldsw + _i * 8192), 16, 0, 0); } while (0)
; #define PG8_LDA(dst, b, h) do { _Pragma("unroll") for (int m = 0; m < 4; ++m) _Pragma("unroll") for (int k = 0; k < 2; ++k) dst[m][k] = *(const LAS bf16x8*)(lds + PG8_SA(b, h) + aoff + m * 2048 + k * 1024); } while (0)
; #define PG8_LDB(dst, b, h) do { _Pragma("unroll") for (int n = 0; n < 2; ++n) _Pragma("unroll") for (int k = 0; k < 2; ++k) dst[n][k] = *(const LAS bf16x8*)(lds + PG8_SB(b, h) + boff + n * 2048 + k * 1024); } while (0)
; #define PG8_MMA(ai, bj, At, Bt) do { __builtin_amdgcn_s_setprio(1); _Pragma("unroll") for (int m = 0; m < 4; ++m) _Pragma("unroll") for (int n = 0; n < 2; ++n) _Pragma("unroll") for (int k = 0; k < 2; ++k) \
;         acc[ai][bj][m][n] = __builtin_amdgcn_mfma_f32_16x16x32_bf16(Bt[n][k], At[m][k], acc[ai][bj][m][n], 0, 0, 0); __builtin_amdgcn_s_setprio(0); } while (0)
; #define PG8_WAIT_V(n) asm volatile("s_waitcnt vmcnt(" #n ")" ::: "memory")
; #define PG8_WAIT_L(n) asm volatile("s_waitcnt lgkmcnt(" #n ")" ::: "memory")
; #define PG8_BAR __builtin_amdgcn_s_barrier()
; #define PG8_SCHED __builtin_amdgcn_sched_barrier(0)
; template <class Epi, class Sched>
; DI void gemm_phase(LAS unsigned char* lds, const Gemm g, const Sched& S, const Epi& E) {
;     ...
;             PG8_LDB(B0, 0, 0); PG8_SCHED; PG8_LDA(At, 0, 0); PG8_STAGE(PG8_SA(1, 1), a1 + hstep, voffA);
;             PG8_WAIT_L(8); PG8_BAR; PG8_WAIT_L(0); PG8_MMA(0, 0, At, B0); PG8_BAR; PG8_SCHED;
;             PG8_LDB(B1, 0, 1); PG8_STAGE(PG8_SB(0, 0), b2, voffB);
;     ...
;             PG8_BAR; PG8_WAIT_L(0); PG8_MMA(1, 0, At, B0); PG8_BAR; PG8_SCHED;
;             PG8_STAGE(PG8_SB(1, 1), b3 + hstep, voffB);
;             PG8_WAIT_V(6); PG8_BAR; PG8_MMA(1, 1, At, B1); PG8_BAR;
	s_waitcnt lgkmcnt(0)
	s_setprio 1
	v_mfma_f32_16x16x32_bf16 v[60:63], v[146:149], v[166:169], v[60:63]
	v_mfma_f32_16x16x32_bf16 v[56:59], v[158:161], v[166:169], v[56:59]
	v_mfma_f32_16x16x32_bf16 v[52:55], v[146:149], v[174:177], v[52:55]
	v_mfma_f32_16x16x32_bf16 v[48:51], v[158:161], v[174:177], v[48:51]
	v_mfma_f32_16x16x32_bf16 v[40:43], v[146:149], v[188:191], v[40:43]
	v_mfma_f32_16x16x32_bf16 v[32:35], v[158:161], v[188:191], v[32:35]
	v_mfma_f32_16x16x32_bf16 v[24:27], v[146:149], v[210:213], v[24:27]
	v_mfma_f32_16x16x32_bf16 v[16:19], v[158:161], v[210:213], v[16:19]
	v_mfma_f32_16x16x32_bf16 v[60:63], v[154:157], v[170:173], v[60:63]
	v_mfma_f32_16x16x32_bf16 v[56:59], v[162:165], v[170:173], v[56:59]
	v_mfma_f32_16x16x32_bf16 v[52:55], v[154:157], v[178:181], v[52:55]
	v_mfma_f32_16x16x32_bf16 v[48:51], v[162:165], v[178:181], v[48:51]
	v_mfma_f32_16x16x32_bf16 v[40:43], v[154:157], v[206:209], v[40:43]
	v_mfma_f32_16x16x32_bf16 v[32:35], v[162:165], v[206:209], v[32:35]
	v_mfma_f32_16x16x32_bf16 v[24:27], v[154:157], v[214:217], v[24:27]
	v_mfma_f32_16x16x32_bf16 v[16:19], v[162:165], v[214:217], v[16:19]
	s_setprio 0
	s_barrier
	s_add_i32 s4, s4, s35
	s_mov_b32 s10, s4
	s_mov_b32 m0, s4
	s_add_u32 s0, s30, 0x160080
	s_addc_u32 s1, s31, 0
	global_load_lds_dwordx4 v130, s[0:1]
	s_add_i32 m0, s4, 0x2000
	s_nop 0
	global_load_lds_dwordx4 v128, s[0:1]
	s_waitcnt vmcnt(6)
	s_barrier
	s_setprio 1
	v_mfma_f32_16x16x32_bf16 v[44:47], v[218:221], v[166:169], v[44:47]
	v_mfma_f32_16x16x32_bf16 v[36:39], v[226:229], v[166:169], v[36:39]
	v_mfma_f32_16x16x32_bf16 v[28:31], v[218:221], v[174:177], v[28:31]
	v_mfma_f32_16x16x32_bf16 v[20:23], v[226:229], v[174:177], v[20:23]
	v_mfma_f32_16x16x32_bf16 v[12:15], v[218:221], v[188:191], v[12:15]
	v_mfma_f32_16x16x32_bf16 v[8:11], v[226:229], v[188:191], v[8:11]
	v_mfma_f32_16x16x32_bf16 v[4:7], v[218:221], v[210:213], v[4:7]
	v_mfma_f32_16x16x32_bf16 v[0:3], v[226:229], v[210:213], v[0:3]
	v_mfma_f32_16x16x32_bf16 v[44:47], v[222:225], v[170:173], v[44:47]
	v_mfma_f32_16x16x32_bf16 v[36:39], v[230:233], v[170:173], v[36:39]
	v_mfma_f32_16x16x32_bf16 v[28:31], v[222:225], v[178:181], v[28:31]
	v_mfma_f32_16x16x32_bf16 v[20:23], v[230:233], v[178:181], v[20:23]
	v_mfma_f32_16x16x32_bf16 v[12:15], v[222:225], v[206:209], v[12:15]
	v_mfma_f32_16x16x32_bf16 v[8:11], v[230:233], v[206:209], v[8:11]
	v_mfma_f32_16x16x32_bf16 v[4:7], v[222:225], v[214:217], v[4:7]
	v_mfma_f32_16x16x32_bf16 v[0:3], v[230:233], v[214:217], v[0:3]
	s_setprio 0
	s_add_i32 s66, s66, 2
	s_add_u32 s8, s8, 0x100
	s_addc_u32 s9, s9, 0
	s_add_u32 s64, s64, 0x100
	s_addc_u32 s65, s65, 0
	s_cmp_gt_u32 s66, 5
	s_barrier
	s_cbranch_scc0 .LBB0_1775
	s_branch .Lpeel_done_1775
.LBB0_1775:
	ds_read_b128 v[146:149], v141
	ds_read_b128 v[154:157], v141 offset:1024
	ds_read_b128 v[158:161], v141 offset:2048
	ds_read_b128 v[162:165], v141 offset:3072
	s_add_u32 s0, s8, 0xffea0080
	s_addc_u32 s1, s9, -1
	s_cmp_eq_u32 s66, 4
	s_cselect_b32 s37, s15, s1
	s_cselect_b32 s36, s17, s0
	s_cselect_b32 s31, s19, s65
	s_cselect_b32 s30, s18, s64
	s_mov_b32 m0, s56
	ds_read_b128 v[166:169], v142
	ds_read_b128 v[170:173], v142 offset:1024
	ds_read_b128 v[174:177], v142 offset:2048
	ds_read_b128 v[178:181], v142 offset:3072
	ds_read_b128 v[188:191], v142 offset:4096
	ds_read_b128 v[206:209], v142 offset:5120
	ds_read_b128 v[210:213], v142 offset:6144
	global_load_lds_dwordx4 v132, s[8:9]
	s_mov_b32 m0, s57
	ds_read_b128 v[214:217], v142 offset:7168
	global_load_lds_dwordx4 v134, s[8:9]
	s_waitcnt lgkmcnt(8)
	s_barrier
	s_waitcnt lgkmcnt(0)
	s_setprio 1
	v_mfma_f32_16x16x32_bf16 v[124:127], v[146:149], v[166:169], v[124:127]
	v_mfma_f32_16x16x32_bf16 v[120:123], v[158:161], v[166:169], v[120:123]
	v_mfma_f32_16x16x32_bf16 v[116:119], v[146:149], v[174:177], v[116:119]
	v_mfma_f32_16x16x32_bf16 v[112:115], v[158:161], v[174:177], v[112:115]
	v_mfma_f32_16x16x32_bf16 v[104:107], v[146:149], v[188:191], v[104:107]
	v_mfma_f32_16x16x32_bf16 v[96:99], v[158:161], v[188:191], v[96:99]
	v_mfma_f32_16x16x32_bf16 v[88:91], v[146:149], v[210:213], v[88:91]
	v_mfma_f32_16x16x32_bf16 v[80:83], v[158:161], v[210:213], v[80:83]
	v_mfma_f32_16x16x32_bf16 v[124:127], v[154:157], v[170:173], v[124:127]
	v_mfma_f32_16x16x32_bf16 v[120:123], v[162:165], v[170:173], v[120:123]
	v_mfma_f32_16x16x32_bf16 v[116:119], v[154:157], v[178:181], v[116:119]
	v_mfma_f32_16x16x32_bf16 v[112:115], v[162:165], v[178:181], v[112:115]
	v_mfma_f32_16x16x32_bf16 v[104:107], v[154:157], v[206:209], v[104:107]
	v_mfma_f32_16x16x32_bf16 v[96:99], v[162:165], v[206:209], v[96:99]
	v_mfma_f32_16x16x32_bf16 v[88:91], v[154:157], v[214:217], v[88:91]
	v_mfma_f32_16x16x32_bf16 v[80:83], v[162:165], v[214:217], v[80:83]
	s_setprio 0
	s_barrier
	s_mov_b32 m0, s58
	ds_read_b128 v[218:221], v143
	ds_read_b128 v[222:225], v143 offset:1024
	ds_read_b128 v[226:229], v143 offset:2048
	global_load_lds_dwordx4 v130, s[30:31]
	s_mov_b32 m0, s59
	ds_read_b128 v[230:233], v143 offset:3072
	global_load_lds_dwordx4 v128, s[30:31]
	s_barrier
; #define PG8_STAGE(bufoff, gbase, voff) do { _Pragma("unroll") for (int _i = 0; _i < 2; ++_i) \
;         __builtin_amdgcn_global_load_lds((const unsigned*)((const char*)(gbase) + (voff)[_i]), (LAS unsigned*)(lds + (bufoff) + ldsw + _i * 8192), 16, 0, 0); } while (0)
; #define PG8_LDA(dst, b, h) do { _Pragma("unroll") for (int m = 0; m < 4; ++m) _Pragma("unroll") for (int k = 0; k < 2; ++k) dst[m][k] = *(const LAS bf16x8*)(lds + PG8_SA(b, h) + aoff + m * 2048 + k * 1024); } while (0)
; #define PG8_LDB(dst, b, h) do { _Pragma("unroll") for (int n = 0; n < 2; ++n) _Pragma("unroll") for (int k = 0; k < 2; ++k) dst[n][k] = *(const LAS bf16x8*)(lds + PG8_SB(b, h) + boff + n * 2048 + k * 1024); } while (0)
; #define PG8_MMA(ai, bj, At, Bt) do { __builtin_amdgcn_s_setprio(1); _Pragma("unroll") for (int m = 0; m < 4; ++m) _Pragma("unroll") for (int n = 0; n < 2; ++n) _Pragma("unroll") for (int k = 0; k < 2; ++k) \
;         acc[ai][bj][m][n] = __builtin_amdgcn_mfma_f32_16x16x32_bf16(Bt[n][k], At[m][k], acc[ai][bj][m][n], 0, 0, 0); __builtin_amdgcn_s_setprio(0); } while (0)
; #define PG8_WAIT_V(n) asm volatile("s_waitcnt vmcnt(" #n ")" ::: "memory")
; #define PG8_WAIT_L(n) asm volatile("s_waitcnt lgkmcnt(" #n ")" ::: "memory")
; #define PG8_BAR __builtin_amdgcn_s_barrier()
; #define PG8_SCHED __builtin_amdgcn_sched_barrier(0)
; template <class Epi, class Sched>
; DI void gemm_phase(LAS unsigned char* lds, const Gemm g, const Sched& S, const Epi& E) {
;     ...
;             PG8_BAR; PG8_WAIT_L(0); PG8_MMA(0, 1, At, B1); PG8_BAR;
;             PG8_LDA(At, 0, 1); PG8_STAGE(PG8_SA(0, 0), a2, voffA);
;             PG8_BAR; PG8_WAIT_L(0); PG8_MMA(1, 0, At, B0); PG8_BAR; PG8_SCHED;
;             PG8_STAGE(PG8_SB(0, 1), b2 + hstep, voffB);
;             PG8_WAIT_V(6); PG8_BAR; PG8_MMA(1, 1, At, B1); PG8_BAR;
;             PG8_LDB(B0, 1, 0); PG8_SCHED; PG8_LDA(At, 1, 0); PG8_STAGE(PG8_SA(0, 1), a2 + hstep, voffA);
	s_waitcnt lgkmcnt(0)
	s_setprio 1
	v_mfma_f32_16x16x32_bf16 v[108:111], v[218:221], v[166:169], v[108:111]
	v_mfma_f32_16x16x32_bf16 v[100:103], v[226:229], v[166:169], v[100:103]
	v_mfma_f32_16x16x32_bf16 v[92:95], v[218:221], v[174:177], v[92:95]
	v_mfma_f32_16x16x32_bf16 v[84:87], v[226:229], v[174:177], v[84:87]
	v_mfma_f32_16x16x32_bf16 v[76:79], v[218:221], v[188:191], v[76:79]
	v_mfma_f32_16x16x32_bf16 v[72:75], v[226:229], v[188:191], v[72:75]
	v_mfma_f32_16x16x32_bf16 v[68:71], v[218:221], v[210:213], v[68:71]
	v_mfma_f32_16x16x32_bf16 v[64:67], v[226:229], v[210:213], v[64:67]
	v_mfma_f32_16x16x32_bf16 v[108:111], v[222:225], v[170:173], v[108:111]
	v_mfma_f32_16x16x32_bf16 v[100:103], v[230:233], v[170:173], v[100:103]
	v_mfma_f32_16x16x32_bf16 v[92:95], v[222:225], v[178:181], v[92:95]
	v_mfma_f32_16x16x32_bf16 v[84:87], v[230:233], v[178:181], v[84:87]
	v_mfma_f32_16x16x32_bf16 v[76:79], v[222:225], v[206:209], v[76:79]
	v_mfma_f32_16x16x32_bf16 v[72:75], v[230:233], v[206:209], v[72:75]
	v_mfma_f32_16x16x32_bf16 v[68:71], v[222:225], v[214:217], v[68:71]
	v_mfma_f32_16x16x32_bf16 v[64:67], v[230:233], v[214:217], v[64:67]
	s_setprio 0
	s_mov_b32 m0, s40
	s_barrier
	ds_read_b128 v[166:169], v142 offset:16384
	ds_read_b128 v[170:173], v142 offset:17408
	ds_read_b128 v[174:177], v142 offset:18432
	ds_read_b128 v[178:181], v142 offset:19456
	ds_read_b128 v[188:191], v142 offset:20480
	ds_read_b128 v[206:209], v142 offset:21504
	ds_read_b128 v[210:213], v142 offset:22528
	global_load_lds_dwordx4 v130, s[36:37]
	s_mov_b32 m0, s41
	ds_read_b128 v[214:217], v142 offset:23552
	global_load_lds_dwordx4 v128, s[36:37]
	s_barrier
	s_waitcnt lgkmcnt(0)
	s_setprio 1
	v_mfma_f32_16x16x32_bf16 v[60:63], v[146:149], v[166:169], v[60:63]
	v_mfma_f32_16x16x32_bf16 v[56:59], v[158:161], v[166:169], v[56:59]
	v_mfma_f32_16x16x32_bf16 v[52:55], v[146:149], v[174:177], v[52:55]
	v_mfma_f32_16x16x32_bf16 v[48:51], v[158:161], v[174:177], v[48:51]
	v_mfma_f32_16x16x32_bf16 v[40:43], v[146:149], v[188:191], v[40:43]
	v_mfma_f32_16x16x32_bf16 v[32:35], v[158:161], v[188:191], v[32:35]
	v_mfma_f32_16x16x32_bf16 v[24:27], v[146:149], v[210:213], v[24:27]
	v_mfma_f32_16x16x32_bf16 v[16:19], v[158:161], v[210:213], v[16:19]
	v_mfma_f32_16x16x32_bf16 v[60:63], v[154:157], v[170:173], v[60:63]
	v_mfma_f32_16x16x32_bf16 v[56:59], v[162:165], v[170:173], v[56:59]
	v_mfma_f32_16x16x32_bf16 v[52:55], v[154:157], v[178:181], v[52:55]
	v_mfma_f32_16x16x32_bf16 v[48:51], v[162:165], v[178:181], v[48:51]
	v_mfma_f32_16x16x32_bf16 v[40:43], v[154:157], v[206:209], v[40:43]
	v_mfma_f32_16x16x32_bf16 v[32:35], v[162:165], v[206:209], v[32:35]
	v_mfma_f32_16x16x32_bf16 v[24:27], v[154:157], v[214:217], v[24:27]
	v_mfma_f32_16x16x32_bf16 v[16:19], v[162:165], v[214:217], v[16:19]
	s_setprio 0
	s_barrier
	s_add_u32 s0, s30, 0x160000
	s_addc_u32 s1, s31, 0
	s_mov_b32 m0, s60
	s_nop 0
	global_load_lds_dwordx4 v130, s[0:1]
	s_mov_b32 m0, s61
	s_nop 0
	global_load_lds_dwordx4 v128, s[0:1]
	s_waitcnt vmcnt(6)
	s_barrier
	s_setprio 1
	v_mfma_f32_16x16x32_bf16 v[44:47], v[218:221], v[166:169], v[44:47]
	v_mfma_f32_16x16x32_bf16 v[36:39], v[226:229], v[166:169], v[36:39]
	v_mfma_f32_16x16x32_bf16 v[28:31], v[218:221], v[174:177], v[28:31]
	v_mfma_f32_16x16x32_bf16 v[20:23], v[226:229], v[174:177], v[20:23]
	v_mfma_f32_16x16x32_bf16 v[12:15], v[218:221], v[188:191], v[12:15]
	v_mfma_f32_16x16x32_bf16 v[8:11], v[226:229], v[188:191], v[8:11]
	v_mfma_f32_16x16x32_bf16 v[4:7], v[218:221], v[210:213], v[4:7]
	v_mfma_f32_16x16x32_bf16 v[0:3], v[226:229], v[210:213], v[0:3]
	v_mfma_f32_16x16x32_bf16 v[44:47], v[222:225], v[170:173], v[44:47]
	v_mfma_f32_16x16x32_bf16 v[36:39], v[230:233], v[170:173], v[36:39]
	v_mfma_f32_16x16x32_bf16 v[28:31], v[222:225], v[178:181], v[28:31]
	v_mfma_f32_16x16x32_bf16 v[20:23], v[230:233], v[178:181], v[20:23]
	v_mfma_f32_16x16x32_bf16 v[12:15], v[222:225], v[206:209], v[12:15]
	v_mfma_f32_16x16x32_bf16 v[8:11], v[230:233], v[206:209], v[8:11]
	v_mfma_f32_16x16x32_bf16 v[4:7], v[222:225], v[214:217], v[4:7]
	v_mfma_f32_16x16x32_bf16 v[0:3], v[230:233], v[214:217], v[0:3]
	s_setprio 0
	s_barrier
	ds_read_b128 v[146:149], v144
	ds_read_b128 v[154:157], v144 offset:1024
	ds_read_b128 v[158:161], v144 offset:2048
	ds_read_b128 v[162:165], v144 offset:3072
	s_add_u32 s0, s36, 0x160000
	s_addc_u32 s1, s37, 0
	s_mov_b32 m0, s42
	ds_read_b128 v[166:169], v142 offset:32768
	ds_read_b128 v[170:173], v142 offset:33792
	ds_read_b128 v[174:177], v142 offset:34816
	ds_read_b128 v[178:181], v142 offset:35840
	ds_read_b128 v[188:191], v142 offset:36864
	ds_read_b128 v[206:209], v142 offset:37888
	ds_read_b128 v[210:213], v142 offset:38912
	global_load_lds_dwordx4 v130, s[0:1]
	s_mov_b32 m0, s43
	ds_read_b128 v[214:217], v142 offset:39936
	global_load_lds_dwordx4 v128, s[0:1]
	s_waitcnt lgkmcnt(8)
	s_barrier
; #define PG8_STAGE(bufoff, gbase, voff) do { _Pragma("unroll") for (int _i = 0; _i < 2; ++_i) \
;         __builtin_amdgcn_global_load_lds((const unsigned*)((const char*)(gbase) + (voff)[_i]), (LAS unsigned*)(lds + (bufoff) + ldsw + _i * 8192), 16, 0, 0); } while (0)
; #define PG8_LDA(dst, b, h) do { _Pragma("unroll") for (int m = 0; m < 4; ++m) _Pragma("unroll") for (int k = 0; k < 2; ++k) dst[m][k] = *(const LAS bf16x8*)(lds + PG8_SA(b, h) + aoff + m * 2048 + k * 1024); } while (0)
; #define PG8_LDB(dst, b, h) do { _Pragma("unroll") for (int n = 0; n < 2; ++n) _Pragma("unroll") for (int k = 0; k < 2; ++k) dst[n][k] = *(const LAS bf16x8*)(lds + PG8_SB(b, h) + boff + n * 2048 + k * 1024); } while (0)
; #define PG8_MMA(ai, bj, At, Bt) do { __builtin_amdgcn_s_setprio(1); _Pragma("unroll") for (int m = 0; m < 4; ++m) _Pragma("unroll") for (int n = 0; n < 2; ++n) _Pragma("unroll") for (int k = 0; k < 2; ++k) \
;         acc[ai][bj][m][n] = __builtin_amdgcn_mfma_f32_16x16x32_bf16(Bt[n][k], At[m][k], acc[ai][bj][m][n], 0, 0, 0); __builtin_amdgcn_s_setprio(0); } while (0)
; #define PG8_WAIT_V(n) asm volatile("s_waitcnt vmcnt(" #n ")" ::: "memory")
; #define PG8_WAIT_L(n) asm volatile("s_waitcnt lgkmcnt(" #n ")" ::: "memory")
; #define PG8_BAR __builtin_amdgcn_s_barrier()
; #define PG8_SCHED __builtin_amdgcn_sched_barrier(0)
; template <class Epi, class Sched>
; DI void gemm_phase(LAS unsigned char* lds, const Gemm g, const Sched& S, const Epi& E) {
;     ...
;             PG8_WAIT_L(8); PG8_BAR; PG8_WAIT_L(0); PG8_MMA(0, 0, At, B0); PG8_BAR; PG8_SCHED;
;             PG8_LDB(B1, 1, 1); PG8_STAGE(PG8_SB(1, 0), b3, voffB);
;             PG8_BAR; PG8_WAIT_L(0); PG8_MMA(0, 1, At, B1); PG8_BAR;
;             PG8_LDA(At, 1, 1); PG8_STAGE(PG8_SA(1, 0), a3, voffA);
;             PG8_BAR; PG8_WAIT_L(0); PG8_MMA(1, 0, At, B0); PG8_BAR; PG8_SCHED;
;             PG8_STAGE(PG8_SB(1, 1), b3 + hstep, voffB);
;             PG8_WAIT_V(6); PG8_BAR; PG8_MMA(1, 1, At, B1); PG8_BAR;
	s_waitcnt lgkmcnt(0)
	s_setprio 1
	v_mfma_f32_16x16x32_bf16 v[124:127], v[146:149], v[166:169], v[124:127]
	v_mfma_f32_16x16x32_bf16 v[120:123], v[158:161], v[166:169], v[120:123]
	v_mfma_f32_16x16x32_bf16 v[116:119], v[146:149], v[174:177], v[116:119]
	v_mfma_f32_16x16x32_bf16 v[112:115], v[158:161], v[174:177], v[112:115]
	v_mfma_f32_16x16x32_bf16 v[104:107], v[146:149], v[188:191], v[104:107]
	v_mfma_f32_16x16x32_bf16 v[96:99], v[158:161], v[188:191], v[96:99]
	v_mfma_f32_16x16x32_bf16 v[88:91], v[146:149], v[210:213], v[88:91]
	v_mfma_f32_16x16x32_bf16 v[80:83], v[158:161], v[210:213], v[80:83]
	v_mfma_f32_16x16x32_bf16 v[124:127], v[154:157], v[170:173], v[124:127]
	v_mfma_f32_16x16x32_bf16 v[120:123], v[162:165], v[170:173], v[120:123]
	v_mfma_f32_16x16x32_bf16 v[116:119], v[154:157], v[178:181], v[116:119]
	v_mfma_f32_16x16x32_bf16 v[112:115], v[162:165], v[178:181], v[112:115]
	v_mfma_f32_16x16x32_bf16 v[104:107], v[154:157], v[206:209], v[104:107]
	v_mfma_f32_16x16x32_bf16 v[96:99], v[162:165], v[206:209], v[96:99]
	v_mfma_f32_16x16x32_bf16 v[88:91], v[154:157], v[214:217], v[88:91]
	v_mfma_f32_16x16x32_bf16 v[80:83], v[162:165], v[214:217], v[80:83]
	s_setprio 0
	s_barrier
	s_add_i32 s4, 0, 0x1c000
	v_add_u32_e32 v145, s4, v140
	s_add_i32 m0, s5, 0xffffff80
	ds_read_b128 v[218:221], v145
	ds_read_b128 v[222:225], v145 offset:1024
	ds_read_b128 v[226:229], v145 offset:2048
	global_load_lds_dwordx4 v130, s[30:31] offset:128
	s_add_i32 m0, s5, 0x1f80
	ds_read_b128 v[230:233], v145 offset:3072
	global_load_lds_dwordx4 v128, s[30:31] offset:128
	s_barrier
	s_waitcnt lgkmcnt(0)
	s_setprio 1
	v_mfma_f32_16x16x32_bf16 v[108:111], v[218:221], v[166:169], v[108:111]
	v_mfma_f32_16x16x32_bf16 v[100:103], v[226:229], v[166:169], v[100:103]
	v_mfma_f32_16x16x32_bf16 v[92:95], v[218:221], v[174:177], v[92:95]
	v_mfma_f32_16x16x32_bf16 v[84:87], v[226:229], v[174:177], v[84:87]
	v_mfma_f32_16x16x32_bf16 v[76:79], v[218:221], v[188:191], v[76:79]
	v_mfma_f32_16x16x32_bf16 v[72:75], v[226:229], v[188:191], v[72:75]
	v_mfma_f32_16x16x32_bf16 v[68:71], v[218:221], v[210:213], v[68:71]
	v_mfma_f32_16x16x32_bf16 v[64:67], v[226:229], v[210:213], v[64:67]
	v_mfma_f32_16x16x32_bf16 v[108:111], v[222:225], v[170:173], v[108:111]
	v_mfma_f32_16x16x32_bf16 v[100:103], v[230:233], v[170:173], v[100:103]
	v_mfma_f32_16x16x32_bf16 v[92:95], v[222:225], v[178:181], v[92:95]
	v_mfma_f32_16x16x32_bf16 v[84:87], v[230:233], v[178:181], v[84:87]
	v_mfma_f32_16x16x32_bf16 v[76:79], v[222:225], v[206:209], v[76:79]
	v_mfma_f32_16x16x32_bf16 v[72:75], v[230:233], v[206:209], v[72:75]
	v_mfma_f32_16x16x32_bf16 v[68:71], v[222:225], v[214:217], v[68:71]
	v_mfma_f32_16x16x32_bf16 v[64:67], v[230:233], v[214:217], v[64:67]
	s_setprio 0
	s_add_i32 m0, s54, 0xffffff80
	s_barrier
	ds_read_b128 v[166:169], v142 offset:49152
	ds_read_b128 v[170:173], v142 offset:50176
	ds_read_b128 v[174:177], v142 offset:51200
	ds_read_b128 v[178:181], v142 offset:52224
	ds_read_b128 v[188:191], v142 offset:53248
	ds_read_b128 v[206:209], v142 offset:54272
	ds_read_b128 v[210:213], v142 offset:55296
	global_load_lds_dwordx4 v130, s[36:37] offset:128
	s_add_i32 m0, s55, 0xffffff80
	ds_read_b128 v[214:217], v142 offset:56320
	global_load_lds_dwordx4 v128, s[36:37] offset:128
	s_barrier
	s_waitcnt lgkmcnt(0)
	s_setprio 1
	v_mfma_f32_16x16x32_bf16 v[60:63], v[146:149], v[166:169], v[60:63]
	v_mfma_f32_16x16x32_bf16 v[56:59], v[158:161], v[166:169], v[56:59]
	v_mfma_f32_16x16x32_bf16 v[52:55], v[146:149], v[174:177], v[52:55]
	v_mfma_f32_16x16x32_bf16 v[48:51], v[158:161], v[174:177], v[48:51]
	v_mfma_f32_16x16x32_bf16 v[40:43], v[146:149], v[188:191], v[40:43]
	v_mfma_f32_16x16x32_bf16 v[32:35], v[158:161], v[188:191], v[32:35]
	v_mfma_f32_16x16x32_bf16 v[24:27], v[146:149], v[210:213], v[24:27]
	v_mfma_f32_16x16x32_bf16 v[16:19], v[158:161], v[210:213], v[16:19]
	v_mfma_f32_16x16x32_bf16 v[60:63], v[154:157], v[170:173], v[60:63]
	v_mfma_f32_16x16x32_bf16 v[56:59], v[162:165], v[170:173], v[56:59]
	v_mfma_f32_16x16x32_bf16 v[52:55], v[154:157], v[178:181], v[52:55]
	v_mfma_f32_16x16x32_bf16 v[48:51], v[162:165], v[178:181], v[48:51]
	v_mfma_f32_16x16x32_bf16 v[40:43], v[154:157], v[206:209], v[40:43]
	v_mfma_f32_16x16x32_bf16 v[32:35], v[162:165], v[206:209], v[32:35]
	v_mfma_f32_16x16x32_bf16 v[24:27], v[154:157], v[214:217], v[24:27]
	v_mfma_f32_16x16x32_bf16 v[16:19], v[162:165], v[214:217], v[16:19]
	s_setprio 0
	s_barrier
	s_mov_b32 m0, s10
	s_add_u32 s0, s30, 0x160080
	s_addc_u32 s1, s31, 0
	global_load_lds_dwordx4 v130, s[0:1]
	s_add_i32 m0, s10, 0x2000
	s_nop 0
	global_load_lds_dwordx4 v128, s[0:1]
	s_waitcnt vmcnt(6)
	s_barrier
	s_setprio 1
	v_mfma_f32_16x16x32_bf16 v[44:47], v[218:221], v[166:169], v[44:47]
	v_mfma_f32_16x16x32_bf16 v[36:39], v[226:229], v[166:169], v[36:39]
	v_mfma_f32_16x16x32_bf16 v[28:31], v[218:221], v[174:177], v[28:31]
	v_mfma_f32_16x16x32_bf16 v[20:23], v[226:229], v[174:177], v[20:23]
	v_mfma_f32_16x16x32_bf16 v[12:15], v[218:221], v[188:191], v[12:15]
	v_mfma_f32_16x16x32_bf16 v[8:11], v[226:229], v[188:191], v[8:11]
	v_mfma_f32_16x16x32_bf16 v[4:7], v[218:221], v[210:213], v[4:7]
	v_mfma_f32_16x16x32_bf16 v[0:3], v[226:229], v[210:213], v[0:3]
	v_mfma_f32_16x16x32_bf16 v[44:47], v[222:225], v[170:173], v[44:47]
	v_mfma_f32_16x16x32_bf16 v[36:39], v[230:233], v[170:173], v[36:39]
	v_mfma_f32_16x16x32_bf16 v[28:31], v[222:225], v[178:181], v[28:31]
	v_mfma_f32_16x16x32_bf16 v[20:23], v[230:233], v[178:181], v[20:23]
	v_mfma_f32_16x16x32_bf16 v[12:15], v[222:225], v[206:209], v[12:15]
	v_mfma_f32_16x16x32_bf16 v[8:11], v[230:233], v[206:209], v[8:11]
	v_mfma_f32_16x16x32_bf16 v[4:7], v[222:225], v[214:217], v[4:7]
	v_mfma_f32_16x16x32_bf16 v[0:3], v[230:233], v[214:217], v[0:3]
	s_setprio 0
	s_add_i32 s66, s66, 2
	s_add_u32 s8, s8, 0x100
	s_addc_u32 s9, s9, 0
	s_add_u32 s64, s64, 0x100
	s_addc_u32 s65, s65, 0
	s_cmp_gt_u32 s66, 5
	s_barrier
	s_cbranch_scc0 .LBB0_1775
